# loop-edge edit: in all compiled GEMM k-loops the trailing MFMAs of a k-tile are issued before the vmcnt(0)+s_barrier instead of after it
# baseline (speedup 1.0000x reference)
; #define MFMA(a, b, c) __builtin_amdgcn_mfma_f32_32x32x16_bf16((a), (b), (c), 0, 0, 0)
; #define TIDX opaque_tid()
; template <int AI, int BI>
; DI void gemm_tile(const u16* __restrict__ A, int lda, const u16* __restrict__ B, int ldb, int nk, bool swap,
;                   f32x16 (&acc)[AI][BI], char* lds) {
;   const int tid = TIDX, lane = tid & 63, wid = tid >> 6;
;   gemm_stage<AI, BI>(A, lda, B, ldb, lds, tid);
;   asm volatile("s_waitcnt vmcnt(0)" ::: "memory");
;   __syncthreads();
;   const int wa = wid >> 1, wb = wid & 1, r = lane & 31, h = lane >> 5, sw = (r >> 1) & 7;
;   const int offA = (swap ? 16384 : 0) + (wa * 32 * AI + r) * 128;
;   const int offB = (swap ? 0 : 16384) + (wb * 32 * BI + r) * 128;
;   for (int kt = 0; kt < nk; ++kt) {
;     const char* cur = lds + (kt & 1) * 32768;
;     if (kt + 1 < nk) gemm_stage<AI, BI>(A + (kt + 1) * 64, lda, B + (kt + 1) * 64, ldb, lds + ((kt + 1) & 1) * 32768, tid);
; #pragma unroll
;     for (int ks = 0; ks < 4; ++ks) {
;       const int co = ((ks * 2 + h) ^ sw) << 4;
;       s16x8 fa[AI], fb[BI];
; #pragma unroll
;       for (int i = 0; i < AI; ++i) fa[i] = *(const s16x8*)(cur + offA + i * 4096 + co);
; #pragma unroll
;       for (int i = 0; i < BI; ++i) fb[i] = *(const s16x8*)(cur + offB + i * 4096 + co);
; #pragma unroll
;       for (int i = 0; i < AI; ++i)
; #pragma unroll
;         for (int j = 0; j < BI; ++j) acc[i][j] = MFMA(fa[i], fb[j], acc[i][j]);
;     }
;     asm volatile("s_waitcnt vmcnt(0)" ::: "memory");
;     __syncthreads();
.LBB0_419:
	s_and_b32 s16, s14, 0xffff
	s_mul_hi_u32 s17, s16, 0xba2e8c
	s_mul_i32 s16, s16, 0xba2f
	s_mulk_i32 s17, 0x160
	s_lshr_b32 s16, s16, 24
	s_sub_i32 s17, s14, s17
	s_lshl_b32 s16, s16, 10
	s_and_b32 s18, s15, 0x380
	s_ashr_i32 s17, s17, 3
	s_or_b32 s16, s16, s18
	s_lshl_b32 s28, s17, 7
	s_waitcnt vmcnt(2)
	v_mov_b32_e32 v82, v178
	v_mov_b32_e32 v83, v178
	s_lshl_b32 s18, s16, 11
	v_mov_b32_e32 v12, v178
	s_add_u32 s34, s10, s18
	s_addc_u32 s35, s11, 0
	v_lshrrev_b32_e32 v0, 4, v12
	s_ashr_i32 s29, s28, 31
	v_xor_b32_e32 v0, v0, v12
	v_add_u32_e32 v8, 0x100, v12
	v_add_u32_e32 v10, 0x200, v12
	v_add_u32_e32 v13, 0x300, v12
	s_lshl_b64 s[28:29], s[28:29], 11
	v_lshlrev_b32_e32 v0, 4, v0
	v_ashrrev_i32_e32 v4, 3, v12
	v_ashrrev_i32_e32 v6, 3, v8
	v_lshlrev_b32_e32 v99, 4, v8
	v_ashrrev_i32_e32 v8, 3, v10
	v_lshlrev_b32_e32 v100, 4, v10
	v_ashrrev_i32_e32 v10, 3, v13
	s_add_u32 s28, s12, s28
	v_and_b32_e32 v0, 0x70, v0
	v_ashrrev_i32_e32 v5, 31, v4
	v_ashrrev_i32_e32 v7, 31, v6
	v_ashrrev_i32_e32 v9, 31, v8
	v_ashrrev_i32_e32 v11, 31, v10
	s_addc_u32 s29, s13, s29
	v_lshl_add_u64 v[2:3], s[34:35], 0, v[0:1]
	v_lshlrev_b64 v[4:5], 11, v[4:5]
	v_lshlrev_b32_e32 v95, 4, v12
	v_lshlrev_b64 v[6:7], 11, v[6:7]
	v_lshlrev_b64 v[8:9], 11, v[8:9]
	v_lshlrev_b64 v[10:11], 11, v[10:11]
	v_lshl_add_u64 v[66:67], v[2:3], 0, v[4:5]
	v_lshl_add_u64 v[68:69], v[2:3], 0, v[6:7]
	v_lshl_add_u64 v[70:71], v[2:3], 0, v[8:9]
	v_lshl_add_u64 v[72:73], v[2:3], 0, v[10:11]
	v_lshl_add_u64 v[2:3], s[28:29], 0, v[0:1]
	v_add_u32_e32 v0, 0x4000, v95
	v_readfirstlane_b32 s37, v95
	v_readfirstlane_b32 s28, v0
	v_add_u32_e32 v0, 0x4000, v99
	s_mov_b32 m0, s37
	v_readfirstlane_b32 s48, v99
	v_lshlrev_b32_e32 v101, 4, v13
	v_readfirstlane_b32 s29, v0
	v_add_u32_e32 v0, 0x4000, v100
	global_load_lds_dwordx4 v[66:67], off
	s_mov_b32 m0, s48
	v_readfirstlane_b32 s51, v100
	v_readfirstlane_b32 s34, v0
	v_add_u32_e32 v0, 0x4000, v101
	global_load_lds_dwordx4 v[68:69], off
	s_mov_b32 m0, s51
	v_readfirstlane_b32 s52, v101
	v_lshl_add_u64 v[74:75], v[2:3], 0, v[4:5]
	v_readfirstlane_b32 s35, v0
	v_and_b32_e32 v0, 31, v12
	v_lshrrev_b32_e32 v4, 1, v12
	global_load_lds_dwordx4 v[70:71], off
	s_mov_b32 m0, s52
	v_and_or_b32 v0, v4, s54, v0
	global_load_lds_dwordx4 v[72:73], off
	s_mov_b32 m0, s28
	v_lshl_add_u64 v[76:77], v[2:3], 0, v[6:7]
	v_lshl_add_u64 v[78:79], v[2:3], 0, v[8:9]
	v_lshl_add_u64 v[80:81], v[2:3], 0, v[10:11]
	v_lshrrev_b32_e32 v2, 5, v12
	v_bfe_u32 v5, v12, 1, 3
	v_lshlrev_b32_e32 v85, 7, v0
	v_lshlrev_b32_e32 v0, 7, v12
	global_load_lds_dwordx4 v[74:75], off
	s_mov_b32 m0, s29
	v_bfe_u32 v3, v12, 5, 1
	v_and_b32_e32 v87, 0x2f80, v0
	v_bitop3_b32 v0, v2, v5, 1 bitop3:0x6c
	global_load_lds_dwordx4 v[76:77], off
	s_mov_b32 m0, s34
	v_lshlrev_b32_e32 v6, 4, v0
	v_bitop3_b32 v0, v3, v5, 2 bitop3:0x36
	v_add_u32_e32 v91, 0x8000, v95
	global_load_lds_dwordx4 v[78:79], off
	s_mov_b32 m0, s35
	v_lshlrev_b32_e32 v84, 4, v0
	v_bitop3_b32 v0, v3, v5, 4 bitop3:0x36
	v_readfirstlane_b32 s36, v91
	v_add_u32_e32 v92, 0x8000, v99
	global_load_lds_dwordx4 v[80:81], off
	v_lshlrev_b32_e32 v118, 4, v0
	v_bitop3_b32 v0, v3, v5, 6 bitop3:0x36
	v_lshl_add_u64 v[2:3], v[66:67], 0, s[64:65]
	s_mov_b32 m0, s36
	v_readfirstlane_b32 s40, v92
	v_add_u32_e32 v93, 0x8000, v100
	s_waitcnt vmcnt(0)
	s_waitcnt vmcnt(0) lgkmcnt(0)
	s_barrier
	global_load_lds_dwordx4 v[2:3], off
	v_lshl_add_u64 v[2:3], v[68:69], 0, s[64:65]
	s_mov_b32 m0, s40
	v_readfirstlane_b32 s41, v93
	v_add_u32_e32 v94, 0x8000, v101
	global_load_lds_dwordx4 v[2:3], off
	v_lshl_add_u64 v[2:3], v[70:71], 0, s[64:65]
	s_mov_b32 m0, s41
	v_readfirstlane_b32 s46, v94
	v_add_u32_e32 v96, 0xc000, v95
	global_load_lds_dwordx4 v[2:3], off
	v_lshl_add_u64 v[2:3], v[72:73], 0, s[64:65]
	s_mov_b32 m0, s46
	v_readfirstlane_b32 s47, v96
	v_add_u32_e32 v97, 0xc000, v99
	global_load_lds_dwordx4 v[2:3], off
	v_lshl_add_u64 v[2:3], v[74:75], 0, s[64:65]
	s_mov_b32 m0, s47
	v_readfirstlane_b32 s49, v97
	v_add_u32_e32 v98, 0xc000, v100
	v_lshlrev_b32_e32 v119, 4, v0
	global_load_lds_dwordx4 v[2:3], off
	v_lshl_add_u64 v[2:3], v[76:77], 0, s[64:65]
	s_mov_b32 m0, s49
	v_readfirstlane_b32 s50, v98
	v_add_u32_e32 v0, 0xc000, v101
	global_load_lds_dwordx4 v[2:3], off
	v_lshl_add_u64 v[2:3], v[78:79], 0, s[64:65]
	s_mov_b32 m0, s50
	v_readfirstlane_b32 s18, v0
	global_load_lds_dwordx4 v[2:3], off
	v_lshl_add_u64 v[2:3], v[80:81], 0, s[64:65]
	s_mov_b32 m0, s18
	v_or_b32_e32 v0, v85, v6
	global_load_lds_dwordx4 v[2:3], off
	v_or_b32_e32 v86, v87, v6
	ds_read_b128 v[2:5], v0
	ds_read_b128 v[18:21], v0 offset:4096
	ds_read_b128 v[6:9], v86 offset:16384
	ds_read_b128 v[22:25], v86 offset:20480
	s_waitcnt lgkmcnt(0)
	v_mfma_f32_32x32x16_bf16 v[34:49], v[2:5], v[6:9], 0
	v_or_b32_e32 v88, v85, v84
	v_or_b32_e32 v89, v87, v84
	ds_read_b128 v[102:105], v88
	ds_read_b128 v[106:109], v88 offset:4096
	ds_read_b128 v[110:113], v89 offset:16384
	ds_read_b128 v[114:117], v89 offset:20480
	v_or_b32_e32 v90, v85, v118
	v_or_b32_e32 v84, v87, v118
	v_or_b32_e32 v85, v85, v119
	v_mfma_f32_32x32x16_bf16 v[50:65], v[2:5], v[22:25], 0
	v_or_b32_e32 v87, v87, v119
	s_mov_b32 m0, s37
	s_lshl_b32 s17, s17, 6
	v_mfma_f32_32x32x16_bf16 v[2:17], v[18:21], v[6:9], 0
	v_mfma_f32_32x32x16_bf16 v[18:33], v[18:21], v[22:25], 0
	s_waitcnt lgkmcnt(1)
	v_mfma_f32_32x32x16_bf16 v[34:49], v[102:105], v[110:113], v[34:49]
	s_waitcnt lgkmcnt(0)
	v_mfma_f32_32x32x16_bf16 v[50:65], v[102:105], v[114:117], v[50:65]
	v_mfma_f32_32x32x16_bf16 v[2:17], v[106:109], v[110:113], v[2:17]
	v_mfma_f32_32x32x16_bf16 v[18:33], v[106:109], v[114:117], v[18:33]
	ds_read_b128 v[102:105], v90
	ds_read_b128 v[106:109], v90 offset:4096
	ds_read_b128 v[110:113], v84 offset:16384
	ds_read_b128 v[114:117], v84 offset:20480
	s_waitcnt lgkmcnt(1)
	v_mfma_f32_32x32x16_bf16 v[34:49], v[102:105], v[110:113], v[34:49]
	s_waitcnt lgkmcnt(0)
	v_mfma_f32_32x32x16_bf16 v[50:65], v[102:105], v[114:117], v[50:65]
	v_mfma_f32_32x32x16_bf16 v[2:17], v[106:109], v[110:113], v[2:17]
	v_mfma_f32_32x32x16_bf16 v[18:33], v[106:109], v[114:117], v[18:33]
	ds_read_b128 v[102:105], v85
	ds_read_b128 v[106:109], v85 offset:4096
	ds_read_b128 v[110:113], v87 offset:16384
	ds_read_b128 v[114:117], v87 offset:20480
	s_waitcnt lgkmcnt(0)
	v_mfma_f32_32x32x16_bf16 v[34:49], v[102:105], v[110:113], v[34:49]
	v_mfma_f32_32x32x16_bf16 v[50:65], v[102:105], v[114:117], v[50:65]
	s_waitcnt vmcnt(0)
	s_barrier
; #define MFMA(a, b, c) __builtin_amdgcn_mfma_f32_32x32x16_bf16((a), (b), (c), 0, 0, 0)
; template <int AI, int BI>
; DI void gemm_tile(const u16* __restrict__ A, int lda, const u16* __restrict__ B, int ldb, int nk, bool swap,
;                   f32x16 (&acc)[AI][BI], char* lds) {
;     ...
;   for (int kt = 0; kt < nk; ++kt) {
;     const char* cur = lds + (kt & 1) * 32768;
;     if (kt + 1 < nk) gemm_stage<AI, BI>(A + (kt + 1) * 64, lda, B + (kt + 1) * 64, ldb, lds + ((kt + 1) & 1) * 32768, tid);
; #pragma unroll
;     for (int ks = 0; ks < 4; ++ks) {
;       const int co = ((ks * 2 + h) ^ sw) << 4;
;       s16x8 fa[AI], fb[BI];
; #pragma unroll
;       for (int i = 0; i < AI; ++i) fa[i] = *(const s16x8*)(cur + offA + i * 4096 + co);
; #pragma unroll
;       for (int i = 0; i < BI; ++i) fb[i] = *(const s16x8*)(cur + offB + i * 4096 + co);
; #pragma unroll
;       for (int i = 0; i < AI; ++i)
; #pragma unroll
;         for (int j = 0; j < BI; ++j) acc[i][j] = MFMA(fa[i], fb[j], acc[i][j]);
;     }
;     asm volatile("s_waitcnt vmcnt(0)" ::: "memory");
;     __syncthreads();
	v_lshl_add_u64 v[102:103], v[66:67], 0, s[4:5]
	global_load_lds_dwordx4 v[102:103], off
	v_lshl_add_u64 v[102:103], v[68:69], 0, s[4:5]
	s_mov_b32 m0, s48
	s_nop 0
	global_load_lds_dwordx4 v[102:103], off
	v_lshl_add_u64 v[102:103], v[70:71], 0, s[4:5]
	s_mov_b32 m0, s51
	v_mfma_f32_32x32x16_bf16 v[2:17], v[106:109], v[110:113], v[2:17]
	global_load_lds_dwordx4 v[102:103], off
	v_lshl_add_u64 v[102:103], v[72:73], 0, s[4:5]
	s_mov_b32 m0, s52
	s_nop 0
	global_load_lds_dwordx4 v[102:103], off
	v_lshl_add_u64 v[102:103], v[74:75], 0, s[4:5]
	s_mov_b32 m0, s28
	v_mfma_f32_32x32x16_bf16 v[18:33], v[106:109], v[114:117], v[18:33]
	global_load_lds_dwordx4 v[102:103], off
	v_lshl_add_u64 v[102:103], v[76:77], 0, s[4:5]
	s_mov_b32 m0, s29
	s_nop 0
	global_load_lds_dwordx4 v[102:103], off
	v_lshl_add_u64 v[102:103], v[78:79], 0, s[4:5]
	s_mov_b32 m0, s34
	s_nop 0
	global_load_lds_dwordx4 v[102:103], off
	v_lshl_add_u64 v[102:103], v[80:81], 0, s[4:5]
	s_mov_b32 m0, s35
	s_nop 0
	global_load_lds_dwordx4 v[102:103], off
	ds_read_b128 v[102:105], v0 offset:32768
	ds_read_b128 v[106:109], v0 offset:36864
	ds_read_b128 v[110:113], v86 offset:49152
	ds_read_b128 v[114:117], v86 offset:53248
	s_waitcnt lgkmcnt(0)
	v_mfma_f32_32x32x16_bf16 v[34:49], v[102:105], v[110:113], v[34:49]
	s_mov_b32 m0, s36
	v_mfma_f32_32x32x16_bf16 v[50:65], v[102:105], v[114:117], v[50:65]
	v_mfma_f32_32x32x16_bf16 v[2:17], v[106:109], v[110:113], v[2:17]
	v_mfma_f32_32x32x16_bf16 v[18:33], v[106:109], v[114:117], v[18:33]
	ds_read_b128 v[102:105], v88 offset:32768
	ds_read_b128 v[106:109], v88 offset:36864
	ds_read_b128 v[110:113], v89 offset:49152
	ds_read_b128 v[114:117], v89 offset:53248
	s_waitcnt lgkmcnt(1)
	v_mfma_f32_32x32x16_bf16 v[34:49], v[102:105], v[110:113], v[34:49]
	s_waitcnt lgkmcnt(0)
	v_mfma_f32_32x32x16_bf16 v[50:65], v[102:105], v[114:117], v[50:65]
	v_mfma_f32_32x32x16_bf16 v[2:17], v[106:109], v[110:113], v[2:17]
	v_mfma_f32_32x32x16_bf16 v[18:33], v[106:109], v[114:117], v[18:33]
	ds_read_b128 v[102:105], v90 offset:32768
	ds_read_b128 v[106:109], v90 offset:36864
	ds_read_b128 v[110:113], v84 offset:49152
	ds_read_b128 v[114:117], v84 offset:53248
	s_waitcnt lgkmcnt(1)
	v_mfma_f32_32x32x16_bf16 v[34:49], v[102:105], v[110:113], v[34:49]
	s_waitcnt lgkmcnt(0)
	v_mfma_f32_32x32x16_bf16 v[50:65], v[102:105], v[114:117], v[50:65]
	v_mfma_f32_32x32x16_bf16 v[2:17], v[106:109], v[110:113], v[2:17]
	v_mfma_f32_32x32x16_bf16 v[18:33], v[106:109], v[114:117], v[18:33]
	ds_read_b128 v[102:105], v85 offset:32768
	ds_read_b128 v[106:109], v85 offset:36864
	ds_read_b128 v[110:113], v87 offset:49152
	ds_read_b128 v[114:117], v87 offset:53248
	s_waitcnt lgkmcnt(0)
	v_mfma_f32_32x32x16_bf16 v[34:49], v[102:105], v[110:113], v[34:49]
	v_mfma_f32_32x32x16_bf16 v[50:65], v[102:105], v[114:117], v[50:65]
	s_waitcnt vmcnt(0)
	s_barrier
	v_lshl_add_u64 v[102:103], v[66:67], 0, s[66:67]
	global_load_lds_dwordx4 v[102:103], off
	v_lshl_add_u64 v[102:103], v[68:69], 0, s[66:67]
	s_mov_b32 m0, s40
	s_nop 0
	global_load_lds_dwordx4 v[102:103], off
	v_lshl_add_u64 v[102:103], v[70:71], 0, s[66:67]
	s_mov_b32 m0, s41
	v_mfma_f32_32x32x16_bf16 v[2:17], v[106:109], v[110:113], v[2:17]
	global_load_lds_dwordx4 v[102:103], off
	v_lshl_add_u64 v[102:103], v[72:73], 0, s[66:67]
	s_mov_b32 m0, s46
	s_nop 0
	global_load_lds_dwordx4 v[102:103], off
	v_lshl_add_u64 v[102:103], v[74:75], 0, s[66:67]
	s_mov_b32 m0, s47
	v_mfma_f32_32x32x16_bf16 v[18:33], v[106:109], v[114:117], v[18:33]
	global_load_lds_dwordx4 v[102:103], off
	v_lshl_add_u64 v[102:103], v[76:77], 0, s[66:67]
	s_mov_b32 m0, s49
	s_nop 0
	global_load_lds_dwordx4 v[102:103], off
	v_lshl_add_u64 v[102:103], v[78:79], 0, s[66:67]
	s_mov_b32 m0, s50
	s_nop 0
	global_load_lds_dwordx4 v[102:103], off
	v_lshl_add_u64 v[102:103], v[80:81], 0, s[66:67]
	s_mov_b32 m0, s18
	s_nop 0
	global_load_lds_dwordx4 v[102:103], off
	ds_read_b128 v[102:105], v0
	ds_read_b128 v[106:109], v0 offset:4096
	ds_read_b128 v[110:113], v86 offset:16384
	ds_read_b128 v[114:117], v86 offset:20480
	s_waitcnt lgkmcnt(0)
	v_mfma_f32_32x32x16_bf16 v[34:49], v[102:105], v[110:113], v[34:49]
	s_mov_b32 m0, s37
	v_mfma_f32_32x32x16_bf16 v[50:65], v[102:105], v[114:117], v[50:65]
	v_mfma_f32_32x32x16_bf16 v[2:17], v[106:109], v[110:113], v[2:17]
	v_mfma_f32_32x32x16_bf16 v[18:33], v[106:109], v[114:117], v[18:33]
	ds_read_b128 v[102:105], v88
	ds_read_b128 v[106:109], v88 offset:4096
	ds_read_b128 v[110:113], v89 offset:16384
	ds_read_b128 v[114:117], v89 offset:20480
	s_waitcnt lgkmcnt(1)
	v_mfma_f32_32x32x16_bf16 v[34:49], v[102:105], v[110:113], v[34:49]
	s_waitcnt lgkmcnt(0)
	v_mfma_f32_32x32x16_bf16 v[50:65], v[102:105], v[114:117], v[50:65]
	v_mfma_f32_32x32x16_bf16 v[2:17], v[106:109], v[110:113], v[2:17]
	v_mfma_f32_32x32x16_bf16 v[18:33], v[106:109], v[114:117], v[18:33]
	ds_read_b128 v[102:105], v90
	ds_read_b128 v[106:109], v90 offset:4096
	ds_read_b128 v[110:113], v84 offset:16384
	ds_read_b128 v[114:117], v84 offset:20480
	s_waitcnt lgkmcnt(1)
	v_mfma_f32_32x32x16_bf16 v[34:49], v[102:105], v[110:113], v[34:49]
	s_waitcnt lgkmcnt(0)
	v_mfma_f32_32x32x16_bf16 v[50:65], v[102:105], v[114:117], v[50:65]
	v_mfma_f32_32x32x16_bf16 v[2:17], v[106:109], v[110:113], v[2:17]
	v_mfma_f32_32x32x16_bf16 v[18:33], v[106:109], v[114:117], v[18:33]
	ds_read_b128 v[102:105], v85
	ds_read_b128 v[106:109], v85 offset:4096
	ds_read_b128 v[110:113], v87 offset:16384
	ds_read_b128 v[114:117], v87 offset:20480
	s_waitcnt lgkmcnt(0)
	v_mfma_f32_32x32x16_bf16 v[34:49], v[102:105], v[110:113], v[34:49]
	v_mfma_f32_32x32x16_bf16 v[50:65], v[102:105], v[114:117], v[50:65]
	s_waitcnt vmcnt(0)
	s_barrier
; #define MFMA(a, b, c) __builtin_amdgcn_mfma_f32_32x32x16_bf16((a), (b), (c), 0, 0, 0)
; template <int AI, int BI>
; DI void gemm_tile(const u16* __restrict__ A, int lda, const u16* __restrict__ B, int ldb, int nk, bool swap,
;                   f32x16 (&acc)[AI][BI], char* lds) {
;     ...
;   for (int kt = 0; kt < nk; ++kt) {
;     const char* cur = lds + (kt & 1) * 32768;
;     if (kt + 1 < nk) gemm_stage<AI, BI>(A + (kt + 1) * 64, lda, B + (kt + 1) * 64, ldb, lds + ((kt + 1) & 1) * 32768, tid);
; #pragma unroll
;     for (int ks = 0; ks < 4; ++ks) {
;       const int co = ((ks * 2 + h) ^ sw) << 4;
;       s16x8 fa[AI], fb[BI];
; #pragma unroll
;       for (int i = 0; i < AI; ++i) fa[i] = *(const s16x8*)(cur + offA + i * 4096 + co);
; #pragma unroll
;       for (int i = 0; i < BI; ++i) fb[i] = *(const s16x8*)(cur + offB + i * 4096 + co);
; #pragma unroll
;       for (int i = 0; i < AI; ++i)
; #pragma unroll
;         for (int j = 0; j < BI; ++j) acc[i][j] = MFMA(fa[i], fb[j], acc[i][j]);
;     }
;     asm volatile("s_waitcnt vmcnt(0)" ::: "memory");
;     __syncthreads();
	v_lshl_add_u64 v[102:103], v[66:67], 0, s[56:57]
	global_load_lds_dwordx4 v[102:103], off
	v_lshl_add_u64 v[102:103], v[68:69], 0, s[56:57]
	s_mov_b32 m0, s48
	s_nop 0
	global_load_lds_dwordx4 v[102:103], off
	v_lshl_add_u64 v[102:103], v[70:71], 0, s[56:57]
	s_mov_b32 m0, s51
	v_mfma_f32_32x32x16_bf16 v[2:17], v[106:109], v[110:113], v[2:17]
	global_load_lds_dwordx4 v[102:103], off
	v_lshl_add_u64 v[102:103], v[72:73], 0, s[56:57]
	s_mov_b32 m0, s52
	s_nop 0
	global_load_lds_dwordx4 v[102:103], off
	v_lshl_add_u64 v[102:103], v[74:75], 0, s[56:57]
	s_mov_b32 m0, s28
	v_mfma_f32_32x32x16_bf16 v[18:33], v[106:109], v[114:117], v[18:33]
	global_load_lds_dwordx4 v[102:103], off
	v_lshl_add_u64 v[102:103], v[76:77], 0, s[56:57]
	s_mov_b32 m0, s29
	s_nop 0
	global_load_lds_dwordx4 v[102:103], off
	v_lshl_add_u64 v[102:103], v[78:79], 0, s[56:57]
	s_mov_b32 m0, s34
	s_nop 0
	global_load_lds_dwordx4 v[102:103], off
	v_lshl_add_u64 v[102:103], v[80:81], 0, s[56:57]
	s_mov_b32 m0, s35
	s_nop 0
	global_load_lds_dwordx4 v[102:103], off
	ds_read_b128 v[102:105], v0 offset:32768
	ds_read_b128 v[106:109], v0 offset:36864
	ds_read_b128 v[110:113], v86 offset:49152
	ds_read_b128 v[114:117], v86 offset:53248
	s_waitcnt lgkmcnt(0)
	v_mfma_f32_32x32x16_bf16 v[34:49], v[102:105], v[110:113], v[34:49]
	s_mov_b32 m0, s36
	v_mfma_f32_32x32x16_bf16 v[50:65], v[102:105], v[114:117], v[50:65]
	v_mfma_f32_32x32x16_bf16 v[2:17], v[106:109], v[110:113], v[2:17]
	v_mfma_f32_32x32x16_bf16 v[18:33], v[106:109], v[114:117], v[18:33]
	ds_read_b128 v[102:105], v88 offset:32768
	ds_read_b128 v[106:109], v88 offset:36864
	ds_read_b128 v[110:113], v89 offset:49152
	ds_read_b128 v[114:117], v89 offset:53248
	s_waitcnt lgkmcnt(1)
	v_mfma_f32_32x32x16_bf16 v[34:49], v[102:105], v[110:113], v[34:49]
	s_waitcnt lgkmcnt(0)
	v_mfma_f32_32x32x16_bf16 v[50:65], v[102:105], v[114:117], v[50:65]
	v_mfma_f32_32x32x16_bf16 v[2:17], v[106:109], v[110:113], v[2:17]
	v_mfma_f32_32x32x16_bf16 v[18:33], v[106:109], v[114:117], v[18:33]
	ds_read_b128 v[102:105], v90 offset:32768
	ds_read_b128 v[106:109], v90 offset:36864
	ds_read_b128 v[110:113], v84 offset:49152
	ds_read_b128 v[114:117], v84 offset:53248
	s_waitcnt lgkmcnt(1)
	v_mfma_f32_32x32x16_bf16 v[34:49], v[102:105], v[110:113], v[34:49]
	s_waitcnt lgkmcnt(0)
	v_mfma_f32_32x32x16_bf16 v[50:65], v[102:105], v[114:117], v[50:65]
	v_mfma_f32_32x32x16_bf16 v[2:17], v[106:109], v[110:113], v[2:17]
	v_mfma_f32_32x32x16_bf16 v[18:33], v[106:109], v[114:117], v[18:33]
	ds_read_b128 v[102:105], v85 offset:32768
	ds_read_b128 v[106:109], v85 offset:36864
	ds_read_b128 v[110:113], v87 offset:49152
	ds_read_b128 v[114:117], v87 offset:53248
	s_waitcnt lgkmcnt(0)
	v_mfma_f32_32x32x16_bf16 v[34:49], v[102:105], v[110:113], v[34:49]
	v_mfma_f32_32x32x16_bf16 v[50:65], v[102:105], v[114:117], v[50:65]
	s_waitcnt vmcnt(0)
	s_barrier
	v_lshl_add_u64 v[102:103], v[66:67], 0, s[68:69]
	global_load_lds_dwordx4 v[102:103], off
	v_lshl_add_u64 v[102:103], v[68:69], 0, s[68:69]
	s_mov_b32 m0, s40
	s_nop 0
	global_load_lds_dwordx4 v[102:103], off
	v_lshl_add_u64 v[102:103], v[70:71], 0, s[68:69]
	s_mov_b32 m0, s41
	v_mfma_f32_32x32x16_bf16 v[2:17], v[106:109], v[110:113], v[2:17]
	global_load_lds_dwordx4 v[102:103], off
	v_lshl_add_u64 v[102:103], v[72:73], 0, s[68:69]
	s_mov_b32 m0, s46
	s_nop 0
	global_load_lds_dwordx4 v[102:103], off
	v_lshl_add_u64 v[102:103], v[74:75], 0, s[68:69]
	s_mov_b32 m0, s47
	v_mfma_f32_32x32x16_bf16 v[18:33], v[106:109], v[114:117], v[18:33]
	global_load_lds_dwordx4 v[102:103], off
	v_lshl_add_u64 v[102:103], v[76:77], 0, s[68:69]
	s_mov_b32 m0, s49
	s_nop 0
	global_load_lds_dwordx4 v[102:103], off
	v_lshl_add_u64 v[102:103], v[78:79], 0, s[68:69]
	s_mov_b32 m0, s50
	s_nop 0
	global_load_lds_dwordx4 v[102:103], off
	v_lshl_add_u64 v[102:103], v[80:81], 0, s[68:69]
	s_mov_b32 m0, s18
	s_nop 0
	global_load_lds_dwordx4 v[102:103], off
	ds_read_b128 v[102:105], v0
	ds_read_b128 v[106:109], v0 offset:4096
	ds_read_b128 v[110:113], v86 offset:16384
	ds_read_b128 v[114:117], v86 offset:20480
	s_waitcnt lgkmcnt(0)
	v_mfma_f32_32x32x16_bf16 v[34:49], v[102:105], v[110:113], v[34:49]
	s_mov_b32 m0, s37
	v_readfirstlane_b32 s37, v99
	v_mfma_f32_32x32x16_bf16 v[50:65], v[102:105], v[114:117], v[50:65]
	v_mfma_f32_32x32x16_bf16 v[2:17], v[106:109], v[110:113], v[2:17]
	v_mfma_f32_32x32x16_bf16 v[18:33], v[106:109], v[114:117], v[18:33]
	ds_read_b128 v[102:105], v88
	ds_read_b128 v[106:109], v88 offset:4096
	ds_read_b128 v[110:113], v89 offset:16384
	ds_read_b128 v[114:117], v89 offset:20480
	s_waitcnt lgkmcnt(1)
	v_mfma_f32_32x32x16_bf16 v[34:49], v[102:105], v[110:113], v[34:49]
	s_waitcnt lgkmcnt(0)
	v_mfma_f32_32x32x16_bf16 v[50:65], v[102:105], v[114:117], v[50:65]
	v_mfma_f32_32x32x16_bf16 v[2:17], v[106:109], v[110:113], v[2:17]
	v_mfma_f32_32x32x16_bf16 v[18:33], v[106:109], v[114:117], v[18:33]
	ds_read_b128 v[102:105], v90
	ds_read_b128 v[106:109], v90 offset:4096
	ds_read_b128 v[110:113], v84 offset:16384
	ds_read_b128 v[114:117], v84 offset:20480
	s_waitcnt lgkmcnt(1)
	v_mfma_f32_32x32x16_bf16 v[34:49], v[102:105], v[110:113], v[34:49]
	s_waitcnt lgkmcnt(0)
	v_mfma_f32_32x32x16_bf16 v[50:65], v[102:105], v[114:117], v[50:65]
	v_mfma_f32_32x32x16_bf16 v[2:17], v[106:109], v[110:113], v[2:17]
	v_mfma_f32_32x32x16_bf16 v[18:33], v[106:109], v[114:117], v[18:33]
	ds_read_b128 v[102:105], v85
	ds_read_b128 v[106:109], v85 offset:4096
	ds_read_b128 v[110:113], v87 offset:16384
	ds_read_b128 v[114:117], v87 offset:20480
	s_waitcnt lgkmcnt(0)
	v_mfma_f32_32x32x16_bf16 v[34:49], v[102:105], v[110:113], v[34:49]
	v_mfma_f32_32x32x16_bf16 v[50:65], v[102:105], v[114:117], v[50:65]
	s_waitcnt vmcnt(0)
	s_barrier
; #define MFMA(a, b, c) __builtin_amdgcn_mfma_f32_32x32x16_bf16((a), (b), (c), 0, 0, 0)
; template <int AI, int BI>
; DI void gemm_tile(const u16* __restrict__ A, int lda, const u16* __restrict__ B, int ldb, int nk, bool swap,
;                   f32x16 (&acc)[AI][BI], char* lds) {
;     ...
;   for (int kt = 0; kt < nk; ++kt) {
;     const char* cur = lds + (kt & 1) * 32768;
;     if (kt + 1 < nk) gemm_stage<AI, BI>(A + (kt + 1) * 64, lda, B + (kt + 1) * 64, ldb, lds + ((kt + 1) & 1) * 32768, tid);
; #pragma unroll
;     for (int ks = 0; ks < 4; ++ks) {
;       const int co = ((ks * 2 + h) ^ sw) << 4;
;       s16x8 fa[AI], fb[BI];
; #pragma unroll
;       for (int i = 0; i < AI; ++i) fa[i] = *(const s16x8*)(cur + offA + i * 4096 + co);
; #pragma unroll
;       for (int i = 0; i < BI; ++i) fb[i] = *(const s16x8*)(cur + offB + i * 4096 + co);
; #pragma unroll
;       for (int i = 0; i < AI; ++i)
; #pragma unroll
;         for (int j = 0; j < BI; ++j) acc[i][j] = MFMA(fa[i], fb[j], acc[i][j]);
;     }
;     asm volatile("s_waitcnt vmcnt(0)" ::: "memory");
;     __syncthreads();
	v_lshl_add_u64 v[102:103], v[66:67], 0, s[70:71]
	global_load_lds_dwordx4 v[102:103], off
	v_lshl_add_u64 v[102:103], v[68:69], 0, s[70:71]
	s_mov_b32 m0, s48
	v_readfirstlane_b32 s48, v93
	global_load_lds_dwordx4 v[102:103], off
	v_lshl_add_u64 v[102:103], v[70:71], 0, s[70:71]
	s_mov_b32 m0, s51
	v_mfma_f32_32x32x16_bf16 v[2:17], v[106:109], v[110:113], v[2:17]
	global_load_lds_dwordx4 v[102:103], off
	v_lshl_add_u64 v[102:103], v[72:73], 0, s[70:71]
	s_mov_b32 m0, s52
	v_readfirstlane_b32 s51, v97
	global_load_lds_dwordx4 v[102:103], off
	v_lshl_add_u64 v[102:103], v[74:75], 0, s[70:71]
	s_mov_b32 m0, s28
	v_mfma_f32_32x32x16_bf16 v[18:33], v[106:109], v[114:117], v[18:33]
	global_load_lds_dwordx4 v[102:103], off
	v_lshl_add_u64 v[102:103], v[76:77], 0, s[70:71]
	s_mov_b32 m0, s29
	v_readfirstlane_b32 s52, v98
	global_load_lds_dwordx4 v[102:103], off
	v_lshl_add_u64 v[102:103], v[78:79], 0, s[70:71]
	s_mov_b32 m0, s34
	s_nop 0
	global_load_lds_dwordx4 v[102:103], off
	v_lshl_add_u64 v[102:103], v[80:81], 0, s[70:71]
	s_mov_b32 m0, s35
	s_nop 0
	global_load_lds_dwordx4 v[102:103], off
	ds_read_b128 v[102:105], v0 offset:32768
	ds_read_b128 v[106:109], v0 offset:36864
	ds_read_b128 v[110:113], v86 offset:49152
	ds_read_b128 v[114:117], v86 offset:53248
	s_waitcnt lgkmcnt(0)
	v_mfma_f32_32x32x16_bf16 v[34:49], v[102:105], v[110:113], v[34:49]
	s_mov_b32 m0, s36
	v_readfirstlane_b32 s36, v95
	v_mfma_f32_32x32x16_bf16 v[50:65], v[102:105], v[114:117], v[50:65]
	v_mfma_f32_32x32x16_bf16 v[2:17], v[106:109], v[110:113], v[2:17]
	v_mfma_f32_32x32x16_bf16 v[18:33], v[106:109], v[114:117], v[18:33]
	ds_read_b128 v[102:105], v88 offset:32768
	ds_read_b128 v[106:109], v88 offset:36864
	ds_read_b128 v[110:113], v89 offset:49152
	ds_read_b128 v[114:117], v89 offset:53248
	s_waitcnt lgkmcnt(1)
	v_mfma_f32_32x32x16_bf16 v[34:49], v[102:105], v[110:113], v[34:49]
	s_waitcnt lgkmcnt(0)
	v_mfma_f32_32x32x16_bf16 v[50:65], v[102:105], v[114:117], v[50:65]
	v_mfma_f32_32x32x16_bf16 v[2:17], v[106:109], v[110:113], v[2:17]
	v_mfma_f32_32x32x16_bf16 v[18:33], v[106:109], v[114:117], v[18:33]
	ds_read_b128 v[102:105], v90 offset:32768
	ds_read_b128 v[106:109], v90 offset:36864
	ds_read_b128 v[110:113], v84 offset:49152
	ds_read_b128 v[114:117], v84 offset:53248
	s_waitcnt lgkmcnt(1)
	v_mfma_f32_32x32x16_bf16 v[34:49], v[102:105], v[110:113], v[34:49]
	s_waitcnt lgkmcnt(0)
	v_mfma_f32_32x32x16_bf16 v[50:65], v[102:105], v[114:117], v[50:65]
	v_mfma_f32_32x32x16_bf16 v[2:17], v[106:109], v[110:113], v[2:17]
	v_mfma_f32_32x32x16_bf16 v[18:33], v[106:109], v[114:117], v[18:33]
	ds_read_b128 v[102:105], v85 offset:32768
	ds_read_b128 v[106:109], v85 offset:36864
	ds_read_b128 v[110:113], v87 offset:49152
	ds_read_b128 v[114:117], v87 offset:53248
	s_waitcnt lgkmcnt(0)
	v_mfma_f32_32x32x16_bf16 v[34:49], v[102:105], v[110:113], v[34:49]
	v_mfma_f32_32x32x16_bf16 v[50:65], v[102:105], v[114:117], v[50:65]
	s_waitcnt vmcnt(0)
	s_barrier
	v_lshl_add_u64 v[102:103], v[66:67], 0, s[72:73]
	global_load_lds_dwordx4 v[102:103], off
	v_lshl_add_u64 v[102:103], v[68:69], 0, s[72:73]
	s_mov_b32 m0, s40
	v_readfirstlane_b32 s40, v100
	global_load_lds_dwordx4 v[102:103], off
	v_lshl_add_u64 v[102:103], v[70:71], 0, s[72:73]
	s_mov_b32 m0, s41
	v_mfma_f32_32x32x16_bf16 v[2:17], v[106:109], v[110:113], v[2:17]
	global_load_lds_dwordx4 v[102:103], off
	v_lshl_add_u64 v[102:103], v[72:73], 0, s[72:73]
	s_mov_b32 m0, s46
	v_readfirstlane_b32 s41, v101
	global_load_lds_dwordx4 v[102:103], off
	v_lshl_add_u64 v[102:103], v[74:75], 0, s[72:73]
	s_mov_b32 m0, s47
	v_mfma_f32_32x32x16_bf16 v[18:33], v[106:109], v[114:117], v[18:33]
	global_load_lds_dwordx4 v[102:103], off
	v_lshl_add_u64 v[102:103], v[76:77], 0, s[72:73]
	s_mov_b32 m0, s49
	v_lshl_add_u64 v[100:101], v[74:75], 0, s[74:75]
	global_load_lds_dwordx4 v[102:103], off
	v_lshl_add_u64 v[102:103], v[78:79], 0, s[72:73]
	s_mov_b32 m0, s50
	v_readfirstlane_b32 s46, v91
	global_load_lds_dwordx4 v[102:103], off
	v_lshl_add_u64 v[102:103], v[80:81], 0, s[72:73]
	s_mov_b32 m0, s18
	v_readfirstlane_b32 s47, v92
	global_load_lds_dwordx4 v[102:103], off
	ds_read_b128 v[102:105], v0
	ds_read_b128 v[106:109], v0 offset:4096
	ds_read_b128 v[110:113], v86 offset:16384
	ds_read_b128 v[114:117], v86 offset:20480
	s_waitcnt lgkmcnt(0)
	v_mfma_f32_32x32x16_bf16 v[34:49], v[102:105], v[110:113], v[34:49]
	s_mov_b32 m0, s36
	v_readfirstlane_b32 s49, v94
	v_lshl_add_u64 v[92:93], v[72:73], 0, s[76:77]
	v_readfirstlane_b32 s50, v96
	v_and_b32_e32 v91, 31, v82
	v_mfma_f32_32x32x16_bf16 v[50:65], v[102:105], v[114:117], v[50:65]
	v_mfma_f32_32x32x16_bf16 v[2:17], v[106:109], v[110:113], v[2:17]
	v_mfma_f32_32x32x16_bf16 v[18:33], v[106:109], v[114:117], v[18:33]
	ds_read_b128 v[102:105], v88
	ds_read_b128 v[106:109], v88 offset:4096
	ds_read_b128 v[110:113], v89 offset:16384
	ds_read_b128 v[114:117], v89 offset:20480
	s_waitcnt lgkmcnt(1)
	v_mfma_f32_32x32x16_bf16 v[34:49], v[102:105], v[110:113], v[34:49]
	s_waitcnt lgkmcnt(0)
	v_mfma_f32_32x32x16_bf16 v[50:65], v[102:105], v[114:117], v[50:65]
	v_mfma_f32_32x32x16_bf16 v[2:17], v[106:109], v[110:113], v[2:17]
	v_mfma_f32_32x32x16_bf16 v[18:33], v[106:109], v[114:117], v[18:33]
	ds_read_b128 v[102:105], v90
	ds_read_b128 v[106:109], v90 offset:4096
	ds_read_b128 v[110:113], v84 offset:16384
	ds_read_b128 v[114:117], v84 offset:20480
	s_waitcnt lgkmcnt(1)
	v_mfma_f32_32x32x16_bf16 v[34:49], v[102:105], v[110:113], v[34:49]
	s_waitcnt lgkmcnt(0)
	v_mfma_f32_32x32x16_bf16 v[50:65], v[102:105], v[114:117], v[50:65]
	v_mfma_f32_32x32x16_bf16 v[2:17], v[106:109], v[110:113], v[2:17]
	v_mfma_f32_32x32x16_bf16 v[18:33], v[106:109], v[114:117], v[18:33]
	ds_read_b128 v[102:105], v85
	ds_read_b128 v[106:109], v85 offset:4096
	ds_read_b128 v[110:113], v87 offset:16384
	ds_read_b128 v[114:117], v87 offset:20480
	s_waitcnt lgkmcnt(0)
	v_mfma_f32_32x32x16_bf16 v[34:49], v[102:105], v[110:113], v[34:49]
	v_mfma_f32_32x32x16_bf16 v[50:65], v[102:105], v[114:117], v[50:65]
	s_waitcnt vmcnt(0)
	s_barrier
; #define MFMA(a, b, c) __builtin_amdgcn_mfma_f32_32x32x16_bf16((a), (b), (c), 0, 0, 0)
; template <int AI, int BI>
; DI void gemm_tile(const u16* __restrict__ A, int lda, const u16* __restrict__ B, int ldb, int nk, bool swap,
;                   f32x16 (&acc)[AI][BI], char* lds) {
;     ...
;   for (int kt = 0; kt < nk; ++kt) {
;     const char* cur = lds + (kt & 1) * 32768;
;     if (kt + 1 < nk) gemm_stage<AI, BI>(A + (kt + 1) * 64, lda, B + (kt + 1) * 64, ldb, lds + ((kt + 1) & 1) * 32768, tid);
; #pragma unroll
;     for (int ks = 0; ks < 4; ++ks) {
;       const int co = ((ks * 2 + h) ^ sw) << 4;
;       s16x8 fa[AI], fb[BI];
; #pragma unroll
;       for (int i = 0; i < AI; ++i) fa[i] = *(const s16x8*)(cur + offA + i * 4096 + co);
; #pragma unroll
;       for (int i = 0; i < BI; ++i) fb[i] = *(const s16x8*)(cur + offB + i * 4096 + co);
; #pragma unroll
;       for (int i = 0; i < AI; ++i)
; #pragma unroll
;         for (int j = 0; j < BI; ++j) acc[i][j] = MFMA(fa[i], fb[j], acc[i][j]);
;     }
;     asm volatile("s_waitcnt vmcnt(0)" ::: "memory");
;     __syncthreads();
	v_lshl_add_u64 v[102:103], v[66:67], 0, s[74:75]
	global_load_lds_dwordx4 v[102:103], off
	v_lshl_add_u64 v[102:103], v[68:69], 0, s[74:75]
	s_mov_b32 m0, s37
	s_nop 0
	global_load_lds_dwordx4 v[102:103], off
	v_lshl_add_u64 v[102:103], v[70:71], 0, s[74:75]
	s_mov_b32 m0, s40
	v_mfma_f32_32x32x16_bf16 v[2:17], v[106:109], v[110:113], v[2:17]
	global_load_lds_dwordx4 v[102:103], off
	v_lshl_add_u64 v[102:103], v[72:73], 0, s[74:75]
	s_mov_b32 m0, s41
	s_nop 0
	global_load_lds_dwordx4 v[102:103], off
	s_mov_b32 m0, s28
	v_mfma_f32_32x32x16_bf16 v[18:33], v[106:109], v[114:117], v[18:33]
	global_load_lds_dwordx4 v[100:101], off
	v_lshl_add_u64 v[100:101], v[76:77], 0, s[74:75]
	s_mov_b32 m0, s29
	s_nop 0
	global_load_lds_dwordx4 v[100:101], off
	v_lshl_add_u64 v[100:101], v[78:79], 0, s[74:75]
	s_mov_b32 m0, s34
	s_nop 0
	global_load_lds_dwordx4 v[100:101], off
	v_lshl_add_u64 v[100:101], v[80:81], 0, s[74:75]
	s_mov_b32 m0, s35
	s_nop 0
	global_load_lds_dwordx4 v[100:101], off
	ds_read_b128 v[100:103], v0 offset:32768
	ds_read_b128 v[104:107], v0 offset:36864
	ds_read_b128 v[108:111], v86 offset:49152
	ds_read_b128 v[112:115], v86 offset:53248
	s_waitcnt lgkmcnt(0)
	v_mfma_f32_32x32x16_bf16 v[34:49], v[100:103], v[108:111], v[34:49]
	s_mov_b32 m0, s46
	v_mfma_f32_32x32x16_bf16 v[50:65], v[100:103], v[112:115], v[50:65]
	v_mfma_f32_32x32x16_bf16 v[2:17], v[104:107], v[108:111], v[2:17]
	v_mfma_f32_32x32x16_bf16 v[18:33], v[104:107], v[112:115], v[18:33]
	ds_read_b128 v[100:103], v88 offset:32768
	ds_read_b128 v[104:107], v88 offset:36864
	ds_read_b128 v[108:111], v89 offset:49152
	ds_read_b128 v[112:115], v89 offset:53248
	s_waitcnt lgkmcnt(1)
	v_mfma_f32_32x32x16_bf16 v[34:49], v[100:103], v[108:111], v[34:49]
	s_waitcnt lgkmcnt(0)
	v_mfma_f32_32x32x16_bf16 v[50:65], v[100:103], v[112:115], v[50:65]
	v_mfma_f32_32x32x16_bf16 v[2:17], v[104:107], v[108:111], v[2:17]
	v_mfma_f32_32x32x16_bf16 v[18:33], v[104:107], v[112:115], v[18:33]
	ds_read_b128 v[100:103], v90 offset:32768
	ds_read_b128 v[104:107], v90 offset:36864
	ds_read_b128 v[108:111], v84 offset:49152
	ds_read_b128 v[112:115], v84 offset:53248
	s_waitcnt lgkmcnt(1)
	v_mfma_f32_32x32x16_bf16 v[34:49], v[100:103], v[108:111], v[34:49]
	s_waitcnt lgkmcnt(0)
	v_mfma_f32_32x32x16_bf16 v[50:65], v[100:103], v[112:115], v[50:65]
	v_mfma_f32_32x32x16_bf16 v[2:17], v[104:107], v[108:111], v[2:17]
	v_mfma_f32_32x32x16_bf16 v[18:33], v[104:107], v[112:115], v[18:33]
	ds_read_b128 v[100:103], v85 offset:32768
	ds_read_b128 v[104:107], v85 offset:36864
	ds_read_b128 v[108:111], v87 offset:49152
	ds_read_b128 v[112:115], v87 offset:53248
	s_waitcnt lgkmcnt(0)
	v_mfma_f32_32x32x16_bf16 v[34:49], v[100:103], v[108:111], v[34:49]
	v_mfma_f32_32x32x16_bf16 v[50:65], v[100:103], v[112:115], v[50:65]
	s_waitcnt vmcnt(0)
	s_barrier
	v_lshl_add_u64 v[100:101], v[66:67], 0, s[76:77]
	global_load_lds_dwordx4 v[100:101], off
	v_lshl_add_u64 v[100:101], v[68:69], 0, s[76:77]
	s_mov_b32 m0, s47
	s_nop 0
	global_load_lds_dwordx4 v[100:101], off
	v_lshl_add_u64 v[100:101], v[70:71], 0, s[76:77]
	s_mov_b32 m0, s48
	v_mfma_f32_32x32x16_bf16 v[2:17], v[104:107], v[108:111], v[2:17]
	global_load_lds_dwordx4 v[100:101], off
	s_mov_b32 m0, s49
	s_nop 0
	global_load_lds_dwordx4 v[92:93], off
	v_lshl_add_u64 v[92:93], v[74:75], 0, s[76:77]
	s_mov_b32 m0, s50
	v_mfma_f32_32x32x16_bf16 v[18:33], v[104:107], v[112:115], v[18:33]
	global_load_lds_dwordx4 v[92:93], off
	v_lshl_add_u64 v[92:93], v[76:77], 0, s[76:77]
	s_mov_b32 m0, s51
	s_nop 0
	global_load_lds_dwordx4 v[92:93], off
	v_lshl_add_u64 v[92:93], v[78:79], 0, s[76:77]
	s_mov_b32 m0, s52
	s_nop 0
	global_load_lds_dwordx4 v[92:93], off
	v_lshl_add_u64 v[92:93], v[80:81], 0, s[76:77]
	s_mov_b32 m0, s18
	s_nop 0
	global_load_lds_dwordx4 v[92:93], off
	ds_read_b128 v[92:95], v0
	ds_read_b128 v[96:99], v0 offset:4096
	ds_read_b128 v[100:103], v86 offset:16384
	ds_read_b128 v[104:107], v86 offset:20480
	s_waitcnt lgkmcnt(0)
	v_mfma_f32_32x32x16_bf16 v[34:49], v[92:95], v[100:103], v[34:49]
	s_mov_b32 m0, s36
	v_mfma_f32_32x32x16_bf16 v[50:65], v[92:95], v[104:107], v[50:65]
	v_mfma_f32_32x32x16_bf16 v[2:17], v[96:99], v[100:103], v[2:17]
	v_mfma_f32_32x32x16_bf16 v[18:33], v[96:99], v[104:107], v[18:33]
	ds_read_b128 v[92:95], v88
	ds_read_b128 v[96:99], v88 offset:4096
	ds_read_b128 v[100:103], v89 offset:16384
	ds_read_b128 v[104:107], v89 offset:20480
	s_waitcnt lgkmcnt(1)
	v_mfma_f32_32x32x16_bf16 v[34:49], v[92:95], v[100:103], v[34:49]
	s_waitcnt lgkmcnt(0)
	v_mfma_f32_32x32x16_bf16 v[50:65], v[92:95], v[104:107], v[50:65]
	v_mfma_f32_32x32x16_bf16 v[2:17], v[96:99], v[100:103], v[2:17]
	v_mfma_f32_32x32x16_bf16 v[18:33], v[96:99], v[104:107], v[18:33]
	ds_read_b128 v[92:95], v90
	ds_read_b128 v[96:99], v90 offset:4096
	ds_read_b128 v[100:103], v84 offset:16384
	ds_read_b128 v[104:107], v84 offset:20480
	s_waitcnt lgkmcnt(1)
	v_mfma_f32_32x32x16_bf16 v[34:49], v[92:95], v[100:103], v[34:49]
	s_waitcnt lgkmcnt(0)
	v_mfma_f32_32x32x16_bf16 v[50:65], v[92:95], v[104:107], v[50:65]
	v_mfma_f32_32x32x16_bf16 v[2:17], v[96:99], v[100:103], v[2:17]
	v_mfma_f32_32x32x16_bf16 v[18:33], v[96:99], v[104:107], v[18:33]
	ds_read_b128 v[92:95], v85
	ds_read_b128 v[96:99], v85 offset:4096
	ds_read_b128 v[100:103], v87 offset:16384
	ds_read_b128 v[104:107], v87 offset:20480
	s_waitcnt lgkmcnt(0)
	v_mfma_f32_32x32x16_bf16 v[34:49], v[92:95], v[100:103], v[34:49]
	v_mfma_f32_32x32x16_bf16 v[50:65], v[92:95], v[104:107], v[50:65]
	s_waitcnt vmcnt(0)
	s_barrier
; #define MFMA(a, b, c) __builtin_amdgcn_mfma_f32_32x32x16_bf16((a), (b), (c), 0, 0, 0)
; template <int AI, int BI>
; DI void gemm_tile(const u16* __restrict__ A, int lda, const u16* __restrict__ B, int ldb, int nk, bool swap,
;                   f32x16 (&acc)[AI][BI], char* lds) {
;     ...
;   for (int kt = 0; kt < nk; ++kt) {
;     const char* cur = lds + (kt & 1) * 32768;
;     if (kt + 1 < nk) gemm_stage<AI, BI>(A + (kt + 1) * 64, lda, B + (kt + 1) * 64, ldb, lds + ((kt + 1) & 1) * 32768, tid);
; #pragma unroll
;     for (int ks = 0; ks < 4; ++ks) {
;       const int co = ((ks * 2 + h) ^ sw) << 4;
;       s16x8 fa[AI], fb[BI];
; #pragma unroll
;       for (int i = 0; i < AI; ++i) fa[i] = *(const s16x8*)(cur + offA + i * 4096 + co);
; #pragma unroll
;       for (int i = 0; i < BI; ++i) fb[i] = *(const s16x8*)(cur + offB + i * 4096 + co);
; #pragma unroll
;       for (int i = 0; i < AI; ++i)
; #pragma unroll
;         for (int j = 0; j < BI; ++j) acc[i][j] = MFMA(fa[i], fb[j], acc[i][j]);
;     }
;     asm volatile("s_waitcnt vmcnt(0)" ::: "memory");
;     __syncthreads();
	v_lshl_add_u64 v[92:93], v[66:67], 0, s[80:81]
	global_load_lds_dwordx4 v[92:93], off
	v_lshl_add_u64 v[92:93], v[68:69], 0, s[80:81]
	s_mov_b32 m0, s37
	s_nop 0
	global_load_lds_dwordx4 v[92:93], off
	v_lshl_add_u64 v[92:93], v[70:71], 0, s[80:81]
	s_mov_b32 m0, s40
	v_mfma_f32_32x32x16_bf16 v[2:17], v[96:99], v[100:103], v[2:17]
	global_load_lds_dwordx4 v[92:93], off
	v_lshl_add_u64 v[92:93], v[72:73], 0, s[80:81]
	s_mov_b32 m0, s41
	s_nop 0
	global_load_lds_dwordx4 v[92:93], off
	v_lshl_add_u64 v[92:93], v[74:75], 0, s[80:81]
	s_mov_b32 m0, s28
	v_mfma_f32_32x32x16_bf16 v[18:33], v[96:99], v[104:107], v[18:33]
	global_load_lds_dwordx4 v[92:93], off
	v_lshl_add_u64 v[92:93], v[76:77], 0, s[80:81]
	s_mov_b32 m0, s29
	s_nop 0
	global_load_lds_dwordx4 v[92:93], off
	v_lshl_add_u64 v[92:93], v[78:79], 0, s[80:81]
	s_mov_b32 m0, s34
	s_nop 0
	global_load_lds_dwordx4 v[92:93], off
	v_lshl_add_u64 v[92:93], v[80:81], 0, s[80:81]
	s_mov_b32 m0, s35
	s_nop 0
	global_load_lds_dwordx4 v[92:93], off
	ds_read_b128 v[92:95], v0 offset:32768
	ds_read_b128 v[96:99], v0 offset:36864
	ds_read_b128 v[100:103], v86 offset:49152
	ds_read_b128 v[104:107], v86 offset:53248
	s_waitcnt lgkmcnt(0)
	v_mfma_f32_32x32x16_bf16 v[34:49], v[92:95], v[100:103], v[34:49]
	s_mov_b32 m0, s46
	v_mfma_f32_32x32x16_bf16 v[50:65], v[92:95], v[104:107], v[50:65]
	v_mfma_f32_32x32x16_bf16 v[2:17], v[96:99], v[100:103], v[2:17]
	v_mfma_f32_32x32x16_bf16 v[18:33], v[96:99], v[104:107], v[18:33]
	ds_read_b128 v[92:95], v88 offset:32768
	ds_read_b128 v[96:99], v88 offset:36864
	ds_read_b128 v[100:103], v89 offset:49152
	ds_read_b128 v[104:107], v89 offset:53248
	s_waitcnt lgkmcnt(1)
	v_mfma_f32_32x32x16_bf16 v[34:49], v[92:95], v[100:103], v[34:49]
	s_waitcnt lgkmcnt(0)
	v_mfma_f32_32x32x16_bf16 v[50:65], v[92:95], v[104:107], v[50:65]
	v_mfma_f32_32x32x16_bf16 v[2:17], v[96:99], v[100:103], v[2:17]
	v_mfma_f32_32x32x16_bf16 v[18:33], v[96:99], v[104:107], v[18:33]
	ds_read_b128 v[92:95], v90 offset:32768
	ds_read_b128 v[96:99], v90 offset:36864
	ds_read_b128 v[100:103], v84 offset:49152
	ds_read_b128 v[104:107], v84 offset:53248
	s_waitcnt lgkmcnt(1)
	v_mfma_f32_32x32x16_bf16 v[34:49], v[92:95], v[100:103], v[34:49]
	s_waitcnt lgkmcnt(0)
	v_mfma_f32_32x32x16_bf16 v[50:65], v[92:95], v[104:107], v[50:65]
	v_mfma_f32_32x32x16_bf16 v[2:17], v[96:99], v[100:103], v[2:17]
	v_mfma_f32_32x32x16_bf16 v[18:33], v[96:99], v[104:107], v[18:33]
	ds_read_b128 v[92:95], v85 offset:32768
	ds_read_b128 v[96:99], v85 offset:36864
	ds_read_b128 v[100:103], v87 offset:49152
	ds_read_b128 v[104:107], v87 offset:53248
	s_waitcnt lgkmcnt(0)
	v_mfma_f32_32x32x16_bf16 v[34:49], v[92:95], v[100:103], v[34:49]
	v_mfma_f32_32x32x16_bf16 v[50:65], v[92:95], v[104:107], v[50:65]
	s_waitcnt vmcnt(0)
	s_barrier
	v_lshl_add_u64 v[92:93], v[66:67], 0, s[82:83]
	global_load_lds_dwordx4 v[92:93], off
	v_lshl_add_u64 v[92:93], v[68:69], 0, s[82:83]
	s_mov_b32 m0, s47
	s_nop 0
	global_load_lds_dwordx4 v[92:93], off
	v_lshl_add_u64 v[92:93], v[70:71], 0, s[82:83]
	s_mov_b32 m0, s48
	v_mfma_f32_32x32x16_bf16 v[2:17], v[96:99], v[100:103], v[2:17]
	global_load_lds_dwordx4 v[92:93], off
	v_lshl_add_u64 v[92:93], v[72:73], 0, s[82:83]
	s_mov_b32 m0, s49
	s_nop 0
	global_load_lds_dwordx4 v[92:93], off
	v_lshl_add_u64 v[92:93], v[74:75], 0, s[82:83]
	s_mov_b32 m0, s50
	v_mfma_f32_32x32x16_bf16 v[18:33], v[96:99], v[104:107], v[18:33]
	global_load_lds_dwordx4 v[92:93], off
	v_lshl_add_u64 v[92:93], v[76:77], 0, s[82:83]
	s_mov_b32 m0, s51
	s_nop 0
	global_load_lds_dwordx4 v[92:93], off
	v_lshl_add_u64 v[92:93], v[78:79], 0, s[82:83]
	s_mov_b32 m0, s52
	s_nop 0
	global_load_lds_dwordx4 v[92:93], off
	v_lshl_add_u64 v[92:93], v[80:81], 0, s[82:83]
	s_mov_b32 m0, s18
	s_nop 0
	global_load_lds_dwordx4 v[92:93], off
	ds_read_b128 v[92:95], v0
	ds_read_b128 v[96:99], v0 offset:4096
	ds_read_b128 v[100:103], v86 offset:16384
	ds_read_b128 v[104:107], v86 offset:20480
	s_waitcnt lgkmcnt(0)
	v_mfma_f32_32x32x16_bf16 v[34:49], v[92:95], v[100:103], v[34:49]
	s_mov_b32 m0, s36
	v_mfma_f32_32x32x16_bf16 v[50:65], v[92:95], v[104:107], v[50:65]
	v_mfma_f32_32x32x16_bf16 v[2:17], v[96:99], v[100:103], v[2:17]
	v_mfma_f32_32x32x16_bf16 v[18:33], v[96:99], v[104:107], v[18:33]
	ds_read_b128 v[92:95], v88
	ds_read_b128 v[96:99], v88 offset:4096
	ds_read_b128 v[100:103], v89 offset:16384
	ds_read_b128 v[104:107], v89 offset:20480
	s_waitcnt lgkmcnt(1)
	v_mfma_f32_32x32x16_bf16 v[34:49], v[92:95], v[100:103], v[34:49]
	s_waitcnt lgkmcnt(0)
	v_mfma_f32_32x32x16_bf16 v[50:65], v[92:95], v[104:107], v[50:65]
	v_mfma_f32_32x32x16_bf16 v[2:17], v[96:99], v[100:103], v[2:17]
	v_mfma_f32_32x32x16_bf16 v[18:33], v[96:99], v[104:107], v[18:33]
	ds_read_b128 v[92:95], v90
	ds_read_b128 v[96:99], v90 offset:4096
	ds_read_b128 v[100:103], v84 offset:16384
	ds_read_b128 v[104:107], v84 offset:20480
	s_waitcnt lgkmcnt(1)
	v_mfma_f32_32x32x16_bf16 v[34:49], v[92:95], v[100:103], v[34:49]
	s_waitcnt lgkmcnt(0)
	v_mfma_f32_32x32x16_bf16 v[50:65], v[92:95], v[104:107], v[50:65]
	v_mfma_f32_32x32x16_bf16 v[2:17], v[96:99], v[100:103], v[2:17]
	v_mfma_f32_32x32x16_bf16 v[18:33], v[96:99], v[104:107], v[18:33]
	ds_read_b128 v[92:95], v85
	ds_read_b128 v[96:99], v85 offset:4096
	ds_read_b128 v[100:103], v87 offset:16384
	ds_read_b128 v[104:107], v87 offset:20480
	s_waitcnt lgkmcnt(0)
	v_mfma_f32_32x32x16_bf16 v[34:49], v[92:95], v[100:103], v[34:49]
	v_mfma_f32_32x32x16_bf16 v[50:65], v[92:95], v[104:107], v[50:65]
	s_waitcnt vmcnt(0)
	s_barrier
; #define MFMA(a, b, c) __builtin_amdgcn_mfma_f32_32x32x16_bf16((a), (b), (c), 0, 0, 0)
; template <int AI, int BI>
; DI void gemm_tile(const u16* __restrict__ A, int lda, const u16* __restrict__ B, int ldb, int nk, bool swap,
;                   f32x16 (&acc)[AI][BI], char* lds) {
;     ...
;   for (int kt = 0; kt < nk; ++kt) {
;     const char* cur = lds + (kt & 1) * 32768;
;     if (kt + 1 < nk) gemm_stage<AI, BI>(A + (kt + 1) * 64, lda, B + (kt + 1) * 64, ldb, lds + ((kt + 1) & 1) * 32768, tid);
; #pragma unroll
;     for (int ks = 0; ks < 4; ++ks) {
;       const int co = ((ks * 2 + h) ^ sw) << 4;
;       s16x8 fa[AI], fb[BI];
; #pragma unroll
;       for (int i = 0; i < AI; ++i) fa[i] = *(const s16x8*)(cur + offA + i * 4096 + co);
; #pragma unroll
;       for (int i = 0; i < BI; ++i) fb[i] = *(const s16x8*)(cur + offB + i * 4096 + co);
; #pragma unroll
;       for (int i = 0; i < AI; ++i)
; #pragma unroll
;         for (int j = 0; j < BI; ++j) acc[i][j] = MFMA(fa[i], fb[j], acc[i][j]);
;     }
;     asm volatile("s_waitcnt vmcnt(0)" ::: "memory");
;     __syncthreads();
	v_lshl_add_u64 v[92:93], v[66:67], 0, s[84:85]
	global_load_lds_dwordx4 v[92:93], off
	v_lshl_add_u64 v[92:93], v[68:69], 0, s[84:85]
	s_mov_b32 m0, s37
	s_nop 0
	global_load_lds_dwordx4 v[92:93], off
	v_lshl_add_u64 v[92:93], v[70:71], 0, s[84:85]
	s_mov_b32 m0, s40
	v_mfma_f32_32x32x16_bf16 v[2:17], v[96:99], v[100:103], v[2:17]
	global_load_lds_dwordx4 v[92:93], off
	v_lshl_add_u64 v[92:93], v[72:73], 0, s[84:85]
	s_mov_b32 m0, s41
	s_nop 0
	global_load_lds_dwordx4 v[92:93], off
	v_lshl_add_u64 v[92:93], v[74:75], 0, s[84:85]
	s_mov_b32 m0, s28
	v_mfma_f32_32x32x16_bf16 v[18:33], v[96:99], v[104:107], v[18:33]
	global_load_lds_dwordx4 v[92:93], off
	v_lshl_add_u64 v[92:93], v[76:77], 0, s[84:85]
	s_mov_b32 m0, s29
	s_nop 0
	global_load_lds_dwordx4 v[92:93], off
	v_lshl_add_u64 v[92:93], v[78:79], 0, s[84:85]
	s_mov_b32 m0, s34
	s_nop 0
	global_load_lds_dwordx4 v[92:93], off
	v_lshl_add_u64 v[92:93], v[80:81], 0, s[84:85]
	s_mov_b32 m0, s35
	s_nop 0
	global_load_lds_dwordx4 v[92:93], off
	ds_read_b128 v[92:95], v0 offset:32768
	ds_read_b128 v[96:99], v0 offset:36864
	ds_read_b128 v[100:103], v86 offset:49152
	ds_read_b128 v[104:107], v86 offset:53248
	s_waitcnt lgkmcnt(0)
	v_mfma_f32_32x32x16_bf16 v[34:49], v[92:95], v[100:103], v[34:49]
	s_mov_b32 m0, s46
	v_mfma_f32_32x32x16_bf16 v[50:65], v[92:95], v[104:107], v[50:65]
	v_mfma_f32_32x32x16_bf16 v[2:17], v[96:99], v[100:103], v[2:17]
	v_mfma_f32_32x32x16_bf16 v[18:33], v[96:99], v[104:107], v[18:33]
	ds_read_b128 v[92:95], v88 offset:32768
	ds_read_b128 v[96:99], v88 offset:36864
	ds_read_b128 v[100:103], v89 offset:49152
	ds_read_b128 v[104:107], v89 offset:53248
	s_waitcnt lgkmcnt(1)
	v_mfma_f32_32x32x16_bf16 v[34:49], v[92:95], v[100:103], v[34:49]
	s_waitcnt lgkmcnt(0)
	v_mfma_f32_32x32x16_bf16 v[50:65], v[92:95], v[104:107], v[50:65]
	v_mfma_f32_32x32x16_bf16 v[2:17], v[96:99], v[100:103], v[2:17]
	v_mfma_f32_32x32x16_bf16 v[18:33], v[96:99], v[104:107], v[18:33]
	ds_read_b128 v[92:95], v90 offset:32768
	ds_read_b128 v[96:99], v90 offset:36864
	ds_read_b128 v[100:103], v84 offset:49152
	ds_read_b128 v[104:107], v84 offset:53248
	s_waitcnt lgkmcnt(1)
	v_mfma_f32_32x32x16_bf16 v[34:49], v[92:95], v[100:103], v[34:49]
	s_waitcnt lgkmcnt(0)
	v_mfma_f32_32x32x16_bf16 v[50:65], v[92:95], v[104:107], v[50:65]
	v_mfma_f32_32x32x16_bf16 v[2:17], v[96:99], v[100:103], v[2:17]
	v_mfma_f32_32x32x16_bf16 v[18:33], v[96:99], v[104:107], v[18:33]
	ds_read_b128 v[92:95], v85 offset:32768
	ds_read_b128 v[96:99], v85 offset:36864
	ds_read_b128 v[100:103], v87 offset:49152
	ds_read_b128 v[104:107], v87 offset:53248
	s_waitcnt lgkmcnt(0)
	v_mfma_f32_32x32x16_bf16 v[34:49], v[92:95], v[100:103], v[34:49]
	v_mfma_f32_32x32x16_bf16 v[50:65], v[92:95], v[104:107], v[50:65]
	s_waitcnt vmcnt(0)
	s_barrier
	v_lshl_add_u64 v[92:93], v[66:67], 0, s[78:79]
	global_load_lds_dwordx4 v[92:93], off
	v_lshl_add_u64 v[92:93], v[68:69], 0, s[78:79]
	s_mov_b32 m0, s47
	s_nop 0
	global_load_lds_dwordx4 v[92:93], off
	v_lshl_add_u64 v[92:93], v[70:71], 0, s[78:79]
	s_mov_b32 m0, s48
	v_mfma_f32_32x32x16_bf16 v[2:17], v[96:99], v[100:103], v[2:17]
	global_load_lds_dwordx4 v[92:93], off
	v_lshl_add_u64 v[92:93], v[72:73], 0, s[78:79]
	s_mov_b32 m0, s49
	s_nop 0
	global_load_lds_dwordx4 v[92:93], off
	v_lshl_add_u64 v[92:93], v[74:75], 0, s[78:79]
	s_mov_b32 m0, s50
	v_mfma_f32_32x32x16_bf16 v[18:33], v[96:99], v[104:107], v[18:33]
	global_load_lds_dwordx4 v[92:93], off
	v_lshl_add_u64 v[92:93], v[76:77], 0, s[78:79]
	s_mov_b32 m0, s51
	s_nop 0
	global_load_lds_dwordx4 v[92:93], off
	v_lshl_add_u64 v[92:93], v[78:79], 0, s[78:79]
	s_mov_b32 m0, s52
	s_nop 0
	global_load_lds_dwordx4 v[92:93], off
	v_lshl_add_u64 v[92:93], v[80:81], 0, s[78:79]
	s_mov_b32 m0, s18
	s_nop 0
	global_load_lds_dwordx4 v[92:93], off
	ds_read_b128 v[92:95], v0
	ds_read_b128 v[96:99], v0 offset:4096
	ds_read_b128 v[100:103], v86 offset:16384
	ds_read_b128 v[104:107], v86 offset:20480
	s_waitcnt lgkmcnt(0)
	v_mfma_f32_32x32x16_bf16 v[34:49], v[92:95], v[100:103], v[34:49]
	s_mov_b32 m0, s36
	v_mfma_f32_32x32x16_bf16 v[50:65], v[92:95], v[104:107], v[50:65]
	v_mfma_f32_32x32x16_bf16 v[2:17], v[96:99], v[100:103], v[2:17]
	v_mfma_f32_32x32x16_bf16 v[18:33], v[96:99], v[104:107], v[18:33]
	ds_read_b128 v[92:95], v88
	ds_read_b128 v[96:99], v88 offset:4096
	ds_read_b128 v[100:103], v89 offset:16384
	ds_read_b128 v[104:107], v89 offset:20480
	s_waitcnt lgkmcnt(1)
	v_mfma_f32_32x32x16_bf16 v[34:49], v[92:95], v[100:103], v[34:49]
	s_waitcnt lgkmcnt(0)
	v_mfma_f32_32x32x16_bf16 v[50:65], v[92:95], v[104:107], v[50:65]
	v_mfma_f32_32x32x16_bf16 v[2:17], v[96:99], v[100:103], v[2:17]
	v_mfma_f32_32x32x16_bf16 v[18:33], v[96:99], v[104:107], v[18:33]
	ds_read_b128 v[92:95], v90
	ds_read_b128 v[96:99], v90 offset:4096
	ds_read_b128 v[100:103], v84 offset:16384
	ds_read_b128 v[104:107], v84 offset:20480
	s_waitcnt lgkmcnt(1)
	v_mfma_f32_32x32x16_bf16 v[34:49], v[92:95], v[100:103], v[34:49]
	s_waitcnt lgkmcnt(0)
	v_mfma_f32_32x32x16_bf16 v[50:65], v[92:95], v[104:107], v[50:65]
	v_mfma_f32_32x32x16_bf16 v[2:17], v[96:99], v[100:103], v[2:17]
	v_mfma_f32_32x32x16_bf16 v[18:33], v[96:99], v[104:107], v[18:33]
	ds_read_b128 v[92:95], v85
	ds_read_b128 v[96:99], v85 offset:4096
	ds_read_b128 v[100:103], v87 offset:16384
	ds_read_b128 v[104:107], v87 offset:20480
	s_waitcnt lgkmcnt(0)
	v_mfma_f32_32x32x16_bf16 v[34:49], v[92:95], v[100:103], v[34:49]
	v_mfma_f32_32x32x16_bf16 v[50:65], v[92:95], v[104:107], v[50:65]
	s_waitcnt vmcnt(0)
	s_barrier
; #define MFMA(a, b, c) __builtin_amdgcn_mfma_f32_32x32x16_bf16((a), (b), (c), 0, 0, 0)
; template <int AI, int BI>
; DI void gemm_tile(const u16* __restrict__ A, int lda, const u16* __restrict__ B, int ldb, int nk, bool swap,
;                   f32x16 (&acc)[AI][BI], char* lds) {
;     ...
;   for (int kt = 0; kt < nk; ++kt) {
;     const char* cur = lds + (kt & 1) * 32768;
;     if (kt + 1 < nk) gemm_stage<AI, BI>(A + (kt + 1) * 64, lda, B + (kt + 1) * 64, ldb, lds + ((kt + 1) & 1) * 32768, tid);
; #pragma unroll
;     for (int ks = 0; ks < 4; ++ks) {
;       const int co = ((ks * 2 + h) ^ sw) << 4;
;       s16x8 fa[AI], fb[BI];
; #pragma unroll
;       for (int i = 0; i < AI; ++i) fa[i] = *(const s16x8*)(cur + offA + i * 4096 + co);
; #pragma unroll
;       for (int i = 0; i < BI; ++i) fb[i] = *(const s16x8*)(cur + offB + i * 4096 + co);
; #pragma unroll
;       for (int i = 0; i < AI; ++i)
; #pragma unroll
;         for (int j = 0; j < BI; ++j) acc[i][j] = MFMA(fa[i], fb[j], acc[i][j]);
;     }
;     asm volatile("s_waitcnt vmcnt(0)" ::: "memory");
;     __syncthreads();
	v_lshl_add_u64 v[92:93], v[66:67], 0, s[2:3]
	global_load_lds_dwordx4 v[92:93], off
	v_lshl_add_u64 v[92:93], v[68:69], 0, s[2:3]
	s_mov_b32 m0, s37
	v_lshl_add_u64 v[66:67], v[66:67], 0, s[30:31]
	global_load_lds_dwordx4 v[92:93], off
	v_lshl_add_u64 v[92:93], v[70:71], 0, s[2:3]
	s_mov_b32 m0, s40
	v_mfma_f32_32x32x16_bf16 v[2:17], v[96:99], v[100:103], v[2:17]
	global_load_lds_dwordx4 v[92:93], off
	v_lshl_add_u64 v[92:93], v[72:73], 0, s[2:3]
	s_mov_b32 m0, s41
	s_nop 0
	global_load_lds_dwordx4 v[92:93], off
	v_lshl_add_u64 v[92:93], v[74:75], 0, s[2:3]
	s_mov_b32 m0, s28
	v_mfma_f32_32x32x16_bf16 v[18:33], v[96:99], v[104:107], v[18:33]
	global_load_lds_dwordx4 v[92:93], off
	v_lshl_add_u64 v[92:93], v[76:77], 0, s[2:3]
	s_mov_b32 m0, s29
	s_movk_i32 s28, 0xb00
	global_load_lds_dwordx4 v[92:93], off
	v_lshl_add_u64 v[92:93], v[78:79], 0, s[2:3]
	s_mov_b32 m0, s34
	s_nop 0
	global_load_lds_dwordx4 v[92:93], off
	v_lshl_add_u64 v[92:93], v[80:81], 0, s[2:3]
	s_mov_b32 m0, s35
	s_nop 0
	global_load_lds_dwordx4 v[92:93], off
	ds_read_b128 v[92:95], v0 offset:32768
	ds_read_b128 v[96:99], v0 offset:36864
	ds_read_b128 v[100:103], v86 offset:49152
	ds_read_b128 v[104:107], v86 offset:53248
	s_waitcnt lgkmcnt(0)
	v_mfma_f32_32x32x16_bf16 v[34:49], v[92:95], v[100:103], v[34:49]
	s_mov_b32 m0, s46
	v_mfma_f32_32x32x16_bf16 v[50:65], v[92:95], v[104:107], v[50:65]
	v_mfma_f32_32x32x16_bf16 v[2:17], v[96:99], v[100:103], v[2:17]
	v_mfma_f32_32x32x16_bf16 v[18:33], v[96:99], v[104:107], v[18:33]
	ds_read_b128 v[92:95], v88 offset:32768
	ds_read_b128 v[96:99], v88 offset:36864
	ds_read_b128 v[100:103], v89 offset:49152
	ds_read_b128 v[104:107], v89 offset:53248
	s_waitcnt lgkmcnt(1)
	v_mfma_f32_32x32x16_bf16 v[34:49], v[92:95], v[100:103], v[34:49]
	s_waitcnt lgkmcnt(0)
	v_mfma_f32_32x32x16_bf16 v[50:65], v[92:95], v[104:107], v[50:65]
	v_mfma_f32_32x32x16_bf16 v[2:17], v[96:99], v[100:103], v[2:17]
	v_mfma_f32_32x32x16_bf16 v[18:33], v[96:99], v[104:107], v[18:33]
	ds_read_b128 v[92:95], v90 offset:32768
	ds_read_b128 v[96:99], v90 offset:36864
	ds_read_b128 v[100:103], v84 offset:49152
	ds_read_b128 v[104:107], v84 offset:53248
	s_waitcnt lgkmcnt(1)
	v_mfma_f32_32x32x16_bf16 v[34:49], v[92:95], v[100:103], v[34:49]
	s_waitcnt lgkmcnt(0)
	v_mfma_f32_32x32x16_bf16 v[50:65], v[92:95], v[104:107], v[50:65]
	v_mfma_f32_32x32x16_bf16 v[2:17], v[96:99], v[100:103], v[2:17]
	v_mfma_f32_32x32x16_bf16 v[18:33], v[96:99], v[104:107], v[18:33]
	ds_read_b128 v[92:95], v85 offset:32768
	ds_read_b128 v[96:99], v85 offset:36864
	ds_read_b128 v[100:103], v87 offset:49152
	ds_read_b128 v[104:107], v87 offset:53248
	s_waitcnt vmcnt(0)
	s_waitcnt lgkmcnt(0)
	s_barrier
	global_load_lds_dwordx4 v[66:67], off
	v_lshl_add_u64 v[66:67], v[68:69], 0, s[30:31]
	s_mov_b32 m0, s47
	v_mfma_f32_32x32x16_bf16 v[34:49], v[92:95], v[100:103], v[34:49]
	global_load_lds_dwordx4 v[66:67], off
	v_lshl_add_u64 v[66:67], v[70:71], 0, s[30:31]
	s_mov_b32 m0, s48
	s_nop 0
	global_load_lds_dwordx4 v[66:67], off
	v_lshl_add_u64 v[66:67], v[72:73], 0, s[30:31]
	s_mov_b32 m0, s49
	v_mfma_f32_32x32x16_bf16 v[50:65], v[92:95], v[104:107], v[50:65]
	global_load_lds_dwordx4 v[66:67], off
	v_lshl_add_u64 v[66:67], v[74:75], 0, s[30:31]
	s_mov_b32 m0, s50
	s_nop 0
	global_load_lds_dwordx4 v[66:67], off
	v_lshl_add_u64 v[66:67], v[76:77], 0, s[30:31]
	s_mov_b32 m0, s51
	v_mfma_f32_32x32x16_bf16 v[2:17], v[96:99], v[100:103], v[2:17]
	global_load_lds_dwordx4 v[66:67], off
	v_lshl_add_u64 v[66:67], v[78:79], 0, s[30:31]
	s_mov_b32 m0, s52
	s_nop 0
	global_load_lds_dwordx4 v[66:67], off
	v_lshl_add_u64 v[66:67], v[80:81], 0, s[30:31]
	s_mov_b32 m0, s18
	v_mfma_f32_32x32x16_bf16 v[18:33], v[96:99], v[104:107], v[18:33]
	global_load_lds_dwordx4 v[66:67], off
	ds_read_b128 v[66:69], v0
	ds_read_b128 v[70:73], v0 offset:4096
	ds_read_b128 v[74:77], v86 offset:16384
	ds_read_b128 v[78:81], v86 offset:20480
	s_waitcnt lgkmcnt(0)
	v_mfma_f32_32x32x16_bf16 v[34:49], v[66:69], v[74:77], v[34:49]
	v_mfma_f32_32x32x16_bf16 v[50:65], v[66:69], v[78:81], v[50:65]
	v_mfma_f32_32x32x16_bf16 v[2:17], v[70:73], v[74:77], v[2:17]
	v_mfma_f32_32x32x16_bf16 v[18:33], v[70:73], v[78:81], v[18:33]
	ds_read_b128 v[66:69], v88
	ds_read_b128 v[70:73], v88 offset:4096
	ds_read_b128 v[74:77], v89 offset:16384
	ds_read_b128 v[78:81], v89 offset:20480
	s_waitcnt lgkmcnt(1)
	v_mfma_f32_32x32x16_bf16 v[34:49], v[66:69], v[74:77], v[34:49]
	s_waitcnt lgkmcnt(0)
	v_mfma_f32_32x32x16_bf16 v[50:65], v[66:69], v[78:81], v[50:65]
	v_mfma_f32_32x32x16_bf16 v[2:17], v[70:73], v[74:77], v[2:17]
	v_mfma_f32_32x32x16_bf16 v[18:33], v[70:73], v[78:81], v[18:33]
	ds_read_b128 v[66:69], v90
	ds_read_b128 v[70:73], v90 offset:4096
	ds_read_b128 v[74:77], v84 offset:16384
	ds_read_b128 v[78:81], v84 offset:20480
	s_waitcnt lgkmcnt(1)
	v_mfma_f32_32x32x16_bf16 v[34:49], v[66:69], v[74:77], v[34:49]
	s_waitcnt lgkmcnt(0)
	v_mfma_f32_32x32x16_bf16 v[50:65], v[66:69], v[78:81], v[50:65]
	v_mfma_f32_32x32x16_bf16 v[2:17], v[70:73], v[74:77], v[2:17]
	v_mfma_f32_32x32x16_bf16 v[18:33], v[70:73], v[78:81], v[18:33]
	ds_read_b128 v[66:69], v85
	ds_read_b128 v[70:73], v85 offset:4096
	ds_read_b128 v[74:77], v87 offset:16384
	ds_read_b128 v[78:81], v87 offset:20480
	s_waitcnt lgkmcnt(0)
	v_mfma_f32_32x32x16_bf16 v[34:49], v[66:69], v[74:77], v[34:49]
	v_mfma_f32_32x32x16_bf16 v[50:65], v[66:69], v[78:81], v[50:65]
	v_mfma_f32_32x32x16_bf16 v[2:17], v[70:73], v[74:77], v[2:17]
	v_mfma_f32_32x32x16_bf16 v[18:33], v[70:73], v[78:81], v[18:33]
	s_waitcnt vmcnt(0)
	s_barrier
; #define MFMA(a, b, c) __builtin_amdgcn_mfma_f32_32x32x16_bf16((a), (b), (c), 0, 0, 0)
; #define GAS __attribute__((address_space(1)))
; DI int opaque0() { int z = 0; asm volatile("" : "+v"(z)); return z; }
; template <int AI, int BI>
; DI void gemm_tile(const u16* __restrict__ A, int lda, const u16* __restrict__ B, int ldb, int nk, bool swap,
;                   f32x16 (&acc)[AI][BI], char* lds) {
;     ...
;   for (int kt = 0; kt < nk; ++kt) {
;     const char* cur = lds + (kt & 1) * 32768;
;     if (kt + 1 < nk) gemm_stage<AI, BI>(A + (kt + 1) * 64, lda, B + (kt + 1) * 64, ldb, lds + ((kt + 1) & 1) * 32768, tid);
; #pragma unroll
;     for (int ks = 0; ks < 4; ++ks) {
;       const int co = ((ks * 2 + h) ^ sw) << 4;
;       s16x8 fa[AI], fb[BI];
; #pragma unroll
;       for (int i = 0; i < AI; ++i) fa[i] = *(const s16x8*)(cur + offA + i * 4096 + co);
; #pragma unroll
;       for (int i = 0; i < BI; ++i) fb[i] = *(const s16x8*)(cur + offB + i * 4096 + co);
; #pragma unroll
;       for (int i = 0; i < AI; ++i)
; #pragma unroll
;         for (int j = 0; j < BI; ++j) acc[i][j] = MFMA(fa[i], fb[j], acc[i][j]);
;     }
;     asm volatile("s_waitcnt vmcnt(0)" ::: "memory");
;     __syncthreads();
; template <int AI>
; DI void gu_tile(char* wsb, int sub, int m0, int n0, char* lds) {
;     ...
;   const int m0e = m0 + opaque0();
;   const int hc = (n0 >> 1) + wb * 32 + r;
;   GAS u16* HIDu = uptr(HID);
;   const unsigned ib = (unsigned)((m0e + wa * 32 * AI + 4 * h) * 2816 + hc);
; #pragma unroll
;   for (int ai = 0; ai < AI; ++ai)
; #pragma unroll
;     for (int reg = 0; reg < 16; ++reg) {
;       float g = acc[ai][0][reg], u = acc[ai][1][reg];
;       float v = g * __builtin_amdgcn_rcpf(1.f + __expf(-g)) * u;
;       HIDu[ib + (unsigned)((ai * 32 + (reg & 3) + 8 * (reg >> 2)) * 2816)] = f2bf(v);
;       if ((reg & 7) == 7) __builtin_amdgcn_sched_barrier(0);
	ds_read_b128 v[66:69], v0 offset:32768
	ds_read_b128 v[70:73], v0 offset:36864
	ds_read_b128 v[74:77], v86 offset:49152
	ds_read_b128 v[78:81], v86 offset:53248
	v_mov_b32_e32 v0, v1
	s_waitcnt lgkmcnt(1)
	v_mfma_f32_32x32x16_bf16 v[34:49], v[66:69], v[74:77], v[34:49]
	s_waitcnt lgkmcnt(0)
	v_mfma_f32_32x32x16_bf16 v[50:65], v[66:69], v[78:81], v[50:65]
	v_mfma_f32_32x32x16_bf16 v[2:17], v[70:73], v[74:77], v[2:17]
	v_mfma_f32_32x32x16_bf16 v[18:33], v[70:73], v[78:81], v[18:33]
	ds_read_b128 v[66:69], v88 offset:32768
	ds_read_b128 v[70:73], v88 offset:36864
	ds_read_b128 v[74:77], v89 offset:49152
	ds_read_b128 v[78:81], v89 offset:53248
	s_waitcnt lgkmcnt(1)
	v_mfma_f32_32x32x16_bf16 v[34:49], v[66:69], v[74:77], v[34:49]
	s_waitcnt lgkmcnt(0)
	v_mfma_f32_32x32x16_bf16 v[50:65], v[66:69], v[78:81], v[50:65]
	v_mfma_f32_32x32x16_bf16 v[2:17], v[70:73], v[74:77], v[2:17]
	v_mfma_f32_32x32x16_bf16 v[18:33], v[70:73], v[78:81], v[18:33]
	ds_read_b128 v[66:69], v90 offset:32768
	ds_read_b128 v[70:73], v90 offset:36864
	ds_read_b128 v[74:77], v84 offset:49152
	ds_read_b128 v[78:81], v84 offset:53248
	s_waitcnt lgkmcnt(1)
	v_mfma_f32_32x32x16_bf16 v[34:49], v[66:69], v[74:77], v[34:49]
	s_waitcnt lgkmcnt(0)
	v_mfma_f32_32x32x16_bf16 v[50:65], v[66:69], v[78:81], v[50:65]
	v_mfma_f32_32x32x16_bf16 v[2:17], v[70:73], v[74:77], v[2:17]
	v_mfma_f32_32x32x16_bf16 v[18:33], v[70:73], v[78:81], v[18:33]
	ds_read_b128 v[66:69], v85 offset:32768
	ds_read_b128 v[70:73], v85 offset:36864
	ds_read_b128 v[74:77], v87 offset:49152
	ds_read_b128 v[78:81], v87 offset:53248
	s_waitcnt vmcnt(0)
	s_waitcnt lgkmcnt(0)
	s_barrier
	v_mfma_f32_32x32x16_bf16 v[34:49], v[66:69], v[74:77], v[34:49]
	v_mfma_f32_32x32x16_bf16 v[50:65], v[66:69], v[78:81], v[50:65]
	v_lshrrev_b32_e32 v66, 1, v83
	v_lshrrev_b32_e32 v68, 3, v82
	v_and_b32_e32 v67, 32, v66
	v_and_b32_e32 v66, 0xffffc0, v66
	v_and_or_b32 v68, v68, 4, s16
	v_add3_u32 v66, v68, v66, v0
	v_or3_b32 v0, s17, v91, v67
	s_nop 3
	v_mul_f32_e32 v67, 0xbfb8aa3b, v34
	v_exp_f32_e32 v67, v67
	v_mfma_f32_32x32x16_bf16 v[2:17], v[70:73], v[74:77], v[2:17]
	v_add_f32_e32 v67, 1.0, v67
	v_rcp_f32_e32 v67, v67
	s_nop 0
	v_mul_f32_e32 v34, v34, v67
	v_mad_u64_u32 v[66:67], s[16:17], v66, s28, v[0:1]
	v_mul_f32_e32 v0, 0xbfb8aa3b, v35
	v_exp_f32_e32 v0, v0
	v_mul_f32_e32 v34, v50, v34
	v_mov_b32_e32 v67, v1
	v_cvt_pk_bf16_f32 v34, v34, s0
	v_add_f32_e32 v0, 1.0, v0
	v_rcp_f32_e32 v0, v0
	v_lshl_add_u64 v[68:69], v[66:67], 1, s[6:7]
	global_store_short v[68:69], v34, off
	v_mfma_f32_32x32x16_bf16 v[18:33], v[70:73], v[78:81], v[18:33]
	v_mul_f32_e32 v0, v35, v0
	v_mul_f32_e32 v0, v51, v0
	v_cvt_pk_bf16_f32 v50, v0, s0
	v_add_u32_e32 v0, 0xb00, v66
	v_lshl_add_u64 v[34:35], v[0:1], 1, s[6:7]
	v_mul_f32_e32 v0, 0xbfb8aa3b, v36
	v_exp_f32_e32 v0, v0
	global_store_short v[34:35], v50, off
	v_add_f32_e32 v0, 1.0, v0
	v_rcp_f32_e32 v0, v0
	s_nop 0
	v_mul_f32_e32 v0, v36, v0
	v_mul_f32_e32 v0, v52, v0
	v_cvt_pk_bf16_f32 v36, v0, s0
	v_add_u32_e32 v0, 0x1600, v66
	v_lshl_add_u64 v[34:35], v[0:1], 1, s[6:7]
	v_mul_f32_e32 v0, 0xbfb8aa3b, v37
	v_exp_f32_e32 v0, v0
	global_store_short v[34:35], v36, off
	v_add_f32_e32 v0, 1.0, v0
	v_rcp_f32_e32 v0, v0
	s_nop 0
	v_mul_f32_e32 v0, v37, v0
	v_mul_f32_e32 v0, v53, v0
	v_cvt_pk_bf16_f32 v36, v0, s0
	v_add_u32_e32 v0, 0x2100, v66
	v_lshl_add_u64 v[34:35], v[0:1], 1, s[6:7]
	v_mul_f32_e32 v0, 0xbfb8aa3b, v38
	v_exp_f32_e32 v0, v0
	global_store_short v[34:35], v36, off
	v_add_f32_e32 v0, 1.0, v0
	v_rcp_f32_e32 v0, v0
	s_nop 0
	v_mul_f32_e32 v0, v38, v0
	v_mul_f32_e32 v0, v54, v0
	v_cvt_pk_bf16_f32 v36, v0, s0
	v_add_u32_e32 v0, 0x5800, v66
	v_lshl_add_u64 v[34:35], v[0:1], 1, s[6:7]
	v_mul_f32_e32 v0, 0xbfb8aa3b, v39
	v_exp_f32_e32 v0, v0
	global_store_short v[34:35], v36, off
	v_add_f32_e32 v0, 1.0, v0
	v_rcp_f32_e32 v0, v0
	s_nop 0
	v_mul_f32_e32 v0, v39, v0
	v_mul_f32_e32 v0, v55, v0
	v_cvt_pk_bf16_f32 v36, v0, s0
	v_add_u32_e32 v0, 0x6300, v66
	v_lshl_add_u64 v[34:35], v[0:1], 1, s[6:7]
	v_mul_f32_e32 v0, 0xbfb8aa3b, v40
	v_exp_f32_e32 v0, v0
	global_store_short v[34:35], v36, off
	v_add_f32_e32 v0, 1.0, v0
	v_rcp_f32_e32 v0, v0
	s_nop 0
	v_mul_f32_e32 v0, v40, v0
	v_mul_f32_e32 v0, v56, v0
	v_cvt_pk_bf16_f32 v36, v0, s0
	v_add_u32_e32 v0, 0x6e00, v66
	v_lshl_add_u64 v[34:35], v[0:1], 1, s[6:7]
	v_mul_f32_e32 v0, 0xbfb8aa3b, v41
	v_exp_f32_e32 v0, v0
	global_store_short v[34:35], v36, off
	v_add_f32_e32 v0, 1.0, v0
	v_rcp_f32_e32 v0, v0
	s_nop 0
	v_mul_f32_e32 v0, v41, v0
	v_mul_f32_e32 v0, v57, v0
	v_cvt_pk_bf16_f32 v36, v0, s0
	v_add_u32_e32 v0, 0x7900, v66
	v_lshl_add_u64 v[34:35], v[0:1], 1, s[6:7]
	global_store_short v[34:35], v36, off
	v_mul_f32_e32 v0, 0xbfb8aa3b, v42
	v_exp_f32_e32 v0, v0
	s_nop 0
	v_add_f32_e32 v0, 1.0, v0
	v_rcp_f32_e32 v0, v0
	s_nop 0
	v_mul_f32_e32 v0, v42, v0
	v_mul_f32_e32 v0, v58, v0
	v_cvt_pk_bf16_f32 v36, v0, s0
	v_add_u32_e32 v0, 0xb000, v66
	v_lshl_add_u64 v[34:35], v[0:1], 1, s[6:7]
	v_mul_f32_e32 v0, 0xbfb8aa3b, v43
	v_exp_f32_e32 v0, v0
	global_store_short v[34:35], v36, off
	v_add_f32_e32 v0, 1.0, v0
	v_rcp_f32_e32 v0, v0
	s_nop 0
	v_mul_f32_e32 v0, v43, v0
	v_mul_f32_e32 v0, v59, v0
	v_cvt_pk_bf16_f32 v36, v0, s0
	v_add_u32_e32 v0, 0xbb00, v66
	v_lshl_add_u64 v[34:35], v[0:1], 1, s[6:7]
	v_mul_f32_e32 v0, 0xbfb8aa3b, v44
	v_exp_f32_e32 v0, v0
	global_store_short v[34:35], v36, off
	v_add_f32_e32 v0, 1.0, v0
	v_rcp_f32_e32 v0, v0
	s_nop 0
	v_mul_f32_e32 v0, v44, v0
	v_mul_f32_e32 v0, v60, v0
	v_cvt_pk_bf16_f32 v36, v0, s0
	v_add_u32_e32 v0, 0xc600, v66
	v_lshl_add_u64 v[34:35], v[0:1], 1, s[6:7]
	v_mul_f32_e32 v0, 0xbfb8aa3b, v45
	v_exp_f32_e32 v0, v0
; template <int AI>
; DI void gu_tile(char* wsb, int sub, int m0, int n0, char* lds) {
;     ...
;   for (int ai = 0; ai < AI; ++ai)
; #pragma unroll
;     for (int reg = 0; reg < 16; ++reg) {
;       float g = acc[ai][0][reg], u = acc[ai][1][reg];
;       float v = g * __builtin_amdgcn_rcpf(1.f + __expf(-g)) * u;
;       HIDu[ib + (unsigned)((ai * 32 + (reg & 3) + 8 * (reg >> 2)) * 2816)] = f2bf(v);
;       if ((reg & 7) == 7) __builtin_amdgcn_sched_barrier(0);
;     }
; }
; DI void phase_gu(const Params& p, char* wsb, int sub, int mrows, char* lds) {
;   int mt, nt;
;   for (int rnd = 0; next_tile(rnd, 128, 44, mt, nt); ++rnd) gu_tile<2>(wsb, sub, mt * 128, nt * 128, lds);
	global_store_short v[34:35], v36, off
	v_add_f32_e32 v0, 1.0, v0
	v_rcp_f32_e32 v0, v0
	s_nop 0
	v_mul_f32_e32 v0, v45, v0
	v_mul_f32_e32 v0, v61, v0
	v_cvt_pk_bf16_f32 v36, v0, s0
	v_add_u32_e32 v0, 0xd100, v66
	v_lshl_add_u64 v[34:35], v[0:1], 1, s[6:7]
	v_mul_f32_e32 v0, 0xbfb8aa3b, v46
	v_exp_f32_e32 v0, v0
	global_store_short v[34:35], v36, off
	v_add_f32_e32 v0, 1.0, v0
	v_rcp_f32_e32 v0, v0
	s_nop 0
	v_mul_f32_e32 v0, v46, v0
	v_mul_f32_e32 v0, v62, v0
	v_cvt_pk_bf16_f32 v36, v0, s0
	v_add_u32_e32 v0, 0x10800, v66
	v_lshl_add_u64 v[34:35], v[0:1], 1, s[6:7]
	v_mul_f32_e32 v0, 0xbfb8aa3b, v47
	v_exp_f32_e32 v0, v0
	global_store_short v[34:35], v36, off
	v_add_f32_e32 v0, 1.0, v0
	v_rcp_f32_e32 v0, v0
	s_nop 0
	v_mul_f32_e32 v0, v47, v0
	v_mul_f32_e32 v0, v63, v0
	v_cvt_pk_bf16_f32 v36, v0, s0
	v_add_u32_e32 v0, 0x11300, v66
	v_lshl_add_u64 v[34:35], v[0:1], 1, s[6:7]
	v_mul_f32_e32 v0, 0xbfb8aa3b, v48
	v_exp_f32_e32 v0, v0
	global_store_short v[34:35], v36, off
	v_add_f32_e32 v0, 1.0, v0
	v_rcp_f32_e32 v0, v0
	s_nop 0
	v_mul_f32_e32 v0, v48, v0
	v_mul_f32_e32 v0, v64, v0
	v_cvt_pk_bf16_f32 v36, v0, s0
	v_add_u32_e32 v0, 0x11e00, v66
	v_lshl_add_u64 v[34:35], v[0:1], 1, s[6:7]
	v_mul_f32_e32 v0, 0xbfb8aa3b, v49
	v_exp_f32_e32 v0, v0
	global_store_short v[34:35], v36, off
	v_add_f32_e32 v0, 1.0, v0
	v_rcp_f32_e32 v0, v0
	s_nop 0
	v_mul_f32_e32 v0, v49, v0
	v_mul_f32_e32 v0, v65, v0
	v_cvt_pk_bf16_f32 v36, v0, s0
	v_add_u32_e32 v0, 0x12900, v66
	v_lshl_add_u64 v[34:35], v[0:1], 1, s[6:7]
	global_store_short v[34:35], v36, off
	v_mul_f32_e32 v0, 0xbfb8aa3b, v2
	v_exp_f32_e32 v0, v0
	s_nop 0
	v_add_f32_e32 v0, 1.0, v0
	v_rcp_f32_e32 v0, v0
	s_nop 0
	v_mul_f32_e32 v0, v2, v0
	v_mul_f32_e32 v0, v18, v0
	v_cvt_pk_bf16_f32 v2, v0, s0
	v_add_u32_e32 v0, 0x16000, v66
	v_lshl_add_u64 v[34:35], v[0:1], 1, s[6:7]
	v_mul_f32_e32 v0, 0xbfb8aa3b, v3
	v_exp_f32_e32 v0, v0
	global_store_short v[34:35], v2, off
	v_add_f32_e32 v0, 1.0, v0
	v_rcp_f32_e32 v0, v0
	s_nop 0
	v_mul_f32_e32 v0, v3, v0
	v_mul_f32_e32 v0, v19, v0
	v_cvt_pk_bf16_f32 v18, v0, s0
	v_add_u32_e32 v0, 0x16b00, v66
	v_lshl_add_u64 v[2:3], v[0:1], 1, s[6:7]
	v_mul_f32_e32 v0, 0xbfb8aa3b, v4
	v_exp_f32_e32 v0, v0
	global_store_short v[2:3], v18, off
	v_add_f32_e32 v0, 1.0, v0
	v_rcp_f32_e32 v0, v0
	s_nop 0
	v_mul_f32_e32 v0, v4, v0
	v_mul_f32_e32 v0, v20, v0
	v_cvt_pk_bf16_f32 v4, v0, s0
	v_add_u32_e32 v0, 0x17600, v66
	v_lshl_add_u64 v[2:3], v[0:1], 1, s[6:7]
	v_mul_f32_e32 v0, 0xbfb8aa3b, v5
	v_exp_f32_e32 v0, v0
	global_store_short v[2:3], v4, off
	v_add_f32_e32 v0, 1.0, v0
	v_rcp_f32_e32 v0, v0
	s_nop 0
	v_mul_f32_e32 v0, v5, v0
	v_mul_f32_e32 v0, v21, v0
	v_cvt_pk_bf16_f32 v4, v0, s0
	v_add_u32_e32 v0, 0x18100, v66
	v_lshl_add_u64 v[2:3], v[0:1], 1, s[6:7]
	v_mul_f32_e32 v0, 0xbfb8aa3b, v6
	v_exp_f32_e32 v0, v0
	global_store_short v[2:3], v4, off
	v_add_f32_e32 v0, 1.0, v0
	v_rcp_f32_e32 v0, v0
	s_nop 0
	v_mul_f32_e32 v0, v6, v0
	v_mul_f32_e32 v0, v22, v0
	v_cvt_pk_bf16_f32 v4, v0, s0
	v_add_u32_e32 v0, 0x1b800, v66
	v_lshl_add_u64 v[2:3], v[0:1], 1, s[6:7]
	v_mul_f32_e32 v0, 0xbfb8aa3b, v7
	v_exp_f32_e32 v0, v0
	global_store_short v[2:3], v4, off
	v_add_f32_e32 v0, 1.0, v0
	v_rcp_f32_e32 v0, v0
	s_nop 0
	v_mul_f32_e32 v0, v7, v0
	v_mul_f32_e32 v0, v23, v0
	v_cvt_pk_bf16_f32 v4, v0, s0
	v_add_u32_e32 v0, 0x1c300, v66
	v_lshl_add_u64 v[2:3], v[0:1], 1, s[6:7]
	v_mul_f32_e32 v0, 0xbfb8aa3b, v8
	v_exp_f32_e32 v0, v0
	global_store_short v[2:3], v4, off
	v_add_f32_e32 v0, 1.0, v0
	v_rcp_f32_e32 v0, v0
	s_nop 0
	v_mul_f32_e32 v0, v8, v0
	v_mul_f32_e32 v0, v24, v0
	v_cvt_pk_bf16_f32 v4, v0, s0
	v_add_u32_e32 v0, 0x1ce00, v66
	v_lshl_add_u64 v[2:3], v[0:1], 1, s[6:7]
	v_mul_f32_e32 v0, 0xbfb8aa3b, v9
	v_exp_f32_e32 v0, v0
	global_store_short v[2:3], v4, off
	v_add_f32_e32 v0, 1.0, v0
	v_rcp_f32_e32 v0, v0
	s_nop 0
	v_mul_f32_e32 v0, v9, v0
	v_mul_f32_e32 v0, v25, v0
	v_cvt_pk_bf16_f32 v4, v0, s0
	v_add_u32_e32 v0, 0x1d900, v66
	v_lshl_add_u64 v[2:3], v[0:1], 1, s[6:7]
	global_store_short v[2:3], v4, off
	v_mul_f32_e32 v0, 0xbfb8aa3b, v10
	v_exp_f32_e32 v0, v0
	s_nop 0
	v_add_f32_e32 v0, 1.0, v0
	v_rcp_f32_e32 v0, v0
	s_nop 0
	v_mul_f32_e32 v0, v10, v0
	v_mul_f32_e32 v0, v26, v0
	v_cvt_pk_bf16_f32 v4, v0, s0
	v_add_u32_e32 v0, 0x21000, v66
	v_lshl_add_u64 v[2:3], v[0:1], 1, s[6:7]
	v_mul_f32_e32 v0, 0xbfb8aa3b, v11
	v_exp_f32_e32 v0, v0
	global_store_short v[2:3], v4, off
	v_add_f32_e32 v0, 1.0, v0
	v_rcp_f32_e32 v0, v0
	s_nop 0
	v_mul_f32_e32 v0, v11, v0
	v_mul_f32_e32 v0, v27, v0
	v_cvt_pk_bf16_f32 v4, v0, s0
	v_add_u32_e32 v0, 0x21b00, v66
	v_lshl_add_u64 v[2:3], v[0:1], 1, s[6:7]
	v_mul_f32_e32 v0, 0xbfb8aa3b, v12
	v_exp_f32_e32 v0, v0
	global_store_short v[2:3], v4, off
	v_add_f32_e32 v0, 1.0, v0
	v_rcp_f32_e32 v0, v0
	s_nop 0
	v_mul_f32_e32 v0, v12, v0
	v_mul_f32_e32 v0, v28, v0
	v_cvt_pk_bf16_f32 v4, v0, s0
	v_add_u32_e32 v0, 0x22600, v66
	v_lshl_add_u64 v[2:3], v[0:1], 1, s[6:7]
	v_mul_f32_e32 v0, 0xbfb8aa3b, v13
	v_exp_f32_e32 v0, v0
	global_store_short v[2:3], v4, off
	v_add_f32_e32 v0, 1.0, v0
	v_rcp_f32_e32 v0, v0
	s_nop 0
	v_mul_f32_e32 v0, v13, v0
	v_mul_f32_e32 v0, v29, v0
	v_cvt_pk_bf16_f32 v4, v0, s0
	v_add_u32_e32 v0, 0x23100, v66
	v_lshl_add_u64 v[2:3], v[0:1], 1, s[6:7]
	v_mul_f32_e32 v0, 0xbfb8aa3b, v14
	v_exp_f32_e32 v0, v0
	global_store_short v[2:3], v4, off
	v_add_f32_e32 v0, 1.0, v0
	v_rcp_f32_e32 v0, v0
	s_nop 0
	v_mul_f32_e32 v0, v14, v0
	v_mul_f32_e32 v0, v30, v0
	v_cvt_pk_bf16_f32 v4, v0, s0
	v_add_u32_e32 v0, 0x26800, v66
	v_lshl_add_u64 v[2:3], v[0:1], 1, s[6:7]
	v_mul_f32_e32 v0, 0xbfb8aa3b, v15
	v_exp_f32_e32 v0, v0
	global_store_short v[2:3], v4, off
	v_add_f32_e32 v0, 1.0, v0
	v_rcp_f32_e32 v0, v0
	s_nop 0
	v_mul_f32_e32 v0, v15, v0
	v_mul_f32_e32 v0, v31, v0
	v_cvt_pk_bf16_f32 v4, v0, s0
	v_add_u32_e32 v0, 0x27300, v66
	v_lshl_add_u64 v[2:3], v[0:1], 1, s[6:7]
	v_mul_f32_e32 v0, 0xbfb8aa3b, v16
	v_exp_f32_e32 v0, v0
	global_store_short v[2:3], v4, off
	v_add_f32_e32 v0, 1.0, v0
	v_rcp_f32_e32 v0, v0
	s_nop 0
	v_mul_f32_e32 v0, v16, v0
	v_mul_f32_e32 v0, v32, v0
	v_cvt_pk_bf16_f32 v4, v0, s0
	v_add_u32_e32 v0, 0x27e00, v66
	v_lshl_add_u64 v[2:3], v[0:1], 1, s[6:7]
	v_mul_f32_e32 v0, 0xbfb8aa3b, v17
	v_exp_f32_e32 v0, v0
	global_store_short v[2:3], v4, off
	v_add_f32_e32 v0, 1.0, v0
	v_rcp_f32_e32 v0, v0
	s_nop 0
	v_mul_f32_e32 v0, v17, v0
	v_mul_f32_e32 v0, v33, v0
	v_cvt_pk_bf16_f32 v4, v0, s0
	v_add_u32_e32 v0, 0x28900, v66
	v_lshl_add_u64 v[2:3], v[0:1], 1, s[6:7]
	global_store_short v[2:3], v4, off
	v_readlane_b32 s16, v245, 0
	s_cmp_eq_u32 s16, 1
	s_cbranch_scc1 .Lgu1_done
	v_readlane_b32 s16, v243, 6
	s_add_i32 s15, s15, s16
	s_add_i32 s14, s14, s53
	s_cmpk_lt_u32 s14, 0x1600
	s_cbranch_scc1 .LBB0_419

; #define MFMA(a, b, c) __builtin_amdgcn_mfma_f32_32x32x16_bf16((a), (b), (c), 0, 0, 0)
; #define TIDX opaque_tid()
; template <int AI, int BI>
; DI void gemm_tile(const u16* __restrict__ A, int lda, const u16* __restrict__ B, int ldb, int nk, bool swap,
;                   f32x16 (&acc)[AI][BI], char* lds) {
;   const int tid = TIDX, lane = tid & 63, wid = tid >> 6;
;   gemm_stage<AI, BI>(A, lda, B, ldb, lds, tid);
;   asm volatile("s_waitcnt vmcnt(0)" ::: "memory");
;   __syncthreads();
;   const int wa = wid >> 1, wb = wid & 1, r = lane & 31, h = lane >> 5, sw = (r >> 1) & 7;
;   const int offA = (swap ? 16384 : 0) + (wa * 32 * AI + r) * 128;
;   const int offB = (swap ? 0 : 16384) + (wb * 32 * BI + r) * 128;
;   for (int kt = 0; kt < nk; ++kt) {
;     const char* cur = lds + (kt & 1) * 32768;
;     if (kt + 1 < nk) gemm_stage<AI, BI>(A + (kt + 1) * 64, lda, B + (kt + 1) * 64, ldb, lds + ((kt + 1) & 1) * 32768, tid);
; #pragma unroll
;     for (int ks = 0; ks < 4; ++ks) {
;       const int co = ((ks * 2 + h) ^ sw) << 4;
;       s16x8 fa[AI], fb[BI];
; #pragma unroll
;       for (int i = 0; i < AI; ++i) fa[i] = *(const s16x8*)(cur + offA + i * 4096 + co);
; #pragma unroll
;       for (int i = 0; i < BI; ++i) fb[i] = *(const s16x8*)(cur + offB + i * 4096 + co);
; #pragma unroll
;       for (int i = 0; i < AI; ++i)
; #pragma unroll
;         for (int j = 0; j < BI; ++j) acc[i][j] = MFMA(fa[i], fb[j], acc[i][j]);
;     }
;     asm volatile("s_waitcnt vmcnt(0)" ::: "memory");
;     __syncthreads();
.LBB0_423:
	s_and_b32 s8, s14, 0xffff
	s_mul_hi_u32 s9, s8, 0xba2e8c
	s_mul_i32 s8, s8, 0xba2f
	s_lshr_b32 s8, s8, 24
	s_lshl_b32 s8, s8, 9
	s_and_b32 s17, s16, 0x1c0
	s_mulk_i32 s9, 0x1600
	s_or_b32 s17, s8, s17
	s_sub_i32 s9, s15, s9
	s_addk_i32 s17, 0x4000
	s_and_b32 s8, s9, 0xffffff80
	v_mov_b32_e32 v46, v178
	v_mov_b32_e32 v47, v178
	s_lshl_b32 s9, s17, 11
	v_mov_b32_e32 v8, v178
	s_add_u32 s28, s10, s9
	s_addc_u32 s29, s11, 0
	v_lshrrev_b32_e32 v0, 4, v8
	s_ashr_i32 s9, s8, 31
	v_xor_b32_e32 v0, v0, v8
	v_add_u32_e32 v9, 0x100, v8
	s_lshl_b64 s[34:35], s[8:9], 11
	v_lshlrev_b32_e32 v0, 4, v0
	v_ashrrev_i32_e32 v4, 3, v8
	v_ashrrev_i32_e32 v6, 3, v9
	s_add_u32 s34, s12, s34
	v_and_b32_e32 v0, 0x70, v0
	v_ashrrev_i32_e32 v5, 31, v4
	v_ashrrev_i32_e32 v7, 31, v6
	s_addc_u32 s35, s13, s35
	v_lshl_add_u64 v[2:3], s[28:29], 0, v[0:1]
	v_lshlrev_b64 v[4:5], 11, v[4:5]
	v_lshlrev_b64 v[6:7], 11, v[6:7]
	v_lshl_add_u64 v[34:35], v[2:3], 0, v[4:5]
	v_lshl_add_u64 v[36:37], v[2:3], 0, v[6:7]
	v_lshl_add_u64 v[2:3], s[34:35], 0, v[0:1]
	v_add_u32_e32 v0, 0x200, v8
	v_lshl_add_u64 v[40:41], v[2:3], 0, v[4:5]
	v_ashrrev_i32_e32 v4, 3, v0
	v_ashrrev_i32_e32 v5, 31, v4
	v_lshl_add_u64 v[38:39], v[2:3], 0, v[6:7]
	v_lshlrev_b64 v[4:5], 11, v[4:5]
	v_add_u32_e32 v6, 0x300, v8
	v_lshl_add_u64 v[42:43], v[2:3], 0, v[4:5]
	v_ashrrev_i32_e32 v4, 3, v6
	v_ashrrev_i32_e32 v5, 31, v4
	v_lshlrev_b32_e32 v55, 4, v8
	v_lshlrev_b64 v[4:5], 11, v[4:5]
	v_readfirstlane_b32 s9, v55
	v_lshlrev_b32_e32 v56, 4, v9
	v_lshl_add_u64 v[44:45], v[2:3], 0, v[4:5]
	v_and_b32_e32 v2, 31, v8
	v_lshrrev_b32_e32 v7, 2, v8
	s_mov_b32 m0, s9
	v_readfirstlane_b32 s18, v56
	v_add_u32_e32 v57, 0x4000, v55
	v_and_or_b32 v2, v7, s49, v2
	global_load_lds_dwordx4 v[34:35], off
	s_mov_b32 m0, s18
	v_readfirstlane_b32 s28, v57
	v_add_u32_e32 v58, 0x4000, v56
	v_lshlrev_b32_e32 v0, 4, v0
	v_lshlrev_b32_e32 v4, 4, v6
	v_lshrrev_b32_e32 v3, 5, v8
	v_bfe_u32 v6, v8, 1, 3
	v_lshlrev_b32_e32 v53, 7, v2
	v_lshlrev_b32_e32 v2, 7, v8
	global_load_lds_dwordx4 v[36:37], off
	s_mov_b32 m0, s28
	v_readfirstlane_b32 s29, v58
	v_add_u32_e32 v65, 0x4000, v0
	v_bfe_u32 v5, v8, 5, 1
	v_and_b32_e32 v67, 0x2f80, v2
	v_bitop3_b32 v2, v3, v6, 1 bitop3:0x6c
	global_load_lds_dwordx4 v[40:41], off
	s_mov_b32 m0, s29
	v_readfirstlane_b32 s34, v65
	v_add_u32_e32 v66, 0x4000, v4
	v_lshlrev_b32_e32 v7, 4, v2
	v_bitop3_b32 v2, v5, v6, 2 bitop3:0x36
	global_load_lds_dwordx4 v[38:39], off
	s_mov_b32 m0, s34
	v_readfirstlane_b32 s41, v66
	v_lshlrev_b32_e32 v49, 4, v2
	v_bitop3_b32 v2, v5, v6, 4 bitop3:0x36
	v_add_u32_e32 v63, 0x8000, v55
	global_load_lds_dwordx4 v[42:43], off
	s_mov_b32 m0, s41
	v_lshlrev_b32_e32 v51, 4, v2
	v_bitop3_b32 v2, v5, v6, 6 bitop3:0x36
	v_readfirstlane_b32 s35, v63
	v_add_u32_e32 v60, 0x8000, v56
	global_load_lds_dwordx4 v[44:45], off
	s_waitcnt vmcnt(0)
	v_lshlrev_b32_e32 v80, 4, v2
	v_lshl_add_u64 v[2:3], v[34:35], 0, s[52:53]
	s_mov_b32 m0, s35
	v_readfirstlane_b32 s36, v60
	v_add_u32_e32 v59, 0xc000, v55
	s_waitcnt vmcnt(0)
	s_waitcnt vmcnt(0) lgkmcnt(0)
	s_barrier
	global_load_lds_dwordx4 v[2:3], off
	v_lshl_add_u64 v[2:3], v[36:37], 0, s[52:53]
	s_mov_b32 m0, s36
	v_readfirstlane_b32 s37, v59
	v_add_u32_e32 v61, 0xc000, v56
	global_load_lds_dwordx4 v[2:3], off
	v_lshl_add_u64 v[2:3], v[40:41], 0, s[52:53]
	s_mov_b32 m0, s37
	v_readfirstlane_b32 s40, v61
	v_add_u32_e32 v62, 0xc000, v0
	global_load_lds_dwordx4 v[2:3], off
	v_lshl_add_u64 v[2:3], v[38:39], 0, s[52:53]
	s_mov_b32 m0, s40
	v_readfirstlane_b32 s46, v62
	v_add_u32_e32 v64, 0xc000, v4
	global_load_lds_dwordx4 v[2:3], off
	v_lshl_add_u64 v[2:3], v[42:43], 0, s[52:53]
	s_mov_b32 m0, s46
	v_readfirstlane_b32 s47, v64
	global_load_lds_dwordx4 v[2:3], off
	v_lshl_add_u64 v[2:3], v[44:45], 0, s[52:53]
	s_mov_b32 m0, s47
	v_or_b32_e32 v0, v53, v7
	global_load_lds_dwordx4 v[2:3], off
	ds_read_b128 v[18:21], v0
	v_or_b32_e32 v50, v67, v7
	ds_read_b128 v[2:5], v50 offset:16384
	ds_read_b128 v[22:25], v50 offset:20480
	v_or_b32_e32 v48, v53, v49
	ds_read_b128 v[68:71], v48
	s_waitcnt lgkmcnt(0)
	v_mfma_f32_32x32x16_bf16 v[2:17], v[18:21], v[2:5], 0
	v_or_b32_e32 v49, v67, v49
	ds_read_b128 v[72:75], v49 offset:16384
	ds_read_b128 v[76:79], v49 offset:20480
	v_or_b32_e32 v52, v53, v51
	v_or_b32_e32 v51, v67, v51
	v_or_b32_e32 v54, v53, v80
	v_or_b32_e32 v53, v67, v80
	s_mov_b32 m0, s9
	v_mfma_f32_32x32x16_bf16 v[18:33], v[18:21], v[22:25], 0
	s_ashr_i32 s8, s8, 1
	s_waitcnt lgkmcnt(1)
	v_mfma_f32_32x32x16_bf16 v[2:17], v[68:71], v[72:75], v[2:17]
	s_waitcnt lgkmcnt(0)
	v_mfma_f32_32x32x16_bf16 v[18:33], v[68:71], v[76:79], v[18:33]
	ds_read_b128 v[68:71], v52
	ds_read_b128 v[72:75], v51 offset:16384
	ds_read_b128 v[76:79], v51 offset:20480
	s_waitcnt lgkmcnt(1)
	v_mfma_f32_32x32x16_bf16 v[2:17], v[68:71], v[72:75], v[2:17]
	s_waitcnt lgkmcnt(0)
	v_mfma_f32_32x32x16_bf16 v[18:33], v[68:71], v[76:79], v[18:33]
	ds_read_b128 v[68:71], v54
	ds_read_b128 v[72:75], v53 offset:16384
	ds_read_b128 v[76:79], v53 offset:20480
	s_waitcnt lgkmcnt(0)
	v_mfma_f32_32x32x16_bf16 v[2:17], v[68:71], v[72:75], v[2:17]
	v_mfma_f32_32x32x16_bf16 v[18:33], v[68:71], v[76:79], v[18:33]
	s_waitcnt vmcnt(0)
	s_barrier
; #define MFMA(a, b, c) __builtin_amdgcn_mfma_f32_32x32x16_bf16((a), (b), (c), 0, 0, 0)
; #define TIDX opaque_tid()
; template <int AI, int BI>
; DI void gemm_stage(const u16* __restrict__ A, int lda, const u16* __restrict__ B, int ldb, char* buf, int tid) {
; #pragma unroll
;   for (int i = 0; i < 2 * AI; ++i) {
;     const int S = tid + NTHR * i, row = S >> 3, c = (S & 7) ^ ((row >> 1) & 7);
;     __builtin_amdgcn_global_load_lds((const unsigned*)(A + (size_t)row * lda + c * 8), (__attribute__((address_space(3))) unsigned*)(buf + S * 16), 16, 0, 0);
;   }
; #pragma unroll
;   for (int i = 0; i < 2 * BI; ++i) {
;     const int S = tid + NTHR * i, row = S >> 3, c = (S & 7) ^ ((row >> 1) & 7);
;     __builtin_amdgcn_global_load_lds((const unsigned*)(B + (size_t)row * ldb + c * 8), (__attribute__((address_space(3))) unsigned*)(buf + 16384 + S * 16), 16, 0, 0);
;   }
; }
; template <int AI, int BI>
; DI void gemm_tile(const u16* __restrict__ A, int lda, const u16* __restrict__ B, int ldb, int nk, bool swap,
;                   f32x16 (&acc)[AI][BI], char* lds) {
;   const int tid = TIDX, lane = tid & 63, wid = tid >> 6;
;   gemm_stage<AI, BI>(A, lda, B, ldb, lds, tid);
;   asm volatile("s_waitcnt vmcnt(0)" ::: "memory");
;   __syncthreads();
;   const int wa = wid >> 1, wb = wid & 1, r = lane & 31, h = lane >> 5, sw = (r >> 1) & 7;
;   const int offA = (swap ? 16384 : 0) + (wa * 32 * AI + r) * 128;
;   const int offB = (swap ? 0 : 16384) + (wb * 32 * BI + r) * 128;
;   for (int kt = 0; kt < nk; ++kt) {
;     const char* cur = lds + (kt & 1) * 32768;
;     if (kt + 1 < nk) gemm_stage<AI, BI>(A + (kt + 1) * 64, lda, B + (kt + 1) * 64, ldb, lds + ((kt + 1) & 1) * 32768, tid);
; #pragma unroll
;     for (int ks = 0; ks < 4; ++ks) {
;       const int co = ((ks * 2 + h) ^ sw) << 4;
;       s16x8 fa[AI], fb[BI];
; #pragma unroll
;       for (int i = 0; i < AI; ++i) fa[i] = *(const s16x8*)(cur + offA + i * 4096 + co);
; #pragma unroll
;       for (int i = 0; i < BI; ++i) fb[i] = *(const s16x8*)(cur + offB + i * 4096 + co);
; #pragma unroll
;       for (int i = 0; i < AI; ++i)
; #pragma unroll
;         for (int j = 0; j < BI; ++j) acc[i][j] = MFMA(fa[i], fb[j], acc[i][j]);
;     }
;     asm volatile("s_waitcnt vmcnt(0)" ::: "memory");
;     __syncthreads();
;   }
	v_lshl_add_u64 v[68:69], v[34:35], 0, s[4:5]
	global_load_lds_dwordx4 v[68:69], off
	v_lshl_add_u64 v[68:69], v[36:37], 0, s[4:5]
	s_mov_b32 m0, s18
	s_nop 0
	global_load_lds_dwordx4 v[68:69], off
	v_lshl_add_u64 v[68:69], v[40:41], 0, s[4:5]
	s_mov_b32 m0, s28
	s_nop 0
	global_load_lds_dwordx4 v[68:69], off
	v_lshl_add_u64 v[68:69], v[38:39], 0, s[4:5]
	s_mov_b32 m0, s29
	s_nop 0
	global_load_lds_dwordx4 v[68:69], off
	v_lshl_add_u64 v[68:69], v[42:43], 0, s[4:5]
	s_mov_b32 m0, s34
	s_nop 0
	global_load_lds_dwordx4 v[68:69], off
	v_lshl_add_u64 v[68:69], v[44:45], 0, s[4:5]
	s_mov_b32 m0, s41
	s_nop 0
	global_load_lds_dwordx4 v[68:69], off
	ds_read_b128 v[68:71], v0 offset:32768
	ds_read_b128 v[72:75], v50 offset:49152
	ds_read_b128 v[76:79], v50 offset:53248
	s_waitcnt lgkmcnt(0)
	v_mfma_f32_32x32x16_bf16 v[2:17], v[68:71], v[72:75], v[2:17]
	s_mov_b32 m0, s35
	v_mfma_f32_32x32x16_bf16 v[18:33], v[68:71], v[76:79], v[18:33]
	ds_read_b128 v[68:71], v48 offset:32768
	ds_read_b128 v[72:75], v49 offset:49152
	ds_read_b128 v[76:79], v49 offset:53248
	s_waitcnt lgkmcnt(1)
	v_mfma_f32_32x32x16_bf16 v[2:17], v[68:71], v[72:75], v[2:17]
	s_waitcnt lgkmcnt(0)
	v_mfma_f32_32x32x16_bf16 v[18:33], v[68:71], v[76:79], v[18:33]
	ds_read_b128 v[68:71], v52 offset:32768
	ds_read_b128 v[72:75], v51 offset:49152
	ds_read_b128 v[76:79], v51 offset:53248
	s_waitcnt lgkmcnt(1)
	v_mfma_f32_32x32x16_bf16 v[2:17], v[68:71], v[72:75], v[2:17]
	s_waitcnt lgkmcnt(0)
	v_mfma_f32_32x32x16_bf16 v[18:33], v[68:71], v[76:79], v[18:33]
	ds_read_b128 v[68:71], v54 offset:32768
	ds_read_b128 v[72:75], v53 offset:49152
	ds_read_b128 v[76:79], v53 offset:53248
	s_waitcnt lgkmcnt(0)
	v_mfma_f32_32x32x16_bf16 v[2:17], v[68:71], v[72:75], v[2:17]
	v_mfma_f32_32x32x16_bf16 v[18:33], v[68:71], v[76:79], v[18:33]
	s_waitcnt vmcnt(0)
	s_barrier
	v_lshl_add_u64 v[68:69], v[34:35], 0, s[54:55]
	global_load_lds_dwordx4 v[68:69], off
	v_lshl_add_u64 v[68:69], v[36:37], 0, s[54:55]
	s_mov_b32 m0, s36
	s_nop 0
	global_load_lds_dwordx4 v[68:69], off
	v_lshl_add_u64 v[68:69], v[40:41], 0, s[54:55]
	s_mov_b32 m0, s37
	s_nop 0
	global_load_lds_dwordx4 v[68:69], off
	v_lshl_add_u64 v[68:69], v[38:39], 0, s[54:55]
	s_mov_b32 m0, s40
	s_nop 0
	global_load_lds_dwordx4 v[68:69], off
	v_lshl_add_u64 v[68:69], v[42:43], 0, s[54:55]
	s_mov_b32 m0, s46
	s_nop 0
	global_load_lds_dwordx4 v[68:69], off
	v_lshl_add_u64 v[68:69], v[44:45], 0, s[54:55]
	s_mov_b32 m0, s47
	s_nop 0
	global_load_lds_dwordx4 v[68:69], off
	ds_read_b128 v[68:71], v0
	ds_read_b128 v[72:75], v50 offset:16384
	ds_read_b128 v[76:79], v50 offset:20480
	s_waitcnt lgkmcnt(0)
	v_mfma_f32_32x32x16_bf16 v[2:17], v[68:71], v[72:75], v[2:17]
	s_mov_b32 m0, s9
	v_mfma_f32_32x32x16_bf16 v[18:33], v[68:71], v[76:79], v[18:33]
	ds_read_b128 v[68:71], v48
	ds_read_b128 v[72:75], v49 offset:16384
	ds_read_b128 v[76:79], v49 offset:20480
	s_waitcnt lgkmcnt(1)
	v_mfma_f32_32x32x16_bf16 v[2:17], v[68:71], v[72:75], v[2:17]
	s_waitcnt lgkmcnt(0)
	v_mfma_f32_32x32x16_bf16 v[18:33], v[68:71], v[76:79], v[18:33]
	ds_read_b128 v[68:71], v52
	ds_read_b128 v[72:75], v51 offset:16384
	ds_read_b128 v[76:79], v51 offset:20480
	s_waitcnt lgkmcnt(1)
	v_mfma_f32_32x32x16_bf16 v[2:17], v[68:71], v[72:75], v[2:17]
	s_waitcnt lgkmcnt(0)
	v_mfma_f32_32x32x16_bf16 v[18:33], v[68:71], v[76:79], v[18:33]
	ds_read_b128 v[68:71], v54
	ds_read_b128 v[72:75], v53 offset:16384
	ds_read_b128 v[76:79], v53 offset:20480
	s_waitcnt lgkmcnt(0)
	v_mfma_f32_32x32x16_bf16 v[2:17], v[68:71], v[72:75], v[2:17]
	v_mfma_f32_32x32x16_bf16 v[18:33], v[68:71], v[76:79], v[18:33]
	s_waitcnt vmcnt(0)
	s_barrier
	v_lshl_add_u64 v[68:69], v[34:35], 0, s[50:51]
	global_load_lds_dwordx4 v[68:69], off
	v_lshl_add_u64 v[68:69], v[36:37], 0, s[50:51]
	s_mov_b32 m0, s18
	s_nop 0
	global_load_lds_dwordx4 v[68:69], off
	v_lshl_add_u64 v[68:69], v[40:41], 0, s[50:51]
	s_mov_b32 m0, s28
	s_nop 0
	global_load_lds_dwordx4 v[68:69], off
	v_lshl_add_u64 v[68:69], v[38:39], 0, s[50:51]
	s_mov_b32 m0, s29
	s_nop 0
	global_load_lds_dwordx4 v[68:69], off
	v_lshl_add_u64 v[68:69], v[42:43], 0, s[50:51]
	s_mov_b32 m0, s34
	s_nop 0
	global_load_lds_dwordx4 v[68:69], off
	v_lshl_add_u64 v[68:69], v[44:45], 0, s[50:51]
	s_mov_b32 m0, s41
	s_nop 0
	global_load_lds_dwordx4 v[68:69], off
	ds_read_b128 v[68:71], v0 offset:32768
	ds_read_b128 v[72:75], v50 offset:49152
	ds_read_b128 v[76:79], v50 offset:53248
	s_waitcnt lgkmcnt(0)
	v_mfma_f32_32x32x16_bf16 v[2:17], v[68:71], v[72:75], v[2:17]
	s_mov_b32 m0, s35
	v_mfma_f32_32x32x16_bf16 v[18:33], v[68:71], v[76:79], v[18:33]
	ds_read_b128 v[68:71], v48 offset:32768
	ds_read_b128 v[72:75], v49 offset:49152
	ds_read_b128 v[76:79], v49 offset:53248
	s_waitcnt lgkmcnt(1)
	v_mfma_f32_32x32x16_bf16 v[2:17], v[68:71], v[72:75], v[2:17]
	s_waitcnt lgkmcnt(0)
	v_mfma_f32_32x32x16_bf16 v[18:33], v[68:71], v[76:79], v[18:33]
	ds_read_b128 v[68:71], v52 offset:32768
	ds_read_b128 v[72:75], v51 offset:49152
	ds_read_b128 v[76:79], v51 offset:53248
	s_waitcnt lgkmcnt(1)
	v_mfma_f32_32x32x16_bf16 v[2:17], v[68:71], v[72:75], v[2:17]
	s_waitcnt lgkmcnt(0)
	v_mfma_f32_32x32x16_bf16 v[18:33], v[68:71], v[76:79], v[18:33]
	ds_read_b128 v[68:71], v54 offset:32768
	ds_read_b128 v[72:75], v53 offset:49152
	ds_read_b128 v[76:79], v53 offset:53248
	s_waitcnt lgkmcnt(0)
	v_mfma_f32_32x32x16_bf16 v[2:17], v[68:71], v[72:75], v[2:17]
	v_mfma_f32_32x32x16_bf16 v[18:33], v[68:71], v[76:79], v[18:33]
	s_waitcnt vmcnt(0)
	s_barrier
; #define MFMA(a, b, c) __builtin_amdgcn_mfma_f32_32x32x16_bf16((a), (b), (c), 0, 0, 0)
; #define TIDX opaque_tid()
; template <int AI, int BI>
; DI void gemm_stage(const u16* __restrict__ A, int lda, const u16* __restrict__ B, int ldb, char* buf, int tid) {
; #pragma unroll
;   for (int i = 0; i < 2 * AI; ++i) {
;     const int S = tid + NTHR * i, row = S >> 3, c = (S & 7) ^ ((row >> 1) & 7);
;     __builtin_amdgcn_global_load_lds((const unsigned*)(A + (size_t)row * lda + c * 8), (__attribute__((address_space(3))) unsigned*)(buf + S * 16), 16, 0, 0);
;   }
; #pragma unroll
;   for (int i = 0; i < 2 * BI; ++i) {
;     const int S = tid + NTHR * i, row = S >> 3, c = (S & 7) ^ ((row >> 1) & 7);
;     __builtin_amdgcn_global_load_lds((const unsigned*)(B + (size_t)row * ldb + c * 8), (__attribute__((address_space(3))) unsigned*)(buf + 16384 + S * 16), 16, 0, 0);
;   }
; }
; template <int AI, int BI>
; DI void gemm_tile(const u16* __restrict__ A, int lda, const u16* __restrict__ B, int ldb, int nk, bool swap,
;                   f32x16 (&acc)[AI][BI], char* lds) {
;   const int tid = TIDX, lane = tid & 63, wid = tid >> 6;
;   gemm_stage<AI, BI>(A, lda, B, ldb, lds, tid);
;   asm volatile("s_waitcnt vmcnt(0)" ::: "memory");
;   __syncthreads();
;   const int wa = wid >> 1, wb = wid & 1, r = lane & 31, h = lane >> 5, sw = (r >> 1) & 7;
;   const int offA = (swap ? 16384 : 0) + (wa * 32 * AI + r) * 128;
;   const int offB = (swap ? 0 : 16384) + (wb * 32 * BI + r) * 128;
;   for (int kt = 0; kt < nk; ++kt) {
;     const char* cur = lds + (kt & 1) * 32768;
;     if (kt + 1 < nk) gemm_stage<AI, BI>(A + (kt + 1) * 64, lda, B + (kt + 1) * 64, ldb, lds + ((kt + 1) & 1) * 32768, tid);
; #pragma unroll
;     for (int ks = 0; ks < 4; ++ks) {
;       const int co = ((ks * 2 + h) ^ sw) << 4;
;       s16x8 fa[AI], fb[BI];
; #pragma unroll
;       for (int i = 0; i < AI; ++i) fa[i] = *(const s16x8*)(cur + offA + i * 4096 + co);
; #pragma unroll
;       for (int i = 0; i < BI; ++i) fb[i] = *(const s16x8*)(cur + offB + i * 4096 + co);
; #pragma unroll
;       for (int i = 0; i < AI; ++i)
; #pragma unroll
;         for (int j = 0; j < BI; ++j) acc[i][j] = MFMA(fa[i], fb[j], acc[i][j]);
;     }
;     asm volatile("s_waitcnt vmcnt(0)" ::: "memory");
;     __syncthreads();
;   }
	v_lshl_add_u64 v[68:69], v[34:35], 0, s[56:57]
	global_load_lds_dwordx4 v[68:69], off
	v_lshl_add_u64 v[68:69], v[36:37], 0, s[56:57]
	s_mov_b32 m0, s36
	s_nop 0
	global_load_lds_dwordx4 v[68:69], off
	v_lshl_add_u64 v[68:69], v[40:41], 0, s[56:57]
	s_mov_b32 m0, s37
	s_nop 0
	global_load_lds_dwordx4 v[68:69], off
	v_lshl_add_u64 v[68:69], v[38:39], 0, s[56:57]
	s_mov_b32 m0, s40
	s_nop 0
	global_load_lds_dwordx4 v[68:69], off
	v_lshl_add_u64 v[68:69], v[42:43], 0, s[56:57]
	s_mov_b32 m0, s46
	s_nop 0
	global_load_lds_dwordx4 v[68:69], off
	v_lshl_add_u64 v[68:69], v[44:45], 0, s[56:57]
	s_mov_b32 m0, s47
	s_nop 0
	global_load_lds_dwordx4 v[68:69], off
	ds_read_b128 v[68:71], v0
	ds_read_b128 v[72:75], v50 offset:16384
	ds_read_b128 v[76:79], v50 offset:20480
	s_waitcnt lgkmcnt(0)
	v_mfma_f32_32x32x16_bf16 v[2:17], v[68:71], v[72:75], v[2:17]
	s_mov_b32 m0, s9
	v_mfma_f32_32x32x16_bf16 v[18:33], v[68:71], v[76:79], v[18:33]
	ds_read_b128 v[68:71], v48
	ds_read_b128 v[72:75], v49 offset:16384
	ds_read_b128 v[76:79], v49 offset:20480
	s_waitcnt lgkmcnt(1)
	v_mfma_f32_32x32x16_bf16 v[2:17], v[68:71], v[72:75], v[2:17]
	s_waitcnt lgkmcnt(0)
	v_mfma_f32_32x32x16_bf16 v[18:33], v[68:71], v[76:79], v[18:33]
	ds_read_b128 v[68:71], v52
	ds_read_b128 v[72:75], v51 offset:16384
	ds_read_b128 v[76:79], v51 offset:20480
	s_waitcnt lgkmcnt(1)
	v_mfma_f32_32x32x16_bf16 v[2:17], v[68:71], v[72:75], v[2:17]
	s_waitcnt lgkmcnt(0)
	v_mfma_f32_32x32x16_bf16 v[18:33], v[68:71], v[76:79], v[18:33]
	ds_read_b128 v[68:71], v54
	ds_read_b128 v[72:75], v53 offset:16384
	ds_read_b128 v[76:79], v53 offset:20480
	s_waitcnt lgkmcnt(0)
	v_mfma_f32_32x32x16_bf16 v[2:17], v[68:71], v[72:75], v[2:17]
	v_mfma_f32_32x32x16_bf16 v[18:33], v[68:71], v[76:79], v[18:33]
	s_waitcnt vmcnt(0)
	s_barrier
	v_lshl_add_u64 v[68:69], v[34:35], 0, s[64:65]
	global_load_lds_dwordx4 v[68:69], off
	v_lshl_add_u64 v[68:69], v[36:37], 0, s[64:65]
	s_mov_b32 m0, s18
	s_nop 0
	global_load_lds_dwordx4 v[68:69], off
	v_lshl_add_u64 v[68:69], v[40:41], 0, s[64:65]
	s_mov_b32 m0, s28
	s_nop 0
	global_load_lds_dwordx4 v[68:69], off
	v_lshl_add_u64 v[68:69], v[38:39], 0, s[64:65]
	s_mov_b32 m0, s29
	s_nop 0
	global_load_lds_dwordx4 v[68:69], off
	v_lshl_add_u64 v[68:69], v[42:43], 0, s[64:65]
	s_mov_b32 m0, s34
	s_nop 0
	global_load_lds_dwordx4 v[68:69], off
	v_lshl_add_u64 v[68:69], v[44:45], 0, s[64:65]
	s_mov_b32 m0, s41
	s_nop 0
	global_load_lds_dwordx4 v[68:69], off
	ds_read_b128 v[68:71], v0 offset:32768
	ds_read_b128 v[72:75], v50 offset:49152
	ds_read_b128 v[76:79], v50 offset:53248
	s_waitcnt lgkmcnt(0)
	v_mfma_f32_32x32x16_bf16 v[2:17], v[68:71], v[72:75], v[2:17]
	s_mov_b32 m0, s35
	v_mfma_f32_32x32x16_bf16 v[18:33], v[68:71], v[76:79], v[18:33]
	ds_read_b128 v[68:71], v48 offset:32768
	ds_read_b128 v[72:75], v49 offset:49152
	ds_read_b128 v[76:79], v49 offset:53248
	s_waitcnt lgkmcnt(1)
	v_mfma_f32_32x32x16_bf16 v[2:17], v[68:71], v[72:75], v[2:17]
	s_waitcnt lgkmcnt(0)
	v_mfma_f32_32x32x16_bf16 v[18:33], v[68:71], v[76:79], v[18:33]
	ds_read_b128 v[68:71], v52 offset:32768
	ds_read_b128 v[72:75], v51 offset:49152
	ds_read_b128 v[76:79], v51 offset:53248
	s_waitcnt lgkmcnt(1)
	v_mfma_f32_32x32x16_bf16 v[2:17], v[68:71], v[72:75], v[2:17]
	s_waitcnt lgkmcnt(0)
	v_mfma_f32_32x32x16_bf16 v[18:33], v[68:71], v[76:79], v[18:33]
	ds_read_b128 v[68:71], v54 offset:32768
	ds_read_b128 v[72:75], v53 offset:49152
	ds_read_b128 v[76:79], v53 offset:53248
	s_waitcnt lgkmcnt(0)
	v_mfma_f32_32x32x16_bf16 v[2:17], v[68:71], v[72:75], v[2:17]
	v_mfma_f32_32x32x16_bf16 v[18:33], v[68:71], v[76:79], v[18:33]
	s_waitcnt vmcnt(0)
	s_barrier
	v_lshl_add_u64 v[68:69], v[34:35], 0, s[66:67]
	global_load_lds_dwordx4 v[68:69], off
	v_lshl_add_u64 v[68:69], v[36:37], 0, s[66:67]
	s_mov_b32 m0, s36
	s_nop 0
	global_load_lds_dwordx4 v[68:69], off
	v_lshl_add_u64 v[68:69], v[40:41], 0, s[66:67]
	s_mov_b32 m0, s37
	s_nop 0
	global_load_lds_dwordx4 v[68:69], off
	v_lshl_add_u64 v[68:69], v[38:39], 0, s[66:67]
	s_mov_b32 m0, s40
	s_nop 0
	global_load_lds_dwordx4 v[68:69], off
	v_lshl_add_u64 v[68:69], v[42:43], 0, s[66:67]
	s_mov_b32 m0, s46
	s_nop 0
	global_load_lds_dwordx4 v[68:69], off
	v_lshl_add_u64 v[68:69], v[44:45], 0, s[66:67]
	s_mov_b32 m0, s47
	s_nop 0
	global_load_lds_dwordx4 v[68:69], off
	ds_read_b128 v[68:71], v0
	ds_read_b128 v[72:75], v50 offset:16384
	ds_read_b128 v[76:79], v50 offset:20480
	s_waitcnt lgkmcnt(0)
	v_mfma_f32_32x32x16_bf16 v[2:17], v[68:71], v[72:75], v[2:17]
	s_mov_b32 m0, s9
	v_mfma_f32_32x32x16_bf16 v[18:33], v[68:71], v[76:79], v[18:33]
	ds_read_b128 v[68:71], v48
	ds_read_b128 v[72:75], v49 offset:16384
	ds_read_b128 v[76:79], v49 offset:20480
	s_waitcnt lgkmcnt(1)
	v_mfma_f32_32x32x16_bf16 v[2:17], v[68:71], v[72:75], v[2:17]
	s_waitcnt lgkmcnt(0)
	v_mfma_f32_32x32x16_bf16 v[18:33], v[68:71], v[76:79], v[18:33]
	ds_read_b128 v[68:71], v52
	ds_read_b128 v[72:75], v51 offset:16384
	ds_read_b128 v[76:79], v51 offset:20480
	s_waitcnt lgkmcnt(1)
	v_mfma_f32_32x32x16_bf16 v[2:17], v[68:71], v[72:75], v[2:17]
	s_waitcnt lgkmcnt(0)
	v_mfma_f32_32x32x16_bf16 v[18:33], v[68:71], v[76:79], v[18:33]
	ds_read_b128 v[68:71], v54
	ds_read_b128 v[72:75], v53 offset:16384
	ds_read_b128 v[76:79], v53 offset:20480
	s_waitcnt lgkmcnt(0)
	v_mfma_f32_32x32x16_bf16 v[2:17], v[68:71], v[72:75], v[2:17]
	v_mfma_f32_32x32x16_bf16 v[18:33], v[68:71], v[76:79], v[18:33]
	s_waitcnt vmcnt(0)
	s_barrier
; #define MFMA(a, b, c) __builtin_amdgcn_mfma_f32_32x32x16_bf16((a), (b), (c), 0, 0, 0)
; #define TIDX opaque_tid()
; template <int AI, int BI>
; DI void gemm_stage(const u16* __restrict__ A, int lda, const u16* __restrict__ B, int ldb, char* buf, int tid) {
; #pragma unroll
;   for (int i = 0; i < 2 * AI; ++i) {
;     const int S = tid + NTHR * i, row = S >> 3, c = (S & 7) ^ ((row >> 1) & 7);
;     __builtin_amdgcn_global_load_lds((const unsigned*)(A + (size_t)row * lda + c * 8), (__attribute__((address_space(3))) unsigned*)(buf + S * 16), 16, 0, 0);
;   }
; #pragma unroll
;   for (int i = 0; i < 2 * BI; ++i) {
;     const int S = tid + NTHR * i, row = S >> 3, c = (S & 7) ^ ((row >> 1) & 7);
;     __builtin_amdgcn_global_load_lds((const unsigned*)(B + (size_t)row * ldb + c * 8), (__attribute__((address_space(3))) unsigned*)(buf + 16384 + S * 16), 16, 0, 0);
;   }
; }
; template <int AI, int BI>
; DI void gemm_tile(const u16* __restrict__ A, int lda, const u16* __restrict__ B, int ldb, int nk, bool swap,
;                   f32x16 (&acc)[AI][BI], char* lds) {
;   const int tid = TIDX, lane = tid & 63, wid = tid >> 6;
;   gemm_stage<AI, BI>(A, lda, B, ldb, lds, tid);
;   asm volatile("s_waitcnt vmcnt(0)" ::: "memory");
;   __syncthreads();
;   const int wa = wid >> 1, wb = wid & 1, r = lane & 31, h = lane >> 5, sw = (r >> 1) & 7;
;   const int offA = (swap ? 16384 : 0) + (wa * 32 * AI + r) * 128;
;   const int offB = (swap ? 0 : 16384) + (wb * 32 * BI + r) * 128;
;   for (int kt = 0; kt < nk; ++kt) {
;     const char* cur = lds + (kt & 1) * 32768;
;     if (kt + 1 < nk) gemm_stage<AI, BI>(A + (kt + 1) * 64, lda, B + (kt + 1) * 64, ldb, lds + ((kt + 1) & 1) * 32768, tid);
; #pragma unroll
;     for (int ks = 0; ks < 4; ++ks) {
;       const int co = ((ks * 2 + h) ^ sw) << 4;
;       s16x8 fa[AI], fb[BI];
; #pragma unroll
;       for (int i = 0; i < AI; ++i) fa[i] = *(const s16x8*)(cur + offA + i * 4096 + co);
; #pragma unroll
;       for (int i = 0; i < BI; ++i) fb[i] = *(const s16x8*)(cur + offB + i * 4096 + co);
; #pragma unroll
;       for (int i = 0; i < AI; ++i)
; #pragma unroll
;         for (int j = 0; j < BI; ++j) acc[i][j] = MFMA(fa[i], fb[j], acc[i][j]);
;     }
;     asm volatile("s_waitcnt vmcnt(0)" ::: "memory");
;     __syncthreads();
;   }
	v_lshl_add_u64 v[68:69], v[34:35], 0, s[68:69]
	global_load_lds_dwordx4 v[68:69], off
	v_lshl_add_u64 v[68:69], v[36:37], 0, s[68:69]
	s_mov_b32 m0, s18
	s_nop 0
	global_load_lds_dwordx4 v[68:69], off
	v_lshl_add_u64 v[68:69], v[40:41], 0, s[68:69]
	s_mov_b32 m0, s28
	s_nop 0
	global_load_lds_dwordx4 v[68:69], off
	v_lshl_add_u64 v[68:69], v[38:39], 0, s[68:69]
	s_mov_b32 m0, s29
	s_nop 0
	global_load_lds_dwordx4 v[68:69], off
	v_lshl_add_u64 v[68:69], v[42:43], 0, s[68:69]
	s_mov_b32 m0, s34
	s_nop 0
	global_load_lds_dwordx4 v[68:69], off
	v_lshl_add_u64 v[68:69], v[44:45], 0, s[68:69]
	s_mov_b32 m0, s41
	s_nop 0
	global_load_lds_dwordx4 v[68:69], off
	ds_read_b128 v[68:71], v0 offset:32768
	ds_read_b128 v[72:75], v50 offset:49152
	ds_read_b128 v[76:79], v50 offset:53248
	s_waitcnt lgkmcnt(0)
	v_mfma_f32_32x32x16_bf16 v[2:17], v[68:71], v[72:75], v[2:17]
	s_mov_b32 m0, s35
	v_mfma_f32_32x32x16_bf16 v[18:33], v[68:71], v[76:79], v[18:33]
	ds_read_b128 v[68:71], v48 offset:32768
	ds_read_b128 v[72:75], v49 offset:49152
	ds_read_b128 v[76:79], v49 offset:53248
	s_waitcnt lgkmcnt(1)
	v_mfma_f32_32x32x16_bf16 v[2:17], v[68:71], v[72:75], v[2:17]
	s_waitcnt lgkmcnt(0)
	v_mfma_f32_32x32x16_bf16 v[18:33], v[68:71], v[76:79], v[18:33]
	ds_read_b128 v[68:71], v52 offset:32768
	ds_read_b128 v[72:75], v51 offset:49152
	ds_read_b128 v[76:79], v51 offset:53248
	s_waitcnt lgkmcnt(1)
	v_mfma_f32_32x32x16_bf16 v[2:17], v[68:71], v[72:75], v[2:17]
	s_waitcnt lgkmcnt(0)
	v_mfma_f32_32x32x16_bf16 v[18:33], v[68:71], v[76:79], v[18:33]
	ds_read_b128 v[68:71], v54 offset:32768
	ds_read_b128 v[72:75], v53 offset:49152
	ds_read_b128 v[76:79], v53 offset:53248
	s_waitcnt lgkmcnt(0)
	v_mfma_f32_32x32x16_bf16 v[2:17], v[68:71], v[72:75], v[2:17]
	v_mfma_f32_32x32x16_bf16 v[18:33], v[68:71], v[76:79], v[18:33]
	s_waitcnt vmcnt(0)
	s_barrier
	v_lshl_add_u64 v[68:69], v[34:35], 0, s[70:71]
	global_load_lds_dwordx4 v[68:69], off
	v_lshl_add_u64 v[68:69], v[36:37], 0, s[70:71]
	s_mov_b32 m0, s36
	s_nop 0
	global_load_lds_dwordx4 v[68:69], off
	v_lshl_add_u64 v[68:69], v[40:41], 0, s[70:71]
	s_mov_b32 m0, s37
	s_nop 0
	global_load_lds_dwordx4 v[68:69], off
	v_lshl_add_u64 v[68:69], v[38:39], 0, s[70:71]
	s_mov_b32 m0, s40
	s_nop 0
	global_load_lds_dwordx4 v[68:69], off
	v_lshl_add_u64 v[68:69], v[42:43], 0, s[70:71]
	s_mov_b32 m0, s46
	s_nop 0
	global_load_lds_dwordx4 v[68:69], off
	v_lshl_add_u64 v[68:69], v[44:45], 0, s[70:71]
	s_mov_b32 m0, s47
	s_nop 0
	global_load_lds_dwordx4 v[68:69], off
	ds_read_b128 v[68:71], v0
	ds_read_b128 v[72:75], v50 offset:16384
	ds_read_b128 v[76:79], v50 offset:20480
	s_waitcnt lgkmcnt(0)
	v_mfma_f32_32x32x16_bf16 v[2:17], v[68:71], v[72:75], v[2:17]
	s_mov_b32 m0, s9
	v_readfirstlane_b32 s9, v55
	v_and_b32_e32 v55, 31, v46
	v_mfma_f32_32x32x16_bf16 v[18:33], v[68:71], v[76:79], v[18:33]
	ds_read_b128 v[68:71], v48
	ds_read_b128 v[72:75], v49 offset:16384
	ds_read_b128 v[76:79], v49 offset:20480
	s_waitcnt lgkmcnt(1)
	v_mfma_f32_32x32x16_bf16 v[2:17], v[68:71], v[72:75], v[2:17]
	s_waitcnt lgkmcnt(0)
	v_mfma_f32_32x32x16_bf16 v[18:33], v[68:71], v[76:79], v[18:33]
	ds_read_b128 v[68:71], v52
	ds_read_b128 v[72:75], v51 offset:16384
	ds_read_b128 v[76:79], v51 offset:20480
	s_waitcnt lgkmcnt(1)
	v_mfma_f32_32x32x16_bf16 v[2:17], v[68:71], v[72:75], v[2:17]
	s_waitcnt lgkmcnt(0)
	v_mfma_f32_32x32x16_bf16 v[18:33], v[68:71], v[76:79], v[18:33]
	ds_read_b128 v[68:71], v54
	ds_read_b128 v[72:75], v53 offset:16384
	ds_read_b128 v[76:79], v53 offset:20480
	s_waitcnt lgkmcnt(0)
	v_mfma_f32_32x32x16_bf16 v[2:17], v[68:71], v[72:75], v[2:17]
	v_mfma_f32_32x32x16_bf16 v[18:33], v[68:71], v[76:79], v[18:33]
	s_waitcnt vmcnt(0)
	s_barrier
	v_lshl_add_u64 v[68:69], v[34:35], 0, s[72:73]
	global_load_lds_dwordx4 v[68:69], off
	v_lshl_add_u64 v[68:69], v[36:37], 0, s[72:73]
	s_mov_b32 m0, s18
	v_readfirstlane_b32 s18, v56
	global_load_lds_dwordx4 v[68:69], off
	v_lshl_add_u64 v[68:69], v[40:41], 0, s[72:73]
	s_mov_b32 m0, s28
	v_readfirstlane_b32 s28, v57
	global_load_lds_dwordx4 v[68:69], off
	v_lshl_add_u64 v[68:69], v[38:39], 0, s[72:73]
	s_mov_b32 m0, s29
	v_readfirstlane_b32 s29, v58
	global_load_lds_dwordx4 v[68:69], off
	v_lshl_add_u64 v[68:69], v[42:43], 0, s[72:73]
	s_mov_b32 m0, s34
	v_lshl_add_u64 v[56:57], v[38:39], 0, s[76:77]
	global_load_lds_dwordx4 v[68:69], off
	v_lshl_add_u64 v[68:69], v[44:45], 0, s[72:73]
	s_mov_b32 m0, s41
	v_readfirstlane_b32 s34, v65
	global_load_lds_dwordx4 v[68:69], off
	ds_read_b128 v[68:71], v0 offset:32768
	ds_read_b128 v[72:75], v50 offset:49152
	ds_read_b128 v[76:79], v50 offset:53248
	s_waitcnt lgkmcnt(0)
	v_mfma_f32_32x32x16_bf16 v[2:17], v[68:71], v[72:75], v[2:17]
	s_mov_b32 m0, s35
	v_readfirstlane_b32 s35, v66
	v_readfirstlane_b32 s41, v61
	v_mfma_f32_32x32x16_bf16 v[18:33], v[68:71], v[76:79], v[18:33]
	ds_read_b128 v[68:71], v48 offset:32768
	ds_read_b128 v[72:75], v49 offset:49152
	ds_read_b128 v[76:79], v49 offset:53248
	s_waitcnt lgkmcnt(1)
	v_mfma_f32_32x32x16_bf16 v[2:17], v[68:71], v[72:75], v[2:17]
	s_waitcnt lgkmcnt(0)
	v_mfma_f32_32x32x16_bf16 v[18:33], v[68:71], v[76:79], v[18:33]
	ds_read_b128 v[68:71], v52 offset:32768
	ds_read_b128 v[72:75], v51 offset:49152
	ds_read_b128 v[76:79], v51 offset:53248
	s_waitcnt lgkmcnt(1)
	v_mfma_f32_32x32x16_bf16 v[2:17], v[68:71], v[72:75], v[2:17]
	s_waitcnt lgkmcnt(0)
	v_mfma_f32_32x32x16_bf16 v[18:33], v[68:71], v[76:79], v[18:33]
	ds_read_b128 v[68:71], v54 offset:32768
	ds_read_b128 v[72:75], v53 offset:49152
	ds_read_b128 v[76:79], v53 offset:53248
	s_waitcnt lgkmcnt(0)
	v_mfma_f32_32x32x16_bf16 v[2:17], v[68:71], v[72:75], v[2:17]
	v_mfma_f32_32x32x16_bf16 v[18:33], v[68:71], v[76:79], v[18:33]
	s_waitcnt vmcnt(0)
	s_barrier
; #define MFMA(a, b, c) __builtin_amdgcn_mfma_f32_32x32x16_bf16((a), (b), (c), 0, 0, 0)
; #define TIDX opaque_tid()
; template <int AI, int BI>
; DI void gemm_stage(const u16* __restrict__ A, int lda, const u16* __restrict__ B, int ldb, char* buf, int tid) {
; #pragma unroll
;   for (int i = 0; i < 2 * AI; ++i) {
;     const int S = tid + NTHR * i, row = S >> 3, c = (S & 7) ^ ((row >> 1) & 7);
;     __builtin_amdgcn_global_load_lds((const unsigned*)(A + (size_t)row * lda + c * 8), (__attribute__((address_space(3))) unsigned*)(buf + S * 16), 16, 0, 0);
;   }
; #pragma unroll
;   for (int i = 0; i < 2 * BI; ++i) {
;     const int S = tid + NTHR * i, row = S >> 3, c = (S & 7) ^ ((row >> 1) & 7);
;     __builtin_amdgcn_global_load_lds((const unsigned*)(B + (size_t)row * ldb + c * 8), (__attribute__((address_space(3))) unsigned*)(buf + 16384 + S * 16), 16, 0, 0);
;   }
; }
; template <int AI, int BI>
; DI void gemm_tile(const u16* __restrict__ A, int lda, const u16* __restrict__ B, int ldb, int nk, bool swap,
;                   f32x16 (&acc)[AI][BI], char* lds) {
;   const int tid = TIDX, lane = tid & 63, wid = tid >> 6;
;   gemm_stage<AI, BI>(A, lda, B, ldb, lds, tid);
;   asm volatile("s_waitcnt vmcnt(0)" ::: "memory");
;   __syncthreads();
;   const int wa = wid >> 1, wb = wid & 1, r = lane & 31, h = lane >> 5, sw = (r >> 1) & 7;
;   const int offA = (swap ? 16384 : 0) + (wa * 32 * AI + r) * 128;
;   const int offB = (swap ? 0 : 16384) + (wb * 32 * BI + r) * 128;
;   for (int kt = 0; kt < nk; ++kt) {
;     const char* cur = lds + (kt & 1) * 32768;
;     if (kt + 1 < nk) gemm_stage<AI, BI>(A + (kt + 1) * 64, lda, B + (kt + 1) * 64, ldb, lds + ((kt + 1) & 1) * 32768, tid);
; #pragma unroll
;     for (int ks = 0; ks < 4; ++ks) {
;       const int co = ((ks * 2 + h) ^ sw) << 4;
;       s16x8 fa[AI], fb[BI];
; #pragma unroll
;       for (int i = 0; i < AI; ++i) fa[i] = *(const s16x8*)(cur + offA + i * 4096 + co);
; #pragma unroll
;       for (int i = 0; i < BI; ++i) fb[i] = *(const s16x8*)(cur + offB + i * 4096 + co);
; #pragma unroll
;       for (int i = 0; i < AI; ++i)
; #pragma unroll
;         for (int j = 0; j < BI; ++j) acc[i][j] = MFMA(fa[i], fb[j], acc[i][j]);
;     }
;     asm volatile("s_waitcnt vmcnt(0)" ::: "memory");
;     __syncthreads();
;   }
	v_lshl_add_u64 v[68:69], v[34:35], 0, s[74:75]
	global_load_lds_dwordx4 v[68:69], off
	v_lshl_add_u64 v[68:69], v[36:37], 0, s[74:75]
	s_mov_b32 m0, s36
	v_readfirstlane_b32 s36, v63
	global_load_lds_dwordx4 v[68:69], off
	v_lshl_add_u64 v[68:69], v[40:41], 0, s[74:75]
	s_mov_b32 m0, s37
	v_readfirstlane_b32 s37, v60
	global_load_lds_dwordx4 v[68:69], off
	v_lshl_add_u64 v[68:69], v[38:39], 0, s[74:75]
	s_mov_b32 m0, s40
	v_readfirstlane_b32 s40, v59
	global_load_lds_dwordx4 v[68:69], off
	v_lshl_add_u64 v[68:69], v[42:43], 0, s[74:75]
	s_mov_b32 m0, s46
	v_readfirstlane_b32 s46, v62
	global_load_lds_dwordx4 v[68:69], off
	v_lshl_add_u64 v[68:69], v[44:45], 0, s[74:75]
	s_mov_b32 m0, s47
	v_readfirstlane_b32 s47, v64
	global_load_lds_dwordx4 v[68:69], off
	ds_read_b128 v[68:71], v0
	ds_read_b128 v[72:75], v50 offset:16384
	ds_read_b128 v[76:79], v50 offset:20480
	s_waitcnt lgkmcnt(0)
	v_mfma_f32_32x32x16_bf16 v[2:17], v[68:71], v[72:75], v[2:17]
	s_mov_b32 m0, s9
	v_mfma_f32_32x32x16_bf16 v[18:33], v[68:71], v[76:79], v[18:33]
	ds_read_b128 v[68:71], v48
	ds_read_b128 v[72:75], v49 offset:16384
	ds_read_b128 v[76:79], v49 offset:20480
	s_waitcnt lgkmcnt(1)
	v_mfma_f32_32x32x16_bf16 v[2:17], v[68:71], v[72:75], v[2:17]
	s_waitcnt lgkmcnt(0)
	v_mfma_f32_32x32x16_bf16 v[18:33], v[68:71], v[76:79], v[18:33]
	ds_read_b128 v[68:71], v52
	ds_read_b128 v[72:75], v51 offset:16384
	ds_read_b128 v[76:79], v51 offset:20480
	s_waitcnt lgkmcnt(1)
	v_mfma_f32_32x32x16_bf16 v[2:17], v[68:71], v[72:75], v[2:17]
	s_waitcnt lgkmcnt(0)
	v_mfma_f32_32x32x16_bf16 v[18:33], v[68:71], v[76:79], v[18:33]
	ds_read_b128 v[68:71], v54
	ds_read_b128 v[72:75], v53 offset:16384
	ds_read_b128 v[76:79], v53 offset:20480
	s_waitcnt lgkmcnt(0)
	v_mfma_f32_32x32x16_bf16 v[2:17], v[68:71], v[72:75], v[2:17]
	v_mfma_f32_32x32x16_bf16 v[18:33], v[68:71], v[76:79], v[18:33]
	s_waitcnt vmcnt(0)
	s_barrier
	v_lshl_add_u64 v[68:69], v[34:35], 0, s[76:77]
	global_load_lds_dwordx4 v[68:69], off
	v_lshl_add_u64 v[68:69], v[36:37], 0, s[76:77]
	s_mov_b32 m0, s18
	s_nop 0
	global_load_lds_dwordx4 v[68:69], off
	v_lshl_add_u64 v[68:69], v[40:41], 0, s[76:77]
	s_mov_b32 m0, s28
	s_nop 0
	global_load_lds_dwordx4 v[68:69], off
	s_mov_b32 m0, s29
	s_nop 0
	global_load_lds_dwordx4 v[56:57], off
	v_lshl_add_u64 v[56:57], v[42:43], 0, s[76:77]
	s_mov_b32 m0, s34
	s_nop 0
	global_load_lds_dwordx4 v[56:57], off
	v_lshl_add_u64 v[56:57], v[44:45], 0, s[76:77]
	s_mov_b32 m0, s35
	s_nop 0
	global_load_lds_dwordx4 v[56:57], off
	ds_read_b128 v[66:69], v0 offset:32768
	ds_read_b128 v[70:73], v50 offset:49152
	ds_read_b128 v[74:77], v50 offset:53248
	s_waitcnt lgkmcnt(0)
	v_mfma_f32_32x32x16_bf16 v[2:17], v[66:69], v[70:73], v[2:17]
	v_lshl_add_u64 v[56:57], v[34:35], 0, s[78:79]
	s_mov_b32 m0, s36
	v_mfma_f32_32x32x16_bf16 v[18:33], v[66:69], v[74:77], v[18:33]
	ds_read_b128 v[66:69], v48 offset:32768
	ds_read_b128 v[70:73], v49 offset:49152
	ds_read_b128 v[74:77], v49 offset:53248
	s_waitcnt lgkmcnt(1)
	v_mfma_f32_32x32x16_bf16 v[2:17], v[66:69], v[70:73], v[2:17]
	s_waitcnt lgkmcnt(0)
	v_mfma_f32_32x32x16_bf16 v[18:33], v[66:69], v[74:77], v[18:33]
	ds_read_b128 v[66:69], v52 offset:32768
	ds_read_b128 v[70:73], v51 offset:49152
	ds_read_b128 v[74:77], v51 offset:53248
	s_waitcnt lgkmcnt(1)
	v_mfma_f32_32x32x16_bf16 v[2:17], v[66:69], v[70:73], v[2:17]
	s_waitcnt lgkmcnt(0)
	v_mfma_f32_32x32x16_bf16 v[18:33], v[66:69], v[74:77], v[18:33]
	ds_read_b128 v[66:69], v54 offset:32768
	ds_read_b128 v[70:73], v53 offset:49152
	ds_read_b128 v[74:77], v53 offset:53248
	s_waitcnt vmcnt(0)
	s_waitcnt lgkmcnt(0)
	s_barrier
	global_load_lds_dwordx4 v[56:57], off
	v_lshl_add_u64 v[56:57], v[36:37], 0, s[78:79]
	s_mov_b32 m0, s37
	v_mfma_f32_32x32x16_bf16 v[2:17], v[66:69], v[70:73], v[2:17]
	global_load_lds_dwordx4 v[56:57], off
	v_lshl_add_u64 v[56:57], v[40:41], 0, s[78:79]
	s_mov_b32 m0, s40
	s_nop 0
	global_load_lds_dwordx4 v[56:57], off
	v_lshl_add_u64 v[56:57], v[38:39], 0, s[78:79]
	s_mov_b32 m0, s41
	v_mfma_f32_32x32x16_bf16 v[18:33], v[66:69], v[74:77], v[18:33]
	global_load_lds_dwordx4 v[56:57], off
	v_lshl_add_u64 v[56:57], v[42:43], 0, s[78:79]
	s_mov_b32 m0, s46
	s_nop 0
	global_load_lds_dwordx4 v[56:57], off
	v_lshl_add_u64 v[56:57], v[44:45], 0, s[78:79]
	s_mov_b32 m0, s47
	s_nop 0
	global_load_lds_dwordx4 v[56:57], off
	ds_read_b128 v[56:59], v0
	ds_read_b128 v[60:63], v50 offset:16384
	ds_read_b128 v[64:67], v50 offset:20480
	s_waitcnt lgkmcnt(0)
	v_mfma_f32_32x32x16_bf16 v[2:17], v[56:59], v[60:63], v[2:17]
	s_mov_b32 m0, s9
	s_movk_i32 s9, 0xb00
	v_mfma_f32_32x32x16_bf16 v[18:33], v[56:59], v[64:67], v[18:33]
	ds_read_b128 v[56:59], v48
	ds_read_b128 v[60:63], v49 offset:16384
	ds_read_b128 v[64:67], v49 offset:20480
	s_waitcnt lgkmcnt(1)
	v_mfma_f32_32x32x16_bf16 v[2:17], v[56:59], v[60:63], v[2:17]
	s_waitcnt lgkmcnt(0)
	v_mfma_f32_32x32x16_bf16 v[18:33], v[56:59], v[64:67], v[18:33]
	ds_read_b128 v[56:59], v52
	ds_read_b128 v[60:63], v51 offset:16384
	ds_read_b128 v[64:67], v51 offset:20480
	s_waitcnt lgkmcnt(1)
	v_mfma_f32_32x32x16_bf16 v[2:17], v[56:59], v[60:63], v[2:17]
	s_waitcnt lgkmcnt(0)
	v_mfma_f32_32x32x16_bf16 v[18:33], v[56:59], v[64:67], v[18:33]
	ds_read_b128 v[56:59], v54
	ds_read_b128 v[60:63], v53 offset:16384
	ds_read_b128 v[64:67], v53 offset:20480
	s_waitcnt lgkmcnt(0)
	v_mfma_f32_32x32x16_bf16 v[2:17], v[56:59], v[60:63], v[2:17]
	v_mfma_f32_32x32x16_bf16 v[18:33], v[56:59], v[64:67], v[18:33]
	s_waitcnt vmcnt(0)
	s_barrier
; #define MFMA(a, b, c) __builtin_amdgcn_mfma_f32_32x32x16_bf16((a), (b), (c), 0, 0, 0)
; #define TIDX opaque_tid()
; template <int AI, int BI>
; DI void gemm_stage(const u16* __restrict__ A, int lda, const u16* __restrict__ B, int ldb, char* buf, int tid) {
; #pragma unroll
;   for (int i = 0; i < 2 * AI; ++i) {
;     const int S = tid + NTHR * i, row = S >> 3, c = (S & 7) ^ ((row >> 1) & 7);
;     __builtin_amdgcn_global_load_lds((const unsigned*)(A + (size_t)row * lda + c * 8), (__attribute__((address_space(3))) unsigned*)(buf + S * 16), 16, 0, 0);
;   }
; #pragma unroll
;   for (int i = 0; i < 2 * BI; ++i) {
;     const int S = tid + NTHR * i, row = S >> 3, c = (S & 7) ^ ((row >> 1) & 7);
;     __builtin_amdgcn_global_load_lds((const unsigned*)(B + (size_t)row * ldb + c * 8), (__attribute__((address_space(3))) unsigned*)(buf + 16384 + S * 16), 16, 0, 0);
;   }
; }
; template <int AI, int BI>
; DI void gemm_tile(const u16* __restrict__ A, int lda, const u16* __restrict__ B, int ldb, int nk, bool swap,
;                   f32x16 (&acc)[AI][BI], char* lds) {
;   const int tid = TIDX, lane = tid & 63, wid = tid >> 6;
;   gemm_stage<AI, BI>(A, lda, B, ldb, lds, tid);
;   asm volatile("s_waitcnt vmcnt(0)" ::: "memory");
;   __syncthreads();
;   const int wa = wid >> 1, wb = wid & 1, r = lane & 31, h = lane >> 5, sw = (r >> 1) & 7;
;   const int offA = (swap ? 16384 : 0) + (wa * 32 * AI + r) * 128;
;   const int offB = (swap ? 0 : 16384) + (wb * 32 * BI + r) * 128;
;   for (int kt = 0; kt < nk; ++kt) {
;     const char* cur = lds + (kt & 1) * 32768;
;     if (kt + 1 < nk) gemm_stage<AI, BI>(A + (kt + 1) * 64, lda, B + (kt + 1) * 64, ldb, lds + ((kt + 1) & 1) * 32768, tid);
; #pragma unroll
;     for (int ks = 0; ks < 4; ++ks) {
;       const int co = ((ks * 2 + h) ^ sw) << 4;
;       s16x8 fa[AI], fb[BI];
; #pragma unroll
;       for (int i = 0; i < AI; ++i) fa[i] = *(const s16x8*)(cur + offA + i * 4096 + co);
; #pragma unroll
;       for (int i = 0; i < BI; ++i) fb[i] = *(const s16x8*)(cur + offB + i * 4096 + co);
; #pragma unroll
;       for (int i = 0; i < AI; ++i)
; #pragma unroll
;         for (int j = 0; j < BI; ++j) acc[i][j] = MFMA(fa[i], fb[j], acc[i][j]);
;     }
;     asm volatile("s_waitcnt vmcnt(0)" ::: "memory");
;     __syncthreads();
;   }
	v_lshl_add_u64 v[56:57], v[34:35], 0, s[2:3]
	global_load_lds_dwordx4 v[56:57], off
	v_lshl_add_u64 v[56:57], v[36:37], 0, s[2:3]
	s_mov_b32 m0, s18
	v_lshl_add_u64 v[34:35], v[34:35], 0, s[30:31]
	global_load_lds_dwordx4 v[56:57], off
	v_lshl_add_u64 v[56:57], v[40:41], 0, s[2:3]
	s_mov_b32 m0, s28
	s_mov_b32 s18, 0xffffe0
	global_load_lds_dwordx4 v[56:57], off
	v_lshl_add_u64 v[56:57], v[38:39], 0, s[2:3]
	s_mov_b32 m0, s29
	s_nop 0
	global_load_lds_dwordx4 v[56:57], off
	v_lshl_add_u64 v[56:57], v[42:43], 0, s[2:3]
	s_mov_b32 m0, s34
	s_nop 0
	global_load_lds_dwordx4 v[56:57], off
	v_lshl_add_u64 v[56:57], v[44:45], 0, s[2:3]
	s_mov_b32 m0, s35
	s_nop 0
	global_load_lds_dwordx4 v[56:57], off
	ds_read_b128 v[56:59], v0 offset:32768
	ds_read_b128 v[60:63], v50 offset:49152
	ds_read_b128 v[64:67], v50 offset:53248
	s_waitcnt lgkmcnt(0)
	v_mfma_f32_32x32x16_bf16 v[2:17], v[56:59], v[60:63], v[2:17]
	s_mov_b32 m0, s36
	v_mfma_f32_32x32x16_bf16 v[18:33], v[56:59], v[64:67], v[18:33]
	ds_read_b128 v[56:59], v48 offset:32768
	ds_read_b128 v[60:63], v49 offset:49152
	ds_read_b128 v[64:67], v49 offset:53248
	s_waitcnt lgkmcnt(1)
	v_mfma_f32_32x32x16_bf16 v[2:17], v[56:59], v[60:63], v[2:17]
	s_waitcnt lgkmcnt(0)
	v_mfma_f32_32x32x16_bf16 v[18:33], v[56:59], v[64:67], v[18:33]
	ds_read_b128 v[56:59], v52 offset:32768
	ds_read_b128 v[60:63], v51 offset:49152
	ds_read_b128 v[64:67], v51 offset:53248
	s_waitcnt lgkmcnt(1)
	v_mfma_f32_32x32x16_bf16 v[2:17], v[56:59], v[60:63], v[2:17]
	s_waitcnt lgkmcnt(0)
	v_mfma_f32_32x32x16_bf16 v[18:33], v[56:59], v[64:67], v[18:33]
	ds_read_b128 v[56:59], v54 offset:32768
	ds_read_b128 v[60:63], v53 offset:49152
	ds_read_b128 v[64:67], v53 offset:53248
	s_waitcnt vmcnt(0)
	s_waitcnt lgkmcnt(0)
	s_barrier
	global_load_lds_dwordx4 v[34:35], off
	v_lshl_add_u64 v[34:35], v[36:37], 0, s[30:31]
	s_mov_b32 m0, s37
	v_mfma_f32_32x32x16_bf16 v[2:17], v[56:59], v[60:63], v[2:17]
	global_load_lds_dwordx4 v[34:35], off
	v_lshl_add_u64 v[34:35], v[40:41], 0, s[30:31]
	s_mov_b32 m0, s40
	s_nop 0
	global_load_lds_dwordx4 v[34:35], off
	v_lshl_add_u64 v[34:35], v[38:39], 0, s[30:31]
	s_mov_b32 m0, s41
	v_mfma_f32_32x32x16_bf16 v[18:33], v[56:59], v[64:67], v[18:33]
	global_load_lds_dwordx4 v[34:35], off
	v_lshl_add_u64 v[34:35], v[42:43], 0, s[30:31]
	s_mov_b32 m0, s46
	s_nop 0
	global_load_lds_dwordx4 v[34:35], off
	v_lshl_add_u64 v[34:35], v[44:45], 0, s[30:31]
	s_mov_b32 m0, s47
	s_nop 0
	global_load_lds_dwordx4 v[34:35], off
	ds_read_b128 v[34:37], v0
	ds_read_b128 v[38:41], v50 offset:16384
	ds_read_b128 v[42:45], v50 offset:20480
	s_waitcnt lgkmcnt(0)
	v_mfma_f32_32x32x16_bf16 v[2:17], v[34:37], v[38:41], v[2:17]
	v_mfma_f32_32x32x16_bf16 v[18:33], v[34:37], v[42:45], v[18:33]
	ds_read_b128 v[34:37], v48
	ds_read_b128 v[38:41], v49 offset:16384
	ds_read_b128 v[42:45], v49 offset:20480
	s_waitcnt lgkmcnt(1)
	v_mfma_f32_32x32x16_bf16 v[2:17], v[34:37], v[38:41], v[2:17]
	s_waitcnt lgkmcnt(0)
	v_mfma_f32_32x32x16_bf16 v[18:33], v[34:37], v[42:45], v[18:33]
	ds_read_b128 v[34:37], v52
	ds_read_b128 v[38:41], v51 offset:16384
	ds_read_b128 v[42:45], v51 offset:20480
	s_waitcnt lgkmcnt(1)
	v_mfma_f32_32x32x16_bf16 v[2:17], v[34:37], v[38:41], v[2:17]
	s_waitcnt lgkmcnt(0)
	v_mfma_f32_32x32x16_bf16 v[18:33], v[34:37], v[42:45], v[18:33]
	ds_read_b128 v[34:37], v54
	ds_read_b128 v[38:41], v53 offset:16384
	ds_read_b128 v[42:45], v53 offset:20480
	s_waitcnt lgkmcnt(0)
	v_mfma_f32_32x32x16_bf16 v[2:17], v[34:37], v[38:41], v[2:17]
	v_mfma_f32_32x32x16_bf16 v[18:33], v[34:37], v[42:45], v[18:33]
	s_waitcnt vmcnt(0)
	s_barrier
	ds_read_b128 v[34:37], v50 offset:53248
	ds_read_b128 v[38:41], v50 offset:49152
	ds_read_b128 v[42:45], v0 offset:32768
	v_mov_b32_e32 v0, v1
	s_waitcnt lgkmcnt(0)
	v_mfma_f32_32x32x16_bf16 v[2:17], v[42:45], v[38:41], v[2:17]
	v_mfma_f32_32x32x16_bf16 v[18:33], v[42:45], v[34:37], v[18:33]
	ds_read_b128 v[34:37], v48 offset:32768
	ds_read_b128 v[38:41], v49 offset:49152
	ds_read_b128 v[42:45], v49 offset:53248
	s_waitcnt lgkmcnt(1)
	v_mfma_f32_32x32x16_bf16 v[2:17], v[34:37], v[38:41], v[2:17]
	s_waitcnt lgkmcnt(0)
	v_mfma_f32_32x32x16_bf16 v[18:33], v[34:37], v[42:45], v[18:33]
	ds_read_b128 v[34:37], v52 offset:32768
	ds_read_b128 v[38:41], v51 offset:49152
	ds_read_b128 v[42:45], v51 offset:53248
	s_waitcnt lgkmcnt(1)
	v_mfma_f32_32x32x16_bf16 v[2:17], v[34:37], v[38:41], v[2:17]
	s_waitcnt lgkmcnt(0)
	v_mfma_f32_32x32x16_bf16 v[18:33], v[34:37], v[42:45], v[18:33]
	ds_read_b128 v[34:37], v54 offset:32768
	ds_read_b128 v[38:41], v53 offset:49152
	ds_read_b128 v[42:45], v53 offset:53248
	s_waitcnt vmcnt(0)
	s_waitcnt lgkmcnt(0)
	s_barrier
; #define TIDX opaque_tid()
; #define GAS __attribute__((address_space(1)))
; DI int opaque0() { int z = 0; asm volatile("" : "+v"(z)); return z; }
; template <int AI>
; DI void gu_tile(char* wsb, int sub, int m0, int n0, char* lds) {
;     ...
;   const int lane = TIDX & 63, wid = TIDX >> 6, wa = wid >> 1, wb = wid & 1, r = lane & 31, h = lane >> 5;
;   f32x16 acc[AI][2]; zero_acc<AI, 2>(acc);
;   gemm_tile<AI, 2>(H + (size_t)m0 * 1024, 1024, W + (size_t)n0 * 1024, 1024, 16, false, acc, lds);
;   const int m0e = m0 + opaque0();
;   const int hc = (n0 >> 1) + wb * 32 + r;
;   GAS u16* HIDu = uptr(HID);
;   const unsigned ib = (unsigned)((m0e + wa * 32 * AI + 4 * h) * 2816 + hc);
; #pragma unroll
;   for (int ai = 0; ai < AI; ++ai)
; #pragma unroll
;     for (int reg = 0; reg < 16; ++reg) {
;       float g = acc[ai][0][reg], u = acc[ai][1][reg];
;       float v = g * __builtin_amdgcn_rcpf(1.f + __expf(-g)) * u;
;       HIDu[ib + (unsigned)((ai * 32 + (reg & 3) + 8 * (reg >> 2)) * 2816)] = f2bf(v);
;       if ((reg & 7) == 7) __builtin_amdgcn_sched_barrier(0);
;     }
; }
; DI void phase_gu(const Params& p, char* wsb, int sub, int mrows, char* lds) {
;   int mt, nt;
;   for (int rnd = 0; next_tile(rnd, 128, 44, mt, nt); ++rnd) gu_tile<2>(wsb, sub, mt * 128, nt * 128, lds);
;   if (mrows > TL)
;     for (int rnd = 0; next_tile(rnd, 32, 44, mt, nt); ++rnd) gu_tile<1>(wsb, sub, TL + mt * 64, nt * 128, lds);
	v_mfma_f32_32x32x16_bf16 v[2:17], v[34:37], v[38:41], v[2:17]
	v_mfma_f32_32x32x16_bf16 v[18:33], v[34:37], v[42:45], v[18:33]
	v_lshrrev_b32_e32 v36, 3, v46
	v_lshrrev_b32_e32 v34, 1, v47
	v_lshrrev_b32_e32 v35, 2, v47
	v_and_b32_e32 v36, 4, v36
	v_and_b32_e32 v34, 32, v34
	v_and_or_b32 v35, v35, s18, v36
	v_add3_u32 v35, v35, s17, v0
	v_or3_b32 v0, v34, v55, s8
	s_nop 2
	v_mul_f32_e32 v34, 0xbfb8aa3b, v2
	v_exp_f32_e32 v34, v34
	s_nop 0
	v_add_f32_e32 v34, 1.0, v34
	v_rcp_f32_e32 v34, v34
	s_nop 0
	v_mul_f32_e32 v2, v2, v34
	v_mad_u64_u32 v[34:35], s[8:9], v35, s9, v[0:1]
	v_mul_f32_e32 v0, 0xbfb8aa3b, v3
	v_exp_f32_e32 v0, v0
	v_mul_f32_e32 v2, v18, v2
	v_mov_b32_e32 v35, v1
	v_cvt_pk_bf16_f32 v2, v2, s0
	v_add_f32_e32 v0, 1.0, v0
	v_rcp_f32_e32 v0, v0
	v_lshl_add_u64 v[36:37], v[34:35], 1, s[6:7]
	global_store_short v[36:37], v2, off
	v_mul_f32_e32 v0, v3, v0
	v_mul_f32_e32 v0, v19, v0
	v_cvt_pk_bf16_f32 v18, v0, s0
	v_add_u32_e32 v0, 0xb00, v34
	v_lshl_add_u64 v[2:3], v[0:1], 1, s[6:7]
	v_mul_f32_e32 v0, 0xbfb8aa3b, v4
	v_exp_f32_e32 v0, v0
	global_store_short v[2:3], v18, off
	v_add_f32_e32 v0, 1.0, v0
	v_rcp_f32_e32 v0, v0
	s_nop 0
	v_mul_f32_e32 v0, v4, v0
	v_mul_f32_e32 v0, v20, v0
	v_cvt_pk_bf16_f32 v4, v0, s0
	v_add_u32_e32 v0, 0x1600, v34
	v_lshl_add_u64 v[2:3], v[0:1], 1, s[6:7]
	v_mul_f32_e32 v0, 0xbfb8aa3b, v5
	v_exp_f32_e32 v0, v0
	global_store_short v[2:3], v4, off
	v_add_f32_e32 v0, 1.0, v0
	v_rcp_f32_e32 v0, v0
	s_nop 0
	v_mul_f32_e32 v0, v5, v0
	v_mul_f32_e32 v0, v21, v0
	v_cvt_pk_bf16_f32 v4, v0, s0
	v_add_u32_e32 v0, 0x2100, v34
	v_lshl_add_u64 v[2:3], v[0:1], 1, s[6:7]
	v_mul_f32_e32 v0, 0xbfb8aa3b, v6
	v_exp_f32_e32 v0, v0
	global_store_short v[2:3], v4, off
	v_add_f32_e32 v0, 1.0, v0
	v_rcp_f32_e32 v0, v0
	s_nop 0
	v_mul_f32_e32 v0, v6, v0
	v_mul_f32_e32 v0, v22, v0
	v_cvt_pk_bf16_f32 v4, v0, s0
	v_add_u32_e32 v0, 0x5800, v34
	v_lshl_add_u64 v[2:3], v[0:1], 1, s[6:7]
	v_mul_f32_e32 v0, 0xbfb8aa3b, v7
	v_exp_f32_e32 v0, v0
	global_store_short v[2:3], v4, off
	v_add_f32_e32 v0, 1.0, v0
	v_rcp_f32_e32 v0, v0
	s_nop 0
	v_mul_f32_e32 v0, v7, v0
	v_mul_f32_e32 v0, v23, v0
	v_cvt_pk_bf16_f32 v4, v0, s0
	v_add_u32_e32 v0, 0x6300, v34
	v_lshl_add_u64 v[2:3], v[0:1], 1, s[6:7]
	v_mul_f32_e32 v0, 0xbfb8aa3b, v8
	v_exp_f32_e32 v0, v0
	global_store_short v[2:3], v4, off
	v_add_f32_e32 v0, 1.0, v0
	v_rcp_f32_e32 v0, v0
	s_nop 0
	v_mul_f32_e32 v0, v8, v0
	v_mul_f32_e32 v0, v24, v0
	v_cvt_pk_bf16_f32 v4, v0, s0
	v_add_u32_e32 v0, 0x6e00, v34
	v_lshl_add_u64 v[2:3], v[0:1], 1, s[6:7]
	v_mul_f32_e32 v0, 0xbfb8aa3b, v9
	v_exp_f32_e32 v0, v0
	global_store_short v[2:3], v4, off
	v_add_f32_e32 v0, 1.0, v0
	v_rcp_f32_e32 v0, v0
	s_nop 0
	v_mul_f32_e32 v0, v9, v0
	v_mul_f32_e32 v0, v25, v0
	v_cvt_pk_bf16_f32 v4, v0, s0
	v_add_u32_e32 v0, 0x7900, v34
	v_lshl_add_u64 v[2:3], v[0:1], 1, s[6:7]
	global_store_short v[2:3], v4, off
	v_mul_f32_e32 v0, 0xbfb8aa3b, v10
	v_exp_f32_e32 v0, v0
	s_nop 0
	v_add_f32_e32 v0, 1.0, v0
	v_rcp_f32_e32 v0, v0
	s_nop 0
	v_mul_f32_e32 v0, v10, v0
	v_mul_f32_e32 v0, v26, v0
	v_cvt_pk_bf16_f32 v4, v0, s0
	v_add_u32_e32 v0, 0xb000, v34
	v_lshl_add_u64 v[2:3], v[0:1], 1, s[6:7]
	v_mul_f32_e32 v0, 0xbfb8aa3b, v11
	v_exp_f32_e32 v0, v0
	global_store_short v[2:3], v4, off
	v_add_f32_e32 v0, 1.0, v0
	v_rcp_f32_e32 v0, v0
	s_nop 0
	v_mul_f32_e32 v0, v11, v0
	v_mul_f32_e32 v0, v27, v0
	v_cvt_pk_bf16_f32 v4, v0, s0
	v_add_u32_e32 v0, 0xbb00, v34
	v_lshl_add_u64 v[2:3], v[0:1], 1, s[6:7]
	v_mul_f32_e32 v0, 0xbfb8aa3b, v12
	v_exp_f32_e32 v0, v0
	global_store_short v[2:3], v4, off
	v_add_f32_e32 v0, 1.0, v0
	v_rcp_f32_e32 v0, v0
	s_nop 0
	v_mul_f32_e32 v0, v12, v0
	v_mul_f32_e32 v0, v28, v0
	v_cvt_pk_bf16_f32 v4, v0, s0
	v_add_u32_e32 v0, 0xc600, v34
	v_lshl_add_u64 v[2:3], v[0:1], 1, s[6:7]
	v_mul_f32_e32 v0, 0xbfb8aa3b, v13
	v_exp_f32_e32 v0, v0
	global_store_short v[2:3], v4, off
	v_add_f32_e32 v0, 1.0, v0
	v_rcp_f32_e32 v0, v0
	s_nop 0
	v_mul_f32_e32 v0, v13, v0
	v_mul_f32_e32 v0, v29, v0
	v_cvt_pk_bf16_f32 v4, v0, s0
	v_add_u32_e32 v0, 0xd100, v34
	v_lshl_add_u64 v[2:3], v[0:1], 1, s[6:7]
	v_mul_f32_e32 v0, 0xbfb8aa3b, v14
	v_exp_f32_e32 v0, v0
	global_store_short v[2:3], v4, off
	v_add_f32_e32 v0, 1.0, v0
	v_rcp_f32_e32 v0, v0
	s_nop 0
	v_mul_f32_e32 v0, v14, v0
	v_mul_f32_e32 v0, v30, v0
	v_cvt_pk_bf16_f32 v4, v0, s0
	v_add_u32_e32 v0, 0x10800, v34
	v_lshl_add_u64 v[2:3], v[0:1], 1, s[6:7]
	v_mul_f32_e32 v0, 0xbfb8aa3b, v15
	v_exp_f32_e32 v0, v0
	global_store_short v[2:3], v4, off
	v_add_f32_e32 v0, 1.0, v0
	v_rcp_f32_e32 v0, v0
	s_nop 0
	v_mul_f32_e32 v0, v15, v0
	v_mul_f32_e32 v0, v31, v0
	v_cvt_pk_bf16_f32 v4, v0, s0
	v_add_u32_e32 v0, 0x11300, v34
	v_lshl_add_u64 v[2:3], v[0:1], 1, s[6:7]
	v_mul_f32_e32 v0, 0xbfb8aa3b, v16
	v_exp_f32_e32 v0, v0
	global_store_short v[2:3], v4, off
	v_add_f32_e32 v0, 1.0, v0
	v_rcp_f32_e32 v0, v0
	s_nop 0
	v_mul_f32_e32 v0, v16, v0
	v_mul_f32_e32 v0, v32, v0
	v_cvt_pk_bf16_f32 v4, v0, s0
	v_add_u32_e32 v0, 0x11e00, v34
	v_lshl_add_u64 v[2:3], v[0:1], 1, s[6:7]
	v_mul_f32_e32 v0, 0xbfb8aa3b, v17
	v_exp_f32_e32 v0, v0
	global_store_short v[2:3], v4, off
	v_add_f32_e32 v0, 1.0, v0
	v_rcp_f32_e32 v0, v0
	s_nop 0
	v_mul_f32_e32 v0, v17, v0
	v_mul_f32_e32 v0, v33, v0
	v_cvt_pk_bf16_f32 v4, v0, s0
	v_add_u32_e32 v0, 0x12900, v34
	v_lshl_add_u64 v[2:3], v[0:1], 1, s[6:7]
	global_store_short v[2:3], v4, off
	v_readlane_b32 s8, v243, 9
	s_add_i32 s16, s16, s8
	v_readlane_b32 s8, v243, 11
	s_add_i32 s15, s15, s8
	s_add_i32 s14, s14, s48
	s_cmpk_gt_u32 s14, 0x57f
	s_cbranch_scc0 .LBB0_423

; #define MFMA(a, b, c) __builtin_amdgcn_mfma_f32_32x32x16_bf16((a), (b), (c), 0, 0, 0)
; #define TIDX opaque_tid()
; template <int AI, int BI>
; DI void gemm_stage(const u16* __restrict__ A, int lda, const u16* __restrict__ B, int ldb, char* buf, int tid) {
; #pragma unroll
;   for (int i = 0; i < 2 * AI; ++i) {
;     const int S = tid + NTHR * i, row = S >> 3, c = (S & 7) ^ ((row >> 1) & 7);
;     __builtin_amdgcn_global_load_lds((const unsigned*)(A + (size_t)row * lda + c * 8), (__attribute__((address_space(3))) unsigned*)(buf + S * 16), 16, 0, 0);
;   }
; #pragma unroll
;   for (int i = 0; i < 2 * BI; ++i) {
;     const int S = tid + NTHR * i, row = S >> 3, c = (S & 7) ^ ((row >> 1) & 7);
;     __builtin_amdgcn_global_load_lds((const unsigned*)(B + (size_t)row * ldb + c * 8), (__attribute__((address_space(3))) unsigned*)(buf + 16384 + S * 16), 16, 0, 0);
;   }
; }
; template <int AI, int BI>
; DI void gemm_tile(const u16* __restrict__ A, int lda, const u16* __restrict__ B, int ldb, int nk, bool swap,
;                   f32x16 (&acc)[AI][BI], char* lds) {
;   const int tid = TIDX, lane = tid & 63, wid = tid >> 6;
;   gemm_stage<AI, BI>(A, lda, B, ldb, lds, tid);
;   asm volatile("s_waitcnt vmcnt(0)" ::: "memory");
;   __syncthreads();
;   const int wa = wid >> 1, wb = wid & 1, r = lane & 31, h = lane >> 5, sw = (r >> 1) & 7;
;   const int offA = (swap ? 16384 : 0) + (wa * 32 * AI + r) * 128;
;   const int offB = (swap ? 0 : 16384) + (wb * 32 * BI + r) * 128;
;   for (int kt = 0; kt < nk; ++kt) {
;     const char* cur = lds + (kt & 1) * 32768;
;     if (kt + 1 < nk) gemm_stage<AI, BI>(A + (kt + 1) * 64, lda, B + (kt + 1) * 64, ldb, lds + ((kt + 1) & 1) * 32768, tid);
; #pragma unroll
;     for (int ks = 0; ks < 4; ++ks) {
;       const int co = ((ks * 2 + h) ^ sw) << 4;
;       s16x8 fa[AI], fb[BI];
; #pragma unroll
;       for (int i = 0; i < AI; ++i) fa[i] = *(const s16x8*)(cur + offA + i * 4096 + co);
; #pragma unroll
;       for (int i = 0; i < BI; ++i) fb[i] = *(const s16x8*)(cur + offB + i * 4096 + co);
; #pragma unroll
;       for (int i = 0; i < AI; ++i)
; #pragma unroll
;         for (int j = 0; j < BI; ++j) acc[i][j] = MFMA(fa[i], fb[j], acc[i][j]);
;     }
;     asm volatile("s_waitcnt vmcnt(0)" ::: "memory");
;     __syncthreads();
;   }
.LBB0_476:
	s_add_i32 s40, s37, 0xffff8000
	s_and_b32 s41, s40, 0x8000
	s_and_b32 s40, s37, 0x8000
	v_add_u32_e32 v93, s40, v85
	v_add_u32_e32 v96, s40, v86
	v_readfirstlane_b32 s46, v93
	v_lshl_add_u64 v[94:95], v[66:67], 0, s[10:11]
	s_mov_b32 m0, s46
	v_readfirstlane_b32 s46, v96
	v_add_u32_e32 v97, s40, v88
	global_load_lds_dwordx4 v[94:95], off
	v_lshl_add_u64 v[94:95], v[68:69], 0, s[10:11]
	s_mov_b32 m0, s46
	v_readfirstlane_b32 s46, v97
	v_add_u32_e32 v98, s40, v89
	global_load_lds_dwordx4 v[94:95], off
	v_lshl_add_u64 v[94:95], v[70:71], 0, s[10:11]
	s_mov_b32 m0, s46
	v_readfirstlane_b32 s46, v98
	v_add_u32_e32 v93, 0x4000, v93
	global_load_lds_dwordx4 v[94:95], off
	v_lshl_add_u64 v[94:95], v[72:73], 0, s[10:11]
	s_mov_b32 m0, s46
	v_readfirstlane_b32 s46, v93
	v_add_u32_e32 v93, 0x4000, v96
	global_load_lds_dwordx4 v[94:95], off
	v_lshl_add_u64 v[94:95], v[74:75], 0, s[10:11]
	s_mov_b32 m0, s46
	v_readfirstlane_b32 s46, v93
	v_add_u32_e32 v93, 0x4000, v97
	global_load_lds_dwordx4 v[94:95], off
	v_lshl_add_u64 v[94:95], v[76:77], 0, s[10:11]
	s_mov_b32 m0, s46
	v_readfirstlane_b32 s46, v93
	v_add_u32_e32 v93, 0x4000, v98
	global_load_lds_dwordx4 v[94:95], off
	v_lshl_add_u64 v[94:95], v[78:79], 0, s[10:11]
	s_mov_b32 m0, s46
	v_readfirstlane_b32 s46, v93
	global_load_lds_dwordx4 v[94:95], off
	v_lshl_add_u64 v[94:95], v[80:81], 0, s[10:11]
	s_mov_b32 m0, s46
	v_add_u32_e32 v93, s41, v91
	global_load_lds_dwordx4 v[94:95], off
	v_or_b32_e32 v110, s41, v92
	v_add_u32_e32 v98, v93, v90
	v_add_u32_e32 v106, v110, v90
	ds_read_b128 v[94:97], v98
	ds_read_b128 v[98:101], v98 offset:4096
	ds_read_b128 v[102:105], v106 offset:16384
	ds_read_b128 v[106:109], v106 offset:20480
	s_waitcnt lgkmcnt(0)
	v_mfma_f32_32x32x16_bf16 v[50:65], v[94:97], v[102:105], v[50:65]
	s_add_u32 s10, s10, 0x80
	s_addc_u32 s11, s11, 0
	s_add_i32 s37, s37, 0x8000
	s_cmpk_eq_i32 s10, 0x1580
	v_mfma_f32_32x32x16_bf16 v[18:33], v[94:97], v[106:109], v[18:33]
	v_mfma_f32_32x32x16_bf16 v[34:49], v[98:101], v[102:105], v[34:49]
	v_mfma_f32_32x32x16_bf16 v[2:17], v[98:101], v[106:109], v[2:17]
	v_add_u32_e32 v98, v93, v87
	v_add_u32_e32 v106, v110, v87
	ds_read_b128 v[94:97], v98
	ds_read_b128 v[98:101], v98 offset:4096
	ds_read_b128 v[102:105], v106 offset:16384
	ds_read_b128 v[106:109], v106 offset:20480
	s_waitcnt lgkmcnt(1)
	v_mfma_f32_32x32x16_bf16 v[50:65], v[94:97], v[102:105], v[50:65]
	s_waitcnt lgkmcnt(0)
	v_mfma_f32_32x32x16_bf16 v[18:33], v[94:97], v[106:109], v[18:33]
	v_mfma_f32_32x32x16_bf16 v[34:49], v[98:101], v[102:105], v[34:49]
	v_mfma_f32_32x32x16_bf16 v[2:17], v[98:101], v[106:109], v[2:17]
	v_add_u32_e32 v98, v93, v84
	v_add_u32_e32 v106, v110, v84
	ds_read_b128 v[94:97], v98
	ds_read_b128 v[98:101], v98 offset:4096
	ds_read_b128 v[102:105], v106 offset:16384
	ds_read_b128 v[106:109], v106 offset:20480
	v_add_u32_e32 v93, v93, v0
	s_waitcnt lgkmcnt(1)
	v_mfma_f32_32x32x16_bf16 v[50:65], v[94:97], v[102:105], v[50:65]
	s_waitcnt lgkmcnt(0)
	v_mfma_f32_32x32x16_bf16 v[18:33], v[94:97], v[106:109], v[18:33]
	v_mfma_f32_32x32x16_bf16 v[34:49], v[98:101], v[102:105], v[34:49]
	v_mfma_f32_32x32x16_bf16 v[2:17], v[98:101], v[106:109], v[2:17]
	ds_read_b128 v[94:97], v93
	ds_read_b128 v[98:101], v93 offset:4096
	v_add_u32_e32 v93, v110, v0
	ds_read_b128 v[102:105], v93 offset:16384
	ds_read_b128 v[106:109], v93 offset:20480
	s_waitcnt lgkmcnt(0)
	v_mfma_f32_32x32x16_bf16 v[50:65], v[94:97], v[102:105], v[50:65]
	v_mfma_f32_32x32x16_bf16 v[18:33], v[94:97], v[106:109], v[18:33]
	v_mfma_f32_32x32x16_bf16 v[34:49], v[98:101], v[102:105], v[34:49]
	v_mfma_f32_32x32x16_bf16 v[2:17], v[98:101], v[106:109], v[2:17]
	s_waitcnt vmcnt(0)
	s_barrier
	s_cbranch_scc0 .LBB0_476
	v_add_u32_e32 v86, s40, v91
	v_add_u32_e32 v88, s40, v92
	v_add_u32_e32 v70, v86, v90
	v_add_u32_e32 v78, v88, v90
	ds_read_b128 v[66:69], v70
	ds_read_b128 v[70:73], v70 offset:4096
	ds_read_b128 v[74:77], v78 offset:16384
	ds_read_b128 v[78:81], v78 offset:20480
	s_waitcnt lgkmcnt(1)
	v_mfma_f32_32x32x16_bf16 v[50:65], v[66:69], v[74:77], v[50:65]
	s_lshr_b32 s10, s34, 7
	s_lshl_b32 s36, s36, 7
	s_mul_i32 s10, s10, 0x9000
	s_add_u32 s10, s13, s10
	v_and_b32_e32 v85, 31, v82
	s_addc_u32 s11, s18, 0
	s_add_u32 s10, s10, 0x6000
	s_waitcnt lgkmcnt(0)
	v_mfma_f32_32x32x16_bf16 v[18:33], v[66:69], v[78:81], v[18:33]
	s_addc_u32 s11, s11, 0
	v_mfma_f32_32x32x16_bf16 v[34:49], v[70:73], v[74:77], v[34:49]
	v_mfma_f32_32x32x16_bf16 v[2:17], v[70:73], v[78:81], v[2:17]
	v_add_u32_e32 v70, v86, v87
	v_add_u32_e32 v78, v88, v87
	ds_read_b128 v[66:69], v70
	ds_read_b128 v[70:73], v70 offset:4096
	ds_read_b128 v[74:77], v78 offset:16384
	ds_read_b128 v[78:81], v78 offset:20480
	s_waitcnt lgkmcnt(1)
	v_mfma_f32_32x32x16_bf16 v[50:65], v[66:69], v[74:77], v[50:65]
	s_waitcnt lgkmcnt(0)
	v_mfma_f32_32x32x16_bf16 v[18:33], v[66:69], v[78:81], v[18:33]
	v_mfma_f32_32x32x16_bf16 v[34:49], v[70:73], v[74:77], v[34:49]
	v_mfma_f32_32x32x16_bf16 v[2:17], v[70:73], v[78:81], v[2:17]
	v_add_u32_e32 v70, v86, v84
	v_add_u32_e32 v78, v88, v84
	ds_read_b128 v[66:69], v70
	ds_read_b128 v[70:73], v70 offset:4096
	ds_read_b128 v[74:77], v78 offset:16384
	ds_read_b128 v[78:81], v78 offset:20480
	s_waitcnt lgkmcnt(1)
	v_mfma_f32_32x32x16_bf16 v[50:65], v[66:69], v[74:77], v[50:65]
	s_waitcnt lgkmcnt(0)
	v_mfma_f32_32x32x16_bf16 v[18:33], v[66:69], v[78:81], v[18:33]
	v_mfma_f32_32x32x16_bf16 v[34:49], v[70:73], v[74:77], v[34:49]
	v_mfma_f32_32x32x16_bf16 v[2:17], v[70:73], v[78:81], v[2:17]
	v_add_u32_e32 v70, v86, v0
	v_add_u32_e32 v0, v88, v0
	ds_read_b128 v[66:69], v70
	ds_read_b128 v[70:73], v70 offset:4096
	ds_read_b128 v[74:77], v0 offset:16384
	ds_read_b128 v[78:81], v0 offset:20480
	v_mov_b32_e32 v0, v1
	s_waitcnt vmcnt(0)
	s_waitcnt lgkmcnt(0)
	v_mfma_f32_32x32x16_bf16 v[50:65], v[66:69], v[74:77], v[50:65]
	s_barrier
; #define GAS __attribute__((address_space(1)))
; DI int opaque0() { int z = 0; asm volatile("" : "+v"(z)); return z; }
; template <int AI, int BI>
; DI void dn_tile(const Params& p, char* wsb, int layer, int sub, bool final_out, int m0, int n0, char* lds) {
;     ...
;   const int m0e = m0 + opaque0();
;   const int mr = m0 < TL ? (m0 >> 11) : 8;
;   const float* gate = mods + (size_t)mr * 9216 + (2 + 6 * sub) * 1024;
;   GAS float* xsu = uptr(xs);
;   GAS float* outu = uptr(p.out);
; #pragma unroll
;   for (int bi = 0; bi < BI; ++bi) {
;     const int n = n0 + wb * 32 * BI + bi * 32 + r;
;     const float gv = 0.5f * gate[n];
;     const unsigned ib = (unsigned)((m0e + wa * 32 * AI + 4 * h) * 1024 + n);
; #pragma unroll
;     for (int ai = 0; ai < AI; ++ai)
; #pragma unroll
;       for (int reg = 0; reg < 16; ++reg) {
;         const unsigned idx = ib + (unsigned)((ai * 32 + (reg & 3) + 8 * (reg >> 2)) * 1024);
;         float v = xsu[idx] + gv * acc[ai][bi][reg];
;         if (final_out) outu[idx] = v; else xsu[idx] = v;
;         if ((reg & 7) == 7) __builtin_amdgcn_sched_barrier(0);
;       }
	v_mfma_f32_32x32x16_bf16 v[18:33], v[66:69], v[78:81], v[18:33]
	v_mfma_f32_32x32x16_bf16 v[34:49], v[70:73], v[74:77], v[34:49]
	v_mfma_f32_32x32x16_bf16 v[2:17], v[70:73], v[78:81], v[2:17]
	v_and_b32_e32 v143, 31, v178
	v_and_b32_e32 v140, 64, v178
	v_or_b32_e32 v140, v140, v143
	v_bfe_u32 v143, v178, 5, 1
	v_bfe_u32 v139, v178, 7, 1
	v_lshlrev_b32_e32 v139, 6, v139
	v_lshl_add_u32 v139, v143, 2, v139
	v_lshl_add_u32 v139, v139, 10, v140
	v_lshlrev_b32_e32 v139, 2, v139
	v_add_u32_e32 v140, s35, v140
	v_lshlrev_b32_e32 v140, 2, v140
	global_load_dword v141, v140, s[10:11]
	global_load_dword v142, v140, s[10:11] offset:128
	s_lshl_b32 s56, s36, 10
	s_add_u32 s56, s56, s35
	s_lshl_b32 s56, s56, 2
	s_add_u32 s54, s6, s56
	s_addc_u32 s55, s7, 0
	s_mov_b64 s[52:53], s[54:55]
	global_load_dword v66, v139, s[52:53]
	global_load_dword v67, v139, s[52:53] offset:128
	s_add_u32 s52, s52, 4096
	s_addc_u32 s53, s53, 0
	global_load_dword v68, v139, s[52:53]
	global_load_dword v69, v139, s[52:53] offset:128
	s_add_u32 s52, s52, 4096
	s_addc_u32 s53, s53, 0
	global_load_dword v70, v139, s[52:53]
	global_load_dword v71, v139, s[52:53] offset:128
	s_add_u32 s52, s52, 4096
	s_addc_u32 s53, s53, 0
	global_load_dword v72, v139, s[52:53]
	global_load_dword v73, v139, s[52:53] offset:128
	s_add_u32 s52, s52, 20480
	s_addc_u32 s53, s53, 0
	global_load_dword v74, v139, s[52:53]
	global_load_dword v75, v139, s[52:53] offset:128
	s_add_u32 s52, s52, 4096
	s_addc_u32 s53, s53, 0
	global_load_dword v76, v139, s[52:53]
	global_load_dword v77, v139, s[52:53] offset:128
	s_add_u32 s52, s52, 4096
	s_addc_u32 s53, s53, 0
	global_load_dword v78, v139, s[52:53]
	global_load_dword v79, v139, s[52:53] offset:128
	s_add_u32 s52, s52, 4096
	s_addc_u32 s53, s53, 0
	global_load_dword v80, v139, s[52:53]
	global_load_dword v81, v139, s[52:53] offset:128
	s_add_u32 s52, s52, 20480
	s_addc_u32 s53, s53, 0
	global_load_dword v82, v139, s[52:53]
	global_load_dword v83, v139, s[52:53] offset:128
	s_add_u32 s52, s52, 4096
	s_addc_u32 s53, s53, 0
	global_load_dword v84, v139, s[52:53]
	global_load_dword v85, v139, s[52:53] offset:128
	s_add_u32 s52, s52, 4096
	s_addc_u32 s53, s53, 0
	global_load_dword v86, v139, s[52:53]
	global_load_dword v87, v139, s[52:53] offset:128
	s_add_u32 s52, s52, 4096
	s_addc_u32 s53, s53, 0
	global_load_dword v88, v139, s[52:53]
	global_load_dword v89, v139, s[52:53] offset:128
	s_add_u32 s52, s52, 20480
	s_addc_u32 s53, s53, 0
	global_load_dword v90, v139, s[52:53]
	global_load_dword v91, v139, s[52:53] offset:128
	s_add_u32 s52, s52, 4096
	s_addc_u32 s53, s53, 0
	global_load_dword v92, v139, s[52:53]
	global_load_dword v93, v139, s[52:53] offset:128
	s_add_u32 s52, s52, 4096
	s_addc_u32 s53, s53, 0
	global_load_dword v94, v139, s[52:53]
	global_load_dword v95, v139, s[52:53] offset:128
	s_add_u32 s52, s52, 4096
	s_addc_u32 s53, s53, 0
	global_load_dword v96, v139, s[52:53]
	global_load_dword v97, v139, s[52:53] offset:128
	s_add_u32 s52, s52, 20480
	s_addc_u32 s53, s53, 0
	global_load_dword v98, v139, s[52:53]
	global_load_dword v99, v139, s[52:53] offset:128
	s_add_u32 s52, s52, 4096
	s_addc_u32 s53, s53, 0
	global_load_dword v100, v139, s[52:53]
	global_load_dword v101, v139, s[52:53] offset:128
	s_add_u32 s52, s52, 4096
	s_addc_u32 s53, s53, 0
	global_load_dword v102, v139, s[52:53]
	global_load_dword v103, v139, s[52:53] offset:128
	s_add_u32 s52, s52, 4096
	s_addc_u32 s53, s53, 0
	global_load_dword v104, v139, s[52:53]
	global_load_dword v105, v139, s[52:53] offset:128
	s_add_u32 s52, s52, 20480
	s_addc_u32 s53, s53, 0
	global_load_dword v106, v139, s[52:53]
	global_load_dword v107, v139, s[52:53] offset:128
	s_add_u32 s52, s52, 4096
	s_addc_u32 s53, s53, 0
	global_load_dword v108, v139, s[52:53]
	global_load_dword v109, v139, s[52:53] offset:128
	s_add_u32 s52, s52, 4096
	s_addc_u32 s53, s53, 0
	global_load_dword v110, v139, s[52:53]
	global_load_dword v111, v139, s[52:53] offset:128
	s_add_u32 s52, s52, 4096
	s_addc_u32 s53, s53, 0
	global_load_dword v112, v139, s[52:53]
	global_load_dword v113, v139, s[52:53] offset:128
	s_add_u32 s52, s52, 20480
	s_addc_u32 s53, s53, 0
	global_load_dword v114, v139, s[52:53]
	global_load_dword v115, v139, s[52:53] offset:128
	s_add_u32 s52, s52, 4096
	s_addc_u32 s53, s53, 0
	global_load_dword v116, v139, s[52:53]
	global_load_dword v117, v139, s[52:53] offset:128
	s_add_u32 s52, s52, 4096
	s_addc_u32 s53, s53, 0
	global_load_dword v118, v139, s[52:53]
	global_load_dword v119, v139, s[52:53] offset:128
	s_add_u32 s52, s52, 4096
	s_addc_u32 s53, s53, 0
	global_load_dword v120, v139, s[52:53]
	global_load_dword v121, v139, s[52:53] offset:128
	s_add_u32 s52, s52, 20480
	s_addc_u32 s53, s53, 0
	global_load_dword v122, v139, s[52:53]
	global_load_dword v123, v139, s[52:53] offset:128
	s_add_u32 s52, s52, 4096
	s_addc_u32 s53, s53, 0
	global_load_dword v124, v139, s[52:53]
	global_load_dword v134, v139, s[52:53] offset:128
	s_add_u32 s52, s52, 4096
	s_addc_u32 s53, s53, 0
	global_load_dword v135, v139, s[52:53]
	global_load_dword v136, v139, s[52:53] offset:128
	s_add_u32 s52, s52, 4096
	s_addc_u32 s53, s53, 0
	global_load_dword v137, v139, s[52:53]
	global_load_dword v138, v139, s[52:53] offset:128
	s_waitcnt vmcnt(48)
	v_mul_f32_e32 v141, 0.5, v141
	v_mul_f32_e32 v142, 0.5, v142
	v_fmac_f32_e32 v66, v50, v141
	v_fmac_f32_e32 v67, v18, v142
	v_fmac_f32_e32 v68, v51, v141
	v_fmac_f32_e32 v69, v19, v142
	v_fmac_f32_e32 v70, v52, v141
	v_fmac_f32_e32 v71, v20, v142
	v_fmac_f32_e32 v72, v53, v141
	v_fmac_f32_e32 v73, v21, v142
	v_fmac_f32_e32 v74, v54, v141
	v_fmac_f32_e32 v75, v22, v142
	v_fmac_f32_e32 v76, v55, v141
	v_fmac_f32_e32 v77, v23, v142
	v_fmac_f32_e32 v78, v56, v141
	v_fmac_f32_e32 v79, v24, v142
	v_fmac_f32_e32 v80, v57, v141
	v_fmac_f32_e32 v81, v25, v142
	s_waitcnt vmcnt(32)
; template <int AI, int BI>
; DI void dn_tile(const Params& p, char* wsb, int layer, int sub, bool final_out, int m0, int n0, char* lds) {
;     ...
;   for (int bi = 0; bi < BI; ++bi) {
;     const int n = n0 + wb * 32 * BI + bi * 32 + r;
;     const float gv = 0.5f * gate[n];
;     const unsigned ib = (unsigned)((m0e + wa * 32 * AI + 4 * h) * 1024 + n);
; #pragma unroll
;     for (int ai = 0; ai < AI; ++ai)
; #pragma unroll
;       for (int reg = 0; reg < 16; ++reg) {
;         const unsigned idx = ib + (unsigned)((ai * 32 + (reg & 3) + 8 * (reg >> 2)) * 1024);
;         float v = xsu[idx] + gv * acc[ai][bi][reg];
;         if (final_out) outu[idx] = v; else xsu[idx] = v;
;         if ((reg & 7) == 7) __builtin_amdgcn_sched_barrier(0);
;       }
;   }
; }
; DI void phase_dn(const Params& p, char* wsb, int layer, int sub, int mrows, bool final_out, char* lds) {
;   int mt, nt;
;   for (int rnd = 0; next_tile(rnd, 128, 8, mt, nt); ++rnd) dn_tile<2, 2>(p, wsb, layer, sub, final_out, mt * 128, nt * 128, lds);
	v_fmac_f32_e32 v82, v58, v141
	v_fmac_f32_e32 v83, v26, v142
	v_fmac_f32_e32 v84, v59, v141
	v_fmac_f32_e32 v85, v27, v142
	v_fmac_f32_e32 v86, v60, v141
	v_fmac_f32_e32 v87, v28, v142
	v_fmac_f32_e32 v88, v61, v141
	v_fmac_f32_e32 v89, v29, v142
	v_fmac_f32_e32 v90, v62, v141
	v_fmac_f32_e32 v91, v30, v142
	v_fmac_f32_e32 v92, v63, v141
	v_fmac_f32_e32 v93, v31, v142
	v_fmac_f32_e32 v94, v64, v141
	v_fmac_f32_e32 v95, v32, v142
	v_fmac_f32_e32 v96, v65, v141
	v_fmac_f32_e32 v97, v33, v142
	s_waitcnt vmcnt(16)
	v_fmac_f32_e32 v98, v34, v141
	v_fmac_f32_e32 v99, v2, v142
	v_fmac_f32_e32 v100, v35, v141
	v_fmac_f32_e32 v101, v3, v142
	v_fmac_f32_e32 v102, v36, v141
	v_fmac_f32_e32 v103, v4, v142
	v_fmac_f32_e32 v104, v37, v141
	v_fmac_f32_e32 v105, v5, v142
	v_fmac_f32_e32 v106, v38, v141
	v_fmac_f32_e32 v107, v6, v142
	v_fmac_f32_e32 v108, v39, v141
	v_fmac_f32_e32 v109, v7, v142
	v_fmac_f32_e32 v110, v40, v141
	v_fmac_f32_e32 v111, v8, v142
	v_fmac_f32_e32 v112, v41, v141
	v_fmac_f32_e32 v113, v9, v142
	s_waitcnt vmcnt(0)
	v_fmac_f32_e32 v114, v42, v141
	v_fmac_f32_e32 v115, v10, v142
	v_fmac_f32_e32 v116, v43, v141
	v_fmac_f32_e32 v117, v11, v142
	v_fmac_f32_e32 v118, v44, v141
	v_fmac_f32_e32 v119, v12, v142
	v_fmac_f32_e32 v120, v45, v141
	v_fmac_f32_e32 v121, v13, v142
	v_fmac_f32_e32 v122, v46, v141
	v_fmac_f32_e32 v123, v14, v142
	v_fmac_f32_e32 v124, v47, v141
	v_fmac_f32_e32 v134, v15, v142
	v_fmac_f32_e32 v135, v48, v141
	v_fmac_f32_e32 v136, v16, v142
	v_fmac_f32_e32 v137, v49, v141
	v_fmac_f32_e32 v138, v17, v142
	s_mov_b64 s[52:53], s[54:55]
	global_store_dword v139, v66, s[52:53]
	global_store_dword v139, v67, s[52:53] offset:128
	s_add_u32 s52, s52, 4096
	s_addc_u32 s53, s53, 0
	global_store_dword v139, v68, s[52:53]
	global_store_dword v139, v69, s[52:53] offset:128
	s_add_u32 s52, s52, 4096
	s_addc_u32 s53, s53, 0
	global_store_dword v139, v70, s[52:53]
	global_store_dword v139, v71, s[52:53] offset:128
	s_add_u32 s52, s52, 4096
	s_addc_u32 s53, s53, 0
	global_store_dword v139, v72, s[52:53]
	global_store_dword v139, v73, s[52:53] offset:128
	s_add_u32 s52, s52, 20480
	s_addc_u32 s53, s53, 0
	global_store_dword v139, v74, s[52:53]
	global_store_dword v139, v75, s[52:53] offset:128
	s_add_u32 s52, s52, 4096
	s_addc_u32 s53, s53, 0
	global_store_dword v139, v76, s[52:53]
	global_store_dword v139, v77, s[52:53] offset:128
	s_add_u32 s52, s52, 4096
	s_addc_u32 s53, s53, 0
	global_store_dword v139, v78, s[52:53]
	global_store_dword v139, v79, s[52:53] offset:128
	s_add_u32 s52, s52, 4096
	s_addc_u32 s53, s53, 0
	global_store_dword v139, v80, s[52:53]
	global_store_dword v139, v81, s[52:53] offset:128
	s_add_u32 s52, s52, 20480
	s_addc_u32 s53, s53, 0
	global_store_dword v139, v82, s[52:53]
	global_store_dword v139, v83, s[52:53] offset:128
	s_add_u32 s52, s52, 4096
	s_addc_u32 s53, s53, 0
	global_store_dword v139, v84, s[52:53]
	global_store_dword v139, v85, s[52:53] offset:128
	s_add_u32 s52, s52, 4096
	s_addc_u32 s53, s53, 0
	global_store_dword v139, v86, s[52:53]
	global_store_dword v139, v87, s[52:53] offset:128
	s_add_u32 s52, s52, 4096
	s_addc_u32 s53, s53, 0
	global_store_dword v139, v88, s[52:53]
	global_store_dword v139, v89, s[52:53] offset:128
	s_add_u32 s52, s52, 20480
	s_addc_u32 s53, s53, 0
	global_store_dword v139, v90, s[52:53]
	global_store_dword v139, v91, s[52:53] offset:128
	s_add_u32 s52, s52, 4096
	s_addc_u32 s53, s53, 0
	global_store_dword v139, v92, s[52:53]
	global_store_dword v139, v93, s[52:53] offset:128
	s_add_u32 s52, s52, 4096
	s_addc_u32 s53, s53, 0
	global_store_dword v139, v94, s[52:53]
	global_store_dword v139, v95, s[52:53] offset:128
	s_add_u32 s52, s52, 4096
	s_addc_u32 s53, s53, 0
	global_store_dword v139, v96, s[52:53]
	global_store_dword v139, v97, s[52:53] offset:128
	s_add_u32 s52, s52, 20480
	s_addc_u32 s53, s53, 0
	global_store_dword v139, v98, s[52:53]
	global_store_dword v139, v99, s[52:53] offset:128
	s_add_u32 s52, s52, 4096
	s_addc_u32 s53, s53, 0
	global_store_dword v139, v100, s[52:53]
	global_store_dword v139, v101, s[52:53] offset:128
	s_add_u32 s52, s52, 4096
	s_addc_u32 s53, s53, 0
	global_store_dword v139, v102, s[52:53]
	global_store_dword v139, v103, s[52:53] offset:128
	s_add_u32 s52, s52, 4096
	s_addc_u32 s53, s53, 0
	global_store_dword v139, v104, s[52:53]
	global_store_dword v139, v105, s[52:53] offset:128
	s_add_u32 s52, s52, 20480
	s_addc_u32 s53, s53, 0
	global_store_dword v139, v106, s[52:53]
	global_store_dword v139, v107, s[52:53] offset:128
	s_add_u32 s52, s52, 4096
	s_addc_u32 s53, s53, 0
	global_store_dword v139, v108, s[52:53]
	global_store_dword v139, v109, s[52:53] offset:128
	s_add_u32 s52, s52, 4096
	s_addc_u32 s53, s53, 0
	global_store_dword v139, v110, s[52:53]
	global_store_dword v139, v111, s[52:53] offset:128
	s_add_u32 s52, s52, 4096
	s_addc_u32 s53, s53, 0
	global_store_dword v139, v112, s[52:53]
	global_store_dword v139, v113, s[52:53] offset:128
	s_add_u32 s52, s52, 20480
	s_addc_u32 s53, s53, 0
	global_store_dword v139, v114, s[52:53]
	global_store_dword v139, v115, s[52:53] offset:128
	s_add_u32 s52, s52, 4096
	s_addc_u32 s53, s53, 0
	global_store_dword v139, v116, s[52:53]
	global_store_dword v139, v117, s[52:53] offset:128
	s_add_u32 s52, s52, 4096
	s_addc_u32 s53, s53, 0
	global_store_dword v139, v118, s[52:53]
	global_store_dword v139, v119, s[52:53] offset:128
	s_add_u32 s52, s52, 4096
	s_addc_u32 s53, s53, 0
	global_store_dword v139, v120, s[52:53]
	global_store_dword v139, v121, s[52:53] offset:128
	s_add_u32 s52, s52, 20480
	s_addc_u32 s53, s53, 0
	global_store_dword v139, v122, s[52:53]
	global_store_dword v139, v123, s[52:53] offset:128
	s_add_u32 s52, s52, 4096
	s_addc_u32 s53, s53, 0
	global_store_dword v139, v124, s[52:53]
	global_store_dword v139, v134, s[52:53] offset:128
	s_add_u32 s52, s52, 4096
	s_addc_u32 s53, s53, 0
	global_store_dword v139, v135, s[52:53]
	global_store_dword v139, v136, s[52:53] offset:128
	s_add_u32 s52, s52, 4096
	s_addc_u32 s53, s53, 0
	global_store_dword v139, v137, s[52:53]
	global_store_dword v139, v138, s[52:53] offset:128
	v_readlane_b32 s10, v243, 7
	s_add_i32 s34, s34, s10
	s_cmpk_gt_u32 s34, 0x3ff
	s_cbranch_scc0 .LBB0_475

; #define MFMA(a, b, c) __builtin_amdgcn_mfma_f32_32x32x16_bf16((a), (b), (c), 0, 0, 0)
; template <int AI, int BI>
; DI void gemm_tile(const u16* __restrict__ A, int lda, const u16* __restrict__ B, int ldb, int nk, bool swap,
;                   f32x16 (&acc)[AI][BI], char* lds) {
;     ...
;   for (int kt = 0; kt < nk; ++kt) {
;     const char* cur = lds + (kt & 1) * 32768;
;     if (kt + 1 < nk) gemm_stage<AI, BI>(A + (kt + 1) * 64, lda, B + (kt + 1) * 64, ldb, lds + ((kt + 1) & 1) * 32768, tid);
; #pragma unroll
;     for (int ks = 0; ks < 4; ++ks) {
;       const int co = ((ks * 2 + h) ^ sw) << 4;
;       s16x8 fa[AI], fb[BI];
; #pragma unroll
;       for (int i = 0; i < AI; ++i) fa[i] = *(const s16x8*)(cur + offA + i * 4096 + co);
; #pragma unroll
;       for (int i = 0; i < BI; ++i) fb[i] = *(const s16x8*)(cur + offB + i * 4096 + co);
; #pragma unroll
;       for (int i = 0; i < AI; ++i)
; #pragma unroll
;         for (int j = 0; j < BI; ++j) acc[i][j] = MFMA(fa[i], fb[j], acc[i][j]);
;     }
;     asm volatile("s_waitcnt vmcnt(0)" ::: "memory");
;     __syncthreads();
;   }
; template <int AI, int BI>
; DI void dn_tile(const Params& p, char* wsb, int layer, int sub, bool final_out, int m0, int n0, char* lds) {
;     ...
;   const int m0e = m0 + opaque0();
;   const int mr = m0 < TL ? (m0 >> 11) : 8;
;   const float* gate = mods + (size_t)mr * 9216 + (2 + 6 * sub) * 1024;
;   GAS float* xsu = uptr(xs);
;   GAS float* outu = uptr(p.out);
; #pragma unroll
;   for (int bi = 0; bi < BI; ++bi) {
;     const int n = n0 + wb * 32 * BI + bi * 32 + r;
;     const float gv = 0.5f * gate[n];
;     const unsigned ib = (unsigned)((m0e + wa * 32 * AI + 4 * h) * 1024 + n);
; #pragma unroll
;     for (int ai = 0; ai < AI; ++ai)
; #pragma unroll
;       for (int reg = 0; reg < 16; ++reg) {
;         const unsigned idx = ib + (unsigned)((ai * 32 + (reg & 3) + 8 * (reg >> 2)) * 1024);
;         float v = xsu[idx] + gv * acc[ai][bi][reg];
;         if (final_out) outu[idx] = v; else xsu[idx] = v;
;         if ((reg & 7) == 7) __builtin_amdgcn_sched_barrier(0);
;       }
;   }
; }
; DI void phase_dn(const Params& p, char* wsb, int layer, int sub, int mrows, bool final_out, char* lds) {
;   int mt, nt;
;   for (int rnd = 0; next_tile(rnd, 128, 8, mt, nt); ++rnd) dn_tile<2, 2>(p, wsb, layer, sub, final_out, mt * 128, nt * 128, lds);
;   if (mrows > TL)
.LBB0_481:
	s_add_i32 s40, s37, 0xffff8000
	s_and_b32 s41, s40, 0x8000
	s_and_b32 s40, s37, 0x8000
	v_add_u32_e32 v35, s40, v28
	v_add_u32_e32 v38, s40, v29
	v_readfirstlane_b32 s46, v35
	v_lshl_add_u64 v[36:37], v[18:19], 0, s[12:13]
	s_mov_b32 m0, s46
	v_readfirstlane_b32 s46, v38
	v_add_u32_e32 v35, 0x4000, v35
	global_load_lds_dwordx4 v[36:37], off
	v_lshl_add_u64 v[36:37], v[20:21], 0, s[12:13]
	s_mov_b32 m0, s46
	v_readfirstlane_b32 s46, v35
	v_add_u32_e32 v35, 0x4000, v38
	global_load_lds_dwordx4 v[36:37], off
	v_lshl_add_u64 v[36:37], v[22:23], 0, s[12:13]
	s_mov_b32 m0, s46
	v_readfirstlane_b32 s46, v35
	global_load_lds_dwordx4 v[36:37], off
	v_lshl_add_u64 v[36:37], v[24:25], 0, s[12:13]
	s_mov_b32 m0, s46
	v_add_u32_e32 v35, s41, v33
	global_load_lds_dwordx4 v[36:37], off
	v_add_u32_e32 v36, v35, v32
	ds_read_b128 v[36:39], v36
	v_or_b32_e32 v44, s41, v34
	v_add_u32_e32 v40, v44, v32
	ds_read_b128 v[40:43], v40 offset:16384
	s_add_u32 s12, s12, 0x80
	s_waitcnt lgkmcnt(0)
	v_mfma_f32_32x32x16_bf16 v[2:17], v[36:39], v[40:43], v[2:17]
	v_add_u32_e32 v36, v35, v31
	ds_read_b128 v[36:39], v36
	v_add_u32_e32 v40, v44, v31
	ds_read_b128 v[40:43], v40 offset:16384
	s_addc_u32 s13, s13, 0
	s_add_i32 s37, s37, 0x8000
	s_cmpk_eq_i32 s12, 0x1580
	s_waitcnt lgkmcnt(0)
	v_mfma_f32_32x32x16_bf16 v[2:17], v[36:39], v[40:43], v[2:17]
	v_add_u32_e32 v36, v35, v30
	ds_read_b128 v[36:39], v36
	v_add_u32_e32 v40, v44, v30
	ds_read_b128 v[40:43], v40 offset:16384
	v_add_u32_e32 v35, v35, v0
	s_waitcnt lgkmcnt(0)
	v_mfma_f32_32x32x16_bf16 v[2:17], v[36:39], v[40:43], v[2:17]
	ds_read_b128 v[36:39], v35
	v_add_u32_e32 v35, v44, v0
	ds_read_b128 v[40:43], v35 offset:16384
	s_waitcnt lgkmcnt(0)
	v_mfma_f32_32x32x16_bf16 v[2:17], v[36:39], v[40:43], v[2:17]
	s_waitcnt vmcnt(0)
	s_barrier
	s_cbranch_scc0 .LBB0_481
	v_add_u32_e32 v29, s40, v33
	v_add_u32_e32 v18, v29, v32
	ds_read_b128 v[18:21], v18
	v_add_u32_e32 v33, s40, v34
	v_add_u32_e32 v22, v33, v32
	ds_read_b128 v[22:25], v22 offset:16384
	v_and_b32_e32 v28, 31, v26
	s_waitcnt lgkmcnt(0)
	v_mfma_f32_32x32x16_bf16 v[2:17], v[18:21], v[22:25], v[2:17]
	v_add_u32_e32 v18, v29, v31
	ds_read_b128 v[18:21], v18
	v_add_u32_e32 v22, v33, v31
	ds_read_b128 v[22:25], v22 offset:16384
	s_waitcnt lgkmcnt(0)
	v_mfma_f32_32x32x16_bf16 v[2:17], v[18:21], v[22:25], v[2:17]
	v_add_u32_e32 v18, v29, v30
	ds_read_b128 v[18:21], v18
	v_add_u32_e32 v22, v33, v30
	ds_read_b128 v[22:25], v22 offset:16384
	s_waitcnt lgkmcnt(0)
	v_mfma_f32_32x32x16_bf16 v[2:17], v[18:21], v[22:25], v[2:17]
	v_add_u32_e32 v18, v29, v0
	ds_read_b128 v[18:21], v18
	v_add_u32_e32 v0, v33, v0
	ds_read_b128 v[22:25], v0 offset:16384
	v_mov_b32_e32 v0, v1
	s_waitcnt vmcnt(0)
	s_waitcnt lgkmcnt(0)
	v_mfma_f32_32x32x16_bf16 v[2:17], v[18:21], v[22:25], v[2:17]
	v_lshrrev_b32_e32 v18, 1, v27
	v_and_b32_e32 v18, 32, v18
	v_or3_b32 v18, v28, v18, s36
	v_lshlrev_b32_e32 v19, 2, v18
	s_barrier
	global_load_dword v19, v19, s[8:9]
	v_lshrrev_b32_e32 v20, 2, v27
	v_lshrrev_b32_e32 v21, 3, v26
	v_and_b32_e32 v20, 0x3fffe0, v20
	v_and_or_b32 v21, v21, 4, s35
	v_add3_u32 v0, v21, v20, v0
	v_lshl_or_b32 v0, v0, 10, v18
	s_waitcnt vmcnt(0)
	v_mul_f32_e32 v20, 0.5, v19
	v_lshl_add_u64 v[18:19], v[0:1], 2, s[6:7]
	global_load_dword v21, v[18:19], off
	s_waitcnt vmcnt(0)
	v_fmac_f32_e32 v21, v2, v20
	global_store_dword v[18:19], v21, off
	v_add_u32_e32 v18, 0x400, v0
	v_mov_b32_e32 v19, v1
	v_lshl_add_u64 v[18:19], v[18:19], 2, s[6:7]
	global_load_dword v2, v[18:19], off
	s_waitcnt vmcnt(0)
	v_fmac_f32_e32 v2, v3, v20
	global_store_dword v[18:19], v2, off
	v_add_u32_e32 v2, 0x800, v0
	v_mov_b32_e32 v3, v1
	v_lshl_add_u64 v[2:3], v[2:3], 2, s[6:7]
	global_load_dword v18, v[2:3], off
	s_waitcnt vmcnt(0)
	v_fmac_f32_e32 v18, v4, v20
	global_store_dword v[2:3], v18, off
	v_add_u32_e32 v2, 0xc00, v0
	v_mov_b32_e32 v3, v1
	v_lshl_add_u64 v[2:3], v[2:3], 2, s[6:7]
	global_load_dword v4, v[2:3], off
	s_waitcnt vmcnt(0)
	v_fmac_f32_e32 v4, v5, v20
	global_store_dword v[2:3], v4, off
	v_add_u32_e32 v2, 0x2000, v0
	v_mov_b32_e32 v3, v1
	v_lshl_add_u64 v[2:3], v[2:3], 2, s[6:7]
	global_load_dword v4, v[2:3], off
	s_waitcnt vmcnt(0)
	v_fmac_f32_e32 v4, v6, v20
	global_store_dword v[2:3], v4, off
	v_add_u32_e32 v2, 0x2400, v0
	v_mov_b32_e32 v3, v1
	v_lshl_add_u64 v[2:3], v[2:3], 2, s[6:7]
	global_load_dword v4, v[2:3], off
	s_waitcnt vmcnt(0)
	v_fmac_f32_e32 v4, v7, v20
	global_store_dword v[2:3], v4, off
	v_add_u32_e32 v2, 0x2800, v0
	v_mov_b32_e32 v3, v1
	v_lshl_add_u64 v[2:3], v[2:3], 2, s[6:7]
	global_load_dword v4, v[2:3], off
	s_waitcnt vmcnt(0)
	v_fmac_f32_e32 v4, v8, v20
	global_store_dword v[2:3], v4, off
	v_add_u32_e32 v2, 0x2c00, v0
	v_mov_b32_e32 v3, v1
	v_lshl_add_u64 v[2:3], v[2:3], 2, s[6:7]
	global_load_dword v4, v[2:3], off
	s_waitcnt vmcnt(0)
	v_fmac_f32_e32 v4, v9, v20
	global_store_dword v[2:3], v4, off
	v_add_u32_e32 v2, 0x4000, v0
	v_mov_b32_e32 v3, v1
	v_lshl_add_u64 v[2:3], v[2:3], 2, s[6:7]
	global_load_dword v4, v[2:3], off
	s_waitcnt vmcnt(0)
	v_fmac_f32_e32 v4, v10, v20
	global_store_dword v[2:3], v4, off
	v_add_u32_e32 v2, 0x4400, v0
	v_mov_b32_e32 v3, v1
	v_lshl_add_u64 v[2:3], v[2:3], 2, s[6:7]
	global_load_dword v4, v[2:3], off
	s_waitcnt vmcnt(0)
	v_fmac_f32_e32 v4, v11, v20
	global_store_dword v[2:3], v4, off
	v_add_u32_e32 v2, 0x4800, v0
	v_mov_b32_e32 v3, v1
	v_lshl_add_u64 v[2:3], v[2:3], 2, s[6:7]
	global_load_dword v4, v[2:3], off
	s_waitcnt vmcnt(0)
	v_fmac_f32_e32 v4, v12, v20
	global_store_dword v[2:3], v4, off
	v_add_u32_e32 v2, 0x4c00, v0
	v_mov_b32_e32 v3, v1
	v_lshl_add_u64 v[2:3], v[2:3], 2, s[6:7]
	global_load_dword v4, v[2:3], off
	s_waitcnt vmcnt(0)
	v_fmac_f32_e32 v4, v13, v20
	global_store_dword v[2:3], v4, off
	v_add_u32_e32 v2, 0x6000, v0
	v_mov_b32_e32 v3, v1
	v_lshl_add_u64 v[2:3], v[2:3], 2, s[6:7]
	global_load_dword v4, v[2:3], off
	s_waitcnt vmcnt(0)
	v_fmac_f32_e32 v4, v14, v20
	global_store_dword v[2:3], v4, off
	v_add_u32_e32 v2, 0x6400, v0
	v_mov_b32_e32 v3, v1
	v_lshl_add_u64 v[2:3], v[2:3], 2, s[6:7]
	global_load_dword v4, v[2:3], off
	s_waitcnt vmcnt(0)
	v_fmac_f32_e32 v4, v15, v20
	global_store_dword v[2:3], v4, off
	v_add_u32_e32 v2, 0x6800, v0
	v_mov_b32_e32 v3, v1
	v_lshl_add_u64 v[2:3], v[2:3], 2, s[6:7]
	global_load_dword v4, v[2:3], off
	v_add_u32_e32 v0, 0x6c00, v0
	s_waitcnt vmcnt(0)
	v_fmac_f32_e32 v4, v16, v20
	global_store_dword v[2:3], v4, off
	v_lshl_add_u64 v[2:3], v[0:1], 2, s[6:7]
	global_load_dword v0, v[2:3], off
	s_waitcnt vmcnt(0)
	v_fmac_f32_e32 v0, v17, v20
	global_store_dword v[2:3], v0, off
	v_readlane_b32 s12, v243, 7
	s_add_i32 s34, s34, s12
	s_add_i32 s29, s29, s49
	s_cmpk_gt_u32 s34, 0x1ff
	s_cbranch_scc0 .LBB0_480

; #define MFMA(a, b, c) __builtin_amdgcn_mfma_f32_32x32x16_bf16((a), (b), (c), 0, 0, 0)
; #define TIDX opaque_tid()
; template <int AI, int BI>
; DI void gemm_tile(const u16* __restrict__ A, int lda, const u16* __restrict__ B, int ldb, int nk, bool swap,
;                   f32x16 (&acc)[AI][BI], char* lds) {
;   const int tid = TIDX, lane = tid & 63, wid = tid >> 6;
;   gemm_stage<AI, BI>(A, lda, B, ldb, lds, tid);
;   asm volatile("s_waitcnt vmcnt(0)" ::: "memory");
;   __syncthreads();
;   const int wa = wid >> 1, wb = wid & 1, r = lane & 31, h = lane >> 5, sw = (r >> 1) & 7;
;   const int offA = (swap ? 16384 : 0) + (wa * 32 * AI + r) * 128;
;   const int offB = (swap ? 0 : 16384) + (wb * 32 * BI + r) * 128;
;   for (int kt = 0; kt < nk; ++kt) {
;     const char* cur = lds + (kt & 1) * 32768;
;     if (kt + 1 < nk) gemm_stage<AI, BI>(A + (kt + 1) * 64, lda, B + (kt + 1) * 64, ldb, lds + ((kt + 1) & 1) * 32768, tid);
; #pragma unroll
;     for (int ks = 0; ks < 4; ++ks) {
;       const int co = ((ks * 2 + h) ^ sw) << 4;
;       s16x8 fa[AI], fb[BI];
; #pragma unroll
;       for (int i = 0; i < AI; ++i) fa[i] = *(const s16x8*)(cur + offA + i * 4096 + co);
; #pragma unroll
;       for (int i = 0; i < BI; ++i) fb[i] = *(const s16x8*)(cur + offB + i * 4096 + co);
; #pragma unroll
;       for (int i = 0; i < AI; ++i)
; #pragma unroll
;         for (int j = 0; j < BI; ++j) acc[i][j] = MFMA(fa[i], fb[j], acc[i][j]);
;     }
;     asm volatile("s_waitcnt vmcnt(0)" ::: "memory");
;     __syncthreads();
;   }
; DI void phase_in(const Params& p, char* wsb, int layer, char* lds) {
;     ...
;     const bool swap = n0 < 3840;
;     f32x16 acc[2][2]; zero_acc<2, 2>(acc);
;     gemm_tile<2, 2>(H + (size_t)m0 * 1024, 1024, W + (size_t)n0 * 1024, 1024, 16, swap, acc, lds);
.LBB0_591:
	s_add_i32 s55, s54, 0xffff8000
	s_and_b32 s56, s55, 0x8000
	s_and_b32 s55, s54, 0x8000
	v_add_u32_e32 v103, s55, v94
	v_add_u32_e32 v106, s55, v95
	v_readfirstlane_b32 s57, v103
	v_lshl_add_u64 v[104:105], v[78:79], 0, s[12:13]
	s_mov_b32 m0, s57
	v_readfirstlane_b32 s57, v106
	v_add_u32_e32 v107, s55, v96
	global_load_lds_dwordx4 v[104:105], off
	v_lshl_add_u64 v[104:105], v[80:81], 0, s[12:13]
	s_mov_b32 m0, s57
	v_readfirstlane_b32 s57, v107
	v_add_u32_e32 v108, s55, v98
	global_load_lds_dwordx4 v[104:105], off
	v_lshl_add_u64 v[104:105], v[82:83], 0, s[12:13]
	s_mov_b32 m0, s57
	v_readfirstlane_b32 s57, v108
	v_add_u32_e32 v103, 0x4000, v103
	global_load_lds_dwordx4 v[104:105], off
	v_lshl_add_u64 v[104:105], v[84:85], 0, s[12:13]
	s_mov_b32 m0, s57
	v_readfirstlane_b32 s57, v103
	v_add_u32_e32 v103, 0x4000, v106
	global_load_lds_dwordx4 v[104:105], off
	v_lshl_add_u64 v[104:105], v[86:87], 0, s[12:13]
	s_mov_b32 m0, s57
	v_readfirstlane_b32 s57, v103
	v_add_u32_e32 v103, 0x4000, v107
	global_load_lds_dwordx4 v[104:105], off
	v_lshl_add_u64 v[104:105], v[88:89], 0, s[12:13]
	s_mov_b32 m0, s57
	v_readfirstlane_b32 s57, v103
	v_add_u32_e32 v103, 0x4000, v108
	global_load_lds_dwordx4 v[104:105], off
	v_lshl_add_u64 v[104:105], v[90:91], 0, s[12:13]
	s_mov_b32 m0, s57
	v_readfirstlane_b32 s57, v103
	global_load_lds_dwordx4 v[104:105], off
	v_lshl_add_u64 v[104:105], v[92:93], 0, s[12:13]
	s_mov_b32 m0, s57
	s_or_b32 s57, s56, s51
	global_load_lds_dwordx4 v[104:105], off
	s_or_b32 s56, s56, s7
	v_add_u32_e32 v103, s57, v102
	v_add_u32_e32 v119, s56, v100
	v_add_u32_e32 v108, v103, v101
	v_add_u32_e32 v120, v119, v101
	ds_read_b128 v[104:107], v108
	ds_read_b128 v[108:111], v108 offset:4096
	ds_read_b128 v[112:115], v120
	ds_read_b128 v[120:123], v120 offset:4096
	s_waitcnt lgkmcnt(0)
	v_mfma_f32_32x32x16_bf16 v[50:65], v[104:107], v[112:115], v[50:65]
	s_add_u32 s12, s12, 0x80
	s_addc_u32 s13, s13, 0
	s_add_i32 s54, s54, 0x8000
	s_cmpk_eq_i32 s12, 0x780
	v_mfma_f32_32x32x16_bf16 v[18:33], v[104:107], v[120:123], v[18:33]
	v_mfma_f32_32x32x16_bf16 v[34:49], v[108:111], v[112:115], v[34:49]
	v_mfma_f32_32x32x16_bf16 v[2:17], v[108:111], v[120:123], v[2:17]
	v_add_u32_e32 v108, v103, v99
	v_add_u32_e32 v120, v119, v99
	ds_read_b128 v[104:107], v108
	ds_read_b128 v[108:111], v108 offset:4096
	ds_read_b128 v[112:115], v120
	ds_read_b128 v[120:123], v120 offset:4096
	s_waitcnt lgkmcnt(1)
	v_mfma_f32_32x32x16_bf16 v[50:65], v[104:107], v[112:115], v[50:65]
	s_waitcnt lgkmcnt(0)
	v_mfma_f32_32x32x16_bf16 v[18:33], v[104:107], v[120:123], v[18:33]
	v_mfma_f32_32x32x16_bf16 v[34:49], v[108:111], v[112:115], v[34:49]
	v_mfma_f32_32x32x16_bf16 v[2:17], v[108:111], v[120:123], v[2:17]
	v_add_u32_e32 v108, v103, v97
	v_add_u32_e32 v120, v119, v97
	ds_read_b128 v[104:107], v108
	ds_read_b128 v[108:111], v108 offset:4096
	ds_read_b128 v[112:115], v120
	ds_read_b128 v[120:123], v120 offset:4096
	v_add_u32_e32 v103, v103, v0
	s_waitcnt lgkmcnt(1)
	v_mfma_f32_32x32x16_bf16 v[50:65], v[104:107], v[112:115], v[50:65]
	s_waitcnt lgkmcnt(0)
	v_mfma_f32_32x32x16_bf16 v[18:33], v[104:107], v[120:123], v[18:33]
	v_mfma_f32_32x32x16_bf16 v[34:49], v[108:111], v[112:115], v[34:49]
	v_mfma_f32_32x32x16_bf16 v[2:17], v[108:111], v[120:123], v[2:17]
	ds_read_b128 v[104:107], v103
	ds_read_b128 v[108:111], v103 offset:4096
	v_add_u32_e32 v103, v119, v0
	ds_read_b128 v[112:115], v103
	ds_read_b128 v[120:123], v103 offset:4096
	s_waitcnt lgkmcnt(0)
	v_mfma_f32_32x32x16_bf16 v[50:65], v[104:107], v[112:115], v[50:65]
	v_mfma_f32_32x32x16_bf16 v[18:33], v[104:107], v[120:123], v[18:33]
	v_mfma_f32_32x32x16_bf16 v[34:49], v[108:111], v[112:115], v[34:49]
	v_mfma_f32_32x32x16_bf16 v[2:17], v[108:111], v[120:123], v[2:17]
	s_waitcnt vmcnt(0)
	s_barrier
	s_cbranch_scc0 .LBB0_591
	s_add_i32 s12, s55, s51
	v_add_u32_e32 v90, s12, v102
	v_add_u32_e32 v91, v90, v101
	ds_read_b128 v[78:81], v91
	s_add_i32 s55, s55, s7
	v_add_u32_e32 v92, s55, v100
	v_add_u32_e32 v86, v92, v101
	ds_read_b128 v[82:85], v86
	ds_read_b128 v[86:89], v86 offset:4096
	s_and_b64 vcc, exec, s[10:11]
	s_waitcnt lgkmcnt(1)
	v_mfma_f32_32x32x16_bf16 v[50:65], v[78:81], v[82:85], v[50:65]
	s_waitcnt lgkmcnt(0)
	v_mfma_f32_32x32x16_bf16 v[18:33], v[78:81], v[86:89], v[18:33]
	ds_read_b128 v[78:81], v91 offset:4096
	v_add_u32_e32 v91, v90, v99
	s_waitcnt lgkmcnt(0)
	v_mfma_f32_32x32x16_bf16 v[34:49], v[78:81], v[82:85], v[34:49]
	v_mfma_f32_32x32x16_bf16 v[2:17], v[78:81], v[86:89], v[2:17]
	ds_read_b128 v[78:81], v91
	v_add_u32_e32 v86, v92, v99
	ds_read_b128 v[82:85], v86
	ds_read_b128 v[86:89], v86 offset:4096
	s_waitcnt lgkmcnt(1)
	v_mfma_f32_32x32x16_bf16 v[50:65], v[78:81], v[82:85], v[50:65]
	s_waitcnt lgkmcnt(0)
	v_mfma_f32_32x32x16_bf16 v[18:33], v[78:81], v[86:89], v[18:33]
	ds_read_b128 v[78:81], v91 offset:4096
	v_add_u32_e32 v91, v90, v97
	v_add_u32_e32 v90, v90, v0
	v_add_u32_e32 v0, v92, v0
	s_waitcnt lgkmcnt(0)
	v_mfma_f32_32x32x16_bf16 v[34:49], v[78:81], v[82:85], v[34:49]
	v_mfma_f32_32x32x16_bf16 v[2:17], v[78:81], v[86:89], v[2:17]
	ds_read_b128 v[78:81], v91
	v_add_u32_e32 v86, v92, v97
	ds_read_b128 v[82:85], v86
	ds_read_b128 v[86:89], v86 offset:4096
	s_waitcnt lgkmcnt(1)
	v_mfma_f32_32x32x16_bf16 v[50:65], v[78:81], v[82:85], v[50:65]
	s_waitcnt lgkmcnt(0)
	v_mfma_f32_32x32x16_bf16 v[18:33], v[78:81], v[86:89], v[18:33]
	ds_read_b128 v[78:81], v91 offset:4096
	s_waitcnt lgkmcnt(0)
	v_mfma_f32_32x32x16_bf16 v[34:49], v[78:81], v[82:85], v[34:49]
	ds_read_b128 v[82:85], v0
	v_mfma_f32_32x32x16_bf16 v[2:17], v[78:81], v[86:89], v[2:17]
	ds_read_b128 v[78:81], v90
	ds_read_b128 v[86:89], v0 offset:4096
	v_mov_b32_e32 v0, v1
	s_waitcnt lgkmcnt(1)
	v_mfma_f32_32x32x16_bf16 v[50:65], v[78:81], v[82:85], v[50:65]
	s_waitcnt lgkmcnt(0)
	v_mfma_f32_32x32x16_bf16 v[18:33], v[78:81], v[86:89], v[18:33]
	ds_read_b128 v[78:81], v90 offset:4096
	s_waitcnt vmcnt(0)
	s_waitcnt lgkmcnt(0)
	s_barrier
; #define GAS __attribute__((address_space(1)))
; DI int opaque0() { int z = 0; asm volatile("" : "+v"(z)); return z; }
; DI float sigmoidf_(float x) { return __builtin_amdgcn_rcpf(1.f + __expf(-x)); }
; DI void phase_in(const Params& p, char* wsb, int layer, char* lds) {
;     ...
;     const int m0e = m0 + opaque0();
;     if (!swap) {
;       GAS u16* G = uptr((u16*)(wsb + OFF_GATE));
; #pragma unroll
;       for (int bi = 0; bi < 2; ++bi) {
;         const int n = n0 - 3840 + wb * 64 + bi * 32 + r;
;         const unsigned ib = (unsigned)((m0e + wa * 64 + 4 * h) * 3072 + n);
; #pragma unroll
;         for (int ai = 0; ai < 2; ++ai)
; #pragma unroll
;           for (int reg = 0; reg < 16; ++reg)
;             G[ib + (unsigned)((ai * 32 + (reg & 3) + 8 * (reg >> 2)) * 3072)] = f2bf(sigmoidf_(acc[ai][bi][reg]));
	v_mfma_f32_32x32x16_bf16 v[34:49], v[78:81], v[82:85], v[34:49]
	v_add_u32_e32 v119, s6, v0
	s_mov_b64 s[6:7], -1
	v_mfma_f32_32x32x16_bf16 v[2:17], v[78:81], v[86:89], v[2:17]
	s_cbranch_vccz .LBB0_594
	s_nop 1
	v_mul_f32_e32 v78, 0xbfb8aa3b, v50
	v_exp_f32_e32 v78, v78
	v_add_u32_e32 v0, v119, v116
	s_movk_i32 s6, 0xc00
	v_add_u32_e32 v79, s50, v118
	v_add_f32_e32 v78, 1.0, v78
	v_rcp_f32_e32 v78, v78
	s_nop 0
	v_cvt_pk_bf16_f32 v82, v78, s0
	v_mul_lo_u32 v78, v0, s6
	v_add_u32_e32 v0, v78, v79
	v_lshl_add_u64 v[80:81], v[0:1], 1, s[16:17]
	v_mul_f32_e32 v0, 0xbfb8aa3b, v51
	v_exp_f32_e32 v0, v0
	global_store_short v[80:81], v82, off
	v_add_u32_e32 v81, 0xc00, v78
	s_mov_b64 s[6:7], 0
	v_add_f32_e32 v0, 1.0, v0
	v_rcp_f32_e32 v0, v0
	s_nop 0
	v_cvt_pk_bf16_f32 v80, v0, s0
	v_add_u32_e32 v0, v81, v79
	v_lshl_add_u64 v[82:83], v[0:1], 1, s[16:17]
	v_mul_f32_e32 v0, 0xbfb8aa3b, v52
	v_exp_f32_e32 v0, v0
	global_store_short v[82:83], v80, off
	v_add_u32_e32 v80, 0x1800, v78
	v_add_f32_e32 v0, 1.0, v0
	v_rcp_f32_e32 v0, v0
	s_nop 0
	v_cvt_pk_bf16_f32 v84, v0, s0
	v_add_u32_e32 v0, v80, v79
	v_lshl_add_u64 v[82:83], v[0:1], 1, s[16:17]
	v_mul_f32_e32 v0, 0xbfb8aa3b, v53
	v_exp_f32_e32 v0, v0
	global_store_short v[82:83], v84, off
	v_add_u32_e32 v83, 0x2400, v78
	v_add_f32_e32 v0, 1.0, v0
	v_rcp_f32_e32 v0, v0
	s_nop 0
	v_cvt_pk_bf16_f32 v82, v0, s0
	v_add_u32_e32 v0, v83, v79
	v_lshl_add_u64 v[84:85], v[0:1], 1, s[16:17]
	v_mul_f32_e32 v0, 0xbfb8aa3b, v54
	v_exp_f32_e32 v0, v0
	global_store_short v[84:85], v82, off
	v_add_u32_e32 v82, 0x6000, v78
	v_add_f32_e32 v0, 1.0, v0
	v_rcp_f32_e32 v0, v0
	s_nop 0
	v_cvt_pk_bf16_f32 v86, v0, s0
	v_add_u32_e32 v0, v82, v79
	v_lshl_add_u64 v[84:85], v[0:1], 1, s[16:17]
	v_mul_f32_e32 v0, 0xbfb8aa3b, v55
	v_exp_f32_e32 v0, v0
	global_store_short v[84:85], v86, off
	v_add_u32_e32 v85, 0x6c00, v78
	v_add_f32_e32 v0, 1.0, v0
	v_rcp_f32_e32 v0, v0
	s_nop 0
	v_cvt_pk_bf16_f32 v84, v0, s0
	v_add_u32_e32 v0, v85, v79
	v_lshl_add_u64 v[86:87], v[0:1], 1, s[16:17]
	v_mul_f32_e32 v0, 0xbfb8aa3b, v56
	v_exp_f32_e32 v0, v0
	global_store_short v[86:87], v84, off
	v_add_u32_e32 v84, 0x7800, v78
	v_add_f32_e32 v0, 1.0, v0
	v_rcp_f32_e32 v0, v0
	s_nop 0
	v_cvt_pk_bf16_f32 v88, v0, s0
	v_add_u32_e32 v0, v84, v79
	v_lshl_add_u64 v[86:87], v[0:1], 1, s[16:17]
	v_mul_f32_e32 v0, 0xbfb8aa3b, v57
	v_exp_f32_e32 v0, v0
	global_store_short v[86:87], v88, off
	v_add_u32_e32 v87, 0x8400, v78
	v_add_f32_e32 v0, 1.0, v0
	v_rcp_f32_e32 v0, v0
	s_nop 0
	v_cvt_pk_bf16_f32 v86, v0, s0
	v_add_u32_e32 v0, v87, v79
	v_lshl_add_u64 v[88:89], v[0:1], 1, s[16:17]
	v_mul_f32_e32 v0, 0xbfb8aa3b, v58
	v_exp_f32_e32 v0, v0
	global_store_short v[88:89], v86, off
	v_add_u32_e32 v86, 0xc000, v78
	v_add_f32_e32 v0, 1.0, v0
	v_rcp_f32_e32 v0, v0
	s_nop 0
	v_cvt_pk_bf16_f32 v90, v0, s0
	v_add_u32_e32 v0, v86, v79
	v_lshl_add_u64 v[88:89], v[0:1], 1, s[16:17]
	v_mul_f32_e32 v0, 0xbfb8aa3b, v59
	v_exp_f32_e32 v0, v0
	global_store_short v[88:89], v90, off
	v_add_u32_e32 v89, 0xcc00, v78
	v_add_f32_e32 v0, 1.0, v0
	v_rcp_f32_e32 v0, v0
	s_nop 0
	v_cvt_pk_bf16_f32 v88, v0, s0
	v_add_u32_e32 v0, v89, v79
	v_lshl_add_u64 v[90:91], v[0:1], 1, s[16:17]
	v_mul_f32_e32 v0, 0xbfb8aa3b, v60
	v_exp_f32_e32 v0, v0
	global_store_short v[90:91], v88, off
	v_add_u32_e32 v88, 0xd800, v78
	v_add_f32_e32 v0, 1.0, v0
	v_rcp_f32_e32 v0, v0
	s_nop 0
	v_cvt_pk_bf16_f32 v92, v0, s0
	v_add_u32_e32 v0, v88, v79
	v_lshl_add_u64 v[90:91], v[0:1], 1, s[16:17]
	v_mul_f32_e32 v0, 0xbfb8aa3b, v61
	v_exp_f32_e32 v0, v0
	global_store_short v[90:91], v92, off
	v_add_u32_e32 v91, 0xe400, v78
	v_add_f32_e32 v0, 1.0, v0
	v_rcp_f32_e32 v0, v0
	s_nop 0
	v_cvt_pk_bf16_f32 v90, v0, s0
	v_add_u32_e32 v0, v91, v79
	v_lshl_add_u64 v[92:93], v[0:1], 1, s[16:17]
	v_mul_f32_e32 v0, 0xbfb8aa3b, v62
	v_exp_f32_e32 v0, v0
	global_store_short v[92:93], v90, off
	v_add_u32_e32 v90, 0x12000, v78
	v_add_f32_e32 v0, 1.0, v0
	v_rcp_f32_e32 v0, v0
	s_nop 0
	v_cvt_pk_bf16_f32 v94, v0, s0
	v_add_u32_e32 v0, v90, v79
	v_lshl_add_u64 v[92:93], v[0:1], 1, s[16:17]
	v_mul_f32_e32 v0, 0xbfb8aa3b, v63
	v_exp_f32_e32 v0, v0
	global_store_short v[92:93], v94, off
	v_add_u32_e32 v93, 0x12c00, v78
	v_add_f32_e32 v0, 1.0, v0
	v_rcp_f32_e32 v0, v0
	s_nop 0
	v_cvt_pk_bf16_f32 v92, v0, s0
	v_add_u32_e32 v0, v93, v79
	v_lshl_add_u64 v[94:95], v[0:1], 1, s[16:17]
	v_mul_f32_e32 v0, 0xbfb8aa3b, v64
	v_exp_f32_e32 v0, v0
	global_store_short v[94:95], v92, off
	v_add_u32_e32 v92, 0x13800, v78
	v_add_f32_e32 v0, 1.0, v0
	v_rcp_f32_e32 v0, v0
	s_nop 0
	v_cvt_pk_bf16_f32 v96, v0, s0
	v_add_u32_e32 v0, v92, v79
	v_lshl_add_u64 v[94:95], v[0:1], 1, s[16:17]
	v_mul_f32_e32 v0, 0xbfb8aa3b, v65
	v_exp_f32_e32 v0, v0
	global_store_short v[94:95], v96, off
	v_add_u32_e32 v95, 0x14400, v78
	v_add_f32_e32 v0, 1.0, v0
	v_rcp_f32_e32 v0, v0
	s_nop 0
	v_cvt_pk_bf16_f32 v94, v0, s0
	v_add_u32_e32 v0, v95, v79
	v_lshl_add_u64 v[96:97], v[0:1], 1, s[16:17]
	v_mul_f32_e32 v0, 0xbfb8aa3b, v34
	v_exp_f32_e32 v0, v0
	global_store_short v[96:97], v94, off
	v_add_u32_e32 v94, 0x18000, v78
	v_add_f32_e32 v0, 1.0, v0
	v_rcp_f32_e32 v0, v0
	s_nop 0
	v_cvt_pk_bf16_f32 v98, v0, s0
	v_add_u32_e32 v0, v94, v79
	v_lshl_add_u64 v[96:97], v[0:1], 1, s[16:17]
	v_mul_f32_e32 v0, 0xbfb8aa3b, v35
	v_exp_f32_e32 v0, v0
	global_store_short v[96:97], v98, off
	v_add_u32_e32 v97, 0x18c00, v78
	v_add_f32_e32 v0, 1.0, v0
	v_rcp_f32_e32 v0, v0
	s_nop 0
	v_cvt_pk_bf16_f32 v96, v0, s0
	v_add_u32_e32 v0, v97, v79
	v_lshl_add_u64 v[98:99], v[0:1], 1, s[16:17]
	v_mul_f32_e32 v0, 0xbfb8aa3b, v36
	v_exp_f32_e32 v0, v0
	global_store_short v[98:99], v96, off
	v_add_u32_e32 v96, 0x19800, v78
; #define GAS __attribute__((address_space(1)))
; DI float sigmoidf_(float x) { return __builtin_amdgcn_rcpf(1.f + __expf(-x)); }
; DI void phase_in(const Params& p, char* wsb, int layer, char* lds) {
;     ...
;     if (!swap) {
;       GAS u16* G = uptr((u16*)(wsb + OFF_GATE));
; #pragma unroll
;       for (int bi = 0; bi < 2; ++bi) {
;         const int n = n0 - 3840 + wb * 64 + bi * 32 + r;
;         const unsigned ib = (unsigned)((m0e + wa * 64 + 4 * h) * 3072 + n);
; #pragma unroll
;         for (int ai = 0; ai < 2; ++ai)
; #pragma unroll
;           for (int reg = 0; reg < 16; ++reg)
;             G[ib + (unsigned)((ai * 32 + (reg & 3) + 8 * (reg >> 2)) * 3072)] = f2bf(sigmoidf_(acc[ai][bi][reg]));
	v_add_f32_e32 v0, 1.0, v0
	v_rcp_f32_e32 v0, v0
	s_nop 0
	v_cvt_pk_bf16_f32 v100, v0, s0
	v_add_u32_e32 v0, v96, v79
	v_lshl_add_u64 v[98:99], v[0:1], 1, s[16:17]
	v_mul_f32_e32 v0, 0xbfb8aa3b, v37
	v_exp_f32_e32 v0, v0
	global_store_short v[98:99], v100, off
	v_add_u32_e32 v99, 0x1a400, v78
	v_add_f32_e32 v0, 1.0, v0
	v_rcp_f32_e32 v0, v0
	s_nop 0
	v_cvt_pk_bf16_f32 v98, v0, s0
	v_add_u32_e32 v0, v99, v79
	v_lshl_add_u64 v[100:101], v[0:1], 1, s[16:17]
	v_mul_f32_e32 v0, 0xbfb8aa3b, v38
	v_exp_f32_e32 v0, v0
	global_store_short v[100:101], v98, off
	v_add_u32_e32 v98, 0x1e000, v78
	v_add_f32_e32 v0, 1.0, v0
	v_rcp_f32_e32 v0, v0
	s_nop 0
	v_cvt_pk_bf16_f32 v102, v0, s0
	v_add_u32_e32 v0, v98, v79
	v_lshl_add_u64 v[100:101], v[0:1], 1, s[16:17]
	v_mul_f32_e32 v0, 0xbfb8aa3b, v39
	v_exp_f32_e32 v0, v0
	global_store_short v[100:101], v102, off
	v_add_u32_e32 v101, 0x1ec00, v78
	v_add_f32_e32 v0, 1.0, v0
	v_rcp_f32_e32 v0, v0
	s_nop 0
	v_cvt_pk_bf16_f32 v100, v0, s0
	v_add_u32_e32 v0, v101, v79
	v_lshl_add_u64 v[102:103], v[0:1], 1, s[16:17]
	v_mul_f32_e32 v0, 0xbfb8aa3b, v40
	v_exp_f32_e32 v0, v0
	global_store_short v[102:103], v100, off
	v_add_u32_e32 v100, 0x1f800, v78
	v_add_f32_e32 v0, 1.0, v0
	v_rcp_f32_e32 v0, v0
	s_nop 0
	v_cvt_pk_bf16_f32 v104, v0, s0
	v_add_u32_e32 v0, v100, v79
	v_lshl_add_u64 v[102:103], v[0:1], 1, s[16:17]
	v_mul_f32_e32 v0, 0xbfb8aa3b, v41
	v_exp_f32_e32 v0, v0
	global_store_short v[102:103], v104, off
	v_add_u32_e32 v103, 0x20400, v78
	v_add_f32_e32 v0, 1.0, v0
	v_rcp_f32_e32 v0, v0
	s_nop 0
	v_cvt_pk_bf16_f32 v102, v0, s0
	v_add_u32_e32 v0, v103, v79
	v_lshl_add_u64 v[104:105], v[0:1], 1, s[16:17]
	v_mul_f32_e32 v0, 0xbfb8aa3b, v42
	v_exp_f32_e32 v0, v0
	global_store_short v[104:105], v102, off
	v_add_u32_e32 v102, 0x24000, v78
	v_add_f32_e32 v0, 1.0, v0
	v_rcp_f32_e32 v0, v0
	s_nop 0
	v_cvt_pk_bf16_f32 v106, v0, s0
	v_add_u32_e32 v0, v102, v79
	v_lshl_add_u64 v[104:105], v[0:1], 1, s[16:17]
	v_mul_f32_e32 v0, 0xbfb8aa3b, v43
	v_exp_f32_e32 v0, v0
	global_store_short v[104:105], v106, off
	v_add_u32_e32 v105, 0x24c00, v78
	v_add_f32_e32 v0, 1.0, v0
	v_rcp_f32_e32 v0, v0
	s_nop 0
	v_cvt_pk_bf16_f32 v104, v0, s0
	v_add_u32_e32 v0, v105, v79
	v_lshl_add_u64 v[106:107], v[0:1], 1, s[16:17]
	v_mul_f32_e32 v0, 0xbfb8aa3b, v44
	v_exp_f32_e32 v0, v0
	global_store_short v[106:107], v104, off
	v_add_u32_e32 v104, 0x25800, v78
	v_add_f32_e32 v0, 1.0, v0
	v_rcp_f32_e32 v0, v0
	s_nop 0
	v_cvt_pk_bf16_f32 v108, v0, s0
	v_add_u32_e32 v0, v104, v79
	v_lshl_add_u64 v[106:107], v[0:1], 1, s[16:17]
	v_mul_f32_e32 v0, 0xbfb8aa3b, v45
	v_exp_f32_e32 v0, v0
	global_store_short v[106:107], v108, off
	v_add_u32_e32 v107, 0x26400, v78
	v_add_f32_e32 v0, 1.0, v0
	v_rcp_f32_e32 v0, v0
	s_nop 0
	v_cvt_pk_bf16_f32 v106, v0, s0
	v_add_u32_e32 v0, v107, v79
	v_lshl_add_u64 v[108:109], v[0:1], 1, s[16:17]
	v_mul_f32_e32 v0, 0xbfb8aa3b, v46
	v_exp_f32_e32 v0, v0
	global_store_short v[108:109], v106, off
	v_add_u32_e32 v106, 0x2a000, v78
	v_add_f32_e32 v0, 1.0, v0
	v_rcp_f32_e32 v0, v0
	s_nop 0
	v_cvt_pk_bf16_f32 v110, v0, s0
	v_add_u32_e32 v0, v106, v79
	v_lshl_add_u64 v[108:109], v[0:1], 1, s[16:17]
	v_mul_f32_e32 v0, 0xbfb8aa3b, v47
	v_exp_f32_e32 v0, v0
	global_store_short v[108:109], v110, off
	v_add_u32_e32 v108, 0x2ac00, v78
	v_add_f32_e32 v0, 1.0, v0
	v_rcp_f32_e32 v0, v0
	s_nop 0
	v_cvt_pk_bf16_f32 v109, v0, s0
	v_add_u32_e32 v0, v108, v79
	v_lshl_add_u64 v[110:111], v[0:1], 1, s[16:17]
	v_mul_f32_e32 v0, 0xbfb8aa3b, v48
	v_exp_f32_e32 v0, v0
	global_store_short v[110:111], v109, off
	v_add_u32_e32 v109, 0x2b800, v78
	v_add_f32_e32 v0, 1.0, v0
	v_rcp_f32_e32 v0, v0
	s_nop 0
	v_cvt_pk_bf16_f32 v112, v0, s0
	v_add_u32_e32 v0, v109, v79
	v_lshl_add_u64 v[110:111], v[0:1], 1, s[16:17]
	v_mul_f32_e32 v0, 0xbfb8aa3b, v49
	v_exp_f32_e32 v0, v0
	global_store_short v[110:111], v112, off
	v_add_u32_e32 v110, 0x2c400, v78
	v_add_f32_e32 v0, 1.0, v0
	v_rcp_f32_e32 v0, v0
	s_nop 0
	v_cvt_pk_bf16_f32 v111, v0, s0
	v_add_u32_e32 v0, v110, v79
	v_lshl_add_u64 v[112:113], v[0:1], 1, s[16:17]
	v_mul_f32_e32 v0, 0xbfb8aa3b, v18
	v_exp_f32_e32 v0, v0
	v_or_b32_e32 v79, 32, v79
	global_store_short v[112:113], v111, off
	v_add_f32_e32 v0, 1.0, v0
	v_rcp_f32_e32 v0, v0
	s_nop 0
	v_cvt_pk_bf16_f32 v111, v0, s0
	v_add_u32_e32 v0, v78, v79
	v_lshl_add_u64 v[112:113], v[0:1], 1, s[16:17]
	v_mul_f32_e32 v0, 0xbfb8aa3b, v19
	v_exp_f32_e32 v0, v0
	global_store_short v[112:113], v111, off
	v_add_f32_e32 v0, 1.0, v0
	v_rcp_f32_e32 v0, v0
	s_nop 0
	v_cvt_pk_bf16_f32 v78, v0, s0
	v_add_u32_e32 v0, v81, v79
	v_lshl_add_u64 v[112:113], v[0:1], 1, s[16:17]
	v_mul_f32_e32 v0, 0xbfb8aa3b, v20
	v_exp_f32_e32 v0, v0
	global_store_short v[112:113], v78, off
	v_add_f32_e32 v0, 1.0, v0
	v_rcp_f32_e32 v0, v0
	s_nop 0
	v_cvt_pk_bf16_f32 v78, v0, s0
	v_add_u32_e32 v0, v80, v79
	v_lshl_add_u64 v[80:81], v[0:1], 1, s[16:17]
	v_mul_f32_e32 v0, 0xbfb8aa3b, v21
	v_exp_f32_e32 v0, v0
	global_store_short v[80:81], v78, off
	v_add_f32_e32 v0, 1.0, v0
	v_rcp_f32_e32 v0, v0
	s_nop 0
	v_cvt_pk_bf16_f32 v78, v0, s0
	v_add_u32_e32 v0, v83, v79
	v_lshl_add_u64 v[80:81], v[0:1], 1, s[16:17]
	v_mul_f32_e32 v0, 0xbfb8aa3b, v22
	v_exp_f32_e32 v0, v0
	global_store_short v[80:81], v78, off
	v_add_f32_e32 v0, 1.0, v0
	v_rcp_f32_e32 v0, v0
	s_nop 0
	v_cvt_pk_bf16_f32 v78, v0, s0
	v_add_u32_e32 v0, v82, v79
	v_lshl_add_u64 v[80:81], v[0:1], 1, s[16:17]
	v_mul_f32_e32 v0, 0xbfb8aa3b, v23
	v_exp_f32_e32 v0, v0
	global_store_short v[80:81], v78, off
	v_add_f32_e32 v0, 1.0, v0
	v_rcp_f32_e32 v0, v0
	s_nop 0
	v_cvt_pk_bf16_f32 v78, v0, s0
	v_add_u32_e32 v0, v85, v79
	v_lshl_add_u64 v[80:81], v[0:1], 1, s[16:17]
; #define GAS __attribute__((address_space(1)))
; DI float sigmoidf_(float x) { return __builtin_amdgcn_rcpf(1.f + __expf(-x)); }
; DI void phase_in(const Params& p, char* wsb, int layer, char* lds) {
;     ...
;     if (!swap) {
;       GAS u16* G = uptr((u16*)(wsb + OFF_GATE));
; #pragma unroll
;       for (int bi = 0; bi < 2; ++bi) {
;         const int n = n0 - 3840 + wb * 64 + bi * 32 + r;
;         const unsigned ib = (unsigned)((m0e + wa * 64 + 4 * h) * 3072 + n);
; #pragma unroll
;         for (int ai = 0; ai < 2; ++ai)
; #pragma unroll
;           for (int reg = 0; reg < 16; ++reg)
;             G[ib + (unsigned)((ai * 32 + (reg & 3) + 8 * (reg >> 2)) * 3072)] = f2bf(sigmoidf_(acc[ai][bi][reg]));
;       }
;       continue;
	v_mul_f32_e32 v0, 0xbfb8aa3b, v24
	v_exp_f32_e32 v0, v0
	global_store_short v[80:81], v78, off
	v_add_f32_e32 v0, 1.0, v0
	v_rcp_f32_e32 v0, v0
	s_nop 0
	v_cvt_pk_bf16_f32 v78, v0, s0
	v_add_u32_e32 v0, v84, v79
	v_lshl_add_u64 v[80:81], v[0:1], 1, s[16:17]
	v_mul_f32_e32 v0, 0xbfb8aa3b, v25
	v_exp_f32_e32 v0, v0
	global_store_short v[80:81], v78, off
	v_add_f32_e32 v0, 1.0, v0
	v_rcp_f32_e32 v0, v0
	s_nop 0
	v_cvt_pk_bf16_f32 v78, v0, s0
	v_add_u32_e32 v0, v87, v79
	v_lshl_add_u64 v[80:81], v[0:1], 1, s[16:17]
	v_mul_f32_e32 v0, 0xbfb8aa3b, v26
	v_exp_f32_e32 v0, v0
	global_store_short v[80:81], v78, off
	v_add_f32_e32 v0, 1.0, v0
	v_rcp_f32_e32 v0, v0
	s_nop 0
	v_cvt_pk_bf16_f32 v78, v0, s0
	v_add_u32_e32 v0, v86, v79
	v_lshl_add_u64 v[80:81], v[0:1], 1, s[16:17]
	v_mul_f32_e32 v0, 0xbfb8aa3b, v27
	v_exp_f32_e32 v0, v0
	global_store_short v[80:81], v78, off
	v_add_f32_e32 v0, 1.0, v0
	v_rcp_f32_e32 v0, v0
	s_nop 0
	v_cvt_pk_bf16_f32 v78, v0, s0
	v_add_u32_e32 v0, v89, v79
	v_lshl_add_u64 v[80:81], v[0:1], 1, s[16:17]
	v_mul_f32_e32 v0, 0xbfb8aa3b, v28
	v_exp_f32_e32 v0, v0
	global_store_short v[80:81], v78, off
	v_add_f32_e32 v0, 1.0, v0
	v_rcp_f32_e32 v0, v0
	s_nop 0
	v_cvt_pk_bf16_f32 v78, v0, s0
	v_add_u32_e32 v0, v88, v79
	v_lshl_add_u64 v[80:81], v[0:1], 1, s[16:17]
	v_mul_f32_e32 v0, 0xbfb8aa3b, v29
	v_exp_f32_e32 v0, v0
	global_store_short v[80:81], v78, off
	v_add_f32_e32 v0, 1.0, v0
	v_rcp_f32_e32 v0, v0
	s_nop 0
	v_cvt_pk_bf16_f32 v78, v0, s0
	v_add_u32_e32 v0, v91, v79
	v_lshl_add_u64 v[80:81], v[0:1], 1, s[16:17]
	v_mul_f32_e32 v0, 0xbfb8aa3b, v30
	v_exp_f32_e32 v0, v0
	global_store_short v[80:81], v78, off
	v_add_f32_e32 v0, 1.0, v0
	v_rcp_f32_e32 v0, v0
	s_nop 0
	v_cvt_pk_bf16_f32 v78, v0, s0
	v_add_u32_e32 v0, v90, v79
	v_lshl_add_u64 v[80:81], v[0:1], 1, s[16:17]
	v_mul_f32_e32 v0, 0xbfb8aa3b, v31
	v_exp_f32_e32 v0, v0
	global_store_short v[80:81], v78, off
	v_add_f32_e32 v0, 1.0, v0
	v_rcp_f32_e32 v0, v0
	s_nop 0
	v_cvt_pk_bf16_f32 v78, v0, s0
	v_add_u32_e32 v0, v93, v79
	v_lshl_add_u64 v[80:81], v[0:1], 1, s[16:17]
	v_mul_f32_e32 v0, 0xbfb8aa3b, v32
	v_exp_f32_e32 v0, v0
	global_store_short v[80:81], v78, off
	v_add_f32_e32 v0, 1.0, v0
	v_rcp_f32_e32 v0, v0
	s_nop 0
	v_cvt_pk_bf16_f32 v78, v0, s0
	v_add_u32_e32 v0, v92, v79
	v_lshl_add_u64 v[80:81], v[0:1], 1, s[16:17]
	v_mul_f32_e32 v0, 0xbfb8aa3b, v33
	v_exp_f32_e32 v0, v0
	global_store_short v[80:81], v78, off
	v_add_f32_e32 v0, 1.0, v0
	v_rcp_f32_e32 v0, v0
	s_nop 0
	v_cvt_pk_bf16_f32 v78, v0, s0
	v_add_u32_e32 v0, v95, v79
	v_lshl_add_u64 v[80:81], v[0:1], 1, s[16:17]
	v_mul_f32_e32 v0, 0xbfb8aa3b, v2
	v_exp_f32_e32 v0, v0
	global_store_short v[80:81], v78, off
	v_add_f32_e32 v0, 1.0, v0
	v_rcp_f32_e32 v0, v0
	s_nop 0
	v_cvt_pk_bf16_f32 v78, v0, s0
	v_add_u32_e32 v0, v94, v79
	v_lshl_add_u64 v[80:81], v[0:1], 1, s[16:17]
	v_mul_f32_e32 v0, 0xbfb8aa3b, v3
	v_exp_f32_e32 v0, v0
	global_store_short v[80:81], v78, off
	v_add_f32_e32 v0, 1.0, v0
	v_rcp_f32_e32 v0, v0
	s_nop 0
	v_cvt_pk_bf16_f32 v78, v0, s0
	v_add_u32_e32 v0, v97, v79
	v_lshl_add_u64 v[80:81], v[0:1], 1, s[16:17]
	v_mul_f32_e32 v0, 0xbfb8aa3b, v4
	v_exp_f32_e32 v0, v0
	global_store_short v[80:81], v78, off
	v_add_f32_e32 v0, 1.0, v0
	v_rcp_f32_e32 v0, v0
	s_nop 0
	v_cvt_pk_bf16_f32 v78, v0, s0
	v_add_u32_e32 v0, v96, v79
	v_lshl_add_u64 v[80:81], v[0:1], 1, s[16:17]
	v_mul_f32_e32 v0, 0xbfb8aa3b, v5
	v_exp_f32_e32 v0, v0
	global_store_short v[80:81], v78, off
	v_add_f32_e32 v0, 1.0, v0
	v_rcp_f32_e32 v0, v0
	s_nop 0
	v_cvt_pk_bf16_f32 v78, v0, s0
	v_add_u32_e32 v0, v99, v79
	v_lshl_add_u64 v[80:81], v[0:1], 1, s[16:17]
	v_mul_f32_e32 v0, 0xbfb8aa3b, v6
	v_exp_f32_e32 v0, v0
	global_store_short v[80:81], v78, off
	v_add_f32_e32 v0, 1.0, v0
	v_rcp_f32_e32 v0, v0
	s_nop 0
	v_cvt_pk_bf16_f32 v78, v0, s0
	v_add_u32_e32 v0, v98, v79
	v_lshl_add_u64 v[80:81], v[0:1], 1, s[16:17]
	v_mul_f32_e32 v0, 0xbfb8aa3b, v7
	v_exp_f32_e32 v0, v0
	global_store_short v[80:81], v78, off
	v_add_f32_e32 v0, 1.0, v0
	v_rcp_f32_e32 v0, v0
	s_nop 0
	v_cvt_pk_bf16_f32 v78, v0, s0
	v_add_u32_e32 v0, v101, v79
	v_lshl_add_u64 v[80:81], v[0:1], 1, s[16:17]
	v_mul_f32_e32 v0, 0xbfb8aa3b, v8
	v_exp_f32_e32 v0, v0
	global_store_short v[80:81], v78, off
	v_add_f32_e32 v0, 1.0, v0
	v_rcp_f32_e32 v0, v0
	s_nop 0
	v_cvt_pk_bf16_f32 v78, v0, s0
	v_add_u32_e32 v0, v100, v79
	v_lshl_add_u64 v[80:81], v[0:1], 1, s[16:17]
	v_mul_f32_e32 v0, 0xbfb8aa3b, v9
	v_exp_f32_e32 v0, v0
	global_store_short v[80:81], v78, off
	v_add_f32_e32 v0, 1.0, v0
	v_rcp_f32_e32 v0, v0
	s_nop 0
	v_cvt_pk_bf16_f32 v78, v0, s0
	v_add_u32_e32 v0, v103, v79
	v_lshl_add_u64 v[80:81], v[0:1], 1, s[16:17]
	v_mul_f32_e32 v0, 0xbfb8aa3b, v10
	v_exp_f32_e32 v0, v0
	global_store_short v[80:81], v78, off
	v_add_f32_e32 v0, 1.0, v0
	v_rcp_f32_e32 v0, v0
	s_nop 0
	v_cvt_pk_bf16_f32 v78, v0, s0
	v_add_u32_e32 v0, v102, v79
	v_lshl_add_u64 v[80:81], v[0:1], 1, s[16:17]
	v_mul_f32_e32 v0, 0xbfb8aa3b, v11
	v_exp_f32_e32 v0, v0
	global_store_short v[80:81], v78, off
	v_add_f32_e32 v0, 1.0, v0
	v_rcp_f32_e32 v0, v0
	s_nop 0
	v_cvt_pk_bf16_f32 v78, v0, s0
	v_add_u32_e32 v0, v105, v79
	v_lshl_add_u64 v[80:81], v[0:1], 1, s[16:17]
	v_mul_f32_e32 v0, 0xbfb8aa3b, v12
	v_exp_f32_e32 v0, v0
	global_store_short v[80:81], v78, off
	v_add_f32_e32 v0, 1.0, v0
	v_rcp_f32_e32 v0, v0
	s_nop 0
	v_cvt_pk_bf16_f32 v78, v0, s0
	v_add_u32_e32 v0, v104, v79
	v_lshl_add_u64 v[80:81], v[0:1], 1, s[16:17]
	v_mul_f32_e32 v0, 0xbfb8aa3b, v13
	v_exp_f32_e32 v0, v0
	global_store_short v[80:81], v78, off
	v_add_f32_e32 v0, 1.0, v0
	v_rcp_f32_e32 v0, v0
	s_nop 0
	v_cvt_pk_bf16_f32 v78, v0, s0
	v_add_u32_e32 v0, v107, v79
	v_lshl_add_u64 v[80:81], v[0:1], 1, s[16:17]
	v_mul_f32_e32 v0, 0xbfb8aa3b, v14
	v_exp_f32_e32 v0, v0
	global_store_short v[80:81], v78, off
	v_add_f32_e32 v0, 1.0, v0
	v_rcp_f32_e32 v0, v0
	s_nop 0
	v_cvt_pk_bf16_f32 v78, v0, s0
	v_add_u32_e32 v0, v106, v79
	v_lshl_add_u64 v[80:81], v[0:1], 1, s[16:17]
	v_mul_f32_e32 v0, 0xbfb8aa3b, v15
	v_exp_f32_e32 v0, v0
	global_store_short v[80:81], v78, off
	v_add_f32_e32 v0, 1.0, v0
	v_rcp_f32_e32 v0, v0
	s_nop 0
	v_cvt_pk_bf16_f32 v78, v0, s0
	v_add_u32_e32 v0, v108, v79
	v_lshl_add_u64 v[80:81], v[0:1], 1, s[16:17]
	v_mul_f32_e32 v0, 0xbfb8aa3b, v16
	v_exp_f32_e32 v0, v0
	global_store_short v[80:81], v78, off
	v_add_f32_e32 v0, 1.0, v0
	v_rcp_f32_e32 v0, v0
	s_nop 0
	v_cvt_pk_bf16_f32 v78, v0, s0
	v_add_u32_e32 v0, v109, v79
	v_lshl_add_u64 v[80:81], v[0:1], 1, s[16:17]
	v_mul_f32_e32 v0, 0xbfb8aa3b, v17
	v_exp_f32_e32 v0, v0
	global_store_short v[80:81], v78, off
	v_add_f32_e32 v0, 1.0, v0
	v_rcp_f32_e32 v0, v0
	s_nop 0
	v_cvt_pk_bf16_f32 v80, v0, s0
	v_add_u32_e32 v0, v110, v79
	v_lshl_add_u64 v[78:79], v[0:1], 1, s[16:17]
	global_store_short v[78:79], v80, off

; #define TIDX opaque_tid()
; template <int AI, int BI>
; DI void gemm_stage(const u16* __restrict__ A, int lda, const u16* __restrict__ B, int ldb, char* buf, int tid) {
; #pragma unroll
;   for (int i = 0; i < 2 * AI; ++i) {
;     const int S = tid + NTHR * i, row = S >> 3, c = (S & 7) ^ ((row >> 1) & 7);
;     __builtin_amdgcn_global_load_lds((const unsigned*)(A + (size_t)row * lda + c * 8), (__attribute__((address_space(3))) unsigned*)(buf + S * 16), 16, 0, 0);
;   }
; #pragma unroll
;   for (int i = 0; i < 2 * BI; ++i) {
;     const int S = tid + NTHR * i, row = S >> 3, c = (S & 7) ^ ((row >> 1) & 7);
;     __builtin_amdgcn_global_load_lds((const unsigned*)(B + (size_t)row * ldb + c * 8), (__attribute__((address_space(3))) unsigned*)(buf + 16384 + S * 16), 16, 0, 0);
;   }
; }
; template <int AI, int BI>
; DI void gemm_tile(const u16* __restrict__ A, int lda, const u16* __restrict__ B, int ldb, int nk, bool swap,
;                   f32x16 (&acc)[AI][BI], char* lds) {
;   const int tid = TIDX, lane = tid & 63, wid = tid >> 6;
;   gemm_stage<AI, BI>(A, lda, B, ldb, lds, tid);
;   asm volatile("s_waitcnt vmcnt(0)" ::: "memory");
;   __syncthreads();
;   const int wa = wid >> 1, wb = wid & 1, r = lane & 31, h = lane >> 5, sw = (r >> 1) & 7;
;   const int offA = (swap ? 16384 : 0) + (wa * 32 * AI + r) * 128;
;   const int offB = (swap ? 0 : 16384) + (wb * 32 * BI + r) * 128;
;   for (int kt = 0; kt < nk; ++kt) {
;     const char* cur = lds + (kt & 1) * 32768;
;     if (kt + 1 < nk) gemm_stage<AI, BI>(A + (kt + 1) * 64, lda, B + (kt + 1) * 64, ldb, lds + ((kt + 1) & 1) * 32768, tid);
; #pragma unroll
;     for (int ks = 0; ks < 4; ++ks) {
;       const int co = ((ks * 2 + h) ^ sw) << 4;
;       s16x8 fa[AI], fb[BI];
; #pragma unroll
;       for (int i = 0; i < AI; ++i) fa[i] = *(const s16x8*)(cur + offA + i * 4096 + co);
; #pragma unroll
;       for (int i = 0; i < BI; ++i) fb[i] = *(const s16x8*)(cur + offB + i * 4096 + co);
; #pragma unroll
;       for (int i = 0; i < AI; ++i)
; #pragma unroll
;         for (int j = 0; j < BI; ++j) acc[i][j] = MFMA(fa[i], fb[j], acc[i][j]);
;     }
;     asm volatile("s_waitcnt vmcnt(0)" ::: "memory");
;     __syncthreads();
;   }
; DI bool next_tile(int rnd, int MT, int NT, int& mt, int& nt) {
;   const int G8 = gridDim.x >> 3, x = blockIdx.x & 7, slot = blockIdx.x >> 3;
;   const int T = (rnd * 8 + x) * G8 + slot;
.LBB0_1099:
	s_lshr_b32 s10, s34, 3
	s_and_b32 s10, s10, 0x78
	s_and_b32 s11, s34, 7
	s_or_b32 s10, s10, s11
	s_waitcnt vmcnt(2)
	v_mov_b32_e32 v82, v178
	v_mov_b32_e32 v83, v178
	v_mov_b32_e32 v12, v178
	s_and_b32 s35, s29, 0x380
	s_lshl_b32 s11, s10, 18
	s_add_u32 s36, s14, s11
	v_lshrrev_b32_e32 v0, 4, v12
	v_xor_b32_e32 v0, v0, v12
	v_add_u32_e32 v8, 0x100, v12
	v_add_u32_e32 v10, 0x200, v12
	v_add_u32_e32 v13, 0x300, v12
	s_addc_u32 s37, s15, 0
	s_lshl_b32 s11, s35, 11
	v_lshlrev_b32_e32 v0, 4, v0
	v_ashrrev_i32_e32 v4, 3, v12
	v_ashrrev_i32_e32 v6, 3, v8
	v_lshlrev_b32_e32 v99, 4, v8
	v_ashrrev_i32_e32 v8, 3, v10
	v_lshlrev_b32_e32 v100, 4, v10
	v_ashrrev_i32_e32 v10, 3, v13
	s_add_u32 s40, s16, s11
	v_and_b32_e32 v0, 0x70, v0
	v_ashrrev_i32_e32 v5, 31, v4
	v_ashrrev_i32_e32 v7, 31, v6
	v_ashrrev_i32_e32 v9, 31, v8
	v_ashrrev_i32_e32 v11, 31, v10
	s_addc_u32 s41, s17, 0
	v_lshl_add_u64 v[2:3], s[36:37], 0, v[0:1]
	v_lshlrev_b64 v[4:5], 11, v[4:5]
	v_lshlrev_b32_e32 v96, 4, v12
	v_lshlrev_b64 v[6:7], 11, v[6:7]
	v_lshlrev_b64 v[8:9], 11, v[8:9]
	v_lshlrev_b64 v[10:11], 11, v[10:11]
	v_lshl_add_u64 v[66:67], v[2:3], 0, v[4:5]
	v_lshl_add_u64 v[68:69], v[2:3], 0, v[6:7]
	v_lshl_add_u64 v[70:71], v[2:3], 0, v[8:9]
	v_lshl_add_u64 v[72:73], v[2:3], 0, v[10:11]
	v_lshl_add_u64 v[2:3], s[40:41], 0, v[0:1]
	v_add_u32_e32 v0, 0x4000, v96
	v_readfirstlane_b32 s47, v96
	v_readfirstlane_b32 s36, v0
	v_add_u32_e32 v0, 0x4000, v99
	s_mov_b32 m0, s47
	v_readfirstlane_b32 s52, v99
	v_lshlrev_b32_e32 v101, 4, v13
	v_readfirstlane_b32 s37, v0
	v_add_u32_e32 v0, 0x4000, v100
	global_load_lds_dwordx4 v[66:67], off
	s_mov_b32 m0, s52
	v_readfirstlane_b32 s55, v100
	v_readfirstlane_b32 s40, v0
	v_add_u32_e32 v0, 0x4000, v101
	global_load_lds_dwordx4 v[68:69], off
	s_mov_b32 m0, s55
	v_readfirstlane_b32 s56, v101
	v_lshl_add_u64 v[74:75], v[2:3], 0, v[4:5]
	v_readfirstlane_b32 s41, v0
	v_and_b32_e32 v0, 31, v12
	v_lshrrev_b32_e32 v4, 1, v12
	global_load_lds_dwordx4 v[70:71], off
	s_mov_b32 m0, s56
	v_and_or_b32 v0, v4, s65, v0
	global_load_lds_dwordx4 v[72:73], off
	s_mov_b32 m0, s36
	v_lshl_add_u64 v[76:77], v[2:3], 0, v[6:7]
	v_lshl_add_u64 v[78:79], v[2:3], 0, v[8:9]
	v_lshl_add_u64 v[80:81], v[2:3], 0, v[10:11]
	v_lshrrev_b32_e32 v2, 5, v12
	v_bfe_u32 v5, v12, 1, 3
	v_lshlrev_b32_e32 v86, 7, v0
	v_lshlrev_b32_e32 v0, 7, v12
	global_load_lds_dwordx4 v[74:75], off
	s_mov_b32 m0, s37
	v_bfe_u32 v3, v12, 5, 1
	v_and_b32_e32 v88, 0x2f80, v0
	v_bitop3_b32 v0, v2, v5, 1 bitop3:0x6c
	global_load_lds_dwordx4 v[76:77], off
	s_mov_b32 m0, s40
	v_lshlrev_b32_e32 v10, 4, v0
	v_bitop3_b32 v0, v3, v5, 2 bitop3:0x36
	v_add_u32_e32 v91, 0x8000, v96
	global_load_lds_dwordx4 v[78:79], off
	s_mov_b32 m0, s41
	v_lshlrev_b32_e32 v85, 4, v0
	v_bitop3_b32 v0, v3, v5, 4 bitop3:0x36
	v_readfirstlane_b32 s46, v91
	v_add_u32_e32 v92, 0x8000, v99
	global_load_lds_dwordx4 v[80:81], off
	v_lshlrev_b32_e32 v87, 4, v0
	v_bitop3_b32 v0, v3, v5, 6 bitop3:0x36
	v_lshl_add_u64 v[2:3], v[66:67], 0, s[68:69]
	s_mov_b32 m0, s46
	v_readfirstlane_b32 s48, v92
	v_add_u32_e32 v93, 0x8000, v100
	s_waitcnt vmcnt(0)
	s_waitcnt vmcnt(0) lgkmcnt(0)
	s_barrier
	global_load_lds_dwordx4 v[2:3], off
	v_lshl_add_u64 v[2:3], v[68:69], 0, s[68:69]
	s_mov_b32 m0, s48
	v_readfirstlane_b32 s49, v93
	v_add_u32_e32 v94, 0x8000, v101
	global_load_lds_dwordx4 v[2:3], off
	v_lshl_add_u64 v[2:3], v[70:71], 0, s[68:69]
	s_mov_b32 m0, s49
	v_readfirstlane_b32 s50, v94
	v_add_u32_e32 v95, 0xc000, v96
	global_load_lds_dwordx4 v[2:3], off
	v_lshl_add_u64 v[2:3], v[72:73], 0, s[68:69]
	s_mov_b32 m0, s50
	v_readfirstlane_b32 s51, v95
	v_add_u32_e32 v97, 0xc000, v99
	global_load_lds_dwordx4 v[2:3], off
	v_lshl_add_u64 v[2:3], v[74:75], 0, s[68:69]
	s_mov_b32 m0, s51
	v_readfirstlane_b32 s53, v97
	v_add_u32_e32 v98, 0xc000, v100
	v_lshlrev_b32_e32 v118, 4, v0
	global_load_lds_dwordx4 v[2:3], off
	v_lshl_add_u64 v[2:3], v[76:77], 0, s[68:69]
	s_mov_b32 m0, s53
	v_readfirstlane_b32 s54, v98
	v_add_u32_e32 v0, 0xc000, v101
	global_load_lds_dwordx4 v[2:3], off
	v_lshl_add_u64 v[2:3], v[78:79], 0, s[68:69]
	s_mov_b32 m0, s54
	v_readfirstlane_b32 s11, v0
	global_load_lds_dwordx4 v[2:3], off
	v_lshl_add_u64 v[2:3], v[80:81], 0, s[68:69]
	s_mov_b32 m0, s11
	v_or_b32_e32 v0, v86, v10
	global_load_lds_dwordx4 v[2:3], off
	v_or_b32_e32 v84, v88, v10
	ds_read_b128 v[2:5], v0
	ds_read_b128 v[6:9], v0 offset:4096
	ds_read_b128 v[10:13], v84 offset:16384
	ds_read_b128 v[14:17], v84 offset:20480
	s_waitcnt lgkmcnt(0)
	v_mfma_f32_32x32x16_bf16 v[50:65], v[2:5], v[10:13], 0
	v_or_b32_e32 v89, v86, v85
	v_or_b32_e32 v90, v88, v85
	ds_read_b128 v[102:105], v89
	ds_read_b128 v[106:109], v89 offset:4096
	ds_read_b128 v[110:113], v90 offset:16384
	ds_read_b128 v[114:117], v90 offset:20480
	v_or_b32_e32 v85, v86, v87
	v_or_b32_e32 v87, v88, v87
	v_or_b32_e32 v86, v86, v118
	v_mfma_f32_32x32x16_bf16 v[18:33], v[2:5], v[14:17], 0
	v_or_b32_e32 v88, v88, v118
	s_mov_b32 m0, s47
	v_mfma_f32_32x32x16_bf16 v[34:49], v[6:9], v[10:13], 0
	v_mfma_f32_32x32x16_bf16 v[2:17], v[6:9], v[14:17], 0
	s_waitcnt lgkmcnt(1)
	v_mfma_f32_32x32x16_bf16 v[50:65], v[102:105], v[110:113], v[50:65]
	s_waitcnt lgkmcnt(0)
	v_mfma_f32_32x32x16_bf16 v[18:33], v[102:105], v[114:117], v[18:33]
	v_mfma_f32_32x32x16_bf16 v[34:49], v[106:109], v[110:113], v[34:49]
	v_mfma_f32_32x32x16_bf16 v[2:17], v[106:109], v[114:117], v[2:17]
	ds_read_b128 v[102:105], v85
	ds_read_b128 v[106:109], v85 offset:4096
	ds_read_b128 v[110:113], v87 offset:16384
	ds_read_b128 v[114:117], v87 offset:20480
	s_waitcnt lgkmcnt(1)
	v_mfma_f32_32x32x16_bf16 v[50:65], v[102:105], v[110:113], v[50:65]
	s_waitcnt lgkmcnt(0)
	v_mfma_f32_32x32x16_bf16 v[18:33], v[102:105], v[114:117], v[18:33]
	v_mfma_f32_32x32x16_bf16 v[34:49], v[106:109], v[110:113], v[34:49]
	v_mfma_f32_32x32x16_bf16 v[2:17], v[106:109], v[114:117], v[2:17]
	ds_read_b128 v[102:105], v86
	ds_read_b128 v[106:109], v86 offset:4096
	ds_read_b128 v[110:113], v88 offset:16384
	ds_read_b128 v[114:117], v88 offset:20480
	s_waitcnt lgkmcnt(0)
	v_mfma_f32_32x32x16_bf16 v[50:65], v[102:105], v[110:113], v[50:65]
	v_mfma_f32_32x32x16_bf16 v[18:33], v[102:105], v[114:117], v[18:33]
	s_waitcnt vmcnt(0)
	s_barrier
; #define MFMA(a, b, c) __builtin_amdgcn_mfma_f32_32x32x16_bf16((a), (b), (c), 0, 0, 0)
; #define TIDX opaque_tid()
; template <int AI, int BI>
; DI void gemm_stage(const u16* __restrict__ A, int lda, const u16* __restrict__ B, int ldb, char* buf, int tid) {
; #pragma unroll
;   for (int i = 0; i < 2 * AI; ++i) {
;     const int S = tid + NTHR * i, row = S >> 3, c = (S & 7) ^ ((row >> 1) & 7);
;     __builtin_amdgcn_global_load_lds((const unsigned*)(A + (size_t)row * lda + c * 8), (__attribute__((address_space(3))) unsigned*)(buf + S * 16), 16, 0, 0);
;   }
; #pragma unroll
;   for (int i = 0; i < 2 * BI; ++i) {
;     const int S = tid + NTHR * i, row = S >> 3, c = (S & 7) ^ ((row >> 1) & 7);
;     __builtin_amdgcn_global_load_lds((const unsigned*)(B + (size_t)row * ldb + c * 8), (__attribute__((address_space(3))) unsigned*)(buf + 16384 + S * 16), 16, 0, 0);
;   }
; }
; template <int AI, int BI>
; DI void gemm_tile(const u16* __restrict__ A, int lda, const u16* __restrict__ B, int ldb, int nk, bool swap,
;                   f32x16 (&acc)[AI][BI], char* lds) {
;   const int tid = TIDX, lane = tid & 63, wid = tid >> 6;
;   gemm_stage<AI, BI>(A, lda, B, ldb, lds, tid);
;   asm volatile("s_waitcnt vmcnt(0)" ::: "memory");
;   __syncthreads();
;   const int wa = wid >> 1, wb = wid & 1, r = lane & 31, h = lane >> 5, sw = (r >> 1) & 7;
;   const int offA = (swap ? 16384 : 0) + (wa * 32 * AI + r) * 128;
;   const int offB = (swap ? 0 : 16384) + (wb * 32 * BI + r) * 128;
;   for (int kt = 0; kt < nk; ++kt) {
;     const char* cur = lds + (kt & 1) * 32768;
;     if (kt + 1 < nk) gemm_stage<AI, BI>(A + (kt + 1) * 64, lda, B + (kt + 1) * 64, ldb, lds + ((kt + 1) & 1) * 32768, tid);
; #pragma unroll
;     for (int ks = 0; ks < 4; ++ks) {
;       const int co = ((ks * 2 + h) ^ sw) << 4;
;       s16x8 fa[AI], fb[BI];
; #pragma unroll
;       for (int i = 0; i < AI; ++i) fa[i] = *(const s16x8*)(cur + offA + i * 4096 + co);
; #pragma unroll
;       for (int i = 0; i < BI; ++i) fb[i] = *(const s16x8*)(cur + offB + i * 4096 + co);
; #pragma unroll
;       for (int i = 0; i < AI; ++i)
; #pragma unroll
;         for (int j = 0; j < BI; ++j) acc[i][j] = MFMA(fa[i], fb[j], acc[i][j]);
;     }
;     asm volatile("s_waitcnt vmcnt(0)" ::: "memory");
;     __syncthreads();
;   }
	v_lshl_add_u64 v[102:103], v[66:67], 0, s[4:5]
	global_load_lds_dwordx4 v[102:103], off
	v_lshl_add_u64 v[102:103], v[68:69], 0, s[4:5]
	s_mov_b32 m0, s52
	s_nop 0
	global_load_lds_dwordx4 v[102:103], off
	v_lshl_add_u64 v[102:103], v[70:71], 0, s[4:5]
	s_mov_b32 m0, s55
	v_mfma_f32_32x32x16_bf16 v[34:49], v[106:109], v[110:113], v[34:49]
	global_load_lds_dwordx4 v[102:103], off
	v_lshl_add_u64 v[102:103], v[72:73], 0, s[4:5]
	s_mov_b32 m0, s56
	s_nop 0
	global_load_lds_dwordx4 v[102:103], off
	v_lshl_add_u64 v[102:103], v[74:75], 0, s[4:5]
	s_mov_b32 m0, s36
	v_mfma_f32_32x32x16_bf16 v[2:17], v[106:109], v[114:117], v[2:17]
	global_load_lds_dwordx4 v[102:103], off
	v_lshl_add_u64 v[102:103], v[76:77], 0, s[4:5]
	s_mov_b32 m0, s37
	s_nop 0
	global_load_lds_dwordx4 v[102:103], off
	v_lshl_add_u64 v[102:103], v[78:79], 0, s[4:5]
	s_mov_b32 m0, s40
	s_nop 0
	global_load_lds_dwordx4 v[102:103], off
	v_lshl_add_u64 v[102:103], v[80:81], 0, s[4:5]
	s_mov_b32 m0, s41
	s_nop 0
	global_load_lds_dwordx4 v[102:103], off
	ds_read_b128 v[102:105], v0 offset:32768
	ds_read_b128 v[106:109], v0 offset:36864
	ds_read_b128 v[110:113], v84 offset:49152
	ds_read_b128 v[114:117], v84 offset:53248
	s_waitcnt lgkmcnt(0)
	v_mfma_f32_32x32x16_bf16 v[50:65], v[102:105], v[110:113], v[50:65]
	s_mov_b32 m0, s46
	v_mfma_f32_32x32x16_bf16 v[18:33], v[102:105], v[114:117], v[18:33]
	v_mfma_f32_32x32x16_bf16 v[34:49], v[106:109], v[110:113], v[34:49]
	v_mfma_f32_32x32x16_bf16 v[2:17], v[106:109], v[114:117], v[2:17]
	ds_read_b128 v[102:105], v89 offset:32768
	ds_read_b128 v[106:109], v89 offset:36864
	ds_read_b128 v[110:113], v90 offset:49152
	ds_read_b128 v[114:117], v90 offset:53248
	s_waitcnt lgkmcnt(1)
	v_mfma_f32_32x32x16_bf16 v[50:65], v[102:105], v[110:113], v[50:65]
	s_waitcnt lgkmcnt(0)
	v_mfma_f32_32x32x16_bf16 v[18:33], v[102:105], v[114:117], v[18:33]
	v_mfma_f32_32x32x16_bf16 v[34:49], v[106:109], v[110:113], v[34:49]
	v_mfma_f32_32x32x16_bf16 v[2:17], v[106:109], v[114:117], v[2:17]
	ds_read_b128 v[102:105], v85 offset:32768
	ds_read_b128 v[106:109], v85 offset:36864
	ds_read_b128 v[110:113], v87 offset:49152
	ds_read_b128 v[114:117], v87 offset:53248
	s_waitcnt lgkmcnt(1)
	v_mfma_f32_32x32x16_bf16 v[50:65], v[102:105], v[110:113], v[50:65]
	s_waitcnt lgkmcnt(0)
	v_mfma_f32_32x32x16_bf16 v[18:33], v[102:105], v[114:117], v[18:33]
	v_mfma_f32_32x32x16_bf16 v[34:49], v[106:109], v[110:113], v[34:49]
	v_mfma_f32_32x32x16_bf16 v[2:17], v[106:109], v[114:117], v[2:17]
	ds_read_b128 v[102:105], v86 offset:32768
	ds_read_b128 v[106:109], v86 offset:36864
	ds_read_b128 v[110:113], v88 offset:49152
	ds_read_b128 v[114:117], v88 offset:53248
	s_waitcnt lgkmcnt(0)
	v_mfma_f32_32x32x16_bf16 v[50:65], v[102:105], v[110:113], v[50:65]
	v_mfma_f32_32x32x16_bf16 v[18:33], v[102:105], v[114:117], v[18:33]
	s_waitcnt vmcnt(0)
	s_barrier
	v_lshl_add_u64 v[102:103], v[66:67], 0, s[70:71]
	global_load_lds_dwordx4 v[102:103], off
	v_lshl_add_u64 v[102:103], v[68:69], 0, s[70:71]
	s_mov_b32 m0, s48
	s_nop 0
	global_load_lds_dwordx4 v[102:103], off
	v_lshl_add_u64 v[102:103], v[70:71], 0, s[70:71]
	s_mov_b32 m0, s49
	v_mfma_f32_32x32x16_bf16 v[34:49], v[106:109], v[110:113], v[34:49]
	global_load_lds_dwordx4 v[102:103], off
	v_lshl_add_u64 v[102:103], v[72:73], 0, s[70:71]
	s_mov_b32 m0, s50
	s_nop 0
	global_load_lds_dwordx4 v[102:103], off
	v_lshl_add_u64 v[102:103], v[74:75], 0, s[70:71]
	s_mov_b32 m0, s51
	v_mfma_f32_32x32x16_bf16 v[2:17], v[106:109], v[114:117], v[2:17]
	global_load_lds_dwordx4 v[102:103], off
	v_lshl_add_u64 v[102:103], v[76:77], 0, s[70:71]
	s_mov_b32 m0, s53
	s_nop 0
	global_load_lds_dwordx4 v[102:103], off
	v_lshl_add_u64 v[102:103], v[78:79], 0, s[70:71]
	s_mov_b32 m0, s54
	s_nop 0
	global_load_lds_dwordx4 v[102:103], off
	v_lshl_add_u64 v[102:103], v[80:81], 0, s[70:71]
	s_mov_b32 m0, s11
	s_nop 0
	global_load_lds_dwordx4 v[102:103], off
	ds_read_b128 v[102:105], v0
	ds_read_b128 v[106:109], v0 offset:4096
	ds_read_b128 v[110:113], v84 offset:16384
	ds_read_b128 v[114:117], v84 offset:20480
	s_waitcnt lgkmcnt(0)
	v_mfma_f32_32x32x16_bf16 v[50:65], v[102:105], v[110:113], v[50:65]
	s_mov_b32 m0, s47
	v_mfma_f32_32x32x16_bf16 v[18:33], v[102:105], v[114:117], v[18:33]
	v_mfma_f32_32x32x16_bf16 v[34:49], v[106:109], v[110:113], v[34:49]
	v_mfma_f32_32x32x16_bf16 v[2:17], v[106:109], v[114:117], v[2:17]
	ds_read_b128 v[102:105], v89
	ds_read_b128 v[106:109], v89 offset:4096
	ds_read_b128 v[110:113], v90 offset:16384
	ds_read_b128 v[114:117], v90 offset:20480
	s_waitcnt lgkmcnt(1)
	v_mfma_f32_32x32x16_bf16 v[50:65], v[102:105], v[110:113], v[50:65]
	s_waitcnt lgkmcnt(0)
	v_mfma_f32_32x32x16_bf16 v[18:33], v[102:105], v[114:117], v[18:33]
	v_mfma_f32_32x32x16_bf16 v[34:49], v[106:109], v[110:113], v[34:49]
	v_mfma_f32_32x32x16_bf16 v[2:17], v[106:109], v[114:117], v[2:17]
	ds_read_b128 v[102:105], v85
	ds_read_b128 v[106:109], v85 offset:4096
	ds_read_b128 v[110:113], v87 offset:16384
	ds_read_b128 v[114:117], v87 offset:20480
	s_waitcnt lgkmcnt(1)
	v_mfma_f32_32x32x16_bf16 v[50:65], v[102:105], v[110:113], v[50:65]
	s_waitcnt lgkmcnt(0)
	v_mfma_f32_32x32x16_bf16 v[18:33], v[102:105], v[114:117], v[18:33]
	v_mfma_f32_32x32x16_bf16 v[34:49], v[106:109], v[110:113], v[34:49]
	v_mfma_f32_32x32x16_bf16 v[2:17], v[106:109], v[114:117], v[2:17]
	ds_read_b128 v[102:105], v86
	ds_read_b128 v[106:109], v86 offset:4096
	ds_read_b128 v[110:113], v88 offset:16384
	ds_read_b128 v[114:117], v88 offset:20480
	s_waitcnt lgkmcnt(0)
	v_mfma_f32_32x32x16_bf16 v[50:65], v[102:105], v[110:113], v[50:65]
	v_mfma_f32_32x32x16_bf16 v[18:33], v[102:105], v[114:117], v[18:33]
	s_waitcnt vmcnt(0)
	s_barrier
; #define MFMA(a, b, c) __builtin_amdgcn_mfma_f32_32x32x16_bf16((a), (b), (c), 0, 0, 0)
; #define TIDX opaque_tid()
; template <int AI, int BI>
; DI void gemm_stage(const u16* __restrict__ A, int lda, const u16* __restrict__ B, int ldb, char* buf, int tid) {
; #pragma unroll
;   for (int i = 0; i < 2 * AI; ++i) {
;     const int S = tid + NTHR * i, row = S >> 3, c = (S & 7) ^ ((row >> 1) & 7);
;     __builtin_amdgcn_global_load_lds((const unsigned*)(A + (size_t)row * lda + c * 8), (__attribute__((address_space(3))) unsigned*)(buf + S * 16), 16, 0, 0);
;   }
; #pragma unroll
;   for (int i = 0; i < 2 * BI; ++i) {
;     const int S = tid + NTHR * i, row = S >> 3, c = (S & 7) ^ ((row >> 1) & 7);
;     __builtin_amdgcn_global_load_lds((const unsigned*)(B + (size_t)row * ldb + c * 8), (__attribute__((address_space(3))) unsigned*)(buf + 16384 + S * 16), 16, 0, 0);
;   }
; }
; template <int AI, int BI>
; DI void gemm_tile(const u16* __restrict__ A, int lda, const u16* __restrict__ B, int ldb, int nk, bool swap,
;                   f32x16 (&acc)[AI][BI], char* lds) {
;   const int tid = TIDX, lane = tid & 63, wid = tid >> 6;
;   gemm_stage<AI, BI>(A, lda, B, ldb, lds, tid);
;   asm volatile("s_waitcnt vmcnt(0)" ::: "memory");
;   __syncthreads();
;   const int wa = wid >> 1, wb = wid & 1, r = lane & 31, h = lane >> 5, sw = (r >> 1) & 7;
;   const int offA = (swap ? 16384 : 0) + (wa * 32 * AI + r) * 128;
;   const int offB = (swap ? 0 : 16384) + (wb * 32 * BI + r) * 128;
;   for (int kt = 0; kt < nk; ++kt) {
;     const char* cur = lds + (kt & 1) * 32768;
;     if (kt + 1 < nk) gemm_stage<AI, BI>(A + (kt + 1) * 64, lda, B + (kt + 1) * 64, ldb, lds + ((kt + 1) & 1) * 32768, tid);
; #pragma unroll
;     for (int ks = 0; ks < 4; ++ks) {
;       const int co = ((ks * 2 + h) ^ sw) << 4;
;       s16x8 fa[AI], fb[BI];
; #pragma unroll
;       for (int i = 0; i < AI; ++i) fa[i] = *(const s16x8*)(cur + offA + i * 4096 + co);
; #pragma unroll
;       for (int i = 0; i < BI; ++i) fb[i] = *(const s16x8*)(cur + offB + i * 4096 + co);
; #pragma unroll
;       for (int i = 0; i < AI; ++i)
; #pragma unroll
;         for (int j = 0; j < BI; ++j) acc[i][j] = MFMA(fa[i], fb[j], acc[i][j]);
;     }
;     asm volatile("s_waitcnt vmcnt(0)" ::: "memory");
;     __syncthreads();
;   }
	v_lshl_add_u64 v[102:103], v[66:67], 0, s[66:67]
	global_load_lds_dwordx4 v[102:103], off
	v_lshl_add_u64 v[102:103], v[68:69], 0, s[66:67]
	s_mov_b32 m0, s52
	s_nop 0
	global_load_lds_dwordx4 v[102:103], off
	v_lshl_add_u64 v[102:103], v[70:71], 0, s[66:67]
	s_mov_b32 m0, s55
	v_mfma_f32_32x32x16_bf16 v[34:49], v[106:109], v[110:113], v[34:49]
	global_load_lds_dwordx4 v[102:103], off
	v_lshl_add_u64 v[102:103], v[72:73], 0, s[66:67]
	s_mov_b32 m0, s56
	s_nop 0
	global_load_lds_dwordx4 v[102:103], off
	v_lshl_add_u64 v[102:103], v[74:75], 0, s[66:67]
	s_mov_b32 m0, s36
	v_mfma_f32_32x32x16_bf16 v[2:17], v[106:109], v[114:117], v[2:17]
	global_load_lds_dwordx4 v[102:103], off
	v_lshl_add_u64 v[102:103], v[76:77], 0, s[66:67]
	s_mov_b32 m0, s37
	s_nop 0
	global_load_lds_dwordx4 v[102:103], off
	v_lshl_add_u64 v[102:103], v[78:79], 0, s[66:67]
	s_mov_b32 m0, s40
	s_nop 0
	global_load_lds_dwordx4 v[102:103], off
	v_lshl_add_u64 v[102:103], v[80:81], 0, s[66:67]
	s_mov_b32 m0, s41
	s_nop 0
	global_load_lds_dwordx4 v[102:103], off
	ds_read_b128 v[102:105], v0 offset:32768
	ds_read_b128 v[106:109], v0 offset:36864
	ds_read_b128 v[110:113], v84 offset:49152
	ds_read_b128 v[114:117], v84 offset:53248
	s_waitcnt lgkmcnt(0)
	v_mfma_f32_32x32x16_bf16 v[50:65], v[102:105], v[110:113], v[50:65]
	s_mov_b32 m0, s46
	v_mfma_f32_32x32x16_bf16 v[18:33], v[102:105], v[114:117], v[18:33]
	v_mfma_f32_32x32x16_bf16 v[34:49], v[106:109], v[110:113], v[34:49]
	v_mfma_f32_32x32x16_bf16 v[2:17], v[106:109], v[114:117], v[2:17]
	ds_read_b128 v[102:105], v89 offset:32768
	ds_read_b128 v[106:109], v89 offset:36864
	ds_read_b128 v[110:113], v90 offset:49152
	ds_read_b128 v[114:117], v90 offset:53248
	s_waitcnt lgkmcnt(1)
	v_mfma_f32_32x32x16_bf16 v[50:65], v[102:105], v[110:113], v[50:65]
	s_waitcnt lgkmcnt(0)
	v_mfma_f32_32x32x16_bf16 v[18:33], v[102:105], v[114:117], v[18:33]
	v_mfma_f32_32x32x16_bf16 v[34:49], v[106:109], v[110:113], v[34:49]
	v_mfma_f32_32x32x16_bf16 v[2:17], v[106:109], v[114:117], v[2:17]
	ds_read_b128 v[102:105], v85 offset:32768
	ds_read_b128 v[106:109], v85 offset:36864
	ds_read_b128 v[110:113], v87 offset:49152
	ds_read_b128 v[114:117], v87 offset:53248
	s_waitcnt lgkmcnt(1)
	v_mfma_f32_32x32x16_bf16 v[50:65], v[102:105], v[110:113], v[50:65]
	s_waitcnt lgkmcnt(0)
	v_mfma_f32_32x32x16_bf16 v[18:33], v[102:105], v[114:117], v[18:33]
	v_mfma_f32_32x32x16_bf16 v[34:49], v[106:109], v[110:113], v[34:49]
	v_mfma_f32_32x32x16_bf16 v[2:17], v[106:109], v[114:117], v[2:17]
	ds_read_b128 v[102:105], v86 offset:32768
	ds_read_b128 v[106:109], v86 offset:36864
	ds_read_b128 v[110:113], v88 offset:49152
	ds_read_b128 v[114:117], v88 offset:53248
	s_waitcnt lgkmcnt(0)
	v_mfma_f32_32x32x16_bf16 v[50:65], v[102:105], v[110:113], v[50:65]
	v_mfma_f32_32x32x16_bf16 v[18:33], v[102:105], v[114:117], v[18:33]
	s_waitcnt vmcnt(0)
	s_barrier
	v_lshl_add_u64 v[102:103], v[66:67], 0, s[72:73]
	global_load_lds_dwordx4 v[102:103], off
	v_lshl_add_u64 v[102:103], v[68:69], 0, s[72:73]
	s_mov_b32 m0, s48
	s_nop 0
	global_load_lds_dwordx4 v[102:103], off
	v_lshl_add_u64 v[102:103], v[70:71], 0, s[72:73]
	s_mov_b32 m0, s49
	v_mfma_f32_32x32x16_bf16 v[34:49], v[106:109], v[110:113], v[34:49]
	global_load_lds_dwordx4 v[102:103], off
	v_lshl_add_u64 v[102:103], v[72:73], 0, s[72:73]
	s_mov_b32 m0, s50
	s_nop 0
	global_load_lds_dwordx4 v[102:103], off
	v_lshl_add_u64 v[102:103], v[74:75], 0, s[72:73]
	s_mov_b32 m0, s51
	v_mfma_f32_32x32x16_bf16 v[2:17], v[106:109], v[114:117], v[2:17]
	global_load_lds_dwordx4 v[102:103], off
	v_lshl_add_u64 v[102:103], v[76:77], 0, s[72:73]
	s_mov_b32 m0, s53
	s_nop 0
	global_load_lds_dwordx4 v[102:103], off
	v_lshl_add_u64 v[102:103], v[78:79], 0, s[72:73]
	s_mov_b32 m0, s54
	s_nop 0
	global_load_lds_dwordx4 v[102:103], off
	v_lshl_add_u64 v[102:103], v[80:81], 0, s[72:73]
	s_mov_b32 m0, s11
	s_nop 0
	global_load_lds_dwordx4 v[102:103], off
	ds_read_b128 v[102:105], v0
	ds_read_b128 v[106:109], v0 offset:4096
	ds_read_b128 v[110:113], v84 offset:16384
	ds_read_b128 v[114:117], v84 offset:20480
	s_waitcnt lgkmcnt(0)
	v_mfma_f32_32x32x16_bf16 v[50:65], v[102:105], v[110:113], v[50:65]
	s_mov_b32 m0, s47
	v_readfirstlane_b32 s47, v99
	v_mfma_f32_32x32x16_bf16 v[18:33], v[102:105], v[114:117], v[18:33]
	v_mfma_f32_32x32x16_bf16 v[34:49], v[106:109], v[110:113], v[34:49]
	v_mfma_f32_32x32x16_bf16 v[2:17], v[106:109], v[114:117], v[2:17]
	ds_read_b128 v[102:105], v89
	ds_read_b128 v[106:109], v89 offset:4096
	ds_read_b128 v[110:113], v90 offset:16384
	ds_read_b128 v[114:117], v90 offset:20480
	s_waitcnt lgkmcnt(1)
	v_mfma_f32_32x32x16_bf16 v[50:65], v[102:105], v[110:113], v[50:65]
	s_waitcnt lgkmcnt(0)
	v_mfma_f32_32x32x16_bf16 v[18:33], v[102:105], v[114:117], v[18:33]
	v_mfma_f32_32x32x16_bf16 v[34:49], v[106:109], v[110:113], v[34:49]
	v_mfma_f32_32x32x16_bf16 v[2:17], v[106:109], v[114:117], v[2:17]
	ds_read_b128 v[102:105], v85
	ds_read_b128 v[106:109], v85 offset:4096
	ds_read_b128 v[110:113], v87 offset:16384
	ds_read_b128 v[114:117], v87 offset:20480
	s_waitcnt lgkmcnt(1)
	v_mfma_f32_32x32x16_bf16 v[50:65], v[102:105], v[110:113], v[50:65]
	s_waitcnt lgkmcnt(0)
	v_mfma_f32_32x32x16_bf16 v[18:33], v[102:105], v[114:117], v[18:33]
	v_mfma_f32_32x32x16_bf16 v[34:49], v[106:109], v[110:113], v[34:49]
	v_mfma_f32_32x32x16_bf16 v[2:17], v[106:109], v[114:117], v[2:17]
	ds_read_b128 v[102:105], v86
	ds_read_b128 v[106:109], v86 offset:4096
	ds_read_b128 v[110:113], v88 offset:16384
	ds_read_b128 v[114:117], v88 offset:20480
	s_waitcnt lgkmcnt(0)
	v_mfma_f32_32x32x16_bf16 v[50:65], v[102:105], v[110:113], v[50:65]
	v_mfma_f32_32x32x16_bf16 v[18:33], v[102:105], v[114:117], v[18:33]
	s_waitcnt vmcnt(0)
	s_barrier
; #define MFMA(a, b, c) __builtin_amdgcn_mfma_f32_32x32x16_bf16((a), (b), (c), 0, 0, 0)
; #define TIDX opaque_tid()
; template <int AI, int BI>
; DI void gemm_stage(const u16* __restrict__ A, int lda, const u16* __restrict__ B, int ldb, char* buf, int tid) {
; #pragma unroll
;   for (int i = 0; i < 2 * AI; ++i) {
;     const int S = tid + NTHR * i, row = S >> 3, c = (S & 7) ^ ((row >> 1) & 7);
;     __builtin_amdgcn_global_load_lds((const unsigned*)(A + (size_t)row * lda + c * 8), (__attribute__((address_space(3))) unsigned*)(buf + S * 16), 16, 0, 0);
;   }
; #pragma unroll
;   for (int i = 0; i < 2 * BI; ++i) {
;     const int S = tid + NTHR * i, row = S >> 3, c = (S & 7) ^ ((row >> 1) & 7);
;     __builtin_amdgcn_global_load_lds((const unsigned*)(B + (size_t)row * ldb + c * 8), (__attribute__((address_space(3))) unsigned*)(buf + 16384 + S * 16), 16, 0, 0);
;   }
; }
; template <int AI, int BI>
; DI void gemm_tile(const u16* __restrict__ A, int lda, const u16* __restrict__ B, int ldb, int nk, bool swap,
;                   f32x16 (&acc)[AI][BI], char* lds) {
;   const int tid = TIDX, lane = tid & 63, wid = tid >> 6;
;   gemm_stage<AI, BI>(A, lda, B, ldb, lds, tid);
;   asm volatile("s_waitcnt vmcnt(0)" ::: "memory");
;   __syncthreads();
;   const int wa = wid >> 1, wb = wid & 1, r = lane & 31, h = lane >> 5, sw = (r >> 1) & 7;
;   const int offA = (swap ? 16384 : 0) + (wa * 32 * AI + r) * 128;
;   const int offB = (swap ? 0 : 16384) + (wb * 32 * BI + r) * 128;
;   for (int kt = 0; kt < nk; ++kt) {
;     const char* cur = lds + (kt & 1) * 32768;
;     if (kt + 1 < nk) gemm_stage<AI, BI>(A + (kt + 1) * 64, lda, B + (kt + 1) * 64, ldb, lds + ((kt + 1) & 1) * 32768, tid);
; #pragma unroll
;     for (int ks = 0; ks < 4; ++ks) {
;       const int co = ((ks * 2 + h) ^ sw) << 4;
;       s16x8 fa[AI], fb[BI];
; #pragma unroll
;       for (int i = 0; i < AI; ++i) fa[i] = *(const s16x8*)(cur + offA + i * 4096 + co);
; #pragma unroll
;       for (int i = 0; i < BI; ++i) fb[i] = *(const s16x8*)(cur + offB + i * 4096 + co);
; #pragma unroll
;       for (int i = 0; i < AI; ++i)
; #pragma unroll
;         for (int j = 0; j < BI; ++j) acc[i][j] = MFMA(fa[i], fb[j], acc[i][j]);
;     }
;     asm volatile("s_waitcnt vmcnt(0)" ::: "memory");
;     __syncthreads();
;   }
	v_lshl_add_u64 v[102:103], v[66:67], 0, s[74:75]
	global_load_lds_dwordx4 v[102:103], off
	v_lshl_add_u64 v[102:103], v[68:69], 0, s[74:75]
	s_mov_b32 m0, s52
	v_readfirstlane_b32 s52, v93
	global_load_lds_dwordx4 v[102:103], off
	v_lshl_add_u64 v[102:103], v[70:71], 0, s[74:75]
	s_mov_b32 m0, s55
	v_mfma_f32_32x32x16_bf16 v[34:49], v[106:109], v[110:113], v[34:49]
	global_load_lds_dwordx4 v[102:103], off
	v_lshl_add_u64 v[102:103], v[72:73], 0, s[74:75]
	s_mov_b32 m0, s56
	v_readfirstlane_b32 s55, v97
	global_load_lds_dwordx4 v[102:103], off
	v_lshl_add_u64 v[102:103], v[74:75], 0, s[74:75]
	s_mov_b32 m0, s36
	v_mfma_f32_32x32x16_bf16 v[2:17], v[106:109], v[114:117], v[2:17]
	global_load_lds_dwordx4 v[102:103], off
	v_lshl_add_u64 v[102:103], v[76:77], 0, s[74:75]
	s_mov_b32 m0, s37
	v_readfirstlane_b32 s56, v98
	global_load_lds_dwordx4 v[102:103], off
	v_lshl_add_u64 v[102:103], v[78:79], 0, s[74:75]
	s_mov_b32 m0, s40
	s_nop 0
	global_load_lds_dwordx4 v[102:103], off
	v_lshl_add_u64 v[102:103], v[80:81], 0, s[74:75]
	s_mov_b32 m0, s41
	s_nop 0
	global_load_lds_dwordx4 v[102:103], off
	ds_read_b128 v[102:105], v0 offset:32768
	ds_read_b128 v[106:109], v0 offset:36864
	ds_read_b128 v[110:113], v84 offset:49152
	ds_read_b128 v[114:117], v84 offset:53248
	s_waitcnt lgkmcnt(0)
	v_mfma_f32_32x32x16_bf16 v[50:65], v[102:105], v[110:113], v[50:65]
	s_mov_b32 m0, s46
	v_readfirstlane_b32 s46, v96
	v_mfma_f32_32x32x16_bf16 v[18:33], v[102:105], v[114:117], v[18:33]
	v_mfma_f32_32x32x16_bf16 v[34:49], v[106:109], v[110:113], v[34:49]
	v_mfma_f32_32x32x16_bf16 v[2:17], v[106:109], v[114:117], v[2:17]
	ds_read_b128 v[102:105], v89 offset:32768
	ds_read_b128 v[106:109], v89 offset:36864
	ds_read_b128 v[110:113], v90 offset:49152
	ds_read_b128 v[114:117], v90 offset:53248
	s_waitcnt lgkmcnt(1)
	v_mfma_f32_32x32x16_bf16 v[50:65], v[102:105], v[110:113], v[50:65]
	s_waitcnt lgkmcnt(0)
	v_mfma_f32_32x32x16_bf16 v[18:33], v[102:105], v[114:117], v[18:33]
	v_mfma_f32_32x32x16_bf16 v[34:49], v[106:109], v[110:113], v[34:49]
	v_mfma_f32_32x32x16_bf16 v[2:17], v[106:109], v[114:117], v[2:17]
	ds_read_b128 v[102:105], v85 offset:32768
	ds_read_b128 v[106:109], v85 offset:36864
	ds_read_b128 v[110:113], v87 offset:49152
	ds_read_b128 v[114:117], v87 offset:53248
	s_waitcnt lgkmcnt(1)
	v_mfma_f32_32x32x16_bf16 v[50:65], v[102:105], v[110:113], v[50:65]
	s_waitcnt lgkmcnt(0)
	v_mfma_f32_32x32x16_bf16 v[18:33], v[102:105], v[114:117], v[18:33]
	v_mfma_f32_32x32x16_bf16 v[34:49], v[106:109], v[110:113], v[34:49]
	v_mfma_f32_32x32x16_bf16 v[2:17], v[106:109], v[114:117], v[2:17]
	ds_read_b128 v[102:105], v86 offset:32768
	ds_read_b128 v[106:109], v86 offset:36864
	ds_read_b128 v[110:113], v88 offset:49152
	ds_read_b128 v[114:117], v88 offset:53248
	s_waitcnt lgkmcnt(0)
	v_mfma_f32_32x32x16_bf16 v[50:65], v[102:105], v[110:113], v[50:65]
	v_mfma_f32_32x32x16_bf16 v[18:33], v[102:105], v[114:117], v[18:33]
	s_waitcnt vmcnt(0)
	s_barrier
	v_lshl_add_u64 v[102:103], v[66:67], 0, s[76:77]
	global_load_lds_dwordx4 v[102:103], off
	v_lshl_add_u64 v[102:103], v[68:69], 0, s[76:77]
	s_mov_b32 m0, s48
	v_readfirstlane_b32 s48, v100
	global_load_lds_dwordx4 v[102:103], off
	v_lshl_add_u64 v[102:103], v[70:71], 0, s[76:77]
	s_mov_b32 m0, s49
	v_mfma_f32_32x32x16_bf16 v[34:49], v[106:109], v[110:113], v[34:49]
	global_load_lds_dwordx4 v[102:103], off
	v_lshl_add_u64 v[102:103], v[72:73], 0, s[76:77]
	s_mov_b32 m0, s50
	v_readfirstlane_b32 s49, v101
	global_load_lds_dwordx4 v[102:103], off
	v_lshl_add_u64 v[102:103], v[74:75], 0, s[76:77]
	s_mov_b32 m0, s51
	v_mfma_f32_32x32x16_bf16 v[2:17], v[106:109], v[114:117], v[2:17]
	global_load_lds_dwordx4 v[102:103], off
	v_lshl_add_u64 v[102:103], v[76:77], 0, s[76:77]
	s_mov_b32 m0, s53
	v_lshl_add_u64 v[100:101], v[74:75], 0, s[80:81]
	global_load_lds_dwordx4 v[102:103], off
	v_lshl_add_u64 v[102:103], v[78:79], 0, s[76:77]
	s_mov_b32 m0, s54
	v_readfirstlane_b32 s50, v91
	global_load_lds_dwordx4 v[102:103], off
	v_lshl_add_u64 v[102:103], v[80:81], 0, s[76:77]
	s_mov_b32 m0, s11
	v_readfirstlane_b32 s51, v92
	global_load_lds_dwordx4 v[102:103], off
	ds_read_b128 v[102:105], v0
	ds_read_b128 v[106:109], v0 offset:4096
	ds_read_b128 v[110:113], v84 offset:16384
	ds_read_b128 v[114:117], v84 offset:20480
	s_waitcnt lgkmcnt(0)
	v_mfma_f32_32x32x16_bf16 v[50:65], v[102:105], v[110:113], v[50:65]
	s_mov_b32 m0, s46
	v_readfirstlane_b32 s53, v94
	v_lshl_add_u64 v[92:93], v[72:73], 0, s[82:83]
	v_readfirstlane_b32 s54, v95
	v_and_b32_e32 v91, 31, v82
	v_mfma_f32_32x32x16_bf16 v[18:33], v[102:105], v[114:117], v[18:33]
	v_mfma_f32_32x32x16_bf16 v[34:49], v[106:109], v[110:113], v[34:49]
	v_mfma_f32_32x32x16_bf16 v[2:17], v[106:109], v[114:117], v[2:17]
	ds_read_b128 v[102:105], v89
	ds_read_b128 v[106:109], v89 offset:4096
	ds_read_b128 v[110:113], v90 offset:16384
	ds_read_b128 v[114:117], v90 offset:20480
	s_waitcnt lgkmcnt(1)
	v_mfma_f32_32x32x16_bf16 v[50:65], v[102:105], v[110:113], v[50:65]
	s_waitcnt lgkmcnt(0)
	v_mfma_f32_32x32x16_bf16 v[18:33], v[102:105], v[114:117], v[18:33]
	v_mfma_f32_32x32x16_bf16 v[34:49], v[106:109], v[110:113], v[34:49]
	v_mfma_f32_32x32x16_bf16 v[2:17], v[106:109], v[114:117], v[2:17]
	ds_read_b128 v[102:105], v85
	ds_read_b128 v[106:109], v85 offset:4096
	ds_read_b128 v[110:113], v87 offset:16384
	ds_read_b128 v[114:117], v87 offset:20480
	s_waitcnt lgkmcnt(1)
	v_mfma_f32_32x32x16_bf16 v[50:65], v[102:105], v[110:113], v[50:65]
	s_waitcnt lgkmcnt(0)
	v_mfma_f32_32x32x16_bf16 v[18:33], v[102:105], v[114:117], v[18:33]
	v_mfma_f32_32x32x16_bf16 v[34:49], v[106:109], v[110:113], v[34:49]
	v_mfma_f32_32x32x16_bf16 v[2:17], v[106:109], v[114:117], v[2:17]
	ds_read_b128 v[102:105], v86
	ds_read_b128 v[106:109], v86 offset:4096
	ds_read_b128 v[110:113], v88 offset:16384
	ds_read_b128 v[114:117], v88 offset:20480
	s_waitcnt lgkmcnt(0)
	v_mfma_f32_32x32x16_bf16 v[50:65], v[102:105], v[110:113], v[50:65]
	v_mfma_f32_32x32x16_bf16 v[18:33], v[102:105], v[114:117], v[18:33]
	s_waitcnt vmcnt(0)
	s_barrier
; #define MFMA(a, b, c) __builtin_amdgcn_mfma_f32_32x32x16_bf16((a), (b), (c), 0, 0, 0)
; #define TIDX opaque_tid()
; template <int AI, int BI>
; DI void gemm_stage(const u16* __restrict__ A, int lda, const u16* __restrict__ B, int ldb, char* buf, int tid) {
; #pragma unroll
;   for (int i = 0; i < 2 * AI; ++i) {
;     const int S = tid + NTHR * i, row = S >> 3, c = (S & 7) ^ ((row >> 1) & 7);
;     __builtin_amdgcn_global_load_lds((const unsigned*)(A + (size_t)row * lda + c * 8), (__attribute__((address_space(3))) unsigned*)(buf + S * 16), 16, 0, 0);
;   }
; #pragma unroll
;   for (int i = 0; i < 2 * BI; ++i) {
;     const int S = tid + NTHR * i, row = S >> 3, c = (S & 7) ^ ((row >> 1) & 7);
;     __builtin_amdgcn_global_load_lds((const unsigned*)(B + (size_t)row * ldb + c * 8), (__attribute__((address_space(3))) unsigned*)(buf + 16384 + S * 16), 16, 0, 0);
;   }
; }
; template <int AI, int BI>
; DI void gemm_tile(const u16* __restrict__ A, int lda, const u16* __restrict__ B, int ldb, int nk, bool swap,
;                   f32x16 (&acc)[AI][BI], char* lds) {
;   const int tid = TIDX, lane = tid & 63, wid = tid >> 6;
;   gemm_stage<AI, BI>(A, lda, B, ldb, lds, tid);
;   asm volatile("s_waitcnt vmcnt(0)" ::: "memory");
;   __syncthreads();
;   const int wa = wid >> 1, wb = wid & 1, r = lane & 31, h = lane >> 5, sw = (r >> 1) & 7;
;   const int offA = (swap ? 16384 : 0) + (wa * 32 * AI + r) * 128;
;   const int offB = (swap ? 0 : 16384) + (wb * 32 * BI + r) * 128;
;   for (int kt = 0; kt < nk; ++kt) {
;     const char* cur = lds + (kt & 1) * 32768;
;     if (kt + 1 < nk) gemm_stage<AI, BI>(A + (kt + 1) * 64, lda, B + (kt + 1) * 64, ldb, lds + ((kt + 1) & 1) * 32768, tid);
; #pragma unroll
;     for (int ks = 0; ks < 4; ++ks) {
;       const int co = ((ks * 2 + h) ^ sw) << 4;
;       s16x8 fa[AI], fb[BI];
; #pragma unroll
;       for (int i = 0; i < AI; ++i) fa[i] = *(const s16x8*)(cur + offA + i * 4096 + co);
; #pragma unroll
;       for (int i = 0; i < BI; ++i) fb[i] = *(const s16x8*)(cur + offB + i * 4096 + co);
; #pragma unroll
;       for (int i = 0; i < AI; ++i)
; #pragma unroll
;         for (int j = 0; j < BI; ++j) acc[i][j] = MFMA(fa[i], fb[j], acc[i][j]);
;     }
;     asm volatile("s_waitcnt vmcnt(0)" ::: "memory");
;     __syncthreads();
;   }
	v_lshl_add_u64 v[102:103], v[66:67], 0, s[80:81]
	global_load_lds_dwordx4 v[102:103], off
	v_lshl_add_u64 v[102:103], v[68:69], 0, s[80:81]
	s_mov_b32 m0, s47
	s_nop 0
	global_load_lds_dwordx4 v[102:103], off
	v_lshl_add_u64 v[102:103], v[70:71], 0, s[80:81]
	s_mov_b32 m0, s48
	v_mfma_f32_32x32x16_bf16 v[34:49], v[106:109], v[110:113], v[34:49]
	global_load_lds_dwordx4 v[102:103], off
	v_lshl_add_u64 v[102:103], v[72:73], 0, s[80:81]
	s_mov_b32 m0, s49
	s_nop 0
	global_load_lds_dwordx4 v[102:103], off
	s_mov_b32 m0, s36
	v_mfma_f32_32x32x16_bf16 v[2:17], v[106:109], v[114:117], v[2:17]
	global_load_lds_dwordx4 v[100:101], off
	v_lshl_add_u64 v[100:101], v[76:77], 0, s[80:81]
	s_mov_b32 m0, s37
	s_nop 0
	global_load_lds_dwordx4 v[100:101], off
	v_lshl_add_u64 v[100:101], v[78:79], 0, s[80:81]
	s_mov_b32 m0, s40
	s_nop 0
	global_load_lds_dwordx4 v[100:101], off
	v_lshl_add_u64 v[100:101], v[80:81], 0, s[80:81]
	s_mov_b32 m0, s41
	s_nop 0
	global_load_lds_dwordx4 v[100:101], off
	ds_read_b128 v[100:103], v0 offset:32768
	ds_read_b128 v[104:107], v0 offset:36864
	ds_read_b128 v[108:111], v84 offset:49152
	ds_read_b128 v[112:115], v84 offset:53248
	s_waitcnt lgkmcnt(0)
	v_mfma_f32_32x32x16_bf16 v[50:65], v[100:103], v[108:111], v[50:65]
	s_mov_b32 m0, s50
	v_mfma_f32_32x32x16_bf16 v[18:33], v[100:103], v[112:115], v[18:33]
	v_mfma_f32_32x32x16_bf16 v[34:49], v[104:107], v[108:111], v[34:49]
	v_mfma_f32_32x32x16_bf16 v[2:17], v[104:107], v[112:115], v[2:17]
	ds_read_b128 v[100:103], v89 offset:32768
	ds_read_b128 v[104:107], v89 offset:36864
	ds_read_b128 v[108:111], v90 offset:49152
	ds_read_b128 v[112:115], v90 offset:53248
	s_waitcnt lgkmcnt(1)
	v_mfma_f32_32x32x16_bf16 v[50:65], v[100:103], v[108:111], v[50:65]
	s_waitcnt lgkmcnt(0)
	v_mfma_f32_32x32x16_bf16 v[18:33], v[100:103], v[112:115], v[18:33]
	v_mfma_f32_32x32x16_bf16 v[34:49], v[104:107], v[108:111], v[34:49]
	v_mfma_f32_32x32x16_bf16 v[2:17], v[104:107], v[112:115], v[2:17]
	ds_read_b128 v[100:103], v85 offset:32768
	ds_read_b128 v[104:107], v85 offset:36864
	ds_read_b128 v[108:111], v87 offset:49152
	ds_read_b128 v[112:115], v87 offset:53248
	s_waitcnt lgkmcnt(1)
	v_mfma_f32_32x32x16_bf16 v[50:65], v[100:103], v[108:111], v[50:65]
	s_waitcnt lgkmcnt(0)
	v_mfma_f32_32x32x16_bf16 v[18:33], v[100:103], v[112:115], v[18:33]
	v_mfma_f32_32x32x16_bf16 v[34:49], v[104:107], v[108:111], v[34:49]
	v_mfma_f32_32x32x16_bf16 v[2:17], v[104:107], v[112:115], v[2:17]
	ds_read_b128 v[100:103], v86 offset:32768
	ds_read_b128 v[104:107], v86 offset:36864
	ds_read_b128 v[108:111], v88 offset:49152
	ds_read_b128 v[112:115], v88 offset:53248
	s_waitcnt lgkmcnt(0)
	v_mfma_f32_32x32x16_bf16 v[50:65], v[100:103], v[108:111], v[50:65]
	v_mfma_f32_32x32x16_bf16 v[18:33], v[100:103], v[112:115], v[18:33]
	s_waitcnt vmcnt(0)
	s_barrier
	v_lshl_add_u64 v[100:101], v[66:67], 0, s[82:83]
	global_load_lds_dwordx4 v[100:101], off
	v_lshl_add_u64 v[100:101], v[68:69], 0, s[82:83]
	s_mov_b32 m0, s51
	s_nop 0
	global_load_lds_dwordx4 v[100:101], off
	v_lshl_add_u64 v[100:101], v[70:71], 0, s[82:83]
	s_mov_b32 m0, s52
	v_mfma_f32_32x32x16_bf16 v[34:49], v[104:107], v[108:111], v[34:49]
	global_load_lds_dwordx4 v[100:101], off
	s_mov_b32 m0, s53
	s_nop 0
	global_load_lds_dwordx4 v[92:93], off
	v_lshl_add_u64 v[92:93], v[74:75], 0, s[82:83]
	s_mov_b32 m0, s54
	v_mfma_f32_32x32x16_bf16 v[2:17], v[104:107], v[112:115], v[2:17]
	global_load_lds_dwordx4 v[92:93], off
	v_lshl_add_u64 v[92:93], v[76:77], 0, s[82:83]
	s_mov_b32 m0, s55
	s_nop 0
	global_load_lds_dwordx4 v[92:93], off
	v_lshl_add_u64 v[92:93], v[78:79], 0, s[82:83]
	s_mov_b32 m0, s56
	s_nop 0
	global_load_lds_dwordx4 v[92:93], off
	v_lshl_add_u64 v[92:93], v[80:81], 0, s[82:83]
	s_mov_b32 m0, s11
	s_nop 0
	global_load_lds_dwordx4 v[92:93], off
	ds_read_b128 v[92:95], v0
	ds_read_b128 v[96:99], v0 offset:4096
	ds_read_b128 v[100:103], v84 offset:16384
	ds_read_b128 v[104:107], v84 offset:20480
	s_waitcnt lgkmcnt(0)
	v_mfma_f32_32x32x16_bf16 v[50:65], v[92:95], v[100:103], v[50:65]
	s_mov_b32 m0, s46
	v_mfma_f32_32x32x16_bf16 v[18:33], v[92:95], v[104:107], v[18:33]
	v_mfma_f32_32x32x16_bf16 v[34:49], v[96:99], v[100:103], v[34:49]
	v_mfma_f32_32x32x16_bf16 v[2:17], v[96:99], v[104:107], v[2:17]
	ds_read_b128 v[92:95], v89
	ds_read_b128 v[96:99], v89 offset:4096
	ds_read_b128 v[100:103], v90 offset:16384
	ds_read_b128 v[104:107], v90 offset:20480
	s_waitcnt lgkmcnt(1)
	v_mfma_f32_32x32x16_bf16 v[50:65], v[92:95], v[100:103], v[50:65]
	s_waitcnt lgkmcnt(0)
	v_mfma_f32_32x32x16_bf16 v[18:33], v[92:95], v[104:107], v[18:33]
	v_mfma_f32_32x32x16_bf16 v[34:49], v[96:99], v[100:103], v[34:49]
	v_mfma_f32_32x32x16_bf16 v[2:17], v[96:99], v[104:107], v[2:17]
	ds_read_b128 v[92:95], v85
	ds_read_b128 v[96:99], v85 offset:4096
	ds_read_b128 v[100:103], v87 offset:16384
	ds_read_b128 v[104:107], v87 offset:20480
	s_waitcnt lgkmcnt(1)
	v_mfma_f32_32x32x16_bf16 v[50:65], v[92:95], v[100:103], v[50:65]
	s_waitcnt lgkmcnt(0)
	v_mfma_f32_32x32x16_bf16 v[18:33], v[92:95], v[104:107], v[18:33]
	v_mfma_f32_32x32x16_bf16 v[34:49], v[96:99], v[100:103], v[34:49]
	v_mfma_f32_32x32x16_bf16 v[2:17], v[96:99], v[104:107], v[2:17]
	ds_read_b128 v[92:95], v86
	ds_read_b128 v[96:99], v86 offset:4096
	ds_read_b128 v[100:103], v88 offset:16384
	ds_read_b128 v[104:107], v88 offset:20480
	s_waitcnt lgkmcnt(0)
	v_mfma_f32_32x32x16_bf16 v[50:65], v[92:95], v[100:103], v[50:65]
	v_mfma_f32_32x32x16_bf16 v[18:33], v[92:95], v[104:107], v[18:33]
	s_waitcnt vmcnt(0)
	s_barrier
; #define MFMA(a, b, c) __builtin_amdgcn_mfma_f32_32x32x16_bf16((a), (b), (c), 0, 0, 0)
; #define TIDX opaque_tid()
; template <int AI, int BI>
; DI void gemm_stage(const u16* __restrict__ A, int lda, const u16* __restrict__ B, int ldb, char* buf, int tid) {
; #pragma unroll
;   for (int i = 0; i < 2 * AI; ++i) {
;     const int S = tid + NTHR * i, row = S >> 3, c = (S & 7) ^ ((row >> 1) & 7);
;     __builtin_amdgcn_global_load_lds((const unsigned*)(A + (size_t)row * lda + c * 8), (__attribute__((address_space(3))) unsigned*)(buf + S * 16), 16, 0, 0);
;   }
; #pragma unroll
;   for (int i = 0; i < 2 * BI; ++i) {
;     const int S = tid + NTHR * i, row = S >> 3, c = (S & 7) ^ ((row >> 1) & 7);
;     __builtin_amdgcn_global_load_lds((const unsigned*)(B + (size_t)row * ldb + c * 8), (__attribute__((address_space(3))) unsigned*)(buf + 16384 + S * 16), 16, 0, 0);
;   }
; }
; template <int AI, int BI>
; DI void gemm_tile(const u16* __restrict__ A, int lda, const u16* __restrict__ B, int ldb, int nk, bool swap,
;                   f32x16 (&acc)[AI][BI], char* lds) {
;   const int tid = TIDX, lane = tid & 63, wid = tid >> 6;
;   gemm_stage<AI, BI>(A, lda, B, ldb, lds, tid);
;   asm volatile("s_waitcnt vmcnt(0)" ::: "memory");
;   __syncthreads();
;   const int wa = wid >> 1, wb = wid & 1, r = lane & 31, h = lane >> 5, sw = (r >> 1) & 7;
;   const int offA = (swap ? 16384 : 0) + (wa * 32 * AI + r) * 128;
;   const int offB = (swap ? 0 : 16384) + (wb * 32 * BI + r) * 128;
;   for (int kt = 0; kt < nk; ++kt) {
;     const char* cur = lds + (kt & 1) * 32768;
;     if (kt + 1 < nk) gemm_stage<AI, BI>(A + (kt + 1) * 64, lda, B + (kt + 1) * 64, ldb, lds + ((kt + 1) & 1) * 32768, tid);
; #pragma unroll
;     for (int ks = 0; ks < 4; ++ks) {
;       const int co = ((ks * 2 + h) ^ sw) << 4;
;       s16x8 fa[AI], fb[BI];
; #pragma unroll
;       for (int i = 0; i < AI; ++i) fa[i] = *(const s16x8*)(cur + offA + i * 4096 + co);
; #pragma unroll
;       for (int i = 0; i < BI; ++i) fb[i] = *(const s16x8*)(cur + offB + i * 4096 + co);
; #pragma unroll
;       for (int i = 0; i < AI; ++i)
; #pragma unroll
;         for (int j = 0; j < BI; ++j) acc[i][j] = MFMA(fa[i], fb[j], acc[i][j]);
;     }
;     asm volatile("s_waitcnt vmcnt(0)" ::: "memory");
;     __syncthreads();
;   }
	v_lshl_add_u64 v[92:93], v[66:67], 0, s[84:85]
	global_load_lds_dwordx4 v[92:93], off
	v_lshl_add_u64 v[92:93], v[68:69], 0, s[84:85]
	s_mov_b32 m0, s47
	s_nop 0
	global_load_lds_dwordx4 v[92:93], off
	v_lshl_add_u64 v[92:93], v[70:71], 0, s[84:85]
	s_mov_b32 m0, s48
	v_mfma_f32_32x32x16_bf16 v[34:49], v[96:99], v[100:103], v[34:49]
	global_load_lds_dwordx4 v[92:93], off
	v_lshl_add_u64 v[92:93], v[72:73], 0, s[84:85]
	s_mov_b32 m0, s49
	s_nop 0
	global_load_lds_dwordx4 v[92:93], off
	v_lshl_add_u64 v[92:93], v[74:75], 0, s[84:85]
	s_mov_b32 m0, s36
	v_mfma_f32_32x32x16_bf16 v[2:17], v[96:99], v[104:107], v[2:17]
	global_load_lds_dwordx4 v[92:93], off
	v_lshl_add_u64 v[92:93], v[76:77], 0, s[84:85]
	s_mov_b32 m0, s37
	s_nop 0
	global_load_lds_dwordx4 v[92:93], off
	v_lshl_add_u64 v[92:93], v[78:79], 0, s[84:85]
	s_mov_b32 m0, s40
	s_nop 0
	global_load_lds_dwordx4 v[92:93], off
	v_lshl_add_u64 v[92:93], v[80:81], 0, s[84:85]
	s_mov_b32 m0, s41
	s_nop 0
	global_load_lds_dwordx4 v[92:93], off
	ds_read_b128 v[92:95], v0 offset:32768
	ds_read_b128 v[96:99], v0 offset:36864
	ds_read_b128 v[100:103], v84 offset:49152
	ds_read_b128 v[104:107], v84 offset:53248
	s_waitcnt lgkmcnt(0)
	v_mfma_f32_32x32x16_bf16 v[50:65], v[92:95], v[100:103], v[50:65]
	s_mov_b32 m0, s50
	v_mfma_f32_32x32x16_bf16 v[18:33], v[92:95], v[104:107], v[18:33]
	v_mfma_f32_32x32x16_bf16 v[34:49], v[96:99], v[100:103], v[34:49]
	v_mfma_f32_32x32x16_bf16 v[2:17], v[96:99], v[104:107], v[2:17]
	ds_read_b128 v[92:95], v89 offset:32768
	ds_read_b128 v[96:99], v89 offset:36864
	ds_read_b128 v[100:103], v90 offset:49152
	ds_read_b128 v[104:107], v90 offset:53248
	s_waitcnt lgkmcnt(1)
	v_mfma_f32_32x32x16_bf16 v[50:65], v[92:95], v[100:103], v[50:65]
	s_waitcnt lgkmcnt(0)
	v_mfma_f32_32x32x16_bf16 v[18:33], v[92:95], v[104:107], v[18:33]
	v_mfma_f32_32x32x16_bf16 v[34:49], v[96:99], v[100:103], v[34:49]
	v_mfma_f32_32x32x16_bf16 v[2:17], v[96:99], v[104:107], v[2:17]
	ds_read_b128 v[92:95], v85 offset:32768
	ds_read_b128 v[96:99], v85 offset:36864
	ds_read_b128 v[100:103], v87 offset:49152
	ds_read_b128 v[104:107], v87 offset:53248
	s_waitcnt lgkmcnt(1)
	v_mfma_f32_32x32x16_bf16 v[50:65], v[92:95], v[100:103], v[50:65]
	s_waitcnt lgkmcnt(0)
	v_mfma_f32_32x32x16_bf16 v[18:33], v[92:95], v[104:107], v[18:33]
	v_mfma_f32_32x32x16_bf16 v[34:49], v[96:99], v[100:103], v[34:49]
	v_mfma_f32_32x32x16_bf16 v[2:17], v[96:99], v[104:107], v[2:17]
	ds_read_b128 v[92:95], v86 offset:32768
	ds_read_b128 v[96:99], v86 offset:36864
	ds_read_b128 v[100:103], v88 offset:49152
	ds_read_b128 v[104:107], v88 offset:53248
	s_waitcnt lgkmcnt(0)
	v_mfma_f32_32x32x16_bf16 v[50:65], v[92:95], v[100:103], v[50:65]
	v_mfma_f32_32x32x16_bf16 v[18:33], v[92:95], v[104:107], v[18:33]
	s_waitcnt vmcnt(0)
	s_barrier
	v_lshl_add_u64 v[92:93], v[66:67], 0, s[88:89]
	global_load_lds_dwordx4 v[92:93], off
	v_lshl_add_u64 v[92:93], v[68:69], 0, s[88:89]
	s_mov_b32 m0, s51
	s_nop 0
	global_load_lds_dwordx4 v[92:93], off
	v_lshl_add_u64 v[92:93], v[70:71], 0, s[88:89]
	s_mov_b32 m0, s52
	v_mfma_f32_32x32x16_bf16 v[34:49], v[96:99], v[100:103], v[34:49]
	global_load_lds_dwordx4 v[92:93], off
	v_lshl_add_u64 v[92:93], v[72:73], 0, s[88:89]
	s_mov_b32 m0, s53
	s_nop 0
	global_load_lds_dwordx4 v[92:93], off
	v_lshl_add_u64 v[92:93], v[74:75], 0, s[88:89]
	s_mov_b32 m0, s54
	v_mfma_f32_32x32x16_bf16 v[2:17], v[96:99], v[104:107], v[2:17]
	global_load_lds_dwordx4 v[92:93], off
	v_lshl_add_u64 v[92:93], v[76:77], 0, s[88:89]
	s_mov_b32 m0, s55
	s_nop 0
	global_load_lds_dwordx4 v[92:93], off
	v_lshl_add_u64 v[92:93], v[78:79], 0, s[88:89]
	s_mov_b32 m0, s56
	s_nop 0
	global_load_lds_dwordx4 v[92:93], off
	v_lshl_add_u64 v[92:93], v[80:81], 0, s[88:89]
	s_mov_b32 m0, s11
	s_nop 0
	global_load_lds_dwordx4 v[92:93], off
	ds_read_b128 v[92:95], v0
	ds_read_b128 v[96:99], v0 offset:4096
	ds_read_b128 v[100:103], v84 offset:16384
	ds_read_b128 v[104:107], v84 offset:20480
	s_waitcnt lgkmcnt(0)
	v_mfma_f32_32x32x16_bf16 v[50:65], v[92:95], v[100:103], v[50:65]
	s_mov_b32 m0, s46
	v_mfma_f32_32x32x16_bf16 v[18:33], v[92:95], v[104:107], v[18:33]
	v_mfma_f32_32x32x16_bf16 v[34:49], v[96:99], v[100:103], v[34:49]
	v_mfma_f32_32x32x16_bf16 v[2:17], v[96:99], v[104:107], v[2:17]
	ds_read_b128 v[92:95], v89
	ds_read_b128 v[96:99], v89 offset:4096
	ds_read_b128 v[100:103], v90 offset:16384
	ds_read_b128 v[104:107], v90 offset:20480
	s_waitcnt lgkmcnt(1)
	v_mfma_f32_32x32x16_bf16 v[50:65], v[92:95], v[100:103], v[50:65]
	s_waitcnt lgkmcnt(0)
	v_mfma_f32_32x32x16_bf16 v[18:33], v[92:95], v[104:107], v[18:33]
	v_mfma_f32_32x32x16_bf16 v[34:49], v[96:99], v[100:103], v[34:49]
	v_mfma_f32_32x32x16_bf16 v[2:17], v[96:99], v[104:107], v[2:17]
	ds_read_b128 v[92:95], v85
	ds_read_b128 v[96:99], v85 offset:4096
	ds_read_b128 v[100:103], v87 offset:16384
	ds_read_b128 v[104:107], v87 offset:20480
	s_waitcnt lgkmcnt(1)
	v_mfma_f32_32x32x16_bf16 v[50:65], v[92:95], v[100:103], v[50:65]
	s_waitcnt lgkmcnt(0)
	v_mfma_f32_32x32x16_bf16 v[18:33], v[92:95], v[104:107], v[18:33]
	v_mfma_f32_32x32x16_bf16 v[34:49], v[96:99], v[100:103], v[34:49]
	v_mfma_f32_32x32x16_bf16 v[2:17], v[96:99], v[104:107], v[2:17]
	ds_read_b128 v[92:95], v86
	ds_read_b128 v[96:99], v86 offset:4096
	ds_read_b128 v[100:103], v88 offset:16384
	ds_read_b128 v[104:107], v88 offset:20480
	s_waitcnt lgkmcnt(0)
	v_mfma_f32_32x32x16_bf16 v[50:65], v[92:95], v[100:103], v[50:65]
	v_mfma_f32_32x32x16_bf16 v[18:33], v[92:95], v[104:107], v[18:33]
	s_waitcnt vmcnt(0)
	s_barrier
; #define MFMA(a, b, c) __builtin_amdgcn_mfma_f32_32x32x16_bf16((a), (b), (c), 0, 0, 0)
; #define TIDX opaque_tid()
; template <int AI, int BI>
; DI void gemm_stage(const u16* __restrict__ A, int lda, const u16* __restrict__ B, int ldb, char* buf, int tid) {
; #pragma unroll
;   for (int i = 0; i < 2 * AI; ++i) {
;     const int S = tid + NTHR * i, row = S >> 3, c = (S & 7) ^ ((row >> 1) & 7);
;     __builtin_amdgcn_global_load_lds((const unsigned*)(A + (size_t)row * lda + c * 8), (__attribute__((address_space(3))) unsigned*)(buf + S * 16), 16, 0, 0);
;   }
; #pragma unroll
;   for (int i = 0; i < 2 * BI; ++i) {
;     const int S = tid + NTHR * i, row = S >> 3, c = (S & 7) ^ ((row >> 1) & 7);
;     __builtin_amdgcn_global_load_lds((const unsigned*)(B + (size_t)row * ldb + c * 8), (__attribute__((address_space(3))) unsigned*)(buf + 16384 + S * 16), 16, 0, 0);
;   }
; }
; template <int AI, int BI>
; DI void gemm_tile(const u16* __restrict__ A, int lda, const u16* __restrict__ B, int ldb, int nk, bool swap,
;                   f32x16 (&acc)[AI][BI], char* lds) {
;   const int tid = TIDX, lane = tid & 63, wid = tid >> 6;
;   gemm_stage<AI, BI>(A, lda, B, ldb, lds, tid);
;   asm volatile("s_waitcnt vmcnt(0)" ::: "memory");
;   __syncthreads();
;   const int wa = wid >> 1, wb = wid & 1, r = lane & 31, h = lane >> 5, sw = (r >> 1) & 7;
;   const int offA = (swap ? 16384 : 0) + (wa * 32 * AI + r) * 128;
;   const int offB = (swap ? 0 : 16384) + (wb * 32 * BI + r) * 128;
;   for (int kt = 0; kt < nk; ++kt) {
;     const char* cur = lds + (kt & 1) * 32768;
;     if (kt + 1 < nk) gemm_stage<AI, BI>(A + (kt + 1) * 64, lda, B + (kt + 1) * 64, ldb, lds + ((kt + 1) & 1) * 32768, tid);
; #pragma unroll
;     for (int ks = 0; ks < 4; ++ks) {
;       const int co = ((ks * 2 + h) ^ sw) << 4;
;       s16x8 fa[AI], fb[BI];
; #pragma unroll
;       for (int i = 0; i < AI; ++i) fa[i] = *(const s16x8*)(cur + offA + i * 4096 + co);
; #pragma unroll
;       for (int i = 0; i < BI; ++i) fb[i] = *(const s16x8*)(cur + offB + i * 4096 + co);
; #pragma unroll
;       for (int i = 0; i < AI; ++i)
; #pragma unroll
;         for (int j = 0; j < BI; ++j) acc[i][j] = MFMA(fa[i], fb[j], acc[i][j]);
;     }
;     asm volatile("s_waitcnt vmcnt(0)" ::: "memory");
;     __syncthreads();
;   }
	v_lshl_add_u64 v[92:93], v[66:67], 0, vcc
	global_load_lds_dwordx4 v[92:93], off
	v_lshl_add_u64 v[92:93], v[68:69], 0, vcc
	s_mov_b32 m0, s47
	s_nop 0
	global_load_lds_dwordx4 v[92:93], off
	v_lshl_add_u64 v[92:93], v[70:71], 0, vcc
	s_mov_b32 m0, s48
	v_mfma_f32_32x32x16_bf16 v[34:49], v[96:99], v[100:103], v[34:49]
	global_load_lds_dwordx4 v[92:93], off
	v_lshl_add_u64 v[92:93], v[72:73], 0, vcc
	s_mov_b32 m0, s49
	s_nop 0
	global_load_lds_dwordx4 v[92:93], off
	v_lshl_add_u64 v[92:93], v[74:75], 0, vcc
	s_mov_b32 m0, s36
	v_mfma_f32_32x32x16_bf16 v[2:17], v[96:99], v[104:107], v[2:17]
	global_load_lds_dwordx4 v[92:93], off
	v_lshl_add_u64 v[92:93], v[76:77], 0, vcc
	s_mov_b32 m0, s37
	s_nop 0
	global_load_lds_dwordx4 v[92:93], off
	v_lshl_add_u64 v[92:93], v[78:79], 0, vcc
	s_mov_b32 m0, s40
	s_nop 0
	global_load_lds_dwordx4 v[92:93], off
	v_lshl_add_u64 v[92:93], v[80:81], 0, vcc
	s_mov_b32 m0, s41
	s_nop 0
	global_load_lds_dwordx4 v[92:93], off
	ds_read_b128 v[92:95], v0 offset:32768
	ds_read_b128 v[96:99], v0 offset:36864
	ds_read_b128 v[100:103], v84 offset:49152
	ds_read_b128 v[104:107], v84 offset:53248
	s_waitcnt lgkmcnt(0)
	v_mfma_f32_32x32x16_bf16 v[50:65], v[92:95], v[100:103], v[50:65]
	s_mov_b32 m0, s50
	v_mfma_f32_32x32x16_bf16 v[18:33], v[92:95], v[104:107], v[18:33]
	v_mfma_f32_32x32x16_bf16 v[34:49], v[96:99], v[100:103], v[34:49]
	v_mfma_f32_32x32x16_bf16 v[2:17], v[96:99], v[104:107], v[2:17]
	ds_read_b128 v[92:95], v89 offset:32768
	ds_read_b128 v[96:99], v89 offset:36864
	ds_read_b128 v[100:103], v90 offset:49152
	ds_read_b128 v[104:107], v90 offset:53248
	s_waitcnt lgkmcnt(1)
	v_mfma_f32_32x32x16_bf16 v[50:65], v[92:95], v[100:103], v[50:65]
	s_waitcnt lgkmcnt(0)
	v_mfma_f32_32x32x16_bf16 v[18:33], v[92:95], v[104:107], v[18:33]
	v_mfma_f32_32x32x16_bf16 v[34:49], v[96:99], v[100:103], v[34:49]
	v_mfma_f32_32x32x16_bf16 v[2:17], v[96:99], v[104:107], v[2:17]
	ds_read_b128 v[92:95], v85 offset:32768
	ds_read_b128 v[96:99], v85 offset:36864
	ds_read_b128 v[100:103], v87 offset:49152
	ds_read_b128 v[104:107], v87 offset:53248
	s_waitcnt lgkmcnt(1)
	v_mfma_f32_32x32x16_bf16 v[50:65], v[92:95], v[100:103], v[50:65]
	s_waitcnt lgkmcnt(0)
	v_mfma_f32_32x32x16_bf16 v[18:33], v[92:95], v[104:107], v[18:33]
	v_mfma_f32_32x32x16_bf16 v[34:49], v[96:99], v[100:103], v[34:49]
	v_mfma_f32_32x32x16_bf16 v[2:17], v[96:99], v[104:107], v[2:17]
	ds_read_b128 v[92:95], v86 offset:32768
	ds_read_b128 v[96:99], v86 offset:36864
	ds_read_b128 v[100:103], v88 offset:49152
	ds_read_b128 v[104:107], v88 offset:53248
	s_waitcnt lgkmcnt(0)
	v_mfma_f32_32x32x16_bf16 v[50:65], v[92:95], v[100:103], v[50:65]
	v_mfma_f32_32x32x16_bf16 v[18:33], v[92:95], v[104:107], v[18:33]
	s_waitcnt vmcnt(0)
	s_barrier
	v_lshl_add_u64 v[92:93], v[66:67], 0, s[78:79]
	global_load_lds_dwordx4 v[92:93], off
	v_lshl_add_u64 v[92:93], v[68:69], 0, s[78:79]
	s_mov_b32 m0, s51
	s_nop 0
	global_load_lds_dwordx4 v[92:93], off
	v_lshl_add_u64 v[92:93], v[70:71], 0, s[78:79]
	s_mov_b32 m0, s52
	v_mfma_f32_32x32x16_bf16 v[34:49], v[96:99], v[100:103], v[34:49]
	global_load_lds_dwordx4 v[92:93], off
	v_lshl_add_u64 v[92:93], v[72:73], 0, s[78:79]
	s_mov_b32 m0, s53
	s_nop 0
	global_load_lds_dwordx4 v[92:93], off
	v_lshl_add_u64 v[92:93], v[74:75], 0, s[78:79]
	s_mov_b32 m0, s54
	v_mfma_f32_32x32x16_bf16 v[2:17], v[96:99], v[104:107], v[2:17]
	global_load_lds_dwordx4 v[92:93], off
	v_lshl_add_u64 v[92:93], v[76:77], 0, s[78:79]
	s_mov_b32 m0, s55
	s_nop 0
	global_load_lds_dwordx4 v[92:93], off
	v_lshl_add_u64 v[92:93], v[78:79], 0, s[78:79]
	s_mov_b32 m0, s56
	s_nop 0
	global_load_lds_dwordx4 v[92:93], off
	v_lshl_add_u64 v[92:93], v[80:81], 0, s[78:79]
	s_mov_b32 m0, s11
	s_nop 0
	global_load_lds_dwordx4 v[92:93], off
	ds_read_b128 v[92:95], v0
	ds_read_b128 v[96:99], v0 offset:4096
	ds_read_b128 v[100:103], v84 offset:16384
	ds_read_b128 v[104:107], v84 offset:20480
	s_waitcnt lgkmcnt(0)
	v_mfma_f32_32x32x16_bf16 v[50:65], v[92:95], v[100:103], v[50:65]
	s_mov_b32 m0, s46
	v_mfma_f32_32x32x16_bf16 v[18:33], v[92:95], v[104:107], v[18:33]
	v_mfma_f32_32x32x16_bf16 v[34:49], v[96:99], v[100:103], v[34:49]
	v_mfma_f32_32x32x16_bf16 v[2:17], v[96:99], v[104:107], v[2:17]
	ds_read_b128 v[92:95], v89
	ds_read_b128 v[96:99], v89 offset:4096
	ds_read_b128 v[100:103], v90 offset:16384
	ds_read_b128 v[104:107], v90 offset:20480
	s_waitcnt lgkmcnt(1)
	v_mfma_f32_32x32x16_bf16 v[50:65], v[92:95], v[100:103], v[50:65]
	s_waitcnt lgkmcnt(0)
	v_mfma_f32_32x32x16_bf16 v[18:33], v[92:95], v[104:107], v[18:33]
	v_mfma_f32_32x32x16_bf16 v[34:49], v[96:99], v[100:103], v[34:49]
	v_mfma_f32_32x32x16_bf16 v[2:17], v[96:99], v[104:107], v[2:17]
	ds_read_b128 v[92:95], v85
	ds_read_b128 v[96:99], v85 offset:4096
	ds_read_b128 v[100:103], v87 offset:16384
	ds_read_b128 v[104:107], v87 offset:20480
	s_waitcnt lgkmcnt(1)
	v_mfma_f32_32x32x16_bf16 v[50:65], v[92:95], v[100:103], v[50:65]
	s_waitcnt lgkmcnt(0)
	v_mfma_f32_32x32x16_bf16 v[18:33], v[92:95], v[104:107], v[18:33]
	v_mfma_f32_32x32x16_bf16 v[34:49], v[96:99], v[100:103], v[34:49]
	v_mfma_f32_32x32x16_bf16 v[2:17], v[96:99], v[104:107], v[2:17]
	ds_read_b128 v[92:95], v86
	ds_read_b128 v[96:99], v86 offset:4096
	ds_read_b128 v[100:103], v88 offset:16384
	ds_read_b128 v[104:107], v88 offset:20480
	s_waitcnt lgkmcnt(0)
	v_mfma_f32_32x32x16_bf16 v[50:65], v[92:95], v[100:103], v[50:65]
	v_mfma_f32_32x32x16_bf16 v[18:33], v[92:95], v[104:107], v[18:33]
	s_waitcnt vmcnt(0)
	s_barrier
; #define MFMA(a, b, c) __builtin_amdgcn_mfma_f32_32x32x16_bf16((a), (b), (c), 0, 0, 0)
; template <int AI, int BI>
; DI void gemm_tile(const u16* __restrict__ A, int lda, const u16* __restrict__ B, int ldb, int nk, bool swap,
;                   f32x16 (&acc)[AI][BI], char* lds) {
;     ...
;   for (int kt = 0; kt < nk; ++kt) {
;     const char* cur = lds + (kt & 1) * 32768;
;     if (kt + 1 < nk) gemm_stage<AI, BI>(A + (kt + 1) * 64, lda, B + (kt + 1) * 64, ldb, lds + ((kt + 1) & 1) * 32768, tid);
; #pragma unroll
;     for (int ks = 0; ks < 4; ++ks) {
;       const int co = ((ks * 2 + h) ^ sw) << 4;
;       s16x8 fa[AI], fb[BI];
; #pragma unroll
;       for (int i = 0; i < AI; ++i) fa[i] = *(const s16x8*)(cur + offA + i * 4096 + co);
; #pragma unroll
;       for (int i = 0; i < BI; ++i) fb[i] = *(const s16x8*)(cur + offB + i * 4096 + co);
; #pragma unroll
;       for (int i = 0; i < AI; ++i)
; #pragma unroll
;         for (int j = 0; j < BI; ++j) acc[i][j] = MFMA(fa[i], fb[j], acc[i][j]);
;     }
;     asm volatile("s_waitcnt vmcnt(0)" ::: "memory");
;     __syncthreads();
;   }
	v_lshl_add_u64 v[92:93], v[66:67], 0, s[2:3]
	global_load_lds_dwordx4 v[92:93], off
	v_lshl_add_u64 v[92:93], v[68:69], 0, s[2:3]
	s_mov_b32 m0, s47
	v_lshl_add_u64 v[66:67], v[66:67], 0, s[30:31]
	global_load_lds_dwordx4 v[92:93], off
	v_lshl_add_u64 v[92:93], v[70:71], 0, s[2:3]
	s_mov_b32 m0, s48
	v_mfma_f32_32x32x16_bf16 v[34:49], v[96:99], v[100:103], v[34:49]
	global_load_lds_dwordx4 v[92:93], off
	v_lshl_add_u64 v[92:93], v[72:73], 0, s[2:3]
	s_mov_b32 m0, s49
	s_nop 0
	global_load_lds_dwordx4 v[92:93], off
	v_lshl_add_u64 v[92:93], v[74:75], 0, s[2:3]
	s_mov_b32 m0, s36
	v_mfma_f32_32x32x16_bf16 v[2:17], v[96:99], v[104:107], v[2:17]
	global_load_lds_dwordx4 v[92:93], off
	v_lshl_add_u64 v[92:93], v[76:77], 0, s[2:3]
	s_mov_b32 m0, s37
	s_lshl_b32 s36, s10, 7
	global_load_lds_dwordx4 v[92:93], off
	v_lshl_add_u64 v[92:93], v[78:79], 0, s[2:3]
	s_mov_b32 m0, s40
	s_lshr_b32 s10, s34, 7
	global_load_lds_dwordx4 v[92:93], off
	v_lshl_add_u64 v[92:93], v[80:81], 0, s[2:3]
	s_mov_b32 m0, s41
	s_mul_i32 s10, s10, 0x9000
	global_load_lds_dwordx4 v[92:93], off
	ds_read_b128 v[92:95], v0 offset:32768
	ds_read_b128 v[96:99], v0 offset:36864
	ds_read_b128 v[100:103], v84 offset:49152
	ds_read_b128 v[104:107], v84 offset:53248
	s_waitcnt lgkmcnt(0)
	v_mfma_f32_32x32x16_bf16 v[50:65], v[92:95], v[100:103], v[50:65]
	s_mov_b32 m0, s50
	s_add_u32 s10, s18, s10
	v_mfma_f32_32x32x16_bf16 v[18:33], v[92:95], v[104:107], v[18:33]
	v_mfma_f32_32x32x16_bf16 v[34:49], v[96:99], v[100:103], v[34:49]
	v_mfma_f32_32x32x16_bf16 v[2:17], v[96:99], v[104:107], v[2:17]
	ds_read_b128 v[92:95], v89 offset:32768
	ds_read_b128 v[96:99], v89 offset:36864
	ds_read_b128 v[100:103], v90 offset:49152
	ds_read_b128 v[104:107], v90 offset:53248
	s_waitcnt lgkmcnt(1)
	v_mfma_f32_32x32x16_bf16 v[50:65], v[92:95], v[100:103], v[50:65]
	s_waitcnt lgkmcnt(0)
	v_mfma_f32_32x32x16_bf16 v[18:33], v[92:95], v[104:107], v[18:33]
	v_mfma_f32_32x32x16_bf16 v[34:49], v[96:99], v[100:103], v[34:49]
	v_mfma_f32_32x32x16_bf16 v[2:17], v[96:99], v[104:107], v[2:17]
	ds_read_b128 v[92:95], v85 offset:32768
	ds_read_b128 v[96:99], v85 offset:36864
	ds_read_b128 v[100:103], v87 offset:49152
	ds_read_b128 v[104:107], v87 offset:53248
	s_waitcnt lgkmcnt(1)
	v_mfma_f32_32x32x16_bf16 v[50:65], v[92:95], v[100:103], v[50:65]
	s_waitcnt lgkmcnt(0)
	v_mfma_f32_32x32x16_bf16 v[18:33], v[92:95], v[104:107], v[18:33]
	v_mfma_f32_32x32x16_bf16 v[34:49], v[96:99], v[100:103], v[34:49]
	v_mfma_f32_32x32x16_bf16 v[2:17], v[96:99], v[104:107], v[2:17]
	ds_read_b128 v[92:95], v86 offset:32768
	ds_read_b128 v[96:99], v86 offset:36864
	ds_read_b128 v[100:103], v88 offset:49152
	ds_read_b128 v[104:107], v88 offset:53248
	s_waitcnt vmcnt(0)
	s_waitcnt lgkmcnt(0)
	s_barrier
	global_load_lds_dwordx4 v[66:67], off
	v_lshl_add_u64 v[66:67], v[68:69], 0, s[30:31]
	s_mov_b32 m0, s51
	v_mfma_f32_32x32x16_bf16 v[50:65], v[92:95], v[100:103], v[50:65]
	global_load_lds_dwordx4 v[66:67], off
	v_lshl_add_u64 v[66:67], v[70:71], 0, s[30:31]
	s_mov_b32 m0, s52
	s_nop 0
	global_load_lds_dwordx4 v[66:67], off
	v_lshl_add_u64 v[66:67], v[72:73], 0, s[30:31]
	s_mov_b32 m0, s53
	v_mfma_f32_32x32x16_bf16 v[18:33], v[92:95], v[104:107], v[18:33]
	global_load_lds_dwordx4 v[66:67], off
	v_lshl_add_u64 v[66:67], v[74:75], 0, s[30:31]
	s_mov_b32 m0, s54
	s_nop 0
	global_load_lds_dwordx4 v[66:67], off
	v_lshl_add_u64 v[66:67], v[76:77], 0, s[30:31]
	s_mov_b32 m0, s55
	v_mfma_f32_32x32x16_bf16 v[34:49], v[96:99], v[100:103], v[34:49]
	global_load_lds_dwordx4 v[66:67], off
	v_lshl_add_u64 v[66:67], v[78:79], 0, s[30:31]
	s_mov_b32 m0, s56
	s_nop 0
	global_load_lds_dwordx4 v[66:67], off
	v_lshl_add_u64 v[66:67], v[80:81], 0, s[30:31]
	s_mov_b32 m0, s11
	v_mfma_f32_32x32x16_bf16 v[2:17], v[96:99], v[104:107], v[2:17]
	global_load_lds_dwordx4 v[66:67], off
	ds_read_b128 v[66:69], v0
	ds_read_b128 v[70:73], v0 offset:4096
	ds_read_b128 v[74:77], v84 offset:16384
	ds_read_b128 v[78:81], v84 offset:20480
	s_addc_u32 s11, s28, 0
	s_add_u32 s10, s10, 0x9000
	s_addc_u32 s11, s11, 0
	s_waitcnt lgkmcnt(0)
	v_mfma_f32_32x32x16_bf16 v[50:65], v[66:69], v[74:77], v[50:65]
	v_mfma_f32_32x32x16_bf16 v[18:33], v[66:69], v[78:81], v[18:33]
	v_mfma_f32_32x32x16_bf16 v[34:49], v[70:73], v[74:77], v[34:49]
	v_mfma_f32_32x32x16_bf16 v[2:17], v[70:73], v[78:81], v[2:17]
	ds_read_b128 v[66:69], v89
	ds_read_b128 v[70:73], v89 offset:4096
	ds_read_b128 v[74:77], v90 offset:16384
	ds_read_b128 v[78:81], v90 offset:20480
	s_waitcnt lgkmcnt(1)
	v_mfma_f32_32x32x16_bf16 v[50:65], v[66:69], v[74:77], v[50:65]
	s_waitcnt lgkmcnt(0)
	v_mfma_f32_32x32x16_bf16 v[18:33], v[66:69], v[78:81], v[18:33]
	v_mfma_f32_32x32x16_bf16 v[34:49], v[70:73], v[74:77], v[34:49]
	v_mfma_f32_32x32x16_bf16 v[2:17], v[70:73], v[78:81], v[2:17]
	ds_read_b128 v[66:69], v85
	ds_read_b128 v[70:73], v85 offset:4096
	ds_read_b128 v[74:77], v87 offset:16384
	ds_read_b128 v[78:81], v87 offset:20480
	s_waitcnt lgkmcnt(1)
	v_mfma_f32_32x32x16_bf16 v[50:65], v[66:69], v[74:77], v[50:65]
	s_waitcnt lgkmcnt(0)
	v_mfma_f32_32x32x16_bf16 v[18:33], v[66:69], v[78:81], v[18:33]
	v_mfma_f32_32x32x16_bf16 v[34:49], v[70:73], v[74:77], v[34:49]
	v_mfma_f32_32x32x16_bf16 v[2:17], v[70:73], v[78:81], v[2:17]
	ds_read_b128 v[66:69], v86
	ds_read_b128 v[70:73], v86 offset:4096
	ds_read_b128 v[74:77], v88 offset:16384
	ds_read_b128 v[78:81], v88 offset:20480
	s_waitcnt lgkmcnt(0)
	v_mfma_f32_32x32x16_bf16 v[50:65], v[66:69], v[74:77], v[50:65]
	v_mfma_f32_32x32x16_bf16 v[18:33], v[66:69], v[78:81], v[18:33]
	v_mfma_f32_32x32x16_bf16 v[34:49], v[70:73], v[74:77], v[34:49]
	v_mfma_f32_32x32x16_bf16 v[2:17], v[70:73], v[78:81], v[2:17]
	s_waitcnt vmcnt(0)
	s_barrier
; #define MFMA(a, b, c) __builtin_amdgcn_mfma_f32_32x32x16_bf16((a), (b), (c), 0, 0, 0)
; #define GAS __attribute__((address_space(1)))
; DI int opaque0() { int z = 0; asm volatile("" : "+v"(z)); return z; }
; template <int AI, int BI>
; DI void gemm_tile(const u16* __restrict__ A, int lda, const u16* __restrict__ B, int ldb, int nk, bool swap,
;                   f32x16 (&acc)[AI][BI], char* lds) {
;     ...
;   for (int kt = 0; kt < nk; ++kt) {
;     const char* cur = lds + (kt & 1) * 32768;
;     if (kt + 1 < nk) gemm_stage<AI, BI>(A + (kt + 1) * 64, lda, B + (kt + 1) * 64, ldb, lds + ((kt + 1) & 1) * 32768, tid);
; #pragma unroll
;     for (int ks = 0; ks < 4; ++ks) {
;       const int co = ((ks * 2 + h) ^ sw) << 4;
;       s16x8 fa[AI], fb[BI];
; #pragma unroll
;       for (int i = 0; i < AI; ++i) fa[i] = *(const s16x8*)(cur + offA + i * 4096 + co);
; #pragma unroll
;       for (int i = 0; i < BI; ++i) fb[i] = *(const s16x8*)(cur + offB + i * 4096 + co);
; #pragma unroll
;       for (int i = 0; i < AI; ++i)
; #pragma unroll
;         for (int j = 0; j < BI; ++j) acc[i][j] = MFMA(fa[i], fb[j], acc[i][j]);
;     }
;     asm volatile("s_waitcnt vmcnt(0)" ::: "memory");
;     __syncthreads();
;   }
; template <int AI, int BI>
; DI void m2_tile(char* wsb, int layer, int m0, int n0, char* lds) {
;     ...
;   const int m0e = m0 + opaque0();
;   const int mr = m0 < TL ? (m0 >> 11) : 8;
;   const float* gate = mods + (size_t)mr * 9216 + 5 * 1024;
;   GAS float* xsu = uptr(xs);
; #pragma unroll
;   for (int bi = 0; bi < BI; ++bi) {
;     const int n = n0 + wb * 32 * BI + bi * 32 + r;
;     const float gv = gate[n];
;     const unsigned ib = (unsigned)((m0e + wa * 32 * AI + 4 * h) * 1024 + n);
; #pragma unroll
;     for (int ai = 0; ai < AI; ++ai)
; #pragma unroll
;       for (int reg = 0; reg < 16; ++reg) {
;         const unsigned idx = ib + (unsigned)((ai * 32 + (reg & 3) + 8 * (reg >> 2)) * 1024);
;         xsu[idx] += gv * acc[ai][bi][reg];
;         if ((reg & 7) == 7) __builtin_amdgcn_sched_barrier(0);
;       }
	ds_read_b128 v[66:69], v0 offset:32768
	ds_read_b128 v[70:73], v0 offset:36864
	ds_read_b128 v[74:77], v84 offset:49152
	ds_read_b128 v[78:81], v84 offset:53248
	v_mov_b32_e32 v0, v1
	s_waitcnt lgkmcnt(1)
	v_mfma_f32_32x32x16_bf16 v[50:65], v[66:69], v[74:77], v[50:65]
	s_waitcnt lgkmcnt(0)
	v_mfma_f32_32x32x16_bf16 v[18:33], v[66:69], v[78:81], v[18:33]
	v_mfma_f32_32x32x16_bf16 v[34:49], v[70:73], v[74:77], v[34:49]
	v_mfma_f32_32x32x16_bf16 v[2:17], v[70:73], v[78:81], v[2:17]
	ds_read_b128 v[66:69], v89 offset:32768
	ds_read_b128 v[70:73], v89 offset:36864
	ds_read_b128 v[74:77], v90 offset:49152
	ds_read_b128 v[78:81], v90 offset:53248
	s_waitcnt lgkmcnt(1)
	v_mfma_f32_32x32x16_bf16 v[50:65], v[66:69], v[74:77], v[50:65]
	s_waitcnt lgkmcnt(0)
	v_mfma_f32_32x32x16_bf16 v[18:33], v[66:69], v[78:81], v[18:33]
	v_mfma_f32_32x32x16_bf16 v[34:49], v[70:73], v[74:77], v[34:49]
	v_mfma_f32_32x32x16_bf16 v[2:17], v[70:73], v[78:81], v[2:17]
	ds_read_b128 v[66:69], v85 offset:32768
	ds_read_b128 v[70:73], v85 offset:36864
	ds_read_b128 v[74:77], v87 offset:49152
	ds_read_b128 v[78:81], v87 offset:53248
	s_waitcnt lgkmcnt(1)
	v_mfma_f32_32x32x16_bf16 v[50:65], v[66:69], v[74:77], v[50:65]
	s_waitcnt lgkmcnt(0)
	v_mfma_f32_32x32x16_bf16 v[18:33], v[66:69], v[78:81], v[18:33]
	v_mfma_f32_32x32x16_bf16 v[34:49], v[70:73], v[74:77], v[34:49]
	v_mfma_f32_32x32x16_bf16 v[2:17], v[70:73], v[78:81], v[2:17]
	ds_read_b128 v[66:69], v86 offset:32768
	ds_read_b128 v[70:73], v86 offset:36864
	ds_read_b128 v[74:77], v88 offset:49152
	ds_read_b128 v[78:81], v88 offset:53248
	s_waitcnt vmcnt(0)
	s_waitcnt lgkmcnt(0)
	s_barrier
	v_mfma_f32_32x32x16_bf16 v[50:65], v[66:69], v[74:77], v[50:65]
	v_mfma_f32_32x32x16_bf16 v[18:33], v[66:69], v[78:81], v[18:33]
	v_mfma_f32_32x32x16_bf16 v[34:49], v[70:73], v[74:77], v[34:49]
	v_mfma_f32_32x32x16_bf16 v[2:17], v[70:73], v[78:81], v[2:17]
	v_and_b32_e32 v143, 31, v178
	v_and_b32_e32 v140, 64, v178
	v_or_b32_e32 v140, v140, v143
	v_bfe_u32 v143, v178, 5, 1
	v_bfe_u32 v139, v178, 7, 1
	v_lshlrev_b32_e32 v139, 6, v139
	v_lshl_add_u32 v139, v143, 2, v139
	v_lshl_add_u32 v139, v139, 10, v140
	v_lshlrev_b32_e32 v139, 2, v139
	v_add_u32_e32 v140, s35, v140
	v_lshlrev_b32_e32 v140, 2, v140
	global_load_dword v141, v140, s[10:11]
	global_load_dword v142, v140, s[10:11] offset:128
	s_lshl_b32 s56, s36, 10
	s_add_u32 s56, s56, s35
	s_lshl_b32 s56, s56, 2
	s_add_u32 s54, s8, s56
	s_addc_u32 s55, s9, 0
	s_mov_b64 s[52:53], s[54:55]
	global_load_dword v66, v139, s[52:53]
	global_load_dword v67, v139, s[52:53] offset:128
	s_add_u32 s52, s52, 4096
	s_addc_u32 s53, s53, 0
	global_load_dword v68, v139, s[52:53]
	global_load_dword v69, v139, s[52:53] offset:128
	s_add_u32 s52, s52, 4096
	s_addc_u32 s53, s53, 0
	global_load_dword v70, v139, s[52:53]
	global_load_dword v71, v139, s[52:53] offset:128
	s_add_u32 s52, s52, 4096
	s_addc_u32 s53, s53, 0
	global_load_dword v72, v139, s[52:53]
	global_load_dword v73, v139, s[52:53] offset:128
	s_add_u32 s52, s52, 20480
	s_addc_u32 s53, s53, 0
	global_load_dword v74, v139, s[52:53]
	global_load_dword v75, v139, s[52:53] offset:128
	s_add_u32 s52, s52, 4096
	s_addc_u32 s53, s53, 0
	global_load_dword v76, v139, s[52:53]
	global_load_dword v77, v139, s[52:53] offset:128
	s_add_u32 s52, s52, 4096
	s_addc_u32 s53, s53, 0
	global_load_dword v78, v139, s[52:53]
	global_load_dword v79, v139, s[52:53] offset:128
	s_add_u32 s52, s52, 4096
	s_addc_u32 s53, s53, 0
	global_load_dword v80, v139, s[52:53]
	global_load_dword v81, v139, s[52:53] offset:128
	s_add_u32 s52, s52, 20480
	s_addc_u32 s53, s53, 0
	global_load_dword v82, v139, s[52:53]
	global_load_dword v83, v139, s[52:53] offset:128
	s_add_u32 s52, s52, 4096
	s_addc_u32 s53, s53, 0
	global_load_dword v84, v139, s[52:53]
	global_load_dword v85, v139, s[52:53] offset:128
	s_add_u32 s52, s52, 4096
	s_addc_u32 s53, s53, 0
	global_load_dword v86, v139, s[52:53]
	global_load_dword v87, v139, s[52:53] offset:128
	s_add_u32 s52, s52, 4096
	s_addc_u32 s53, s53, 0
	global_load_dword v88, v139, s[52:53]
	global_load_dword v89, v139, s[52:53] offset:128
	s_add_u32 s52, s52, 20480
	s_addc_u32 s53, s53, 0
	global_load_dword v90, v139, s[52:53]
	global_load_dword v91, v139, s[52:53] offset:128
	s_add_u32 s52, s52, 4096
	s_addc_u32 s53, s53, 0
	global_load_dword v92, v139, s[52:53]
	global_load_dword v93, v139, s[52:53] offset:128
	s_add_u32 s52, s52, 4096
	s_addc_u32 s53, s53, 0
	global_load_dword v94, v139, s[52:53]
	global_load_dword v95, v139, s[52:53] offset:128
	s_add_u32 s52, s52, 4096
	s_addc_u32 s53, s53, 0
	global_load_dword v96, v139, s[52:53]
	global_load_dword v97, v139, s[52:53] offset:128
	s_add_u32 s52, s52, 20480
	s_addc_u32 s53, s53, 0
	global_load_dword v98, v139, s[52:53]
	global_load_dword v99, v139, s[52:53] offset:128
	s_add_u32 s52, s52, 4096
	s_addc_u32 s53, s53, 0
	global_load_dword v100, v139, s[52:53]
	global_load_dword v101, v139, s[52:53] offset:128
	s_add_u32 s52, s52, 4096
	s_addc_u32 s53, s53, 0
	global_load_dword v102, v139, s[52:53]
	global_load_dword v103, v139, s[52:53] offset:128
	s_add_u32 s52, s52, 4096
	s_addc_u32 s53, s53, 0
	global_load_dword v104, v139, s[52:53]
	global_load_dword v105, v139, s[52:53] offset:128
	s_add_u32 s52, s52, 20480
	s_addc_u32 s53, s53, 0
	global_load_dword v106, v139, s[52:53]
	global_load_dword v107, v139, s[52:53] offset:128
	s_add_u32 s52, s52, 4096
	s_addc_u32 s53, s53, 0
	global_load_dword v108, v139, s[52:53]
	global_load_dword v109, v139, s[52:53] offset:128
	s_add_u32 s52, s52, 4096
	s_addc_u32 s53, s53, 0
	global_load_dword v110, v139, s[52:53]
	global_load_dword v111, v139, s[52:53] offset:128
	s_add_u32 s52, s52, 4096
	s_addc_u32 s53, s53, 0
	global_load_dword v112, v139, s[52:53]
	global_load_dword v113, v139, s[52:53] offset:128
	s_add_u32 s52, s52, 20480
	s_addc_u32 s53, s53, 0
	global_load_dword v114, v139, s[52:53]
	global_load_dword v115, v139, s[52:53] offset:128
	s_add_u32 s52, s52, 4096
	s_addc_u32 s53, s53, 0
	global_load_dword v116, v139, s[52:53]
	global_load_dword v117, v139, s[52:53] offset:128
	s_add_u32 s52, s52, 4096
	s_addc_u32 s53, s53, 0
	global_load_dword v118, v139, s[52:53]
	global_load_dword v119, v139, s[52:53] offset:128
	s_add_u32 s52, s52, 4096
	s_addc_u32 s53, s53, 0
	global_load_dword v120, v139, s[52:53]
	global_load_dword v121, v139, s[52:53] offset:128
	s_add_u32 s52, s52, 20480
	s_addc_u32 s53, s53, 0
	global_load_dword v122, v139, s[52:53]
	global_load_dword v123, v139, s[52:53] offset:128
	s_add_u32 s52, s52, 4096
	s_addc_u32 s53, s53, 0
	global_load_dword v124, v139, s[52:53]
	global_load_dword v134, v139, s[52:53] offset:128
	s_add_u32 s52, s52, 4096
	s_addc_u32 s53, s53, 0
	global_load_dword v135, v139, s[52:53]
	global_load_dword v136, v139, s[52:53] offset:128
	s_add_u32 s52, s52, 4096
	s_addc_u32 s53, s53, 0
	global_load_dword v137, v139, s[52:53]
	global_load_dword v138, v139, s[52:53] offset:128
	s_waitcnt vmcnt(48)
; #define GAS __attribute__((address_space(1)))
; DI int opaque0() { int z = 0; asm volatile("" : "+v"(z)); return z; }
; template <int AI, int BI>
; DI void m2_tile(char* wsb, int layer, int m0, int n0, char* lds) {
;     ...
;   const int m0e = m0 + opaque0();
;   const int mr = m0 < TL ? (m0 >> 11) : 8;
;   const float* gate = mods + (size_t)mr * 9216 + 5 * 1024;
;   GAS float* xsu = uptr(xs);
; #pragma unroll
;   for (int bi = 0; bi < BI; ++bi) {
;     const int n = n0 + wb * 32 * BI + bi * 32 + r;
;     const float gv = gate[n];
;     const unsigned ib = (unsigned)((m0e + wa * 32 * AI + 4 * h) * 1024 + n);
; #pragma unroll
;     for (int ai = 0; ai < AI; ++ai)
; #pragma unroll
;       for (int reg = 0; reg < 16; ++reg) {
;         const unsigned idx = ib + (unsigned)((ai * 32 + (reg & 3) + 8 * (reg >> 2)) * 1024);
;         xsu[idx] += gv * acc[ai][bi][reg];
;         if ((reg & 7) == 7) __builtin_amdgcn_sched_barrier(0);
;       }
;   }
; }
; DI void phase_m2(const Params& p, char* wsb, int layer, int mrows, char* lds) {
;   int mt, nt;
;   for (int rnd = 0; next_tile(rnd, 128, 8, mt, nt); ++rnd) m2_tile<2, 2>(wsb, layer, mt * 128, nt * 128, lds);
;   if (mrows > TL)
;     for (int rnd = 0; next_tile(rnd, 32, 16, mt, nt); ++rnd) m2_tile<1, 1>(wsb, layer, TL + mt * 64, nt * 64, lds);
	v_fmac_f32_e32 v66, v50, v141
	v_fmac_f32_e32 v67, v18, v142
	v_fmac_f32_e32 v68, v51, v141
	v_fmac_f32_e32 v69, v19, v142
	v_fmac_f32_e32 v70, v52, v141
	v_fmac_f32_e32 v71, v20, v142
	v_fmac_f32_e32 v72, v53, v141
	v_fmac_f32_e32 v73, v21, v142
	v_fmac_f32_e32 v74, v54, v141
	v_fmac_f32_e32 v75, v22, v142
	v_fmac_f32_e32 v76, v55, v141
	v_fmac_f32_e32 v77, v23, v142
	v_fmac_f32_e32 v78, v56, v141
	v_fmac_f32_e32 v79, v24, v142
	v_fmac_f32_e32 v80, v57, v141
	v_fmac_f32_e32 v81, v25, v142
	s_waitcnt vmcnt(32)
	v_fmac_f32_e32 v82, v58, v141
	v_fmac_f32_e32 v83, v26, v142
	v_fmac_f32_e32 v84, v59, v141
	v_fmac_f32_e32 v85, v27, v142
	v_fmac_f32_e32 v86, v60, v141
	v_fmac_f32_e32 v87, v28, v142
	v_fmac_f32_e32 v88, v61, v141
	v_fmac_f32_e32 v89, v29, v142
	v_fmac_f32_e32 v90, v62, v141
	v_fmac_f32_e32 v91, v30, v142
	v_fmac_f32_e32 v92, v63, v141
	v_fmac_f32_e32 v93, v31, v142
	v_fmac_f32_e32 v94, v64, v141
	v_fmac_f32_e32 v95, v32, v142
	v_fmac_f32_e32 v96, v65, v141
	v_fmac_f32_e32 v97, v33, v142
	s_waitcnt vmcnt(16)
	v_fmac_f32_e32 v98, v34, v141
	v_fmac_f32_e32 v99, v2, v142
	v_fmac_f32_e32 v100, v35, v141
	v_fmac_f32_e32 v101, v3, v142
	v_fmac_f32_e32 v102, v36, v141
	v_fmac_f32_e32 v103, v4, v142
	v_fmac_f32_e32 v104, v37, v141
	v_fmac_f32_e32 v105, v5, v142
	v_fmac_f32_e32 v106, v38, v141
	v_fmac_f32_e32 v107, v6, v142
	v_fmac_f32_e32 v108, v39, v141
	v_fmac_f32_e32 v109, v7, v142
	v_fmac_f32_e32 v110, v40, v141
	v_fmac_f32_e32 v111, v8, v142
	v_fmac_f32_e32 v112, v41, v141
	v_fmac_f32_e32 v113, v9, v142
	s_waitcnt vmcnt(0)
	v_fmac_f32_e32 v114, v42, v141
	v_fmac_f32_e32 v115, v10, v142
	v_fmac_f32_e32 v116, v43, v141
	v_fmac_f32_e32 v117, v11, v142
	v_fmac_f32_e32 v118, v44, v141
	v_fmac_f32_e32 v119, v12, v142
	v_fmac_f32_e32 v120, v45, v141
	v_fmac_f32_e32 v121, v13, v142
	v_fmac_f32_e32 v122, v46, v141
	v_fmac_f32_e32 v123, v14, v142
	v_fmac_f32_e32 v124, v47, v141
	v_fmac_f32_e32 v134, v15, v142
	v_fmac_f32_e32 v135, v48, v141
	v_fmac_f32_e32 v136, v16, v142
	v_fmac_f32_e32 v137, v49, v141
	v_fmac_f32_e32 v138, v17, v142
	s_mov_b64 s[52:53], s[54:55]
	global_store_dword v139, v66, s[52:53]
	global_store_dword v139, v67, s[52:53] offset:128
	s_add_u32 s52, s52, 4096
	s_addc_u32 s53, s53, 0
	global_store_dword v139, v68, s[52:53]
	global_store_dword v139, v69, s[52:53] offset:128
	s_add_u32 s52, s52, 4096
	s_addc_u32 s53, s53, 0
	global_store_dword v139, v70, s[52:53]
	global_store_dword v139, v71, s[52:53] offset:128
	s_add_u32 s52, s52, 4096
	s_addc_u32 s53, s53, 0
	global_store_dword v139, v72, s[52:53]
	global_store_dword v139, v73, s[52:53] offset:128
	s_add_u32 s52, s52, 20480
	s_addc_u32 s53, s53, 0
	global_store_dword v139, v74, s[52:53]
	global_store_dword v139, v75, s[52:53] offset:128
	s_add_u32 s52, s52, 4096
	s_addc_u32 s53, s53, 0
	global_store_dword v139, v76, s[52:53]
	global_store_dword v139, v77, s[52:53] offset:128
	s_add_u32 s52, s52, 4096
	s_addc_u32 s53, s53, 0
	global_store_dword v139, v78, s[52:53]
	global_store_dword v139, v79, s[52:53] offset:128
	s_add_u32 s52, s52, 4096
	s_addc_u32 s53, s53, 0
	global_store_dword v139, v80, s[52:53]
	global_store_dword v139, v81, s[52:53] offset:128
	s_add_u32 s52, s52, 20480
	s_addc_u32 s53, s53, 0
	global_store_dword v139, v82, s[52:53]
	global_store_dword v139, v83, s[52:53] offset:128
	s_add_u32 s52, s52, 4096
	s_addc_u32 s53, s53, 0
	global_store_dword v139, v84, s[52:53]
	global_store_dword v139, v85, s[52:53] offset:128
	s_add_u32 s52, s52, 4096
	s_addc_u32 s53, s53, 0
	global_store_dword v139, v86, s[52:53]
	global_store_dword v139, v87, s[52:53] offset:128
	s_add_u32 s52, s52, 4096
	s_addc_u32 s53, s53, 0
	global_store_dword v139, v88, s[52:53]
	global_store_dword v139, v89, s[52:53] offset:128
	s_add_u32 s52, s52, 20480
	s_addc_u32 s53, s53, 0
	global_store_dword v139, v90, s[52:53]
	global_store_dword v139, v91, s[52:53] offset:128
	s_add_u32 s52, s52, 4096
	s_addc_u32 s53, s53, 0
	global_store_dword v139, v92, s[52:53]
	global_store_dword v139, v93, s[52:53] offset:128
	s_add_u32 s52, s52, 4096
	s_addc_u32 s53, s53, 0
	global_store_dword v139, v94, s[52:53]
	global_store_dword v139, v95, s[52:53] offset:128
	s_add_u32 s52, s52, 4096
	s_addc_u32 s53, s53, 0
	global_store_dword v139, v96, s[52:53]
	global_store_dword v139, v97, s[52:53] offset:128
	s_add_u32 s52, s52, 20480
	s_addc_u32 s53, s53, 0
	global_store_dword v139, v98, s[52:53]
	global_store_dword v139, v99, s[52:53] offset:128
	s_add_u32 s52, s52, 4096
	s_addc_u32 s53, s53, 0
	global_store_dword v139, v100, s[52:53]
	global_store_dword v139, v101, s[52:53] offset:128
	s_add_u32 s52, s52, 4096
	s_addc_u32 s53, s53, 0
	global_store_dword v139, v102, s[52:53]
	global_store_dword v139, v103, s[52:53] offset:128
	s_add_u32 s52, s52, 4096
	s_addc_u32 s53, s53, 0
	global_store_dword v139, v104, s[52:53]
	global_store_dword v139, v105, s[52:53] offset:128
	s_add_u32 s52, s52, 20480
	s_addc_u32 s53, s53, 0
	global_store_dword v139, v106, s[52:53]
	global_store_dword v139, v107, s[52:53] offset:128
	s_add_u32 s52, s52, 4096
	s_addc_u32 s53, s53, 0
	global_store_dword v139, v108, s[52:53]
	global_store_dword v139, v109, s[52:53] offset:128
	s_add_u32 s52, s52, 4096
	s_addc_u32 s53, s53, 0
	global_store_dword v139, v110, s[52:53]
	global_store_dword v139, v111, s[52:53] offset:128
	s_add_u32 s52, s52, 4096
	s_addc_u32 s53, s53, 0
	global_store_dword v139, v112, s[52:53]
	global_store_dword v139, v113, s[52:53] offset:128
	s_add_u32 s52, s52, 20480
	s_addc_u32 s53, s53, 0
	global_store_dword v139, v114, s[52:53]
	global_store_dword v139, v115, s[52:53] offset:128
	s_add_u32 s52, s52, 4096
	s_addc_u32 s53, s53, 0
	global_store_dword v139, v116, s[52:53]
	global_store_dword v139, v117, s[52:53] offset:128
	s_add_u32 s52, s52, 4096
	s_addc_u32 s53, s53, 0
	global_store_dword v139, v118, s[52:53]
	global_store_dword v139, v119, s[52:53] offset:128
	s_add_u32 s52, s52, 4096
	s_addc_u32 s53, s53, 0
	global_store_dword v139, v120, s[52:53]
	global_store_dword v139, v121, s[52:53] offset:128
	s_add_u32 s52, s52, 20480
	s_addc_u32 s53, s53, 0
	global_store_dword v139, v122, s[52:53]
	global_store_dword v139, v123, s[52:53] offset:128
	s_add_u32 s52, s52, 4096
	s_addc_u32 s53, s53, 0
	global_store_dword v139, v124, s[52:53]
	global_store_dword v139, v134, s[52:53] offset:128
	s_add_u32 s52, s52, 4096
	s_addc_u32 s53, s53, 0
	global_store_dword v139, v135, s[52:53]
	global_store_dword v139, v136, s[52:53] offset:128
	s_add_u32 s52, s52, 4096
	s_addc_u32 s53, s53, 0
	global_store_dword v139, v137, s[52:53]
	global_store_dword v139, v138, s[52:53] offset:128
	s_add_i32 s34, s34, s57
	s_add_i32 s29, s29, s64
	s_cmpk_lt_u32 s34, 0x400
	s_cbranch_scc1 .LBB0_1099
	v_readlane_b32 s28, v243, 45
	v_readlane_b32 s34, v243, 47
	v_readlane_b32 s29, v243, 46
	v_readlane_b32 s35, v243, 48

; #define MFMA(a, b, c) __builtin_amdgcn_mfma_f32_32x32x16_bf16((a), (b), (c), 0, 0, 0)
; #define TIDX opaque_tid()
; template <int AI, int BI>
; DI void gemm_tile(const u16* __restrict__ A, int lda, const u16* __restrict__ B, int ldb, int nk, bool swap,
;                   f32x16 (&acc)[AI][BI], char* lds) {
;   const int tid = TIDX, lane = tid & 63, wid = tid >> 6;
;   gemm_stage<AI, BI>(A, lda, B, ldb, lds, tid);
;   asm volatile("s_waitcnt vmcnt(0)" ::: "memory");
;   __syncthreads();
;   const int wa = wid >> 1, wb = wid & 1, r = lane & 31, h = lane >> 5, sw = (r >> 1) & 7;
;   const int offA = (swap ? 16384 : 0) + (wa * 32 * AI + r) * 128;
;   const int offB = (swap ? 0 : 16384) + (wb * 32 * BI + r) * 128;
;   for (int kt = 0; kt < nk; ++kt) {
;     const char* cur = lds + (kt & 1) * 32768;
;     if (kt + 1 < nk) gemm_stage<AI, BI>(A + (kt + 1) * 64, lda, B + (kt + 1) * 64, ldb, lds + ((kt + 1) & 1) * 32768, tid);
; #pragma unroll
;     for (int ks = 0; ks < 4; ++ks) {
;       const int co = ((ks * 2 + h) ^ sw) << 4;
;       s16x8 fa[AI], fb[BI];
; #pragma unroll
;       for (int i = 0; i < AI; ++i) fa[i] = *(const s16x8*)(cur + offA + i * 4096 + co);
; #pragma unroll
;       for (int i = 0; i < BI; ++i) fb[i] = *(const s16x8*)(cur + offB + i * 4096 + co);
; #pragma unroll
;       for (int i = 0; i < AI; ++i)
; #pragma unroll
;         for (int j = 0; j < BI; ++j) acc[i][j] = MFMA(fa[i], fb[j], acc[i][j]);
;     }
;     asm volatile("s_waitcnt vmcnt(0)" ::: "memory");
;     __syncthreads();
;   }
.LBB0_1103:
	s_lshr_b32 s16, s12, 4
	s_and_b32 s16, s16, 24
	s_and_b32 s17, s12, 7
	s_or_b32 s16, s16, s17
	s_lshl_b32 s16, s16, 6
	s_bitset1_b32 s16, 14
	v_mov_b32_e32 v26, v178
	v_mov_b32_e32 v27, v178
	v_mov_b32_e32 v8, v178
	s_and_b32 s17, s13, 0x3c0
	s_lshl_b32 s18, s16, 11
	s_add_u32 s28, s10, s18
	v_lshrrev_b32_e32 v0, 4, v8
	v_xor_b32_e32 v0, v0, v8
	v_add_u32_e32 v10, 0x100, v8
	s_addc_u32 s29, s11, 0
	s_lshl_b32 s18, s17, 11
	v_lshlrev_b32_e32 v0, 4, v0
	v_ashrrev_i32_e32 v4, 3, v8
	v_ashrrev_i32_e32 v6, 3, v10
	s_add_u32 s34, s14, s18
	v_and_b32_e32 v0, 0x70, v0
	v_ashrrev_i32_e32 v5, 31, v4
	v_ashrrev_i32_e32 v7, 31, v6
	s_addc_u32 s35, s15, 0
	v_lshl_add_u64 v[2:3], s[28:29], 0, v[0:1]
	v_lshlrev_b64 v[4:5], 11, v[4:5]
	v_lshlrev_b32_e32 v9, 4, v8
	v_lshlrev_b64 v[6:7], 11, v[6:7]
	v_lshl_add_u64 v[18:19], v[2:3], 0, v[4:5]
	v_lshl_add_u64 v[20:21], v[2:3], 0, v[6:7]
	v_lshlrev_b32_e32 v10, 4, v10
	v_lshl_add_u64 v[2:3], s[34:35], 0, v[0:1]
	v_add_u32_e32 v0, 0x4000, v9
	v_readfirstlane_b32 s18, v9
	v_readfirstlane_b32 s29, v0
	v_add_u32_e32 v0, 0x4000, v10
	v_lshl_add_u64 v[22:23], v[2:3], 0, v[4:5]
	v_lshl_add_u64 v[24:25], v[2:3], 0, v[6:7]
	v_readfirstlane_b32 s34, v0
	v_and_b32_e32 v0, 31, v8
	v_lshrrev_b32_e32 v2, 5, v8
	v_bfe_u32 v5, v8, 1, 3
	v_lshrrev_b32_e32 v6, 2, v8
	s_mov_b32 m0, s18
	v_readfirstlane_b32 s28, v10
	v_bfe_u32 v3, v8, 5, 1
	v_and_or_b32 v6, v6, s47, v0
	v_bitop3_b32 v2, v2, v5, 1 bitop3:0x6c
	global_load_lds_dwordx4 v[18:19], off
	s_mov_b32 m0, s28
	v_lshrrev_b32_e32 v4, 1, v8
	v_lshlrev_b32_e32 v36, 7, v6
	v_lshlrev_b32_e32 v6, 4, v2
	v_bitop3_b32 v2, v3, v5, 2 bitop3:0x36
	global_load_lds_dwordx4 v[20:21], off
	s_mov_b32 m0, s29
	v_and_or_b32 v0, v4, 32, v0
	v_lshlrev_b32_e32 v32, 4, v2
	v_bitop3_b32 v2, v3, v5, 4 bitop3:0x36
	v_add_u32_e32 v4, 0x8000, v9
	global_load_lds_dwordx4 v[22:23], off
	s_mov_b32 m0, s34
	v_lshlrev_b32_e32 v37, 4, v2
	v_bitop3_b32 v2, v3, v5, 6 bitop3:0x36
	v_readfirstlane_b32 s35, v4
	v_add_u32_e32 v4, 0x8000, v10
	global_load_lds_dwordx4 v[24:25], off
	v_lshlrev_b32_e32 v38, 4, v2
	v_lshl_add_u64 v[2:3], v[18:19], 0, s[50:51]
	s_mov_b32 m0, s35
	v_readfirstlane_b32 s36, v4
	v_add_u32_e32 v4, 0xc000, v9
	s_waitcnt vmcnt(0)
	s_waitcnt vmcnt(0) lgkmcnt(0)
	s_barrier
	global_load_lds_dwordx4 v[2:3], off
	v_lshl_add_u64 v[2:3], v[20:21], 0, s[50:51]
	s_mov_b32 m0, s36
	v_readfirstlane_b32 s37, v4
	v_add_u32_e32 v4, 0xc000, v10
	global_load_lds_dwordx4 v[2:3], off
	v_lshl_add_u64 v[2:3], v[22:23], 0, s[50:51]
	s_mov_b32 m0, s37
	v_readfirstlane_b32 s40, v4
	global_load_lds_dwordx4 v[2:3], off
	v_lshl_add_u64 v[2:3], v[24:25], 0, s[50:51]
	s_mov_b32 m0, s40
	v_or_b32_e32 v39, v36, v6
	global_load_lds_dwordx4 v[2:3], off
	ds_read_b128 v[2:5], v39
	v_lshlrev_b32_e32 v0, 7, v0
	v_or_b32_e32 v40, v0, v6
	ds_read_b128 v[6:9], v40 offset:16384
	v_or_b32_e32 v41, v36, v32
	ds_read_b128 v[28:31], v41
	s_waitcnt lgkmcnt(0)
	v_mfma_f32_32x32x16_bf16 v[2:17], v[2:5], v[6:9], 0
	v_or_b32_e32 v42, v0, v32
	ds_read_b128 v[32:35], v42 offset:16384
	v_or_b32_e32 v43, v36, v37
	v_or_b32_e32 v37, v0, v37
	v_or_b32_e32 v36, v36, v38
	v_or_b32_e32 v0, v0, v38
	s_mov_b32 m0, s18
	s_waitcnt lgkmcnt(0)
	v_mfma_f32_32x32x16_bf16 v[2:17], v[28:31], v[32:35], v[2:17]
	ds_read_b128 v[28:31], v43
	ds_read_b128 v[32:35], v37 offset:16384
	s_waitcnt lgkmcnt(0)
	v_mfma_f32_32x32x16_bf16 v[2:17], v[28:31], v[32:35], v[2:17]
	ds_read_b128 v[28:31], v36
	ds_read_b128 v[32:35], v0 offset:16384
	s_waitcnt lgkmcnt(0)
	v_mfma_f32_32x32x16_bf16 v[2:17], v[28:31], v[32:35], v[2:17]
	s_waitcnt vmcnt(0)
	s_barrier
	v_lshl_add_u64 v[28:29], v[18:19], 0, s[4:5]
	global_load_lds_dwordx4 v[28:29], off
	v_lshl_add_u64 v[28:29], v[20:21], 0, s[4:5]
	s_mov_b32 m0, s28
	s_nop 0
	global_load_lds_dwordx4 v[28:29], off
	v_lshl_add_u64 v[28:29], v[22:23], 0, s[4:5]
	s_mov_b32 m0, s29
	s_nop 0
	global_load_lds_dwordx4 v[28:29], off
	v_lshl_add_u64 v[28:29], v[24:25], 0, s[4:5]
	s_mov_b32 m0, s34
	s_nop 0
	global_load_lds_dwordx4 v[28:29], off
	ds_read_b128 v[28:31], v39 offset:32768
	ds_read_b128 v[32:35], v40 offset:49152
	s_waitcnt lgkmcnt(0)
	v_mfma_f32_32x32x16_bf16 v[2:17], v[28:31], v[32:35], v[2:17]
	ds_read_b128 v[28:31], v41 offset:32768
	ds_read_b128 v[32:35], v42 offset:49152
	s_mov_b32 m0, s35
	s_waitcnt lgkmcnt(0)
	v_mfma_f32_32x32x16_bf16 v[2:17], v[28:31], v[32:35], v[2:17]
	ds_read_b128 v[28:31], v43 offset:32768
	ds_read_b128 v[32:35], v37 offset:49152
	s_waitcnt lgkmcnt(0)
	v_mfma_f32_32x32x16_bf16 v[2:17], v[28:31], v[32:35], v[2:17]
	ds_read_b128 v[28:31], v36 offset:32768
	ds_read_b128 v[32:35], v0 offset:49152
	s_waitcnt lgkmcnt(0)
	v_mfma_f32_32x32x16_bf16 v[2:17], v[28:31], v[32:35], v[2:17]
	s_waitcnt vmcnt(0)
	s_barrier
	v_lshl_add_u64 v[28:29], v[18:19], 0, s[52:53]
	global_load_lds_dwordx4 v[28:29], off
	v_lshl_add_u64 v[28:29], v[20:21], 0, s[52:53]
	s_mov_b32 m0, s36
	s_nop 0
	global_load_lds_dwordx4 v[28:29], off
	v_lshl_add_u64 v[28:29], v[22:23], 0, s[52:53]
	s_mov_b32 m0, s37
	s_nop 0
	global_load_lds_dwordx4 v[28:29], off
	v_lshl_add_u64 v[28:29], v[24:25], 0, s[52:53]
	s_mov_b32 m0, s40
	s_nop 0
	global_load_lds_dwordx4 v[28:29], off
	ds_read_b128 v[28:31], v39
	ds_read_b128 v[32:35], v40 offset:16384
	s_waitcnt lgkmcnt(0)
	v_mfma_f32_32x32x16_bf16 v[2:17], v[28:31], v[32:35], v[2:17]
	ds_read_b128 v[28:31], v41
	ds_read_b128 v[32:35], v42 offset:16384
	s_mov_b32 m0, s18
	s_waitcnt lgkmcnt(0)
	v_mfma_f32_32x32x16_bf16 v[2:17], v[28:31], v[32:35], v[2:17]
	ds_read_b128 v[28:31], v43
	ds_read_b128 v[32:35], v37 offset:16384
	s_waitcnt lgkmcnt(0)
	v_mfma_f32_32x32x16_bf16 v[2:17], v[28:31], v[32:35], v[2:17]
	ds_read_b128 v[28:31], v36
	ds_read_b128 v[32:35], v0 offset:16384
	s_waitcnt lgkmcnt(0)
	v_mfma_f32_32x32x16_bf16 v[2:17], v[28:31], v[32:35], v[2:17]
	s_waitcnt vmcnt(0)
	s_barrier
; #define MFMA(a, b, c) __builtin_amdgcn_mfma_f32_32x32x16_bf16((a), (b), (c), 0, 0, 0)
; template <int AI, int BI>
; DI void gemm_tile(const u16* __restrict__ A, int lda, const u16* __restrict__ B, int ldb, int nk, bool swap,
;                   f32x16 (&acc)[AI][BI], char* lds) {
;     ...
;   for (int kt = 0; kt < nk; ++kt) {
;     const char* cur = lds + (kt & 1) * 32768;
;     if (kt + 1 < nk) gemm_stage<AI, BI>(A + (kt + 1) * 64, lda, B + (kt + 1) * 64, ldb, lds + ((kt + 1) & 1) * 32768, tid);
; #pragma unroll
;     for (int ks = 0; ks < 4; ++ks) {
;       const int co = ((ks * 2 + h) ^ sw) << 4;
;       s16x8 fa[AI], fb[BI];
; #pragma unroll
;       for (int i = 0; i < AI; ++i) fa[i] = *(const s16x8*)(cur + offA + i * 4096 + co);
; #pragma unroll
;       for (int i = 0; i < BI; ++i) fb[i] = *(const s16x8*)(cur + offB + i * 4096 + co);
; #pragma unroll
;       for (int i = 0; i < AI; ++i)
; #pragma unroll
;         for (int j = 0; j < BI; ++j) acc[i][j] = MFMA(fa[i], fb[j], acc[i][j]);
;     }
;     asm volatile("s_waitcnt vmcnt(0)" ::: "memory");
;     __syncthreads();
;   }
	v_lshl_add_u64 v[28:29], v[18:19], 0, s[48:49]
	global_load_lds_dwordx4 v[28:29], off
	v_lshl_add_u64 v[28:29], v[20:21], 0, s[48:49]
	s_mov_b32 m0, s28
	s_nop 0
	global_load_lds_dwordx4 v[28:29], off
	v_lshl_add_u64 v[28:29], v[22:23], 0, s[48:49]
	s_mov_b32 m0, s29
	s_nop 0
	global_load_lds_dwordx4 v[28:29], off
	v_lshl_add_u64 v[28:29], v[24:25], 0, s[48:49]
	s_mov_b32 m0, s34
	s_nop 0
	global_load_lds_dwordx4 v[28:29], off
	ds_read_b128 v[28:31], v39 offset:32768
	ds_read_b128 v[32:35], v40 offset:49152
	s_waitcnt lgkmcnt(0)
	v_mfma_f32_32x32x16_bf16 v[2:17], v[28:31], v[32:35], v[2:17]
	ds_read_b128 v[28:31], v41 offset:32768
	ds_read_b128 v[32:35], v42 offset:49152
	s_mov_b32 m0, s35
	s_waitcnt lgkmcnt(0)
	v_mfma_f32_32x32x16_bf16 v[2:17], v[28:31], v[32:35], v[2:17]
	ds_read_b128 v[28:31], v43 offset:32768
	ds_read_b128 v[32:35], v37 offset:49152
	s_waitcnt lgkmcnt(0)
	v_mfma_f32_32x32x16_bf16 v[2:17], v[28:31], v[32:35], v[2:17]
	ds_read_b128 v[28:31], v36 offset:32768
	ds_read_b128 v[32:35], v0 offset:49152
	s_waitcnt lgkmcnt(0)
	v_mfma_f32_32x32x16_bf16 v[2:17], v[28:31], v[32:35], v[2:17]
	s_waitcnt vmcnt(0)
	s_barrier
	v_lshl_add_u64 v[28:29], v[18:19], 0, s[56:57]
	global_load_lds_dwordx4 v[28:29], off
	v_lshl_add_u64 v[28:29], v[20:21], 0, s[56:57]
	s_mov_b32 m0, s36
	s_nop 0
	global_load_lds_dwordx4 v[28:29], off
	v_lshl_add_u64 v[28:29], v[22:23], 0, s[56:57]
	s_mov_b32 m0, s37
	s_nop 0
	global_load_lds_dwordx4 v[28:29], off
	v_lshl_add_u64 v[28:29], v[24:25], 0, s[56:57]
	s_mov_b32 m0, s40
	s_nop 0
	global_load_lds_dwordx4 v[28:29], off
	ds_read_b128 v[28:31], v39
	ds_read_b128 v[32:35], v40 offset:16384
	s_waitcnt lgkmcnt(0)
	v_mfma_f32_32x32x16_bf16 v[2:17], v[28:31], v[32:35], v[2:17]
	ds_read_b128 v[28:31], v41
	ds_read_b128 v[32:35], v42 offset:16384
	s_mov_b32 m0, s18
	s_waitcnt lgkmcnt(0)
	v_mfma_f32_32x32x16_bf16 v[2:17], v[28:31], v[32:35], v[2:17]
	ds_read_b128 v[28:31], v43
	ds_read_b128 v[32:35], v37 offset:16384
	s_waitcnt lgkmcnt(0)
	v_mfma_f32_32x32x16_bf16 v[2:17], v[28:31], v[32:35], v[2:17]
	ds_read_b128 v[28:31], v36
	ds_read_b128 v[32:35], v0 offset:16384
	s_waitcnt lgkmcnt(0)
	v_mfma_f32_32x32x16_bf16 v[2:17], v[28:31], v[32:35], v[2:17]
	s_waitcnt vmcnt(0)
	s_barrier
	v_lshl_add_u64 v[28:29], v[18:19], 0, s[64:65]
	global_load_lds_dwordx4 v[28:29], off
	v_lshl_add_u64 v[28:29], v[20:21], 0, s[64:65]
	s_mov_b32 m0, s28
	s_nop 0
	global_load_lds_dwordx4 v[28:29], off
	v_lshl_add_u64 v[28:29], v[22:23], 0, s[64:65]
	s_mov_b32 m0, s29
	s_nop 0
	global_load_lds_dwordx4 v[28:29], off
	v_lshl_add_u64 v[28:29], v[24:25], 0, s[64:65]
	s_mov_b32 m0, s34
	s_nop 0
	global_load_lds_dwordx4 v[28:29], off
	ds_read_b128 v[28:31], v39 offset:32768
	ds_read_b128 v[32:35], v40 offset:49152
	s_waitcnt lgkmcnt(0)
	v_mfma_f32_32x32x16_bf16 v[2:17], v[28:31], v[32:35], v[2:17]
	ds_read_b128 v[28:31], v41 offset:32768
	ds_read_b128 v[32:35], v42 offset:49152
	s_mov_b32 m0, s35
	s_waitcnt lgkmcnt(0)
	v_mfma_f32_32x32x16_bf16 v[2:17], v[28:31], v[32:35], v[2:17]
	ds_read_b128 v[28:31], v43 offset:32768
	ds_read_b128 v[32:35], v37 offset:49152
	s_waitcnt lgkmcnt(0)
	v_mfma_f32_32x32x16_bf16 v[2:17], v[28:31], v[32:35], v[2:17]
	ds_read_b128 v[28:31], v36 offset:32768
	ds_read_b128 v[32:35], v0 offset:49152
	s_waitcnt lgkmcnt(0)
	v_mfma_f32_32x32x16_bf16 v[2:17], v[28:31], v[32:35], v[2:17]
	s_waitcnt vmcnt(0)
	s_barrier
	v_lshl_add_u64 v[28:29], v[18:19], 0, s[66:67]
	global_load_lds_dwordx4 v[28:29], off
	v_lshl_add_u64 v[28:29], v[20:21], 0, s[66:67]
	s_mov_b32 m0, s36
	s_nop 0
	global_load_lds_dwordx4 v[28:29], off
	v_lshl_add_u64 v[28:29], v[22:23], 0, s[66:67]
	s_mov_b32 m0, s37
	s_nop 0
	global_load_lds_dwordx4 v[28:29], off
	v_lshl_add_u64 v[28:29], v[24:25], 0, s[66:67]
	s_mov_b32 m0, s40
	s_nop 0
	global_load_lds_dwordx4 v[28:29], off
	ds_read_b128 v[28:31], v39
	ds_read_b128 v[32:35], v40 offset:16384
	s_waitcnt lgkmcnt(0)
	v_mfma_f32_32x32x16_bf16 v[2:17], v[28:31], v[32:35], v[2:17]
	ds_read_b128 v[28:31], v41
	ds_read_b128 v[32:35], v42 offset:16384
	s_mov_b32 m0, s18
	s_waitcnt lgkmcnt(0)
	v_mfma_f32_32x32x16_bf16 v[2:17], v[28:31], v[32:35], v[2:17]
	ds_read_b128 v[28:31], v43
	ds_read_b128 v[32:35], v37 offset:16384
	s_waitcnt lgkmcnt(0)
	v_mfma_f32_32x32x16_bf16 v[2:17], v[28:31], v[32:35], v[2:17]
	ds_read_b128 v[28:31], v36
	ds_read_b128 v[32:35], v0 offset:16384
	s_waitcnt lgkmcnt(0)
	v_mfma_f32_32x32x16_bf16 v[2:17], v[28:31], v[32:35], v[2:17]
	s_waitcnt vmcnt(0)
	s_barrier
	v_lshl_add_u64 v[28:29], v[18:19], 0, s[68:69]
	global_load_lds_dwordx4 v[28:29], off
	v_lshl_add_u64 v[28:29], v[20:21], 0, s[68:69]
	s_mov_b32 m0, s28
	s_nop 0
	global_load_lds_dwordx4 v[28:29], off
	v_lshl_add_u64 v[28:29], v[22:23], 0, s[68:69]
	s_mov_b32 m0, s29
	s_nop 0
	global_load_lds_dwordx4 v[28:29], off
	v_lshl_add_u64 v[28:29], v[24:25], 0, s[68:69]
	s_mov_b32 m0, s34
	s_nop 0
	global_load_lds_dwordx4 v[28:29], off
	ds_read_b128 v[28:31], v39 offset:32768
	ds_read_b128 v[32:35], v40 offset:49152
	s_waitcnt lgkmcnt(0)
	v_mfma_f32_32x32x16_bf16 v[2:17], v[28:31], v[32:35], v[2:17]
	ds_read_b128 v[28:31], v41 offset:32768
	ds_read_b128 v[32:35], v42 offset:49152
	s_mov_b32 m0, s35
	s_waitcnt lgkmcnt(0)
	v_mfma_f32_32x32x16_bf16 v[2:17], v[28:31], v[32:35], v[2:17]
	ds_read_b128 v[28:31], v43 offset:32768
	ds_read_b128 v[32:35], v37 offset:49152
	s_waitcnt lgkmcnt(0)
	v_mfma_f32_32x32x16_bf16 v[2:17], v[28:31], v[32:35], v[2:17]
	ds_read_b128 v[28:31], v36 offset:32768
	ds_read_b128 v[32:35], v0 offset:49152
	s_waitcnt lgkmcnt(0)
	v_mfma_f32_32x32x16_bf16 v[2:17], v[28:31], v[32:35], v[2:17]
	s_waitcnt vmcnt(0)
	s_barrier
; #define MFMA(a, b, c) __builtin_amdgcn_mfma_f32_32x32x16_bf16((a), (b), (c), 0, 0, 0)
; template <int AI, int BI>
; DI void gemm_tile(const u16* __restrict__ A, int lda, const u16* __restrict__ B, int ldb, int nk, bool swap,
;                   f32x16 (&acc)[AI][BI], char* lds) {
;     ...
;   for (int kt = 0; kt < nk; ++kt) {
;     const char* cur = lds + (kt & 1) * 32768;
;     if (kt + 1 < nk) gemm_stage<AI, BI>(A + (kt + 1) * 64, lda, B + (kt + 1) * 64, ldb, lds + ((kt + 1) & 1) * 32768, tid);
; #pragma unroll
;     for (int ks = 0; ks < 4; ++ks) {
;       const int co = ((ks * 2 + h) ^ sw) << 4;
;       s16x8 fa[AI], fb[BI];
; #pragma unroll
;       for (int i = 0; i < AI; ++i) fa[i] = *(const s16x8*)(cur + offA + i * 4096 + co);
; #pragma unroll
;       for (int i = 0; i < BI; ++i) fb[i] = *(const s16x8*)(cur + offB + i * 4096 + co);
; #pragma unroll
;       for (int i = 0; i < AI; ++i)
; #pragma unroll
;         for (int j = 0; j < BI; ++j) acc[i][j] = MFMA(fa[i], fb[j], acc[i][j]);
;     }
;     asm volatile("s_waitcnt vmcnt(0)" ::: "memory");
;     __syncthreads();
;   }
	v_lshl_add_u64 v[28:29], v[18:19], 0, s[70:71]
	global_load_lds_dwordx4 v[28:29], off
	v_lshl_add_u64 v[28:29], v[20:21], 0, s[70:71]
	s_mov_b32 m0, s36
	s_nop 0
	global_load_lds_dwordx4 v[28:29], off
	v_lshl_add_u64 v[28:29], v[22:23], 0, s[70:71]
	s_mov_b32 m0, s37
	s_nop 0
	global_load_lds_dwordx4 v[28:29], off
	v_lshl_add_u64 v[28:29], v[24:25], 0, s[70:71]
	s_mov_b32 m0, s40
	s_nop 0
	global_load_lds_dwordx4 v[28:29], off
	ds_read_b128 v[28:31], v39
	ds_read_b128 v[32:35], v40 offset:16384
	s_waitcnt lgkmcnt(0)
	v_mfma_f32_32x32x16_bf16 v[2:17], v[28:31], v[32:35], v[2:17]
	ds_read_b128 v[28:31], v41
	ds_read_b128 v[32:35], v42 offset:16384
	s_mov_b32 m0, s18
	s_waitcnt lgkmcnt(0)
	v_mfma_f32_32x32x16_bf16 v[2:17], v[28:31], v[32:35], v[2:17]
	ds_read_b128 v[28:31], v43
	ds_read_b128 v[32:35], v37 offset:16384
	s_waitcnt lgkmcnt(0)
	v_mfma_f32_32x32x16_bf16 v[2:17], v[28:31], v[32:35], v[2:17]
	ds_read_b128 v[28:31], v36
	ds_read_b128 v[32:35], v0 offset:16384
	s_waitcnt lgkmcnt(0)
	v_mfma_f32_32x32x16_bf16 v[2:17], v[28:31], v[32:35], v[2:17]
	s_waitcnt vmcnt(0)
	s_barrier
	v_lshl_add_u64 v[28:29], v[18:19], 0, s[72:73]
	global_load_lds_dwordx4 v[28:29], off
	v_lshl_add_u64 v[28:29], v[20:21], 0, s[72:73]
	s_mov_b32 m0, s28
	s_nop 0
	global_load_lds_dwordx4 v[28:29], off
	v_lshl_add_u64 v[28:29], v[22:23], 0, s[72:73]
	s_mov_b32 m0, s29
	s_nop 0
	global_load_lds_dwordx4 v[28:29], off
	v_lshl_add_u64 v[28:29], v[24:25], 0, s[72:73]
	s_mov_b32 m0, s34
	s_nop 0
	global_load_lds_dwordx4 v[28:29], off
	ds_read_b128 v[28:31], v39 offset:32768
	ds_read_b128 v[32:35], v40 offset:49152
	s_waitcnt lgkmcnt(0)
	v_mfma_f32_32x32x16_bf16 v[2:17], v[28:31], v[32:35], v[2:17]
	ds_read_b128 v[28:31], v41 offset:32768
	ds_read_b128 v[32:35], v42 offset:49152
	s_mov_b32 m0, s35
	s_waitcnt lgkmcnt(0)
	v_mfma_f32_32x32x16_bf16 v[2:17], v[28:31], v[32:35], v[2:17]
	ds_read_b128 v[28:31], v43 offset:32768
	ds_read_b128 v[32:35], v37 offset:49152
	s_waitcnt lgkmcnt(0)
	v_mfma_f32_32x32x16_bf16 v[2:17], v[28:31], v[32:35], v[2:17]
	ds_read_b128 v[28:31], v36 offset:32768
	ds_read_b128 v[32:35], v0 offset:49152
	s_waitcnt lgkmcnt(0)
	v_mfma_f32_32x32x16_bf16 v[2:17], v[28:31], v[32:35], v[2:17]
	s_waitcnt vmcnt(0)
	s_barrier
	v_lshl_add_u64 v[28:29], v[18:19], 0, s[74:75]
	global_load_lds_dwordx4 v[28:29], off
	v_lshl_add_u64 v[28:29], v[20:21], 0, s[74:75]
	s_mov_b32 m0, s36
	s_nop 0
	global_load_lds_dwordx4 v[28:29], off
	v_lshl_add_u64 v[28:29], v[22:23], 0, s[74:75]
	s_mov_b32 m0, s37
	s_nop 0
	global_load_lds_dwordx4 v[28:29], off
	v_lshl_add_u64 v[28:29], v[24:25], 0, s[74:75]
	s_mov_b32 m0, s40
	s_nop 0
	global_load_lds_dwordx4 v[28:29], off
	ds_read_b128 v[28:31], v39
	ds_read_b128 v[32:35], v40 offset:16384
	s_waitcnt lgkmcnt(0)
	v_mfma_f32_32x32x16_bf16 v[2:17], v[28:31], v[32:35], v[2:17]
	ds_read_b128 v[28:31], v41
	ds_read_b128 v[32:35], v42 offset:16384
	s_mov_b32 m0, s18
	s_waitcnt lgkmcnt(0)
	v_mfma_f32_32x32x16_bf16 v[2:17], v[28:31], v[32:35], v[2:17]
	ds_read_b128 v[28:31], v43
	ds_read_b128 v[32:35], v37 offset:16384
	s_waitcnt lgkmcnt(0)
	v_mfma_f32_32x32x16_bf16 v[2:17], v[28:31], v[32:35], v[2:17]
	ds_read_b128 v[28:31], v36
	ds_read_b128 v[32:35], v0 offset:16384
	s_waitcnt lgkmcnt(0)
	v_mfma_f32_32x32x16_bf16 v[2:17], v[28:31], v[32:35], v[2:17]
	s_waitcnt vmcnt(0)
	s_barrier
	v_lshl_add_u64 v[28:29], v[18:19], 0, s[76:77]
	global_load_lds_dwordx4 v[28:29], off
	v_lshl_add_u64 v[28:29], v[20:21], 0, s[76:77]
	s_mov_b32 m0, s28
	s_nop 0
	global_load_lds_dwordx4 v[28:29], off
	v_lshl_add_u64 v[28:29], v[22:23], 0, s[76:77]
	s_mov_b32 m0, s29
	s_nop 0
	global_load_lds_dwordx4 v[28:29], off
	v_lshl_add_u64 v[28:29], v[24:25], 0, s[76:77]
	s_mov_b32 m0, s34
	s_nop 0
	global_load_lds_dwordx4 v[28:29], off
	ds_read_b128 v[28:31], v39 offset:32768
	ds_read_b128 v[32:35], v40 offset:49152
	s_waitcnt lgkmcnt(0)
	v_mfma_f32_32x32x16_bf16 v[2:17], v[28:31], v[32:35], v[2:17]
	ds_read_b128 v[28:31], v41 offset:32768
	ds_read_b128 v[32:35], v42 offset:49152
	s_mov_b32 m0, s35
	s_waitcnt lgkmcnt(0)
	v_mfma_f32_32x32x16_bf16 v[2:17], v[28:31], v[32:35], v[2:17]
	ds_read_b128 v[28:31], v43 offset:32768
	ds_read_b128 v[32:35], v37 offset:49152
	s_waitcnt lgkmcnt(0)
	v_mfma_f32_32x32x16_bf16 v[2:17], v[28:31], v[32:35], v[2:17]
	ds_read_b128 v[28:31], v36 offset:32768
	ds_read_b128 v[32:35], v0 offset:49152
	s_waitcnt lgkmcnt(0)
	v_mfma_f32_32x32x16_bf16 v[2:17], v[28:31], v[32:35], v[2:17]
	s_waitcnt vmcnt(0)
	s_barrier
	v_lshl_add_u64 v[28:29], v[18:19], 0, s[78:79]
	global_load_lds_dwordx4 v[28:29], off
	v_lshl_add_u64 v[28:29], v[20:21], 0, s[78:79]
	s_mov_b32 m0, s36
	s_nop 0
	global_load_lds_dwordx4 v[28:29], off
	v_lshl_add_u64 v[28:29], v[22:23], 0, s[78:79]
	s_mov_b32 m0, s37
	s_nop 0
	global_load_lds_dwordx4 v[28:29], off
	v_lshl_add_u64 v[28:29], v[24:25], 0, s[78:79]
	s_mov_b32 m0, s40
	s_nop 0
	global_load_lds_dwordx4 v[28:29], off
	ds_read_b128 v[28:31], v39
	ds_read_b128 v[32:35], v40 offset:16384
	s_waitcnt lgkmcnt(0)
	v_mfma_f32_32x32x16_bf16 v[2:17], v[28:31], v[32:35], v[2:17]
	ds_read_b128 v[28:31], v41
	ds_read_b128 v[32:35], v42 offset:16384
	s_mov_b32 m0, s18
	s_waitcnt lgkmcnt(0)
	v_mfma_f32_32x32x16_bf16 v[2:17], v[28:31], v[32:35], v[2:17]
	ds_read_b128 v[28:31], v43
	ds_read_b128 v[32:35], v37 offset:16384
	s_waitcnt lgkmcnt(0)
	v_mfma_f32_32x32x16_bf16 v[2:17], v[28:31], v[32:35], v[2:17]
	ds_read_b128 v[28:31], v36
	ds_read_b128 v[32:35], v0 offset:16384
	s_waitcnt lgkmcnt(0)
	v_mfma_f32_32x32x16_bf16 v[2:17], v[28:31], v[32:35], v[2:17]
	s_waitcnt vmcnt(0)
	s_barrier
; #define MFMA(a, b, c) __builtin_amdgcn_mfma_f32_32x32x16_bf16((a), (b), (c), 0, 0, 0)
; #define GAS __attribute__((address_space(1)))
; DI int opaque0() { int z = 0; asm volatile("" : "+v"(z)); return z; }
; template <int AI, int BI>
; DI void gemm_tile(const u16* __restrict__ A, int lda, const u16* __restrict__ B, int ldb, int nk, bool swap,
;                   f32x16 (&acc)[AI][BI], char* lds) {
;     ...
;   for (int kt = 0; kt < nk; ++kt) {
;     const char* cur = lds + (kt & 1) * 32768;
;     if (kt + 1 < nk) gemm_stage<AI, BI>(A + (kt + 1) * 64, lda, B + (kt + 1) * 64, ldb, lds + ((kt + 1) & 1) * 32768, tid);
; #pragma unroll
;     for (int ks = 0; ks < 4; ++ks) {
;       const int co = ((ks * 2 + h) ^ sw) << 4;
;       s16x8 fa[AI], fb[BI];
; #pragma unroll
;       for (int i = 0; i < AI; ++i) fa[i] = *(const s16x8*)(cur + offA + i * 4096 + co);
; #pragma unroll
;       for (int i = 0; i < BI; ++i) fb[i] = *(const s16x8*)(cur + offB + i * 4096 + co);
; #pragma unroll
;       for (int i = 0; i < AI; ++i)
; #pragma unroll
;         for (int j = 0; j < BI; ++j) acc[i][j] = MFMA(fa[i], fb[j], acc[i][j]);
;     }
;     asm volatile("s_waitcnt vmcnt(0)" ::: "memory");
;     __syncthreads();
;   }
; template <int AI, int BI>
; DI void m2_tile(char* wsb, int layer, int m0, int n0, char* lds) {
;     ...
;   const int m0e = m0 + opaque0();
;   const int mr = m0 < TL ? (m0 >> 11) : 8;
;   const float* gate = mods + (size_t)mr * 9216 + 5 * 1024;
;   GAS float* xsu = uptr(xs);
; #pragma unroll
;   for (int bi = 0; bi < BI; ++bi) {
;     const int n = n0 + wb * 32 * BI + bi * 32 + r;
;     const float gv = gate[n];
;     const unsigned ib = (unsigned)((m0e + wa * 32 * AI + 4 * h) * 1024 + n);
; #pragma unroll
;     for (int ai = 0; ai < AI; ++ai)
; #pragma unroll
;       for (int reg = 0; reg < 16; ++reg) {
;         const unsigned idx = ib + (unsigned)((ai * 32 + (reg & 3) + 8 * (reg >> 2)) * 1024);
;         xsu[idx] += gv * acc[ai][bi][reg];
;         if ((reg & 7) == 7) __builtin_amdgcn_sched_barrier(0);
;       }
;   }
; }
; DI void phase_m2(const Params& p, char* wsb, int layer, int mrows, char* lds) {
;   int mt, nt;
;   for (int rnd = 0; next_tile(rnd, 128, 8, mt, nt); ++rnd) m2_tile<2, 2>(wsb, layer, mt * 128, nt * 128, lds);
;   if (mrows > TL)
;     for (int rnd = 0; next_tile(rnd, 32, 16, mt, nt); ++rnd) m2_tile<1, 1>(wsb, layer, TL + mt * 64, nt * 64, lds);
	v_lshl_add_u64 v[28:29], v[18:19], 0, s[2:3]
	global_load_lds_dwordx4 v[28:29], off
	v_lshl_add_u64 v[28:29], v[20:21], 0, s[2:3]
	s_mov_b32 m0, s28
	v_lshl_add_u64 v[18:19], v[18:19], 0, s[30:31]
	global_load_lds_dwordx4 v[28:29], off
	v_lshl_add_u64 v[28:29], v[22:23], 0, s[2:3]
	s_mov_b32 m0, s29
	s_nop 0
	global_load_lds_dwordx4 v[28:29], off
	v_lshl_add_u64 v[28:29], v[24:25], 0, s[2:3]
	s_mov_b32 m0, s34
	s_nop 0
	global_load_lds_dwordx4 v[28:29], off
	ds_read_b128 v[28:31], v39 offset:32768
	ds_read_b128 v[32:35], v40 offset:49152
	s_waitcnt lgkmcnt(0)
	v_mfma_f32_32x32x16_bf16 v[2:17], v[28:31], v[32:35], v[2:17]
	ds_read_b128 v[28:31], v41 offset:32768
	ds_read_b128 v[32:35], v42 offset:49152
	s_mov_b32 m0, s35
	s_waitcnt lgkmcnt(0)
	v_mfma_f32_32x32x16_bf16 v[2:17], v[28:31], v[32:35], v[2:17]
	ds_read_b128 v[28:31], v43 offset:32768
	ds_read_b128 v[32:35], v37 offset:49152
	s_waitcnt lgkmcnt(0)
	v_mfma_f32_32x32x16_bf16 v[2:17], v[28:31], v[32:35], v[2:17]
	ds_read_b128 v[28:31], v36 offset:32768
	ds_read_b128 v[32:35], v0 offset:49152
	s_waitcnt vmcnt(0)
	s_waitcnt lgkmcnt(0)
	s_barrier
	global_load_lds_dwordx4 v[18:19], off
	v_lshl_add_u64 v[18:19], v[20:21], 0, s[30:31]
	s_mov_b32 m0, s36
	v_mfma_f32_32x32x16_bf16 v[2:17], v[28:31], v[32:35], v[2:17]
	global_load_lds_dwordx4 v[18:19], off
	v_lshl_add_u64 v[18:19], v[22:23], 0, s[30:31]
	s_mov_b32 m0, s37
	v_and_b32_e32 v28, 31, v26
	global_load_lds_dwordx4 v[18:19], off
	v_lshl_add_u64 v[18:19], v[24:25], 0, s[30:31]
	s_mov_b32 m0, s40
	s_nop 0
	global_load_lds_dwordx4 v[18:19], off
	ds_read_b128 v[18:21], v39
	ds_read_b128 v[22:25], v40 offset:16384
	s_waitcnt lgkmcnt(0)
	v_mfma_f32_32x32x16_bf16 v[2:17], v[18:21], v[22:25], v[2:17]
	ds_read_b128 v[18:21], v41
	ds_read_b128 v[22:25], v42 offset:16384
	s_waitcnt lgkmcnt(0)
	v_mfma_f32_32x32x16_bf16 v[2:17], v[18:21], v[22:25], v[2:17]
	ds_read_b128 v[18:21], v43
	ds_read_b128 v[22:25], v37 offset:16384
	s_waitcnt lgkmcnt(0)
	v_mfma_f32_32x32x16_bf16 v[2:17], v[18:21], v[22:25], v[2:17]
	ds_read_b128 v[18:21], v36
	ds_read_b128 v[22:25], v0 offset:16384
	s_waitcnt lgkmcnt(0)
	v_mfma_f32_32x32x16_bf16 v[2:17], v[18:21], v[22:25], v[2:17]
	s_waitcnt vmcnt(0)
	s_barrier
	ds_read_b128 v[18:21], v39 offset:32768
	ds_read_b128 v[22:25], v40 offset:49152
	s_waitcnt lgkmcnt(0)
	v_mfma_f32_32x32x16_bf16 v[2:17], v[18:21], v[22:25], v[2:17]
	ds_read_b128 v[18:21], v41 offset:32768
	ds_read_b128 v[22:25], v42 offset:49152
	s_waitcnt lgkmcnt(0)
	v_mfma_f32_32x32x16_bf16 v[2:17], v[18:21], v[22:25], v[2:17]
	ds_read_b128 v[18:21], v43 offset:32768
	ds_read_b128 v[22:25], v37 offset:49152
	s_waitcnt lgkmcnt(0)
	v_mfma_f32_32x32x16_bf16 v[2:17], v[18:21], v[22:25], v[2:17]
	ds_read_b128 v[18:21], v36 offset:32768
	ds_read_b128 v[22:25], v0 offset:49152
	v_mov_b32_e32 v0, v1
	s_waitcnt vmcnt(0)
	s_waitcnt lgkmcnt(0)
	s_barrier
	v_mfma_f32_32x32x16_bf16 v[2:17], v[18:21], v[22:25], v[2:17]
	v_lshrrev_b32_e32 v18, 1, v27
	v_lshrrev_b32_e32 v20, 2, v27
	v_lshrrev_b32_e32 v21, 3, v26
	v_and_b32_e32 v18, 32, v18
	v_and_b32_e32 v20, 0x3fffe0, v20
	v_and_or_b32 v21, v21, 4, s16
	v_or3_b32 v18, v28, v18, s17
	v_add3_u32 v0, v21, v20, v0
	v_lshlrev_b32_e32 v19, 2, v18
	v_lshl_or_b32 v0, v0, 10, v18
	global_load_dword v20, v19, s[8:9]
	v_lshl_add_u64 v[18:19], v[0:1], 2, s[6:7]
	global_load_dword v21, v[18:19], off
	s_waitcnt vmcnt(0)
	v_fmac_f32_e32 v21, v2, v20
	global_store_dword v[18:19], v21, off
	v_add_u32_e32 v18, 0x400, v0
	v_mov_b32_e32 v19, v1
	v_lshl_add_u64 v[18:19], v[18:19], 2, s[6:7]
	global_load_dword v2, v[18:19], off
	s_waitcnt vmcnt(0)
	v_fmac_f32_e32 v2, v3, v20
	global_store_dword v[18:19], v2, off
	v_add_u32_e32 v2, 0x800, v0
	v_mov_b32_e32 v3, v1
	v_lshl_add_u64 v[2:3], v[2:3], 2, s[6:7]
	global_load_dword v18, v[2:3], off
	s_waitcnt vmcnt(0)
	v_fmac_f32_e32 v18, v4, v20
	global_store_dword v[2:3], v18, off
	v_add_u32_e32 v2, 0xc00, v0
	v_mov_b32_e32 v3, v1
	v_lshl_add_u64 v[2:3], v[2:3], 2, s[6:7]
	global_load_dword v4, v[2:3], off
	s_waitcnt vmcnt(0)
	v_fmac_f32_e32 v4, v5, v20
	global_store_dword v[2:3], v4, off
	v_add_u32_e32 v2, 0x2000, v0
	v_mov_b32_e32 v3, v1
	v_lshl_add_u64 v[2:3], v[2:3], 2, s[6:7]
	global_load_dword v4, v[2:3], off
	s_waitcnt vmcnt(0)
	v_fmac_f32_e32 v4, v6, v20
	global_store_dword v[2:3], v4, off
	v_add_u32_e32 v2, 0x2400, v0
	v_mov_b32_e32 v3, v1
	v_lshl_add_u64 v[2:3], v[2:3], 2, s[6:7]
	global_load_dword v4, v[2:3], off
	s_waitcnt vmcnt(0)
	v_fmac_f32_e32 v4, v7, v20
	global_store_dword v[2:3], v4, off
	v_add_u32_e32 v2, 0x2800, v0
	v_mov_b32_e32 v3, v1
	v_lshl_add_u64 v[2:3], v[2:3], 2, s[6:7]
	global_load_dword v4, v[2:3], off
	s_waitcnt vmcnt(0)
	v_fmac_f32_e32 v4, v8, v20
	global_store_dword v[2:3], v4, off
	v_add_u32_e32 v2, 0x2c00, v0
	v_mov_b32_e32 v3, v1
	v_lshl_add_u64 v[2:3], v[2:3], 2, s[6:7]
	global_load_dword v4, v[2:3], off
	s_waitcnt vmcnt(0)
	v_fmac_f32_e32 v4, v9, v20
	global_store_dword v[2:3], v4, off
	v_add_u32_e32 v2, 0x4000, v0
	v_mov_b32_e32 v3, v1
	v_lshl_add_u64 v[2:3], v[2:3], 2, s[6:7]
	global_load_dword v4, v[2:3], off
	s_waitcnt vmcnt(0)
	v_fmac_f32_e32 v4, v10, v20
	global_store_dword v[2:3], v4, off
	v_add_u32_e32 v2, 0x4400, v0
	v_mov_b32_e32 v3, v1
	v_lshl_add_u64 v[2:3], v[2:3], 2, s[6:7]
	global_load_dword v4, v[2:3], off
	s_waitcnt vmcnt(0)
	v_fmac_f32_e32 v4, v11, v20
	global_store_dword v[2:3], v4, off
	v_add_u32_e32 v2, 0x4800, v0
	v_mov_b32_e32 v3, v1
	v_lshl_add_u64 v[2:3], v[2:3], 2, s[6:7]
	global_load_dword v4, v[2:3], off
	s_waitcnt vmcnt(0)
	v_fmac_f32_e32 v4, v12, v20
	global_store_dword v[2:3], v4, off
	v_add_u32_e32 v2, 0x4c00, v0
	v_mov_b32_e32 v3, v1
	v_lshl_add_u64 v[2:3], v[2:3], 2, s[6:7]
	global_load_dword v4, v[2:3], off
	s_waitcnt vmcnt(0)
	v_fmac_f32_e32 v4, v13, v20
	global_store_dword v[2:3], v4, off
	v_add_u32_e32 v2, 0x6000, v0
	v_mov_b32_e32 v3, v1
	v_lshl_add_u64 v[2:3], v[2:3], 2, s[6:7]
	global_load_dword v4, v[2:3], off
	s_waitcnt vmcnt(0)
	v_fmac_f32_e32 v4, v14, v20
	global_store_dword v[2:3], v4, off
	v_add_u32_e32 v2, 0x6400, v0
	v_mov_b32_e32 v3, v1
	v_lshl_add_u64 v[2:3], v[2:3], 2, s[6:7]
	global_load_dword v4, v[2:3], off
	s_waitcnt vmcnt(0)
	v_fmac_f32_e32 v4, v15, v20
	global_store_dword v[2:3], v4, off
	v_add_u32_e32 v2, 0x6800, v0
	v_mov_b32_e32 v3, v1
	v_lshl_add_u64 v[2:3], v[2:3], 2, s[6:7]
	global_load_dword v4, v[2:3], off
	v_add_u32_e32 v0, 0x6c00, v0
	s_waitcnt vmcnt(0)
	v_fmac_f32_e32 v4, v16, v20
	global_store_dword v[2:3], v4, off
	v_lshl_add_u64 v[2:3], v[0:1], 2, s[6:7]
	global_load_dword v0, v[2:3], off
	s_waitcnt vmcnt(0)
	v_fmac_f32_e32 v0, v17, v20
	global_store_dword v[2:3], v0, off
	s_add_i32 s13, s13, s46
	s_add_i32 s12, s12, s41
	s_cmpk_gt_u32 s12, 0x1ff
	s_cbranch_scc0 .LBB0_1103
	v_readlane_b32 s28, v243, 45
	v_readlane_b32 s34, v243, 47
	v_readlane_b32 s29, v243, 46
	v_readlane_b32 s35, v243, 48

; #define MFMA(a, b, c) __builtin_amdgcn_mfma_f32_32x32x16_bf16((a), (b), (c), 0, 0, 0)
; #define TIDX opaque_tid()
; template <int AI, int BI>
; DI void gemm_tile(const u16* __restrict__ A, int lda, const u16* __restrict__ B, int ldb, int nk, bool swap,
;                   f32x16 (&acc)[AI][BI], char* lds) {
;   const int tid = TIDX, lane = tid & 63, wid = tid >> 6;
;   gemm_stage<AI, BI>(A, lda, B, ldb, lds, tid);
;   asm volatile("s_waitcnt vmcnt(0)" ::: "memory");
;   __syncthreads();
;   const int wa = wid >> 1, wb = wid & 1, r = lane & 31, h = lane >> 5, sw = (r >> 1) & 7;
;   const int offA = (swap ? 16384 : 0) + (wa * 32 * AI + r) * 128;
;   const int offB = (swap ? 0 : 16384) + (wb * 32 * BI + r) * 128;
;   for (int kt = 0; kt < nk; ++kt) {
;     const char* cur = lds + (kt & 1) * 32768;
;     if (kt + 1 < nk) gemm_stage<AI, BI>(A + (kt + 1) * 64, lda, B + (kt + 1) * 64, ldb, lds + ((kt + 1) & 1) * 32768, tid);
; #pragma unroll
;     for (int ks = 0; ks < 4; ++ks) {
;       const int co = ((ks * 2 + h) ^ sw) << 4;
;       s16x8 fa[AI], fb[BI];
; #pragma unroll
;       for (int i = 0; i < AI; ++i) fa[i] = *(const s16x8*)(cur + offA + i * 4096 + co);
; #pragma unroll
;       for (int i = 0; i < BI; ++i) fb[i] = *(const s16x8*)(cur + offB + i * 4096 + co);
; #pragma unroll
;       for (int i = 0; i < AI; ++i)
; #pragma unroll
;         for (int j = 0; j < BI; ++j) acc[i][j] = MFMA(fa[i], fb[j], acc[i][j]);
;     }
;     asm volatile("s_waitcnt vmcnt(0)" ::: "memory");
;     __syncthreads();
;   }
.LBB0_1206:
	s_and_b32 s16, s14, 0xffff
	s_mul_hi_u32 s17, s16, 0xba2e8c
	s_mul_i32 s16, s16, 0xba2f
	s_mulk_i32 s17, 0x160
	s_lshr_b32 s16, s16, 24
	s_sub_i32 s17, s14, s17
	s_lshl_b32 s16, s16, 10
	s_and_b32 s18, s15, 0x380
	s_ashr_i32 s17, s17, 3
	s_or_b32 s16, s16, s18
	s_lshl_b32 s28, s17, 7
	v_mov_b32_e32 v82, v178
	v_mov_b32_e32 v83, v178
	s_lshl_b32 s18, s16, 11
	v_mov_b32_e32 v12, v178
	s_add_u32 s34, s10, s18
	s_addc_u32 s35, s11, 0
	v_lshrrev_b32_e32 v0, 4, v12
	s_ashr_i32 s29, s28, 31
	v_xor_b32_e32 v0, v0, v12
	v_add_u32_e32 v8, 0x100, v12
	v_add_u32_e32 v10, 0x200, v12
	v_add_u32_e32 v13, 0x300, v12
	s_lshl_b64 s[28:29], s[28:29], 11
	v_lshlrev_b32_e32 v0, 4, v0
	v_ashrrev_i32_e32 v4, 3, v12
	v_ashrrev_i32_e32 v6, 3, v8
	v_lshlrev_b32_e32 v99, 4, v8
	v_ashrrev_i32_e32 v8, 3, v10
	v_lshlrev_b32_e32 v100, 4, v10
	v_ashrrev_i32_e32 v10, 3, v13
	s_add_u32 s28, s12, s28
	v_and_b32_e32 v0, 0x70, v0
	v_ashrrev_i32_e32 v5, 31, v4
	v_ashrrev_i32_e32 v7, 31, v6
	v_ashrrev_i32_e32 v9, 31, v8
	v_ashrrev_i32_e32 v11, 31, v10
	s_addc_u32 s29, s13, s29
	v_lshl_add_u64 v[2:3], s[34:35], 0, v[0:1]
	v_lshlrev_b64 v[4:5], 11, v[4:5]
	v_lshlrev_b32_e32 v96, 4, v12
	v_lshlrev_b64 v[6:7], 11, v[6:7]
	v_lshlrev_b64 v[8:9], 11, v[8:9]
	v_lshlrev_b64 v[10:11], 11, v[10:11]
	v_lshl_add_u64 v[66:67], v[2:3], 0, v[4:5]
	v_lshl_add_u64 v[68:69], v[2:3], 0, v[6:7]
	v_lshl_add_u64 v[70:71], v[2:3], 0, v[8:9]
	v_lshl_add_u64 v[72:73], v[2:3], 0, v[10:11]
	v_lshl_add_u64 v[2:3], s[28:29], 0, v[0:1]
	v_add_u32_e32 v0, 0x4000, v96
	v_readfirstlane_b32 s37, v96
	v_readfirstlane_b32 s28, v0
	v_add_u32_e32 v0, 0x4000, v99
	s_mov_b32 m0, s37
	v_readfirstlane_b32 s48, v99
	v_lshlrev_b32_e32 v101, 4, v13
	v_readfirstlane_b32 s29, v0
	v_add_u32_e32 v0, 0x4000, v100
	global_load_lds_dwordx4 v[66:67], off
	s_mov_b32 m0, s48
	v_readfirstlane_b32 s51, v100
	v_readfirstlane_b32 s34, v0
	v_add_u32_e32 v0, 0x4000, v101
	global_load_lds_dwordx4 v[68:69], off
	s_mov_b32 m0, s51
	v_readfirstlane_b32 s52, v101
	v_lshl_add_u64 v[74:75], v[2:3], 0, v[4:5]
	v_readfirstlane_b32 s35, v0
	v_and_b32_e32 v0, 31, v12
	v_lshrrev_b32_e32 v4, 1, v12
	global_load_lds_dwordx4 v[70:71], off
	s_mov_b32 m0, s52
	v_and_or_b32 v0, v4, s57, v0
	global_load_lds_dwordx4 v[72:73], off
	s_mov_b32 m0, s28
	v_lshl_add_u64 v[76:77], v[2:3], 0, v[6:7]
	v_lshl_add_u64 v[78:79], v[2:3], 0, v[8:9]
	v_lshl_add_u64 v[80:81], v[2:3], 0, v[10:11]
	v_lshrrev_b32_e32 v2, 5, v12
	v_bfe_u32 v5, v12, 1, 3
	v_lshlrev_b32_e32 v85, 7, v0
	v_lshlrev_b32_e32 v0, 7, v12
	global_load_lds_dwordx4 v[74:75], off
	s_mov_b32 m0, s29
	v_bfe_u32 v3, v12, 5, 1
	v_and_b32_e32 v87, 0x2f80, v0
	v_bitop3_b32 v0, v2, v5, 1 bitop3:0x6c
	global_load_lds_dwordx4 v[76:77], off
	s_mov_b32 m0, s34
	v_lshlrev_b32_e32 v6, 4, v0
	v_bitop3_b32 v0, v3, v5, 2 bitop3:0x36
	v_add_u32_e32 v91, 0x8000, v96
	global_load_lds_dwordx4 v[78:79], off
	s_mov_b32 m0, s35
	v_lshlrev_b32_e32 v84, 4, v0
	v_bitop3_b32 v0, v3, v5, 4 bitop3:0x36
	v_readfirstlane_b32 s36, v91
	v_add_u32_e32 v92, 0x8000, v99
	global_load_lds_dwordx4 v[80:81], off
	v_lshlrev_b32_e32 v118, 4, v0
	v_bitop3_b32 v0, v3, v5, 6 bitop3:0x36
	v_lshl_add_u64 v[2:3], v[66:67], 0, s[68:69]
	s_mov_b32 m0, s36
	v_readfirstlane_b32 s40, v92
	v_add_u32_e32 v93, 0x8000, v100
	s_waitcnt vmcnt(0)
	s_waitcnt vmcnt(0) lgkmcnt(0)
	s_barrier
	global_load_lds_dwordx4 v[2:3], off
	v_lshl_add_u64 v[2:3], v[68:69], 0, s[68:69]
	s_mov_b32 m0, s40
	v_readfirstlane_b32 s41, v93
	v_add_u32_e32 v94, 0x8000, v101
	global_load_lds_dwordx4 v[2:3], off
	v_lshl_add_u64 v[2:3], v[70:71], 0, s[68:69]
	s_mov_b32 m0, s41
	v_readfirstlane_b32 s46, v94
	v_add_u32_e32 v95, 0xc000, v96
	global_load_lds_dwordx4 v[2:3], off
	v_lshl_add_u64 v[2:3], v[72:73], 0, s[68:69]
	s_mov_b32 m0, s46
	v_readfirstlane_b32 s47, v95
	v_add_u32_e32 v97, 0xc000, v99
	global_load_lds_dwordx4 v[2:3], off
	v_lshl_add_u64 v[2:3], v[74:75], 0, s[68:69]
	s_mov_b32 m0, s47
	v_readfirstlane_b32 s49, v97
	v_add_u32_e32 v98, 0xc000, v100
	v_lshlrev_b32_e32 v119, 4, v0
	global_load_lds_dwordx4 v[2:3], off
	v_lshl_add_u64 v[2:3], v[76:77], 0, s[68:69]
	s_mov_b32 m0, s49
	v_readfirstlane_b32 s50, v98
	v_add_u32_e32 v0, 0xc000, v101
	global_load_lds_dwordx4 v[2:3], off
	v_lshl_add_u64 v[2:3], v[78:79], 0, s[68:69]
	s_mov_b32 m0, s50
	v_readfirstlane_b32 s18, v0
	global_load_lds_dwordx4 v[2:3], off
	v_lshl_add_u64 v[2:3], v[80:81], 0, s[68:69]
	s_mov_b32 m0, s18
	v_or_b32_e32 v0, v85, v6
	global_load_lds_dwordx4 v[2:3], off
	v_or_b32_e32 v86, v87, v6
	ds_read_b128 v[2:5], v0
	ds_read_b128 v[18:21], v0 offset:4096
	ds_read_b128 v[6:9], v86 offset:16384
	ds_read_b128 v[22:25], v86 offset:20480
	s_waitcnt lgkmcnt(0)
	v_mfma_f32_32x32x16_bf16 v[34:49], v[2:5], v[6:9], 0
	v_or_b32_e32 v88, v85, v84
	v_or_b32_e32 v89, v87, v84
	ds_read_b128 v[102:105], v88
	ds_read_b128 v[106:109], v88 offset:4096
	ds_read_b128 v[110:113], v89 offset:16384
	ds_read_b128 v[114:117], v89 offset:20480
	v_or_b32_e32 v90, v85, v118
	v_or_b32_e32 v84, v87, v118
	v_or_b32_e32 v85, v85, v119
	v_mfma_f32_32x32x16_bf16 v[50:65], v[2:5], v[22:25], 0
	v_or_b32_e32 v87, v87, v119
	s_mov_b32 m0, s37
	s_lshl_b32 s17, s17, 6
	v_mfma_f32_32x32x16_bf16 v[2:17], v[18:21], v[6:9], 0
	v_mfma_f32_32x32x16_bf16 v[18:33], v[18:21], v[22:25], 0
	s_waitcnt lgkmcnt(1)
	v_mfma_f32_32x32x16_bf16 v[34:49], v[102:105], v[110:113], v[34:49]
	s_waitcnt lgkmcnt(0)
	v_mfma_f32_32x32x16_bf16 v[50:65], v[102:105], v[114:117], v[50:65]
	v_mfma_f32_32x32x16_bf16 v[2:17], v[106:109], v[110:113], v[2:17]
	v_mfma_f32_32x32x16_bf16 v[18:33], v[106:109], v[114:117], v[18:33]
	ds_read_b128 v[102:105], v90
	ds_read_b128 v[106:109], v90 offset:4096
	ds_read_b128 v[110:113], v84 offset:16384
	ds_read_b128 v[114:117], v84 offset:20480
	s_waitcnt lgkmcnt(1)
	v_mfma_f32_32x32x16_bf16 v[34:49], v[102:105], v[110:113], v[34:49]
	s_waitcnt lgkmcnt(0)
	v_mfma_f32_32x32x16_bf16 v[50:65], v[102:105], v[114:117], v[50:65]
	v_mfma_f32_32x32x16_bf16 v[2:17], v[106:109], v[110:113], v[2:17]
	v_mfma_f32_32x32x16_bf16 v[18:33], v[106:109], v[114:117], v[18:33]
	ds_read_b128 v[102:105], v85
	ds_read_b128 v[106:109], v85 offset:4096
	ds_read_b128 v[110:113], v87 offset:16384
	ds_read_b128 v[114:117], v87 offset:20480
	s_waitcnt lgkmcnt(0)
	v_mfma_f32_32x32x16_bf16 v[34:49], v[102:105], v[110:113], v[34:49]
	v_mfma_f32_32x32x16_bf16 v[50:65], v[102:105], v[114:117], v[50:65]
	s_waitcnt vmcnt(0)
	s_barrier
; #define MFMA(a, b, c) __builtin_amdgcn_mfma_f32_32x32x16_bf16((a), (b), (c), 0, 0, 0)
; template <int AI, int BI>
; DI void gemm_tile(const u16* __restrict__ A, int lda, const u16* __restrict__ B, int ldb, int nk, bool swap,
;                   f32x16 (&acc)[AI][BI], char* lds) {
;     ...
;   for (int kt = 0; kt < nk; ++kt) {
;     const char* cur = lds + (kt & 1) * 32768;
;     if (kt + 1 < nk) gemm_stage<AI, BI>(A + (kt + 1) * 64, lda, B + (kt + 1) * 64, ldb, lds + ((kt + 1) & 1) * 32768, tid);
; #pragma unroll
;     for (int ks = 0; ks < 4; ++ks) {
;       const int co = ((ks * 2 + h) ^ sw) << 4;
;       s16x8 fa[AI], fb[BI];
; #pragma unroll
;       for (int i = 0; i < AI; ++i) fa[i] = *(const s16x8*)(cur + offA + i * 4096 + co);
; #pragma unroll
;       for (int i = 0; i < BI; ++i) fb[i] = *(const s16x8*)(cur + offB + i * 4096 + co);
; #pragma unroll
;       for (int i = 0; i < AI; ++i)
; #pragma unroll
;         for (int j = 0; j < BI; ++j) acc[i][j] = MFMA(fa[i], fb[j], acc[i][j]);
;     }
;     asm volatile("s_waitcnt vmcnt(0)" ::: "memory");
;     __syncthreads();
;   }
	v_lshl_add_u64 v[102:103], v[66:67], 0, s[4:5]
	global_load_lds_dwordx4 v[102:103], off
	v_lshl_add_u64 v[102:103], v[68:69], 0, s[4:5]
	s_mov_b32 m0, s48
	s_nop 0
	global_load_lds_dwordx4 v[102:103], off
	v_lshl_add_u64 v[102:103], v[70:71], 0, s[4:5]
	s_mov_b32 m0, s51
	v_mfma_f32_32x32x16_bf16 v[2:17], v[106:109], v[110:113], v[2:17]
	global_load_lds_dwordx4 v[102:103], off
	v_lshl_add_u64 v[102:103], v[72:73], 0, s[4:5]
	s_mov_b32 m0, s52
	s_nop 0
	global_load_lds_dwordx4 v[102:103], off
	v_lshl_add_u64 v[102:103], v[74:75], 0, s[4:5]
	s_mov_b32 m0, s28
	v_mfma_f32_32x32x16_bf16 v[18:33], v[106:109], v[114:117], v[18:33]
	global_load_lds_dwordx4 v[102:103], off
	v_lshl_add_u64 v[102:103], v[76:77], 0, s[4:5]
	s_mov_b32 m0, s29
	s_nop 0
	global_load_lds_dwordx4 v[102:103], off
	v_lshl_add_u64 v[102:103], v[78:79], 0, s[4:5]
	s_mov_b32 m0, s34
	s_nop 0
	global_load_lds_dwordx4 v[102:103], off
	v_lshl_add_u64 v[102:103], v[80:81], 0, s[4:5]
	s_mov_b32 m0, s35
	s_nop 0
	global_load_lds_dwordx4 v[102:103], off
	ds_read_b128 v[102:105], v0 offset:32768
	ds_read_b128 v[106:109], v0 offset:36864
	ds_read_b128 v[110:113], v86 offset:49152
	ds_read_b128 v[114:117], v86 offset:53248
	s_waitcnt lgkmcnt(0)
	v_mfma_f32_32x32x16_bf16 v[34:49], v[102:105], v[110:113], v[34:49]
	s_mov_b32 m0, s36
	v_mfma_f32_32x32x16_bf16 v[50:65], v[102:105], v[114:117], v[50:65]
	v_mfma_f32_32x32x16_bf16 v[2:17], v[106:109], v[110:113], v[2:17]
	v_mfma_f32_32x32x16_bf16 v[18:33], v[106:109], v[114:117], v[18:33]
	ds_read_b128 v[102:105], v88 offset:32768
	ds_read_b128 v[106:109], v88 offset:36864
	ds_read_b128 v[110:113], v89 offset:49152
	ds_read_b128 v[114:117], v89 offset:53248
	s_waitcnt lgkmcnt(1)
	v_mfma_f32_32x32x16_bf16 v[34:49], v[102:105], v[110:113], v[34:49]
	s_waitcnt lgkmcnt(0)
	v_mfma_f32_32x32x16_bf16 v[50:65], v[102:105], v[114:117], v[50:65]
	v_mfma_f32_32x32x16_bf16 v[2:17], v[106:109], v[110:113], v[2:17]
	v_mfma_f32_32x32x16_bf16 v[18:33], v[106:109], v[114:117], v[18:33]
	ds_read_b128 v[102:105], v90 offset:32768
	ds_read_b128 v[106:109], v90 offset:36864
	ds_read_b128 v[110:113], v84 offset:49152
	ds_read_b128 v[114:117], v84 offset:53248
	s_waitcnt lgkmcnt(1)
	v_mfma_f32_32x32x16_bf16 v[34:49], v[102:105], v[110:113], v[34:49]
	s_waitcnt lgkmcnt(0)
	v_mfma_f32_32x32x16_bf16 v[50:65], v[102:105], v[114:117], v[50:65]
	v_mfma_f32_32x32x16_bf16 v[2:17], v[106:109], v[110:113], v[2:17]
	v_mfma_f32_32x32x16_bf16 v[18:33], v[106:109], v[114:117], v[18:33]
	ds_read_b128 v[102:105], v85 offset:32768
	ds_read_b128 v[106:109], v85 offset:36864
	ds_read_b128 v[110:113], v87 offset:49152
	ds_read_b128 v[114:117], v87 offset:53248
	s_waitcnt lgkmcnt(0)
	v_mfma_f32_32x32x16_bf16 v[34:49], v[102:105], v[110:113], v[34:49]
	v_mfma_f32_32x32x16_bf16 v[50:65], v[102:105], v[114:117], v[50:65]
	s_waitcnt vmcnt(0)
	s_barrier
	v_lshl_add_u64 v[102:103], v[66:67], 0, s[70:71]
	global_load_lds_dwordx4 v[102:103], off
	v_lshl_add_u64 v[102:103], v[68:69], 0, s[70:71]
	s_mov_b32 m0, s40
	s_nop 0
	global_load_lds_dwordx4 v[102:103], off
	v_lshl_add_u64 v[102:103], v[70:71], 0, s[70:71]
	s_mov_b32 m0, s41
	v_mfma_f32_32x32x16_bf16 v[2:17], v[106:109], v[110:113], v[2:17]
	global_load_lds_dwordx4 v[102:103], off
	v_lshl_add_u64 v[102:103], v[72:73], 0, s[70:71]
	s_mov_b32 m0, s46
	s_nop 0
	global_load_lds_dwordx4 v[102:103], off
	v_lshl_add_u64 v[102:103], v[74:75], 0, s[70:71]
	s_mov_b32 m0, s47
	v_mfma_f32_32x32x16_bf16 v[18:33], v[106:109], v[114:117], v[18:33]
	global_load_lds_dwordx4 v[102:103], off
	v_lshl_add_u64 v[102:103], v[76:77], 0, s[70:71]
	s_mov_b32 m0, s49
	s_nop 0
	global_load_lds_dwordx4 v[102:103], off
	v_lshl_add_u64 v[102:103], v[78:79], 0, s[70:71]
	s_mov_b32 m0, s50
	s_nop 0
	global_load_lds_dwordx4 v[102:103], off
	v_lshl_add_u64 v[102:103], v[80:81], 0, s[70:71]
	s_mov_b32 m0, s18
	s_nop 0
	global_load_lds_dwordx4 v[102:103], off
	ds_read_b128 v[102:105], v0
	ds_read_b128 v[106:109], v0 offset:4096
	ds_read_b128 v[110:113], v86 offset:16384
	ds_read_b128 v[114:117], v86 offset:20480
	s_waitcnt lgkmcnt(0)
	v_mfma_f32_32x32x16_bf16 v[34:49], v[102:105], v[110:113], v[34:49]
	s_mov_b32 m0, s37
	v_mfma_f32_32x32x16_bf16 v[50:65], v[102:105], v[114:117], v[50:65]
	v_mfma_f32_32x32x16_bf16 v[2:17], v[106:109], v[110:113], v[2:17]
	v_mfma_f32_32x32x16_bf16 v[18:33], v[106:109], v[114:117], v[18:33]
	ds_read_b128 v[102:105], v88
	ds_read_b128 v[106:109], v88 offset:4096
	ds_read_b128 v[110:113], v89 offset:16384
	ds_read_b128 v[114:117], v89 offset:20480
	s_waitcnt lgkmcnt(1)
	v_mfma_f32_32x32x16_bf16 v[34:49], v[102:105], v[110:113], v[34:49]
	s_waitcnt lgkmcnt(0)
	v_mfma_f32_32x32x16_bf16 v[50:65], v[102:105], v[114:117], v[50:65]
	v_mfma_f32_32x32x16_bf16 v[2:17], v[106:109], v[110:113], v[2:17]
	v_mfma_f32_32x32x16_bf16 v[18:33], v[106:109], v[114:117], v[18:33]
	ds_read_b128 v[102:105], v90
	ds_read_b128 v[106:109], v90 offset:4096
	ds_read_b128 v[110:113], v84 offset:16384
	ds_read_b128 v[114:117], v84 offset:20480
	s_waitcnt lgkmcnt(1)
	v_mfma_f32_32x32x16_bf16 v[34:49], v[102:105], v[110:113], v[34:49]
	s_waitcnt lgkmcnt(0)
	v_mfma_f32_32x32x16_bf16 v[50:65], v[102:105], v[114:117], v[50:65]
	v_mfma_f32_32x32x16_bf16 v[2:17], v[106:109], v[110:113], v[2:17]
	v_mfma_f32_32x32x16_bf16 v[18:33], v[106:109], v[114:117], v[18:33]
	ds_read_b128 v[102:105], v85
	ds_read_b128 v[106:109], v85 offset:4096
	ds_read_b128 v[110:113], v87 offset:16384
	ds_read_b128 v[114:117], v87 offset:20480
	s_waitcnt lgkmcnt(0)
	v_mfma_f32_32x32x16_bf16 v[34:49], v[102:105], v[110:113], v[34:49]
	v_mfma_f32_32x32x16_bf16 v[50:65], v[102:105], v[114:117], v[50:65]
	s_waitcnt vmcnt(0)
	s_barrier
; #define MFMA(a, b, c) __builtin_amdgcn_mfma_f32_32x32x16_bf16((a), (b), (c), 0, 0, 0)
; template <int AI, int BI>
; DI void gemm_tile(const u16* __restrict__ A, int lda, const u16* __restrict__ B, int ldb, int nk, bool swap,
;                   f32x16 (&acc)[AI][BI], char* lds) {
;     ...
;   for (int kt = 0; kt < nk; ++kt) {
;     const char* cur = lds + (kt & 1) * 32768;
;     if (kt + 1 < nk) gemm_stage<AI, BI>(A + (kt + 1) * 64, lda, B + (kt + 1) * 64, ldb, lds + ((kt + 1) & 1) * 32768, tid);
; #pragma unroll
;     for (int ks = 0; ks < 4; ++ks) {
;       const int co = ((ks * 2 + h) ^ sw) << 4;
;       s16x8 fa[AI], fb[BI];
; #pragma unroll
;       for (int i = 0; i < AI; ++i) fa[i] = *(const s16x8*)(cur + offA + i * 4096 + co);
; #pragma unroll
;       for (int i = 0; i < BI; ++i) fb[i] = *(const s16x8*)(cur + offB + i * 4096 + co);
; #pragma unroll
;       for (int i = 0; i < AI; ++i)
; #pragma unroll
;         for (int j = 0; j < BI; ++j) acc[i][j] = MFMA(fa[i], fb[j], acc[i][j]);
;     }
;     asm volatile("s_waitcnt vmcnt(0)" ::: "memory");
;     __syncthreads();
;   }
	v_lshl_add_u64 v[102:103], v[66:67], 0, s[66:67]
	global_load_lds_dwordx4 v[102:103], off
	v_lshl_add_u64 v[102:103], v[68:69], 0, s[66:67]
	s_mov_b32 m0, s48
	s_nop 0
	global_load_lds_dwordx4 v[102:103], off
	v_lshl_add_u64 v[102:103], v[70:71], 0, s[66:67]
	s_mov_b32 m0, s51
	v_mfma_f32_32x32x16_bf16 v[2:17], v[106:109], v[110:113], v[2:17]
	global_load_lds_dwordx4 v[102:103], off
	v_lshl_add_u64 v[102:103], v[72:73], 0, s[66:67]
	s_mov_b32 m0, s52
	s_nop 0
	global_load_lds_dwordx4 v[102:103], off
	v_lshl_add_u64 v[102:103], v[74:75], 0, s[66:67]
	s_mov_b32 m0, s28
	v_mfma_f32_32x32x16_bf16 v[18:33], v[106:109], v[114:117], v[18:33]
	global_load_lds_dwordx4 v[102:103], off
	v_lshl_add_u64 v[102:103], v[76:77], 0, s[66:67]
	s_mov_b32 m0, s29
	s_nop 0
	global_load_lds_dwordx4 v[102:103], off
	v_lshl_add_u64 v[102:103], v[78:79], 0, s[66:67]
	s_mov_b32 m0, s34
	s_nop 0
	global_load_lds_dwordx4 v[102:103], off
	v_lshl_add_u64 v[102:103], v[80:81], 0, s[66:67]
	s_mov_b32 m0, s35
	s_nop 0
	global_load_lds_dwordx4 v[102:103], off
	ds_read_b128 v[102:105], v0 offset:32768
	ds_read_b128 v[106:109], v0 offset:36864
	ds_read_b128 v[110:113], v86 offset:49152
	ds_read_b128 v[114:117], v86 offset:53248
	s_waitcnt lgkmcnt(0)
	v_mfma_f32_32x32x16_bf16 v[34:49], v[102:105], v[110:113], v[34:49]
	s_mov_b32 m0, s36
	v_mfma_f32_32x32x16_bf16 v[50:65], v[102:105], v[114:117], v[50:65]
	v_mfma_f32_32x32x16_bf16 v[2:17], v[106:109], v[110:113], v[2:17]
	v_mfma_f32_32x32x16_bf16 v[18:33], v[106:109], v[114:117], v[18:33]
	ds_read_b128 v[102:105], v88 offset:32768
	ds_read_b128 v[106:109], v88 offset:36864
	ds_read_b128 v[110:113], v89 offset:49152
	ds_read_b128 v[114:117], v89 offset:53248
	s_waitcnt lgkmcnt(1)
	v_mfma_f32_32x32x16_bf16 v[34:49], v[102:105], v[110:113], v[34:49]
	s_waitcnt lgkmcnt(0)
	v_mfma_f32_32x32x16_bf16 v[50:65], v[102:105], v[114:117], v[50:65]
	v_mfma_f32_32x32x16_bf16 v[2:17], v[106:109], v[110:113], v[2:17]
	v_mfma_f32_32x32x16_bf16 v[18:33], v[106:109], v[114:117], v[18:33]
	ds_read_b128 v[102:105], v90 offset:32768
	ds_read_b128 v[106:109], v90 offset:36864
	ds_read_b128 v[110:113], v84 offset:49152
	ds_read_b128 v[114:117], v84 offset:53248
	s_waitcnt lgkmcnt(1)
	v_mfma_f32_32x32x16_bf16 v[34:49], v[102:105], v[110:113], v[34:49]
	s_waitcnt lgkmcnt(0)
	v_mfma_f32_32x32x16_bf16 v[50:65], v[102:105], v[114:117], v[50:65]
	v_mfma_f32_32x32x16_bf16 v[2:17], v[106:109], v[110:113], v[2:17]
	v_mfma_f32_32x32x16_bf16 v[18:33], v[106:109], v[114:117], v[18:33]
	ds_read_b128 v[102:105], v85 offset:32768
	ds_read_b128 v[106:109], v85 offset:36864
	ds_read_b128 v[110:113], v87 offset:49152
	ds_read_b128 v[114:117], v87 offset:53248
	s_waitcnt lgkmcnt(0)
	v_mfma_f32_32x32x16_bf16 v[34:49], v[102:105], v[110:113], v[34:49]
	v_mfma_f32_32x32x16_bf16 v[50:65], v[102:105], v[114:117], v[50:65]
	s_waitcnt vmcnt(0)
	s_barrier
	v_lshl_add_u64 v[102:103], v[66:67], 0, s[72:73]
	global_load_lds_dwordx4 v[102:103], off
	v_lshl_add_u64 v[102:103], v[68:69], 0, s[72:73]
	s_mov_b32 m0, s40
	s_nop 0
	global_load_lds_dwordx4 v[102:103], off
	v_lshl_add_u64 v[102:103], v[70:71], 0, s[72:73]
	s_mov_b32 m0, s41
	v_mfma_f32_32x32x16_bf16 v[2:17], v[106:109], v[110:113], v[2:17]
	global_load_lds_dwordx4 v[102:103], off
	v_lshl_add_u64 v[102:103], v[72:73], 0, s[72:73]
	s_mov_b32 m0, s46
	s_nop 0
	global_load_lds_dwordx4 v[102:103], off
	v_lshl_add_u64 v[102:103], v[74:75], 0, s[72:73]
	s_mov_b32 m0, s47
	v_mfma_f32_32x32x16_bf16 v[18:33], v[106:109], v[114:117], v[18:33]
	global_load_lds_dwordx4 v[102:103], off
	v_lshl_add_u64 v[102:103], v[76:77], 0, s[72:73]
	s_mov_b32 m0, s49
	s_nop 0
	global_load_lds_dwordx4 v[102:103], off
	v_lshl_add_u64 v[102:103], v[78:79], 0, s[72:73]
	s_mov_b32 m0, s50
	s_nop 0
	global_load_lds_dwordx4 v[102:103], off
	v_lshl_add_u64 v[102:103], v[80:81], 0, s[72:73]
	s_mov_b32 m0, s18
	s_nop 0
	global_load_lds_dwordx4 v[102:103], off
	ds_read_b128 v[102:105], v0
	ds_read_b128 v[106:109], v0 offset:4096
	ds_read_b128 v[110:113], v86 offset:16384
	ds_read_b128 v[114:117], v86 offset:20480
	s_waitcnt lgkmcnt(0)
	v_mfma_f32_32x32x16_bf16 v[34:49], v[102:105], v[110:113], v[34:49]
	s_mov_b32 m0, s37
	v_readfirstlane_b32 s37, v99
	v_mfma_f32_32x32x16_bf16 v[50:65], v[102:105], v[114:117], v[50:65]
	v_mfma_f32_32x32x16_bf16 v[2:17], v[106:109], v[110:113], v[2:17]
	v_mfma_f32_32x32x16_bf16 v[18:33], v[106:109], v[114:117], v[18:33]
	ds_read_b128 v[102:105], v88
	ds_read_b128 v[106:109], v88 offset:4096
	ds_read_b128 v[110:113], v89 offset:16384
	ds_read_b128 v[114:117], v89 offset:20480
	s_waitcnt lgkmcnt(1)
	v_mfma_f32_32x32x16_bf16 v[34:49], v[102:105], v[110:113], v[34:49]
	s_waitcnt lgkmcnt(0)
	v_mfma_f32_32x32x16_bf16 v[50:65], v[102:105], v[114:117], v[50:65]
	v_mfma_f32_32x32x16_bf16 v[2:17], v[106:109], v[110:113], v[2:17]
	v_mfma_f32_32x32x16_bf16 v[18:33], v[106:109], v[114:117], v[18:33]
	ds_read_b128 v[102:105], v90
	ds_read_b128 v[106:109], v90 offset:4096
	ds_read_b128 v[110:113], v84 offset:16384
	ds_read_b128 v[114:117], v84 offset:20480
	s_waitcnt lgkmcnt(1)
	v_mfma_f32_32x32x16_bf16 v[34:49], v[102:105], v[110:113], v[34:49]
	s_waitcnt lgkmcnt(0)
	v_mfma_f32_32x32x16_bf16 v[50:65], v[102:105], v[114:117], v[50:65]
	v_mfma_f32_32x32x16_bf16 v[2:17], v[106:109], v[110:113], v[2:17]
	v_mfma_f32_32x32x16_bf16 v[18:33], v[106:109], v[114:117], v[18:33]
	ds_read_b128 v[102:105], v85
	ds_read_b128 v[106:109], v85 offset:4096
	ds_read_b128 v[110:113], v87 offset:16384
	ds_read_b128 v[114:117], v87 offset:20480
	s_waitcnt lgkmcnt(0)
	v_mfma_f32_32x32x16_bf16 v[34:49], v[102:105], v[110:113], v[34:49]
	v_mfma_f32_32x32x16_bf16 v[50:65], v[102:105], v[114:117], v[50:65]
	s_waitcnt vmcnt(0)
	s_barrier
; #define MFMA(a, b, c) __builtin_amdgcn_mfma_f32_32x32x16_bf16((a), (b), (c), 0, 0, 0)
; template <int AI, int BI>
; DI void gemm_tile(const u16* __restrict__ A, int lda, const u16* __restrict__ B, int ldb, int nk, bool swap,
;                   f32x16 (&acc)[AI][BI], char* lds) {
;     ...
;   for (int kt = 0; kt < nk; ++kt) {
;     const char* cur = lds + (kt & 1) * 32768;
;     if (kt + 1 < nk) gemm_stage<AI, BI>(A + (kt + 1) * 64, lda, B + (kt + 1) * 64, ldb, lds + ((kt + 1) & 1) * 32768, tid);
; #pragma unroll
;     for (int ks = 0; ks < 4; ++ks) {
;       const int co = ((ks * 2 + h) ^ sw) << 4;
;       s16x8 fa[AI], fb[BI];
; #pragma unroll
;       for (int i = 0; i < AI; ++i) fa[i] = *(const s16x8*)(cur + offA + i * 4096 + co);
; #pragma unroll
;       for (int i = 0; i < BI; ++i) fb[i] = *(const s16x8*)(cur + offB + i * 4096 + co);
; #pragma unroll
;       for (int i = 0; i < AI; ++i)
; #pragma unroll
;         for (int j = 0; j < BI; ++j) acc[i][j] = MFMA(fa[i], fb[j], acc[i][j]);
;     }
;     asm volatile("s_waitcnt vmcnt(0)" ::: "memory");
;     __syncthreads();
;   }
	v_lshl_add_u64 v[102:103], v[66:67], 0, s[74:75]
	global_load_lds_dwordx4 v[102:103], off
	v_lshl_add_u64 v[102:103], v[68:69], 0, s[74:75]
	s_mov_b32 m0, s48
	v_readfirstlane_b32 s48, v93
	global_load_lds_dwordx4 v[102:103], off
	v_lshl_add_u64 v[102:103], v[70:71], 0, s[74:75]
	s_mov_b32 m0, s51
	v_mfma_f32_32x32x16_bf16 v[2:17], v[106:109], v[110:113], v[2:17]
	global_load_lds_dwordx4 v[102:103], off
	v_lshl_add_u64 v[102:103], v[72:73], 0, s[74:75]
	s_mov_b32 m0, s52
	v_readfirstlane_b32 s51, v97
	global_load_lds_dwordx4 v[102:103], off
	v_lshl_add_u64 v[102:103], v[74:75], 0, s[74:75]
	s_mov_b32 m0, s28
	v_mfma_f32_32x32x16_bf16 v[18:33], v[106:109], v[114:117], v[18:33]
	global_load_lds_dwordx4 v[102:103], off
	v_lshl_add_u64 v[102:103], v[76:77], 0, s[74:75]
	s_mov_b32 m0, s29
	v_readfirstlane_b32 s52, v98
	global_load_lds_dwordx4 v[102:103], off
	v_lshl_add_u64 v[102:103], v[78:79], 0, s[74:75]
	s_mov_b32 m0, s34
	s_nop 0
	global_load_lds_dwordx4 v[102:103], off
	v_lshl_add_u64 v[102:103], v[80:81], 0, s[74:75]
	s_mov_b32 m0, s35
	s_nop 0
	global_load_lds_dwordx4 v[102:103], off
	ds_read_b128 v[102:105], v0 offset:32768
	ds_read_b128 v[106:109], v0 offset:36864
	ds_read_b128 v[110:113], v86 offset:49152
	ds_read_b128 v[114:117], v86 offset:53248
	s_waitcnt lgkmcnt(0)
	v_mfma_f32_32x32x16_bf16 v[34:49], v[102:105], v[110:113], v[34:49]
	s_mov_b32 m0, s36
	v_readfirstlane_b32 s36, v96
	v_mfma_f32_32x32x16_bf16 v[50:65], v[102:105], v[114:117], v[50:65]
	v_mfma_f32_32x32x16_bf16 v[2:17], v[106:109], v[110:113], v[2:17]
	v_mfma_f32_32x32x16_bf16 v[18:33], v[106:109], v[114:117], v[18:33]
	ds_read_b128 v[102:105], v88 offset:32768
	ds_read_b128 v[106:109], v88 offset:36864
	ds_read_b128 v[110:113], v89 offset:49152
	ds_read_b128 v[114:117], v89 offset:53248
	s_waitcnt lgkmcnt(1)
	v_mfma_f32_32x32x16_bf16 v[34:49], v[102:105], v[110:113], v[34:49]
	s_waitcnt lgkmcnt(0)
	v_mfma_f32_32x32x16_bf16 v[50:65], v[102:105], v[114:117], v[50:65]
	v_mfma_f32_32x32x16_bf16 v[2:17], v[106:109], v[110:113], v[2:17]
	v_mfma_f32_32x32x16_bf16 v[18:33], v[106:109], v[114:117], v[18:33]
	ds_read_b128 v[102:105], v90 offset:32768
	ds_read_b128 v[106:109], v90 offset:36864
	ds_read_b128 v[110:113], v84 offset:49152
	ds_read_b128 v[114:117], v84 offset:53248
	s_waitcnt lgkmcnt(1)
	v_mfma_f32_32x32x16_bf16 v[34:49], v[102:105], v[110:113], v[34:49]
	s_waitcnt lgkmcnt(0)
	v_mfma_f32_32x32x16_bf16 v[50:65], v[102:105], v[114:117], v[50:65]
	v_mfma_f32_32x32x16_bf16 v[2:17], v[106:109], v[110:113], v[2:17]
	v_mfma_f32_32x32x16_bf16 v[18:33], v[106:109], v[114:117], v[18:33]
	ds_read_b128 v[102:105], v85 offset:32768
	ds_read_b128 v[106:109], v85 offset:36864
	ds_read_b128 v[110:113], v87 offset:49152
	ds_read_b128 v[114:117], v87 offset:53248
	s_waitcnt lgkmcnt(0)
	v_mfma_f32_32x32x16_bf16 v[34:49], v[102:105], v[110:113], v[34:49]
	v_mfma_f32_32x32x16_bf16 v[50:65], v[102:105], v[114:117], v[50:65]
	s_waitcnt vmcnt(0)
	s_barrier
	v_lshl_add_u64 v[102:103], v[66:67], 0, s[76:77]
	global_load_lds_dwordx4 v[102:103], off
	v_lshl_add_u64 v[102:103], v[68:69], 0, s[76:77]
	s_mov_b32 m0, s40
	v_readfirstlane_b32 s40, v100
	global_load_lds_dwordx4 v[102:103], off
	v_lshl_add_u64 v[102:103], v[70:71], 0, s[76:77]
	s_mov_b32 m0, s41
	v_mfma_f32_32x32x16_bf16 v[2:17], v[106:109], v[110:113], v[2:17]
	global_load_lds_dwordx4 v[102:103], off
	v_lshl_add_u64 v[102:103], v[72:73], 0, s[76:77]
	s_mov_b32 m0, s46
	v_readfirstlane_b32 s41, v101
	global_load_lds_dwordx4 v[102:103], off
	v_lshl_add_u64 v[102:103], v[74:75], 0, s[76:77]
	s_mov_b32 m0, s47
	v_mfma_f32_32x32x16_bf16 v[18:33], v[106:109], v[114:117], v[18:33]
	global_load_lds_dwordx4 v[102:103], off
	v_lshl_add_u64 v[102:103], v[76:77], 0, s[76:77]
	s_mov_b32 m0, s49
	v_lshl_add_u64 v[100:101], v[74:75], 0, s[80:81]
	global_load_lds_dwordx4 v[102:103], off
	v_lshl_add_u64 v[102:103], v[78:79], 0, s[76:77]
	s_mov_b32 m0, s50
	v_readfirstlane_b32 s46, v91
	global_load_lds_dwordx4 v[102:103], off
	v_lshl_add_u64 v[102:103], v[80:81], 0, s[76:77]
	s_mov_b32 m0, s18
	v_readfirstlane_b32 s47, v92
	global_load_lds_dwordx4 v[102:103], off
	ds_read_b128 v[102:105], v0
	ds_read_b128 v[106:109], v0 offset:4096
	ds_read_b128 v[110:113], v86 offset:16384
	ds_read_b128 v[114:117], v86 offset:20480
	s_waitcnt lgkmcnt(0)
	v_mfma_f32_32x32x16_bf16 v[34:49], v[102:105], v[110:113], v[34:49]
	s_mov_b32 m0, s36
	v_readfirstlane_b32 s49, v94
	v_lshl_add_u64 v[92:93], v[72:73], 0, s[82:83]
	v_readfirstlane_b32 s50, v95
	v_and_b32_e32 v91, 31, v82
	v_mfma_f32_32x32x16_bf16 v[50:65], v[102:105], v[114:117], v[50:65]
	v_mfma_f32_32x32x16_bf16 v[2:17], v[106:109], v[110:113], v[2:17]
	v_mfma_f32_32x32x16_bf16 v[18:33], v[106:109], v[114:117], v[18:33]
	ds_read_b128 v[102:105], v88
	ds_read_b128 v[106:109], v88 offset:4096
	ds_read_b128 v[110:113], v89 offset:16384
	ds_read_b128 v[114:117], v89 offset:20480
	s_waitcnt lgkmcnt(1)
	v_mfma_f32_32x32x16_bf16 v[34:49], v[102:105], v[110:113], v[34:49]
	s_waitcnt lgkmcnt(0)
	v_mfma_f32_32x32x16_bf16 v[50:65], v[102:105], v[114:117], v[50:65]
	v_mfma_f32_32x32x16_bf16 v[2:17], v[106:109], v[110:113], v[2:17]
	v_mfma_f32_32x32x16_bf16 v[18:33], v[106:109], v[114:117], v[18:33]
	ds_read_b128 v[102:105], v90
	ds_read_b128 v[106:109], v90 offset:4096
	ds_read_b128 v[110:113], v84 offset:16384
	ds_read_b128 v[114:117], v84 offset:20480
	s_waitcnt lgkmcnt(1)
	v_mfma_f32_32x32x16_bf16 v[34:49], v[102:105], v[110:113], v[34:49]
	s_waitcnt lgkmcnt(0)
	v_mfma_f32_32x32x16_bf16 v[50:65], v[102:105], v[114:117], v[50:65]
	v_mfma_f32_32x32x16_bf16 v[2:17], v[106:109], v[110:113], v[2:17]
	v_mfma_f32_32x32x16_bf16 v[18:33], v[106:109], v[114:117], v[18:33]
	ds_read_b128 v[102:105], v85
	ds_read_b128 v[106:109], v85 offset:4096
	ds_read_b128 v[110:113], v87 offset:16384
	ds_read_b128 v[114:117], v87 offset:20480
	s_waitcnt lgkmcnt(0)
	v_mfma_f32_32x32x16_bf16 v[34:49], v[102:105], v[110:113], v[34:49]
	v_mfma_f32_32x32x16_bf16 v[50:65], v[102:105], v[114:117], v[50:65]
	s_waitcnt vmcnt(0)
	s_barrier
; #define MFMA(a, b, c) __builtin_amdgcn_mfma_f32_32x32x16_bf16((a), (b), (c), 0, 0, 0)
; template <int AI, int BI>
; DI void gemm_tile(const u16* __restrict__ A, int lda, const u16* __restrict__ B, int ldb, int nk, bool swap,
;                   f32x16 (&acc)[AI][BI], char* lds) {
;     ...
;   for (int kt = 0; kt < nk; ++kt) {
;     const char* cur = lds + (kt & 1) * 32768;
;     if (kt + 1 < nk) gemm_stage<AI, BI>(A + (kt + 1) * 64, lda, B + (kt + 1) * 64, ldb, lds + ((kt + 1) & 1) * 32768, tid);
; #pragma unroll
;     for (int ks = 0; ks < 4; ++ks) {
;       const int co = ((ks * 2 + h) ^ sw) << 4;
;       s16x8 fa[AI], fb[BI];
; #pragma unroll
;       for (int i = 0; i < AI; ++i) fa[i] = *(const s16x8*)(cur + offA + i * 4096 + co);
; #pragma unroll
;       for (int i = 0; i < BI; ++i) fb[i] = *(const s16x8*)(cur + offB + i * 4096 + co);
; #pragma unroll
;       for (int i = 0; i < AI; ++i)
; #pragma unroll
;         for (int j = 0; j < BI; ++j) acc[i][j] = MFMA(fa[i], fb[j], acc[i][j]);
;     }
;     asm volatile("s_waitcnt vmcnt(0)" ::: "memory");
;     __syncthreads();
;   }
	v_lshl_add_u64 v[102:103], v[66:67], 0, s[80:81]
	global_load_lds_dwordx4 v[102:103], off
	v_lshl_add_u64 v[102:103], v[68:69], 0, s[80:81]
	s_mov_b32 m0, s37
	s_nop 0
	global_load_lds_dwordx4 v[102:103], off
	v_lshl_add_u64 v[102:103], v[70:71], 0, s[80:81]
	s_mov_b32 m0, s40
	v_mfma_f32_32x32x16_bf16 v[2:17], v[106:109], v[110:113], v[2:17]
	global_load_lds_dwordx4 v[102:103], off
	v_lshl_add_u64 v[102:103], v[72:73], 0, s[80:81]
	s_mov_b32 m0, s41
	s_nop 0
	global_load_lds_dwordx4 v[102:103], off
	s_mov_b32 m0, s28
	v_mfma_f32_32x32x16_bf16 v[18:33], v[106:109], v[114:117], v[18:33]
	global_load_lds_dwordx4 v[100:101], off
	v_lshl_add_u64 v[100:101], v[76:77], 0, s[80:81]
	s_mov_b32 m0, s29
	s_nop 0
	global_load_lds_dwordx4 v[100:101], off
	v_lshl_add_u64 v[100:101], v[78:79], 0, s[80:81]
	s_mov_b32 m0, s34
	s_nop 0
	global_load_lds_dwordx4 v[100:101], off
	v_lshl_add_u64 v[100:101], v[80:81], 0, s[80:81]
	s_mov_b32 m0, s35
	s_nop 0
	global_load_lds_dwordx4 v[100:101], off
	ds_read_b128 v[100:103], v0 offset:32768
	ds_read_b128 v[104:107], v0 offset:36864
	ds_read_b128 v[108:111], v86 offset:49152
	ds_read_b128 v[112:115], v86 offset:53248
	s_waitcnt lgkmcnt(0)
	v_mfma_f32_32x32x16_bf16 v[34:49], v[100:103], v[108:111], v[34:49]
	s_mov_b32 m0, s46
	v_mfma_f32_32x32x16_bf16 v[50:65], v[100:103], v[112:115], v[50:65]
	v_mfma_f32_32x32x16_bf16 v[2:17], v[104:107], v[108:111], v[2:17]
	v_mfma_f32_32x32x16_bf16 v[18:33], v[104:107], v[112:115], v[18:33]
	ds_read_b128 v[100:103], v88 offset:32768
	ds_read_b128 v[104:107], v88 offset:36864
	ds_read_b128 v[108:111], v89 offset:49152
	ds_read_b128 v[112:115], v89 offset:53248
	s_waitcnt lgkmcnt(1)
	v_mfma_f32_32x32x16_bf16 v[34:49], v[100:103], v[108:111], v[34:49]
	s_waitcnt lgkmcnt(0)
	v_mfma_f32_32x32x16_bf16 v[50:65], v[100:103], v[112:115], v[50:65]
	v_mfma_f32_32x32x16_bf16 v[2:17], v[104:107], v[108:111], v[2:17]
	v_mfma_f32_32x32x16_bf16 v[18:33], v[104:107], v[112:115], v[18:33]
	ds_read_b128 v[100:103], v90 offset:32768
	ds_read_b128 v[104:107], v90 offset:36864
	ds_read_b128 v[108:111], v84 offset:49152
	ds_read_b128 v[112:115], v84 offset:53248
	s_waitcnt lgkmcnt(1)
	v_mfma_f32_32x32x16_bf16 v[34:49], v[100:103], v[108:111], v[34:49]
	s_waitcnt lgkmcnt(0)
	v_mfma_f32_32x32x16_bf16 v[50:65], v[100:103], v[112:115], v[50:65]
	v_mfma_f32_32x32x16_bf16 v[2:17], v[104:107], v[108:111], v[2:17]
	v_mfma_f32_32x32x16_bf16 v[18:33], v[104:107], v[112:115], v[18:33]
	ds_read_b128 v[100:103], v85 offset:32768
	ds_read_b128 v[104:107], v85 offset:36864
	ds_read_b128 v[108:111], v87 offset:49152
	ds_read_b128 v[112:115], v87 offset:53248
	s_waitcnt lgkmcnt(0)
	v_mfma_f32_32x32x16_bf16 v[34:49], v[100:103], v[108:111], v[34:49]
	v_mfma_f32_32x32x16_bf16 v[50:65], v[100:103], v[112:115], v[50:65]
	s_waitcnt vmcnt(0)
	s_barrier
	v_lshl_add_u64 v[100:101], v[66:67], 0, s[82:83]
	global_load_lds_dwordx4 v[100:101], off
	v_lshl_add_u64 v[100:101], v[68:69], 0, s[82:83]
	s_mov_b32 m0, s47
	s_nop 0
	global_load_lds_dwordx4 v[100:101], off
	v_lshl_add_u64 v[100:101], v[70:71], 0, s[82:83]
	s_mov_b32 m0, s48
	v_mfma_f32_32x32x16_bf16 v[2:17], v[104:107], v[108:111], v[2:17]
	global_load_lds_dwordx4 v[100:101], off
	s_mov_b32 m0, s49
	s_nop 0
	global_load_lds_dwordx4 v[92:93], off
	v_lshl_add_u64 v[92:93], v[74:75], 0, s[82:83]
	s_mov_b32 m0, s50
	v_mfma_f32_32x32x16_bf16 v[18:33], v[104:107], v[112:115], v[18:33]
	global_load_lds_dwordx4 v[92:93], off
	v_lshl_add_u64 v[92:93], v[76:77], 0, s[82:83]
	s_mov_b32 m0, s51
	s_nop 0
	global_load_lds_dwordx4 v[92:93], off
	v_lshl_add_u64 v[92:93], v[78:79], 0, s[82:83]
	s_mov_b32 m0, s52
	s_nop 0
	global_load_lds_dwordx4 v[92:93], off
	v_lshl_add_u64 v[92:93], v[80:81], 0, s[82:83]
	s_mov_b32 m0, s18
	s_nop 0
	global_load_lds_dwordx4 v[92:93], off
	ds_read_b128 v[92:95], v0
	ds_read_b128 v[96:99], v0 offset:4096
	ds_read_b128 v[100:103], v86 offset:16384
	ds_read_b128 v[104:107], v86 offset:20480
	s_waitcnt lgkmcnt(0)
	v_mfma_f32_32x32x16_bf16 v[34:49], v[92:95], v[100:103], v[34:49]
	s_mov_b32 m0, s36
	v_mfma_f32_32x32x16_bf16 v[50:65], v[92:95], v[104:107], v[50:65]
	v_mfma_f32_32x32x16_bf16 v[2:17], v[96:99], v[100:103], v[2:17]
	v_mfma_f32_32x32x16_bf16 v[18:33], v[96:99], v[104:107], v[18:33]
	ds_read_b128 v[92:95], v88
	ds_read_b128 v[96:99], v88 offset:4096
	ds_read_b128 v[100:103], v89 offset:16384
	ds_read_b128 v[104:107], v89 offset:20480
	s_waitcnt lgkmcnt(1)
	v_mfma_f32_32x32x16_bf16 v[34:49], v[92:95], v[100:103], v[34:49]
	s_waitcnt lgkmcnt(0)
	v_mfma_f32_32x32x16_bf16 v[50:65], v[92:95], v[104:107], v[50:65]
	v_mfma_f32_32x32x16_bf16 v[2:17], v[96:99], v[100:103], v[2:17]
	v_mfma_f32_32x32x16_bf16 v[18:33], v[96:99], v[104:107], v[18:33]
	ds_read_b128 v[92:95], v90
	ds_read_b128 v[96:99], v90 offset:4096
	ds_read_b128 v[100:103], v84 offset:16384
	ds_read_b128 v[104:107], v84 offset:20480
	s_waitcnt lgkmcnt(1)
	v_mfma_f32_32x32x16_bf16 v[34:49], v[92:95], v[100:103], v[34:49]
	s_waitcnt lgkmcnt(0)
	v_mfma_f32_32x32x16_bf16 v[50:65], v[92:95], v[104:107], v[50:65]
	v_mfma_f32_32x32x16_bf16 v[2:17], v[96:99], v[100:103], v[2:17]
	v_mfma_f32_32x32x16_bf16 v[18:33], v[96:99], v[104:107], v[18:33]
	ds_read_b128 v[92:95], v85
	ds_read_b128 v[96:99], v85 offset:4096
	ds_read_b128 v[100:103], v87 offset:16384
	ds_read_b128 v[104:107], v87 offset:20480
	s_waitcnt lgkmcnt(0)
	v_mfma_f32_32x32x16_bf16 v[34:49], v[92:95], v[100:103], v[34:49]
	v_mfma_f32_32x32x16_bf16 v[50:65], v[92:95], v[104:107], v[50:65]
	s_waitcnt vmcnt(0)
	s_barrier
; #define MFMA(a, b, c) __builtin_amdgcn_mfma_f32_32x32x16_bf16((a), (b), (c), 0, 0, 0)
; template <int AI, int BI>
; DI void gemm_tile(const u16* __restrict__ A, int lda, const u16* __restrict__ B, int ldb, int nk, bool swap,
;                   f32x16 (&acc)[AI][BI], char* lds) {
;     ...
;   for (int kt = 0; kt < nk; ++kt) {
;     const char* cur = lds + (kt & 1) * 32768;
;     if (kt + 1 < nk) gemm_stage<AI, BI>(A + (kt + 1) * 64, lda, B + (kt + 1) * 64, ldb, lds + ((kt + 1) & 1) * 32768, tid);
; #pragma unroll
;     for (int ks = 0; ks < 4; ++ks) {
;       const int co = ((ks * 2 + h) ^ sw) << 4;
;       s16x8 fa[AI], fb[BI];
; #pragma unroll
;       for (int i = 0; i < AI; ++i) fa[i] = *(const s16x8*)(cur + offA + i * 4096 + co);
; #pragma unroll
;       for (int i = 0; i < BI; ++i) fb[i] = *(const s16x8*)(cur + offB + i * 4096 + co);
; #pragma unroll
;       for (int i = 0; i < AI; ++i)
; #pragma unroll
;         for (int j = 0; j < BI; ++j) acc[i][j] = MFMA(fa[i], fb[j], acc[i][j]);
;     }
;     asm volatile("s_waitcnt vmcnt(0)" ::: "memory");
;     __syncthreads();
;   }
	v_lshl_add_u64 v[92:93], v[66:67], 0, s[84:85]
	global_load_lds_dwordx4 v[92:93], off
	v_lshl_add_u64 v[92:93], v[68:69], 0, s[84:85]
	s_mov_b32 m0, s37
	s_nop 0
	global_load_lds_dwordx4 v[92:93], off
	v_lshl_add_u64 v[92:93], v[70:71], 0, s[84:85]
	s_mov_b32 m0, s40
	v_mfma_f32_32x32x16_bf16 v[2:17], v[96:99], v[100:103], v[2:17]
	global_load_lds_dwordx4 v[92:93], off
	v_lshl_add_u64 v[92:93], v[72:73], 0, s[84:85]
	s_mov_b32 m0, s41
	s_nop 0
	global_load_lds_dwordx4 v[92:93], off
	v_lshl_add_u64 v[92:93], v[74:75], 0, s[84:85]
	s_mov_b32 m0, s28
	v_mfma_f32_32x32x16_bf16 v[18:33], v[96:99], v[104:107], v[18:33]
	global_load_lds_dwordx4 v[92:93], off
	v_lshl_add_u64 v[92:93], v[76:77], 0, s[84:85]
	s_mov_b32 m0, s29
	s_nop 0
	global_load_lds_dwordx4 v[92:93], off
	v_lshl_add_u64 v[92:93], v[78:79], 0, s[84:85]
	s_mov_b32 m0, s34
	s_nop 0
	global_load_lds_dwordx4 v[92:93], off
	v_lshl_add_u64 v[92:93], v[80:81], 0, s[84:85]
	s_mov_b32 m0, s35
	s_nop 0
	global_load_lds_dwordx4 v[92:93], off
	ds_read_b128 v[92:95], v0 offset:32768
	ds_read_b128 v[96:99], v0 offset:36864
	ds_read_b128 v[100:103], v86 offset:49152
	ds_read_b128 v[104:107], v86 offset:53248
	s_waitcnt lgkmcnt(0)
	v_mfma_f32_32x32x16_bf16 v[34:49], v[92:95], v[100:103], v[34:49]
	s_mov_b32 m0, s46
	v_mfma_f32_32x32x16_bf16 v[50:65], v[92:95], v[104:107], v[50:65]
	v_mfma_f32_32x32x16_bf16 v[2:17], v[96:99], v[100:103], v[2:17]
	v_mfma_f32_32x32x16_bf16 v[18:33], v[96:99], v[104:107], v[18:33]
	ds_read_b128 v[92:95], v88 offset:32768
	ds_read_b128 v[96:99], v88 offset:36864
	ds_read_b128 v[100:103], v89 offset:49152
	ds_read_b128 v[104:107], v89 offset:53248
	s_waitcnt lgkmcnt(1)
	v_mfma_f32_32x32x16_bf16 v[34:49], v[92:95], v[100:103], v[34:49]
	s_waitcnt lgkmcnt(0)
	v_mfma_f32_32x32x16_bf16 v[50:65], v[92:95], v[104:107], v[50:65]
	v_mfma_f32_32x32x16_bf16 v[2:17], v[96:99], v[100:103], v[2:17]
	v_mfma_f32_32x32x16_bf16 v[18:33], v[96:99], v[104:107], v[18:33]
	ds_read_b128 v[92:95], v90 offset:32768
	ds_read_b128 v[96:99], v90 offset:36864
	ds_read_b128 v[100:103], v84 offset:49152
	ds_read_b128 v[104:107], v84 offset:53248
	s_waitcnt lgkmcnt(1)
	v_mfma_f32_32x32x16_bf16 v[34:49], v[92:95], v[100:103], v[34:49]
	s_waitcnt lgkmcnt(0)
	v_mfma_f32_32x32x16_bf16 v[50:65], v[92:95], v[104:107], v[50:65]
	v_mfma_f32_32x32x16_bf16 v[2:17], v[96:99], v[100:103], v[2:17]
	v_mfma_f32_32x32x16_bf16 v[18:33], v[96:99], v[104:107], v[18:33]
	ds_read_b128 v[92:95], v85 offset:32768
	ds_read_b128 v[96:99], v85 offset:36864
	ds_read_b128 v[100:103], v87 offset:49152
	ds_read_b128 v[104:107], v87 offset:53248
	s_waitcnt lgkmcnt(0)
	v_mfma_f32_32x32x16_bf16 v[34:49], v[92:95], v[100:103], v[34:49]
	v_mfma_f32_32x32x16_bf16 v[50:65], v[92:95], v[104:107], v[50:65]
	s_waitcnt vmcnt(0)
	s_barrier
	v_lshl_add_u64 v[92:93], v[66:67], 0, s[88:89]
	global_load_lds_dwordx4 v[92:93], off
	v_lshl_add_u64 v[92:93], v[68:69], 0, s[88:89]
	s_mov_b32 m0, s47
	s_nop 0
	global_load_lds_dwordx4 v[92:93], off
	v_lshl_add_u64 v[92:93], v[70:71], 0, s[88:89]
	s_mov_b32 m0, s48
	v_mfma_f32_32x32x16_bf16 v[2:17], v[96:99], v[100:103], v[2:17]
	global_load_lds_dwordx4 v[92:93], off
	v_lshl_add_u64 v[92:93], v[72:73], 0, s[88:89]
	s_mov_b32 m0, s49
	s_nop 0
	global_load_lds_dwordx4 v[92:93], off
	v_lshl_add_u64 v[92:93], v[74:75], 0, s[88:89]
	s_mov_b32 m0, s50
	v_mfma_f32_32x32x16_bf16 v[18:33], v[96:99], v[104:107], v[18:33]
	global_load_lds_dwordx4 v[92:93], off
	v_lshl_add_u64 v[92:93], v[76:77], 0, s[88:89]
	s_mov_b32 m0, s51
	s_nop 0
	global_load_lds_dwordx4 v[92:93], off
	v_lshl_add_u64 v[92:93], v[78:79], 0, s[88:89]
	s_mov_b32 m0, s52
	s_nop 0
	global_load_lds_dwordx4 v[92:93], off
	v_lshl_add_u64 v[92:93], v[80:81], 0, s[88:89]
	s_mov_b32 m0, s18
	s_nop 0
	global_load_lds_dwordx4 v[92:93], off
	ds_read_b128 v[92:95], v0
	ds_read_b128 v[96:99], v0 offset:4096
	ds_read_b128 v[100:103], v86 offset:16384
	ds_read_b128 v[104:107], v86 offset:20480
	s_waitcnt lgkmcnt(0)
	v_mfma_f32_32x32x16_bf16 v[34:49], v[92:95], v[100:103], v[34:49]
	s_mov_b32 m0, s36
	v_mfma_f32_32x32x16_bf16 v[50:65], v[92:95], v[104:107], v[50:65]
	v_mfma_f32_32x32x16_bf16 v[2:17], v[96:99], v[100:103], v[2:17]
	v_mfma_f32_32x32x16_bf16 v[18:33], v[96:99], v[104:107], v[18:33]
	ds_read_b128 v[92:95], v88
	ds_read_b128 v[96:99], v88 offset:4096
	ds_read_b128 v[100:103], v89 offset:16384
	ds_read_b128 v[104:107], v89 offset:20480
	s_waitcnt lgkmcnt(1)
	v_mfma_f32_32x32x16_bf16 v[34:49], v[92:95], v[100:103], v[34:49]
	s_waitcnt lgkmcnt(0)
	v_mfma_f32_32x32x16_bf16 v[50:65], v[92:95], v[104:107], v[50:65]
	v_mfma_f32_32x32x16_bf16 v[2:17], v[96:99], v[100:103], v[2:17]
	v_mfma_f32_32x32x16_bf16 v[18:33], v[96:99], v[104:107], v[18:33]
	ds_read_b128 v[92:95], v90
	ds_read_b128 v[96:99], v90 offset:4096
	ds_read_b128 v[100:103], v84 offset:16384
	ds_read_b128 v[104:107], v84 offset:20480
	s_waitcnt lgkmcnt(1)
	v_mfma_f32_32x32x16_bf16 v[34:49], v[92:95], v[100:103], v[34:49]
	s_waitcnt lgkmcnt(0)
	v_mfma_f32_32x32x16_bf16 v[50:65], v[92:95], v[104:107], v[50:65]
	v_mfma_f32_32x32x16_bf16 v[2:17], v[96:99], v[100:103], v[2:17]
	v_mfma_f32_32x32x16_bf16 v[18:33], v[96:99], v[104:107], v[18:33]
	ds_read_b128 v[92:95], v85
	ds_read_b128 v[96:99], v85 offset:4096
	ds_read_b128 v[100:103], v87 offset:16384
	ds_read_b128 v[104:107], v87 offset:20480
	s_waitcnt lgkmcnt(0)
	v_mfma_f32_32x32x16_bf16 v[34:49], v[92:95], v[100:103], v[34:49]
	v_mfma_f32_32x32x16_bf16 v[50:65], v[92:95], v[104:107], v[50:65]
	s_waitcnt vmcnt(0)
	s_barrier
; #define MFMA(a, b, c) __builtin_amdgcn_mfma_f32_32x32x16_bf16((a), (b), (c), 0, 0, 0)
; template <int AI, int BI>
; DI void gemm_tile(const u16* __restrict__ A, int lda, const u16* __restrict__ B, int ldb, int nk, bool swap,
;                   f32x16 (&acc)[AI][BI], char* lds) {
;     ...
;   for (int kt = 0; kt < nk; ++kt) {
;     const char* cur = lds + (kt & 1) * 32768;
;     if (kt + 1 < nk) gemm_stage<AI, BI>(A + (kt + 1) * 64, lda, B + (kt + 1) * 64, ldb, lds + ((kt + 1) & 1) * 32768, tid);
; #pragma unroll
;     for (int ks = 0; ks < 4; ++ks) {
;       const int co = ((ks * 2 + h) ^ sw) << 4;
;       s16x8 fa[AI], fb[BI];
; #pragma unroll
;       for (int i = 0; i < AI; ++i) fa[i] = *(const s16x8*)(cur + offA + i * 4096 + co);
; #pragma unroll
;       for (int i = 0; i < BI; ++i) fb[i] = *(const s16x8*)(cur + offB + i * 4096 + co);
; #pragma unroll
;       for (int i = 0; i < AI; ++i)
; #pragma unroll
;         for (int j = 0; j < BI; ++j) acc[i][j] = MFMA(fa[i], fb[j], acc[i][j]);
;     }
;     asm volatile("s_waitcnt vmcnt(0)" ::: "memory");
;     __syncthreads();
;   }
	v_lshl_add_u64 v[92:93], v[66:67], 0, vcc
	global_load_lds_dwordx4 v[92:93], off
	v_lshl_add_u64 v[92:93], v[68:69], 0, vcc
	s_mov_b32 m0, s37
	s_nop 0
	global_load_lds_dwordx4 v[92:93], off
	v_lshl_add_u64 v[92:93], v[70:71], 0, vcc
	s_mov_b32 m0, s40
	v_mfma_f32_32x32x16_bf16 v[2:17], v[96:99], v[100:103], v[2:17]
	global_load_lds_dwordx4 v[92:93], off
	v_lshl_add_u64 v[92:93], v[72:73], 0, vcc
	s_mov_b32 m0, s41
	s_nop 0
	global_load_lds_dwordx4 v[92:93], off
	v_lshl_add_u64 v[92:93], v[74:75], 0, vcc
	s_mov_b32 m0, s28
	v_mfma_f32_32x32x16_bf16 v[18:33], v[96:99], v[104:107], v[18:33]
	global_load_lds_dwordx4 v[92:93], off
	v_lshl_add_u64 v[92:93], v[76:77], 0, vcc
	s_mov_b32 m0, s29
	s_nop 0
	global_load_lds_dwordx4 v[92:93], off
	v_lshl_add_u64 v[92:93], v[78:79], 0, vcc
	s_mov_b32 m0, s34
	s_nop 0
	global_load_lds_dwordx4 v[92:93], off
	v_lshl_add_u64 v[92:93], v[80:81], 0, vcc
	s_mov_b32 m0, s35
	s_nop 0
	global_load_lds_dwordx4 v[92:93], off
	ds_read_b128 v[92:95], v0 offset:32768
	ds_read_b128 v[96:99], v0 offset:36864
	ds_read_b128 v[100:103], v86 offset:49152
	ds_read_b128 v[104:107], v86 offset:53248
	s_waitcnt lgkmcnt(0)
	v_mfma_f32_32x32x16_bf16 v[34:49], v[92:95], v[100:103], v[34:49]
	s_mov_b32 m0, s46
	v_mfma_f32_32x32x16_bf16 v[50:65], v[92:95], v[104:107], v[50:65]
	v_mfma_f32_32x32x16_bf16 v[2:17], v[96:99], v[100:103], v[2:17]
	v_mfma_f32_32x32x16_bf16 v[18:33], v[96:99], v[104:107], v[18:33]
	ds_read_b128 v[92:95], v88 offset:32768
	ds_read_b128 v[96:99], v88 offset:36864
	ds_read_b128 v[100:103], v89 offset:49152
	ds_read_b128 v[104:107], v89 offset:53248
	s_waitcnt lgkmcnt(1)
	v_mfma_f32_32x32x16_bf16 v[34:49], v[92:95], v[100:103], v[34:49]
	s_waitcnt lgkmcnt(0)
	v_mfma_f32_32x32x16_bf16 v[50:65], v[92:95], v[104:107], v[50:65]
	v_mfma_f32_32x32x16_bf16 v[2:17], v[96:99], v[100:103], v[2:17]
	v_mfma_f32_32x32x16_bf16 v[18:33], v[96:99], v[104:107], v[18:33]
	ds_read_b128 v[92:95], v90 offset:32768
	ds_read_b128 v[96:99], v90 offset:36864
	ds_read_b128 v[100:103], v84 offset:49152
	ds_read_b128 v[104:107], v84 offset:53248
	s_waitcnt lgkmcnt(1)
	v_mfma_f32_32x32x16_bf16 v[34:49], v[92:95], v[100:103], v[34:49]
	s_waitcnt lgkmcnt(0)
	v_mfma_f32_32x32x16_bf16 v[50:65], v[92:95], v[104:107], v[50:65]
	v_mfma_f32_32x32x16_bf16 v[2:17], v[96:99], v[100:103], v[2:17]
	v_mfma_f32_32x32x16_bf16 v[18:33], v[96:99], v[104:107], v[18:33]
	ds_read_b128 v[92:95], v85 offset:32768
	ds_read_b128 v[96:99], v85 offset:36864
	ds_read_b128 v[100:103], v87 offset:49152
	ds_read_b128 v[104:107], v87 offset:53248
	s_waitcnt lgkmcnt(0)
	v_mfma_f32_32x32x16_bf16 v[34:49], v[92:95], v[100:103], v[34:49]
	v_mfma_f32_32x32x16_bf16 v[50:65], v[92:95], v[104:107], v[50:65]
	s_waitcnt vmcnt(0)
	s_barrier
	v_lshl_add_u64 v[92:93], v[66:67], 0, s[78:79]
	global_load_lds_dwordx4 v[92:93], off
	v_lshl_add_u64 v[92:93], v[68:69], 0, s[78:79]
	s_mov_b32 m0, s47
	s_nop 0
	global_load_lds_dwordx4 v[92:93], off
	v_lshl_add_u64 v[92:93], v[70:71], 0, s[78:79]
	s_mov_b32 m0, s48
	v_mfma_f32_32x32x16_bf16 v[2:17], v[96:99], v[100:103], v[2:17]
	global_load_lds_dwordx4 v[92:93], off
	v_lshl_add_u64 v[92:93], v[72:73], 0, s[78:79]
	s_mov_b32 m0, s49
	s_nop 0
	global_load_lds_dwordx4 v[92:93], off
	v_lshl_add_u64 v[92:93], v[74:75], 0, s[78:79]
	s_mov_b32 m0, s50
	v_mfma_f32_32x32x16_bf16 v[18:33], v[96:99], v[104:107], v[18:33]
	global_load_lds_dwordx4 v[92:93], off
	v_lshl_add_u64 v[92:93], v[76:77], 0, s[78:79]
	s_mov_b32 m0, s51
	s_nop 0
	global_load_lds_dwordx4 v[92:93], off
	v_lshl_add_u64 v[92:93], v[78:79], 0, s[78:79]
	s_mov_b32 m0, s52
	s_nop 0
	global_load_lds_dwordx4 v[92:93], off
	v_lshl_add_u64 v[92:93], v[80:81], 0, s[78:79]
	s_mov_b32 m0, s18
	s_nop 0
	global_load_lds_dwordx4 v[92:93], off
	ds_read_b128 v[92:95], v0
	ds_read_b128 v[96:99], v0 offset:4096
	ds_read_b128 v[100:103], v86 offset:16384
	ds_read_b128 v[104:107], v86 offset:20480
	s_waitcnt lgkmcnt(0)
	v_mfma_f32_32x32x16_bf16 v[34:49], v[92:95], v[100:103], v[34:49]
	s_mov_b32 m0, s36
	v_mfma_f32_32x32x16_bf16 v[50:65], v[92:95], v[104:107], v[50:65]
	v_mfma_f32_32x32x16_bf16 v[2:17], v[96:99], v[100:103], v[2:17]
	v_mfma_f32_32x32x16_bf16 v[18:33], v[96:99], v[104:107], v[18:33]
	ds_read_b128 v[92:95], v88
	ds_read_b128 v[96:99], v88 offset:4096
	ds_read_b128 v[100:103], v89 offset:16384
	ds_read_b128 v[104:107], v89 offset:20480
	s_waitcnt lgkmcnt(1)
	v_mfma_f32_32x32x16_bf16 v[34:49], v[92:95], v[100:103], v[34:49]
	s_waitcnt lgkmcnt(0)
	v_mfma_f32_32x32x16_bf16 v[50:65], v[92:95], v[104:107], v[50:65]
	v_mfma_f32_32x32x16_bf16 v[2:17], v[96:99], v[100:103], v[2:17]
	v_mfma_f32_32x32x16_bf16 v[18:33], v[96:99], v[104:107], v[18:33]
	ds_read_b128 v[92:95], v90
	ds_read_b128 v[96:99], v90 offset:4096
	ds_read_b128 v[100:103], v84 offset:16384
	ds_read_b128 v[104:107], v84 offset:20480
	s_waitcnt lgkmcnt(1)
	v_mfma_f32_32x32x16_bf16 v[34:49], v[92:95], v[100:103], v[34:49]
	s_waitcnt lgkmcnt(0)
	v_mfma_f32_32x32x16_bf16 v[50:65], v[92:95], v[104:107], v[50:65]
	v_mfma_f32_32x32x16_bf16 v[2:17], v[96:99], v[100:103], v[2:17]
	v_mfma_f32_32x32x16_bf16 v[18:33], v[96:99], v[104:107], v[18:33]
	ds_read_b128 v[92:95], v85
	ds_read_b128 v[96:99], v85 offset:4096
	ds_read_b128 v[100:103], v87 offset:16384
	ds_read_b128 v[104:107], v87 offset:20480
	s_waitcnt lgkmcnt(0)
	v_mfma_f32_32x32x16_bf16 v[34:49], v[92:95], v[100:103], v[34:49]
	v_mfma_f32_32x32x16_bf16 v[50:65], v[92:95], v[104:107], v[50:65]
	s_waitcnt vmcnt(0)
	s_barrier
; #define MFMA(a, b, c) __builtin_amdgcn_mfma_f32_32x32x16_bf16((a), (b), (c), 0, 0, 0)
; template <int AI, int BI>
; DI void gemm_tile(const u16* __restrict__ A, int lda, const u16* __restrict__ B, int ldb, int nk, bool swap,
;                   f32x16 (&acc)[AI][BI], char* lds) {
;     ...
;   for (int kt = 0; kt < nk; ++kt) {
;     const char* cur = lds + (kt & 1) * 32768;
;     if (kt + 1 < nk) gemm_stage<AI, BI>(A + (kt + 1) * 64, lda, B + (kt + 1) * 64, ldb, lds + ((kt + 1) & 1) * 32768, tid);
; #pragma unroll
;     for (int ks = 0; ks < 4; ++ks) {
;       const int co = ((ks * 2 + h) ^ sw) << 4;
;       s16x8 fa[AI], fb[BI];
; #pragma unroll
;       for (int i = 0; i < AI; ++i) fa[i] = *(const s16x8*)(cur + offA + i * 4096 + co);
; #pragma unroll
;       for (int i = 0; i < BI; ++i) fb[i] = *(const s16x8*)(cur + offB + i * 4096 + co);
; #pragma unroll
;       for (int i = 0; i < AI; ++i)
; #pragma unroll
;         for (int j = 0; j < BI; ++j) acc[i][j] = MFMA(fa[i], fb[j], acc[i][j]);
;     }
;     asm volatile("s_waitcnt vmcnt(0)" ::: "memory");
;     __syncthreads();
;   }
	v_lshl_add_u64 v[92:93], v[66:67], 0, s[2:3]
	global_load_lds_dwordx4 v[92:93], off
	v_lshl_add_u64 v[92:93], v[68:69], 0, s[2:3]
	s_mov_b32 m0, s37
	v_lshl_add_u64 v[66:67], v[66:67], 0, s[30:31]
	global_load_lds_dwordx4 v[92:93], off
	v_lshl_add_u64 v[92:93], v[70:71], 0, s[2:3]
	s_mov_b32 m0, s40
	v_mfma_f32_32x32x16_bf16 v[2:17], v[96:99], v[100:103], v[2:17]
	global_load_lds_dwordx4 v[92:93], off
	v_lshl_add_u64 v[92:93], v[72:73], 0, s[2:3]
	s_mov_b32 m0, s41
	s_nop 0
	global_load_lds_dwordx4 v[92:93], off
	v_lshl_add_u64 v[92:93], v[74:75], 0, s[2:3]
	s_mov_b32 m0, s28
	v_mfma_f32_32x32x16_bf16 v[18:33], v[96:99], v[104:107], v[18:33]
	global_load_lds_dwordx4 v[92:93], off
	v_lshl_add_u64 v[92:93], v[76:77], 0, s[2:3]
	s_mov_b32 m0, s29
	s_nop 0
	global_load_lds_dwordx4 v[92:93], off
	v_lshl_add_u64 v[92:93], v[78:79], 0, s[2:3]
	s_mov_b32 m0, s34
	s_nop 0
	global_load_lds_dwordx4 v[92:93], off
	v_lshl_add_u64 v[92:93], v[80:81], 0, s[2:3]
	s_mov_b32 m0, s35
	s_nop 0
	global_load_lds_dwordx4 v[92:93], off
	ds_read_b128 v[92:95], v0 offset:32768
	ds_read_b128 v[96:99], v0 offset:36864
	ds_read_b128 v[100:103], v86 offset:49152
	ds_read_b128 v[104:107], v86 offset:53248
	s_waitcnt lgkmcnt(0)
	v_mfma_f32_32x32x16_bf16 v[34:49], v[92:95], v[100:103], v[34:49]
	s_mov_b32 m0, s46
	v_mfma_f32_32x32x16_bf16 v[50:65], v[92:95], v[104:107], v[50:65]
	v_mfma_f32_32x32x16_bf16 v[2:17], v[96:99], v[100:103], v[2:17]
	v_mfma_f32_32x32x16_bf16 v[18:33], v[96:99], v[104:107], v[18:33]
	ds_read_b128 v[92:95], v88 offset:32768
	ds_read_b128 v[96:99], v88 offset:36864
	ds_read_b128 v[100:103], v89 offset:49152
	ds_read_b128 v[104:107], v89 offset:53248
	s_waitcnt lgkmcnt(1)
	v_mfma_f32_32x32x16_bf16 v[34:49], v[92:95], v[100:103], v[34:49]
	s_waitcnt lgkmcnt(0)
	v_mfma_f32_32x32x16_bf16 v[50:65], v[92:95], v[104:107], v[50:65]
	v_mfma_f32_32x32x16_bf16 v[2:17], v[96:99], v[100:103], v[2:17]
	v_mfma_f32_32x32x16_bf16 v[18:33], v[96:99], v[104:107], v[18:33]
	ds_read_b128 v[92:95], v90 offset:32768
	ds_read_b128 v[96:99], v90 offset:36864
	ds_read_b128 v[100:103], v84 offset:49152
	ds_read_b128 v[104:107], v84 offset:53248
	s_waitcnt lgkmcnt(1)
	v_mfma_f32_32x32x16_bf16 v[34:49], v[92:95], v[100:103], v[34:49]
	s_waitcnt lgkmcnt(0)
	v_mfma_f32_32x32x16_bf16 v[50:65], v[92:95], v[104:107], v[50:65]
	v_mfma_f32_32x32x16_bf16 v[2:17], v[96:99], v[100:103], v[2:17]
	v_mfma_f32_32x32x16_bf16 v[18:33], v[96:99], v[104:107], v[18:33]
	ds_read_b128 v[92:95], v85 offset:32768
	ds_read_b128 v[96:99], v85 offset:36864
	ds_read_b128 v[100:103], v87 offset:49152
	ds_read_b128 v[104:107], v87 offset:53248
	s_waitcnt vmcnt(0)
	s_waitcnt lgkmcnt(0)
	s_barrier
	global_load_lds_dwordx4 v[66:67], off
	v_lshl_add_u64 v[66:67], v[68:69], 0, s[30:31]
	s_mov_b32 m0, s47
	v_mfma_f32_32x32x16_bf16 v[34:49], v[92:95], v[100:103], v[34:49]
	global_load_lds_dwordx4 v[66:67], off
	v_lshl_add_u64 v[66:67], v[70:71], 0, s[30:31]
	s_mov_b32 m0, s48
	s_nop 0
	global_load_lds_dwordx4 v[66:67], off
	v_lshl_add_u64 v[66:67], v[72:73], 0, s[30:31]
	s_mov_b32 m0, s49
	v_mfma_f32_32x32x16_bf16 v[50:65], v[92:95], v[104:107], v[50:65]
	global_load_lds_dwordx4 v[66:67], off
	v_lshl_add_u64 v[66:67], v[74:75], 0, s[30:31]
	s_mov_b32 m0, s50
	s_nop 0
	global_load_lds_dwordx4 v[66:67], off
	v_lshl_add_u64 v[66:67], v[76:77], 0, s[30:31]
	s_mov_b32 m0, s51
	v_mfma_f32_32x32x16_bf16 v[2:17], v[96:99], v[100:103], v[2:17]
	global_load_lds_dwordx4 v[66:67], off
	v_lshl_add_u64 v[66:67], v[78:79], 0, s[30:31]
	s_mov_b32 m0, s52
	s_nop 0
	global_load_lds_dwordx4 v[66:67], off
	v_lshl_add_u64 v[66:67], v[80:81], 0, s[30:31]
	s_mov_b32 m0, s18
	v_mfma_f32_32x32x16_bf16 v[18:33], v[96:99], v[104:107], v[18:33]
	global_load_lds_dwordx4 v[66:67], off
	ds_read_b128 v[66:69], v0
	ds_read_b128 v[70:73], v0 offset:4096
	ds_read_b128 v[74:77], v86 offset:16384
	ds_read_b128 v[78:81], v86 offset:20480
	s_waitcnt lgkmcnt(0)
	v_mfma_f32_32x32x16_bf16 v[34:49], v[66:69], v[74:77], v[34:49]
	v_mfma_f32_32x32x16_bf16 v[50:65], v[66:69], v[78:81], v[50:65]
	v_mfma_f32_32x32x16_bf16 v[2:17], v[70:73], v[74:77], v[2:17]
	v_mfma_f32_32x32x16_bf16 v[18:33], v[70:73], v[78:81], v[18:33]
	ds_read_b128 v[66:69], v88
	ds_read_b128 v[70:73], v88 offset:4096
	ds_read_b128 v[74:77], v89 offset:16384
	ds_read_b128 v[78:81], v89 offset:20480
	s_waitcnt lgkmcnt(1)
	v_mfma_f32_32x32x16_bf16 v[34:49], v[66:69], v[74:77], v[34:49]
	s_waitcnt lgkmcnt(0)
	v_mfma_f32_32x32x16_bf16 v[50:65], v[66:69], v[78:81], v[50:65]
	v_mfma_f32_32x32x16_bf16 v[2:17], v[70:73], v[74:77], v[2:17]
	v_mfma_f32_32x32x16_bf16 v[18:33], v[70:73], v[78:81], v[18:33]
	ds_read_b128 v[66:69], v90
	ds_read_b128 v[70:73], v90 offset:4096
	ds_read_b128 v[74:77], v84 offset:16384
	ds_read_b128 v[78:81], v84 offset:20480
	s_waitcnt lgkmcnt(1)
	v_mfma_f32_32x32x16_bf16 v[34:49], v[66:69], v[74:77], v[34:49]
	s_waitcnt lgkmcnt(0)
	v_mfma_f32_32x32x16_bf16 v[50:65], v[66:69], v[78:81], v[50:65]
	v_mfma_f32_32x32x16_bf16 v[2:17], v[70:73], v[74:77], v[2:17]
	v_mfma_f32_32x32x16_bf16 v[18:33], v[70:73], v[78:81], v[18:33]
	ds_read_b128 v[66:69], v85
	ds_read_b128 v[70:73], v85 offset:4096
	ds_read_b128 v[74:77], v87 offset:16384
	ds_read_b128 v[78:81], v87 offset:20480
	s_waitcnt lgkmcnt(0)
	v_mfma_f32_32x32x16_bf16 v[34:49], v[66:69], v[74:77], v[34:49]
	v_mfma_f32_32x32x16_bf16 v[50:65], v[66:69], v[78:81], v[50:65]
	v_mfma_f32_32x32x16_bf16 v[2:17], v[70:73], v[74:77], v[2:17]
	v_mfma_f32_32x32x16_bf16 v[18:33], v[70:73], v[78:81], v[18:33]
	s_waitcnt vmcnt(0)
	s_barrier
; #define MFMA(a, b, c) __builtin_amdgcn_mfma_f32_32x32x16_bf16((a), (b), (c), 0, 0, 0)
; #define GAS __attribute__((address_space(1)))
; DI int opaque0() { int z = 0; asm volatile("" : "+v"(z)); return z; }
; template <int AI, int BI>
; DI void gemm_tile(const u16* __restrict__ A, int lda, const u16* __restrict__ B, int ldb, int nk, bool swap,
;                   f32x16 (&acc)[AI][BI], char* lds) {
;     ...
;   for (int kt = 0; kt < nk; ++kt) {
;     const char* cur = lds + (kt & 1) * 32768;
;     if (kt + 1 < nk) gemm_stage<AI, BI>(A + (kt + 1) * 64, lda, B + (kt + 1) * 64, ldb, lds + ((kt + 1) & 1) * 32768, tid);
; #pragma unroll
;     for (int ks = 0; ks < 4; ++ks) {
;       const int co = ((ks * 2 + h) ^ sw) << 4;
;       s16x8 fa[AI], fb[BI];
; #pragma unroll
;       for (int i = 0; i < AI; ++i) fa[i] = *(const s16x8*)(cur + offA + i * 4096 + co);
; #pragma unroll
;       for (int i = 0; i < BI; ++i) fb[i] = *(const s16x8*)(cur + offB + i * 4096 + co);
; #pragma unroll
;       for (int i = 0; i < AI; ++i)
; #pragma unroll
;         for (int j = 0; j < BI; ++j) acc[i][j] = MFMA(fa[i], fb[j], acc[i][j]);
;     }
;     asm volatile("s_waitcnt vmcnt(0)" ::: "memory");
;     __syncthreads();
;   }
; template <int AI>
; DI void gu_tile(char* wsb, int sub, int m0, int n0, char* lds) {
;     ...
;   const int m0e = m0 + opaque0();
;   const int hc = (n0 >> 1) + wb * 32 + r;
;   GAS u16* HIDu = uptr(HID);
;   const unsigned ib = (unsigned)((m0e + wa * 32 * AI + 4 * h) * 2816 + hc);
; #pragma unroll
;   for (int ai = 0; ai < AI; ++ai)
; #pragma unroll
;     for (int reg = 0; reg < 16; ++reg) {
;       float g = acc[ai][0][reg], u = acc[ai][1][reg];
;       float v = g * __builtin_amdgcn_rcpf(1.f + __expf(-g)) * u;
;       HIDu[ib + (unsigned)((ai * 32 + (reg & 3) + 8 * (reg >> 2)) * 2816)] = f2bf(v);
;       if ((reg & 7) == 7) __builtin_amdgcn_sched_barrier(0);
;     }
	ds_read_b128 v[66:69], v0 offset:32768
	ds_read_b128 v[70:73], v0 offset:36864
	ds_read_b128 v[74:77], v86 offset:49152
	ds_read_b128 v[78:81], v86 offset:53248
	v_mov_b32_e32 v0, v1
	s_waitcnt lgkmcnt(1)
	v_mfma_f32_32x32x16_bf16 v[34:49], v[66:69], v[74:77], v[34:49]
	s_waitcnt lgkmcnt(0)
	v_mfma_f32_32x32x16_bf16 v[50:65], v[66:69], v[78:81], v[50:65]
	v_mfma_f32_32x32x16_bf16 v[2:17], v[70:73], v[74:77], v[2:17]
	v_mfma_f32_32x32x16_bf16 v[18:33], v[70:73], v[78:81], v[18:33]
	ds_read_b128 v[66:69], v88 offset:32768
	ds_read_b128 v[70:73], v88 offset:36864
	ds_read_b128 v[74:77], v89 offset:49152
	ds_read_b128 v[78:81], v89 offset:53248
	s_waitcnt lgkmcnt(1)
	v_mfma_f32_32x32x16_bf16 v[34:49], v[66:69], v[74:77], v[34:49]
	s_waitcnt lgkmcnt(0)
	v_mfma_f32_32x32x16_bf16 v[50:65], v[66:69], v[78:81], v[50:65]
	v_mfma_f32_32x32x16_bf16 v[2:17], v[70:73], v[74:77], v[2:17]
	v_mfma_f32_32x32x16_bf16 v[18:33], v[70:73], v[78:81], v[18:33]
	ds_read_b128 v[66:69], v90 offset:32768
	ds_read_b128 v[70:73], v90 offset:36864
	ds_read_b128 v[74:77], v84 offset:49152
	ds_read_b128 v[78:81], v84 offset:53248
	s_waitcnt lgkmcnt(1)
	v_mfma_f32_32x32x16_bf16 v[34:49], v[66:69], v[74:77], v[34:49]
	s_waitcnt lgkmcnt(0)
	v_mfma_f32_32x32x16_bf16 v[50:65], v[66:69], v[78:81], v[50:65]
	v_mfma_f32_32x32x16_bf16 v[2:17], v[70:73], v[74:77], v[2:17]
	v_mfma_f32_32x32x16_bf16 v[18:33], v[70:73], v[78:81], v[18:33]
	ds_read_b128 v[66:69], v85 offset:32768
	ds_read_b128 v[70:73], v85 offset:36864
	ds_read_b128 v[74:77], v87 offset:49152
	ds_read_b128 v[78:81], v87 offset:53248
	s_waitcnt vmcnt(0)
	s_waitcnt lgkmcnt(0)
	s_barrier
	v_mfma_f32_32x32x16_bf16 v[34:49], v[66:69], v[74:77], v[34:49]
	v_mfma_f32_32x32x16_bf16 v[50:65], v[66:69], v[78:81], v[50:65]
	v_lshrrev_b32_e32 v66, 1, v83
	v_lshrrev_b32_e32 v68, 3, v82
	v_and_b32_e32 v67, 32, v66
	v_and_b32_e32 v66, 0xffffc0, v66
	v_and_or_b32 v68, v68, 4, s16
	v_add3_u32 v66, v68, v66, v0
	v_or3_b32 v0, s17, v91, v67
	s_nop 3
	v_mul_f32_e32 v67, 0xbfb8aa3b, v34
	v_exp_f32_e32 v67, v67
	v_mfma_f32_32x32x16_bf16 v[2:17], v[70:73], v[74:77], v[2:17]
	v_add_f32_e32 v67, 1.0, v67
	v_rcp_f32_e32 v67, v67
	s_nop 0
	v_mul_f32_e32 v34, v34, v67
	v_mad_u64_u32 v[66:67], s[16:17], v66, s64, v[0:1]
	v_mul_f32_e32 v0, 0xbfb8aa3b, v35
	v_exp_f32_e32 v0, v0
	v_mul_f32_e32 v34, v50, v34
	v_mov_b32_e32 v67, v1
	v_cvt_pk_bf16_f32 v34, v34, s0
	v_add_f32_e32 v0, 1.0, v0
	v_rcp_f32_e32 v0, v0
	v_lshl_add_u64 v[68:69], v[66:67], 1, s[6:7]
	global_store_short v[68:69], v34, off
	v_mfma_f32_32x32x16_bf16 v[18:33], v[70:73], v[78:81], v[18:33]
	v_mul_f32_e32 v0, v35, v0
	v_mul_f32_e32 v0, v51, v0
	v_cvt_pk_bf16_f32 v50, v0, s0
	v_add_u32_e32 v0, 0xb00, v66
	v_lshl_add_u64 v[34:35], v[0:1], 1, s[6:7]
	v_mul_f32_e32 v0, 0xbfb8aa3b, v36
	v_exp_f32_e32 v0, v0
	global_store_short v[34:35], v50, off
	v_add_f32_e32 v0, 1.0, v0
	v_rcp_f32_e32 v0, v0
	s_nop 0
	v_mul_f32_e32 v0, v36, v0
	v_mul_f32_e32 v0, v52, v0
	v_cvt_pk_bf16_f32 v36, v0, s0
	v_add_u32_e32 v0, 0x1600, v66
	v_lshl_add_u64 v[34:35], v[0:1], 1, s[6:7]
	v_mul_f32_e32 v0, 0xbfb8aa3b, v37
	v_exp_f32_e32 v0, v0
	global_store_short v[34:35], v36, off
	v_add_f32_e32 v0, 1.0, v0
	v_rcp_f32_e32 v0, v0
	s_nop 0
	v_mul_f32_e32 v0, v37, v0
	v_mul_f32_e32 v0, v53, v0
	v_cvt_pk_bf16_f32 v36, v0, s0
	v_add_u32_e32 v0, 0x2100, v66
	v_lshl_add_u64 v[34:35], v[0:1], 1, s[6:7]
	v_mul_f32_e32 v0, 0xbfb8aa3b, v38
	v_exp_f32_e32 v0, v0
	global_store_short v[34:35], v36, off
	v_add_f32_e32 v0, 1.0, v0
	v_rcp_f32_e32 v0, v0
	s_nop 0
	v_mul_f32_e32 v0, v38, v0
	v_mul_f32_e32 v0, v54, v0
	v_cvt_pk_bf16_f32 v36, v0, s0
	v_add_u32_e32 v0, 0x5800, v66
	v_lshl_add_u64 v[34:35], v[0:1], 1, s[6:7]
	v_mul_f32_e32 v0, 0xbfb8aa3b, v39
	v_exp_f32_e32 v0, v0
	global_store_short v[34:35], v36, off
	v_add_f32_e32 v0, 1.0, v0
	v_rcp_f32_e32 v0, v0
	s_nop 0
	v_mul_f32_e32 v0, v39, v0
	v_mul_f32_e32 v0, v55, v0
	v_cvt_pk_bf16_f32 v36, v0, s0
	v_add_u32_e32 v0, 0x6300, v66
	v_lshl_add_u64 v[34:35], v[0:1], 1, s[6:7]
	v_mul_f32_e32 v0, 0xbfb8aa3b, v40
	v_exp_f32_e32 v0, v0
	global_store_short v[34:35], v36, off
	v_add_f32_e32 v0, 1.0, v0
	v_rcp_f32_e32 v0, v0
	s_nop 0
	v_mul_f32_e32 v0, v40, v0
	v_mul_f32_e32 v0, v56, v0
	v_cvt_pk_bf16_f32 v36, v0, s0
	v_add_u32_e32 v0, 0x6e00, v66
	v_lshl_add_u64 v[34:35], v[0:1], 1, s[6:7]
	v_mul_f32_e32 v0, 0xbfb8aa3b, v41
	v_exp_f32_e32 v0, v0
	global_store_short v[34:35], v36, off
	v_add_f32_e32 v0, 1.0, v0
	v_rcp_f32_e32 v0, v0
	s_nop 0
	v_mul_f32_e32 v0, v41, v0
	v_mul_f32_e32 v0, v57, v0
	v_cvt_pk_bf16_f32 v36, v0, s0
	v_add_u32_e32 v0, 0x7900, v66
	v_lshl_add_u64 v[34:35], v[0:1], 1, s[6:7]
	global_store_short v[34:35], v36, off
	v_mul_f32_e32 v0, 0xbfb8aa3b, v42
	v_exp_f32_e32 v0, v0
	s_nop 0
	v_add_f32_e32 v0, 1.0, v0
	v_rcp_f32_e32 v0, v0
	s_nop 0
	v_mul_f32_e32 v0, v42, v0
	v_mul_f32_e32 v0, v58, v0
	v_cvt_pk_bf16_f32 v36, v0, s0
	v_add_u32_e32 v0, 0xb000, v66
	v_lshl_add_u64 v[34:35], v[0:1], 1, s[6:7]
	v_mul_f32_e32 v0, 0xbfb8aa3b, v43
	v_exp_f32_e32 v0, v0
	global_store_short v[34:35], v36, off
	v_add_f32_e32 v0, 1.0, v0
	v_rcp_f32_e32 v0, v0
	s_nop 0
	v_mul_f32_e32 v0, v43, v0
	v_mul_f32_e32 v0, v59, v0
	v_cvt_pk_bf16_f32 v36, v0, s0
	v_add_u32_e32 v0, 0xbb00, v66
	v_lshl_add_u64 v[34:35], v[0:1], 1, s[6:7]
	v_mul_f32_e32 v0, 0xbfb8aa3b, v44
	v_exp_f32_e32 v0, v0
	global_store_short v[34:35], v36, off
	v_add_f32_e32 v0, 1.0, v0
	v_rcp_f32_e32 v0, v0
	s_nop 0
	v_mul_f32_e32 v0, v44, v0
	v_mul_f32_e32 v0, v60, v0
	v_cvt_pk_bf16_f32 v36, v0, s0
	v_add_u32_e32 v0, 0xc600, v66
	v_lshl_add_u64 v[34:35], v[0:1], 1, s[6:7]
	v_mul_f32_e32 v0, 0xbfb8aa3b, v45
	v_exp_f32_e32 v0, v0
; template <int AI>
; DI void gu_tile(char* wsb, int sub, int m0, int n0, char* lds) {
;     ...
;   const unsigned ib = (unsigned)((m0e + wa * 32 * AI + 4 * h) * 2816 + hc);
; #pragma unroll
;   for (int ai = 0; ai < AI; ++ai)
; #pragma unroll
;     for (int reg = 0; reg < 16; ++reg) {
;       float g = acc[ai][0][reg], u = acc[ai][1][reg];
;       float v = g * __builtin_amdgcn_rcpf(1.f + __expf(-g)) * u;
;       HIDu[ib + (unsigned)((ai * 32 + (reg & 3) + 8 * (reg >> 2)) * 2816)] = f2bf(v);
;       if ((reg & 7) == 7) __builtin_amdgcn_sched_barrier(0);
;     }
; }
; DI void phase_gu(const Params& p, char* wsb, int sub, int mrows, char* lds) {
;   int mt, nt;
;   for (int rnd = 0; next_tile(rnd, 128, 44, mt, nt); ++rnd) gu_tile<2>(wsb, sub, mt * 128, nt * 128, lds);
;   if (mrows > TL)
;     for (int rnd = 0; next_tile(rnd, 32, 44, mt, nt); ++rnd) gu_tile<1>(wsb, sub, TL + mt * 64, nt * 128, lds);
	global_store_short v[34:35], v36, off
	v_add_f32_e32 v0, 1.0, v0
	v_rcp_f32_e32 v0, v0
	s_nop 0
	v_mul_f32_e32 v0, v45, v0
	v_mul_f32_e32 v0, v61, v0
	v_cvt_pk_bf16_f32 v36, v0, s0
	v_add_u32_e32 v0, 0xd100, v66
	v_lshl_add_u64 v[34:35], v[0:1], 1, s[6:7]
	v_mul_f32_e32 v0, 0xbfb8aa3b, v46
	v_exp_f32_e32 v0, v0
	global_store_short v[34:35], v36, off
	v_add_f32_e32 v0, 1.0, v0
	v_rcp_f32_e32 v0, v0
	s_nop 0
	v_mul_f32_e32 v0, v46, v0
	v_mul_f32_e32 v0, v62, v0
	v_cvt_pk_bf16_f32 v36, v0, s0
	v_add_u32_e32 v0, 0x10800, v66
	v_lshl_add_u64 v[34:35], v[0:1], 1, s[6:7]
	v_mul_f32_e32 v0, 0xbfb8aa3b, v47
	v_exp_f32_e32 v0, v0
	global_store_short v[34:35], v36, off
	v_add_f32_e32 v0, 1.0, v0
	v_rcp_f32_e32 v0, v0
	s_nop 0
	v_mul_f32_e32 v0, v47, v0
	v_mul_f32_e32 v0, v63, v0
	v_cvt_pk_bf16_f32 v36, v0, s0
	v_add_u32_e32 v0, 0x11300, v66
	v_lshl_add_u64 v[34:35], v[0:1], 1, s[6:7]
	v_mul_f32_e32 v0, 0xbfb8aa3b, v48
	v_exp_f32_e32 v0, v0
	global_store_short v[34:35], v36, off
	v_add_f32_e32 v0, 1.0, v0
	v_rcp_f32_e32 v0, v0
	s_nop 0
	v_mul_f32_e32 v0, v48, v0
	v_mul_f32_e32 v0, v64, v0
	v_cvt_pk_bf16_f32 v36, v0, s0
	v_add_u32_e32 v0, 0x11e00, v66
	v_lshl_add_u64 v[34:35], v[0:1], 1, s[6:7]
	v_mul_f32_e32 v0, 0xbfb8aa3b, v49
	v_exp_f32_e32 v0, v0
	global_store_short v[34:35], v36, off
	v_add_f32_e32 v0, 1.0, v0
	v_rcp_f32_e32 v0, v0
	s_nop 0
	v_mul_f32_e32 v0, v49, v0
	v_mul_f32_e32 v0, v65, v0
	v_cvt_pk_bf16_f32 v36, v0, s0
	v_add_u32_e32 v0, 0x12900, v66
	v_lshl_add_u64 v[34:35], v[0:1], 1, s[6:7]
	global_store_short v[34:35], v36, off
	v_mul_f32_e32 v0, 0xbfb8aa3b, v2
	v_exp_f32_e32 v0, v0
	s_nop 0
	v_add_f32_e32 v0, 1.0, v0
	v_rcp_f32_e32 v0, v0
	s_nop 0
	v_mul_f32_e32 v0, v2, v0
	v_mul_f32_e32 v0, v18, v0
	v_cvt_pk_bf16_f32 v2, v0, s0
	v_add_u32_e32 v0, 0x16000, v66
	v_lshl_add_u64 v[34:35], v[0:1], 1, s[6:7]
	v_mul_f32_e32 v0, 0xbfb8aa3b, v3
	v_exp_f32_e32 v0, v0
	global_store_short v[34:35], v2, off
	v_add_f32_e32 v0, 1.0, v0
	v_rcp_f32_e32 v0, v0
	s_nop 0
	v_mul_f32_e32 v0, v3, v0
	v_mul_f32_e32 v0, v19, v0
	v_cvt_pk_bf16_f32 v18, v0, s0
	v_add_u32_e32 v0, 0x16b00, v66
	v_lshl_add_u64 v[2:3], v[0:1], 1, s[6:7]
	v_mul_f32_e32 v0, 0xbfb8aa3b, v4
	v_exp_f32_e32 v0, v0
	global_store_short v[2:3], v18, off
	v_add_f32_e32 v0, 1.0, v0
	v_rcp_f32_e32 v0, v0
	s_nop 0
	v_mul_f32_e32 v0, v4, v0
	v_mul_f32_e32 v0, v20, v0
	v_cvt_pk_bf16_f32 v4, v0, s0
	v_add_u32_e32 v0, 0x17600, v66
	v_lshl_add_u64 v[2:3], v[0:1], 1, s[6:7]
	v_mul_f32_e32 v0, 0xbfb8aa3b, v5
	v_exp_f32_e32 v0, v0
	global_store_short v[2:3], v4, off
	v_add_f32_e32 v0, 1.0, v0
	v_rcp_f32_e32 v0, v0
	s_nop 0
	v_mul_f32_e32 v0, v5, v0
	v_mul_f32_e32 v0, v21, v0
	v_cvt_pk_bf16_f32 v4, v0, s0
	v_add_u32_e32 v0, 0x18100, v66
	v_lshl_add_u64 v[2:3], v[0:1], 1, s[6:7]
	v_mul_f32_e32 v0, 0xbfb8aa3b, v6
	v_exp_f32_e32 v0, v0
	global_store_short v[2:3], v4, off
	v_add_f32_e32 v0, 1.0, v0
	v_rcp_f32_e32 v0, v0
	s_nop 0
	v_mul_f32_e32 v0, v6, v0
	v_mul_f32_e32 v0, v22, v0
	v_cvt_pk_bf16_f32 v4, v0, s0
	v_add_u32_e32 v0, 0x1b800, v66
	v_lshl_add_u64 v[2:3], v[0:1], 1, s[6:7]
	v_mul_f32_e32 v0, 0xbfb8aa3b, v7
	v_exp_f32_e32 v0, v0
	global_store_short v[2:3], v4, off
	v_add_f32_e32 v0, 1.0, v0
	v_rcp_f32_e32 v0, v0
	s_nop 0
	v_mul_f32_e32 v0, v7, v0
	v_mul_f32_e32 v0, v23, v0
	v_cvt_pk_bf16_f32 v4, v0, s0
	v_add_u32_e32 v0, 0x1c300, v66
	v_lshl_add_u64 v[2:3], v[0:1], 1, s[6:7]
	v_mul_f32_e32 v0, 0xbfb8aa3b, v8
	v_exp_f32_e32 v0, v0
	global_store_short v[2:3], v4, off
	v_add_f32_e32 v0, 1.0, v0
	v_rcp_f32_e32 v0, v0
	s_nop 0
	v_mul_f32_e32 v0, v8, v0
	v_mul_f32_e32 v0, v24, v0
	v_cvt_pk_bf16_f32 v4, v0, s0
	v_add_u32_e32 v0, 0x1ce00, v66
	v_lshl_add_u64 v[2:3], v[0:1], 1, s[6:7]
	v_mul_f32_e32 v0, 0xbfb8aa3b, v9
	v_exp_f32_e32 v0, v0
	global_store_short v[2:3], v4, off
	v_add_f32_e32 v0, 1.0, v0
	v_rcp_f32_e32 v0, v0
	s_nop 0
	v_mul_f32_e32 v0, v9, v0
	v_mul_f32_e32 v0, v25, v0
	v_cvt_pk_bf16_f32 v4, v0, s0
	v_add_u32_e32 v0, 0x1d900, v66
	v_lshl_add_u64 v[2:3], v[0:1], 1, s[6:7]
	global_store_short v[2:3], v4, off
	v_mul_f32_e32 v0, 0xbfb8aa3b, v10
	v_exp_f32_e32 v0, v0
	s_nop 0
	v_add_f32_e32 v0, 1.0, v0
	v_rcp_f32_e32 v0, v0
	s_nop 0
	v_mul_f32_e32 v0, v10, v0
	v_mul_f32_e32 v0, v26, v0
	v_cvt_pk_bf16_f32 v4, v0, s0
	v_add_u32_e32 v0, 0x21000, v66
	v_lshl_add_u64 v[2:3], v[0:1], 1, s[6:7]
	v_mul_f32_e32 v0, 0xbfb8aa3b, v11
	v_exp_f32_e32 v0, v0
	global_store_short v[2:3], v4, off
	v_add_f32_e32 v0, 1.0, v0
	v_rcp_f32_e32 v0, v0
	s_nop 0
	v_mul_f32_e32 v0, v11, v0
	v_mul_f32_e32 v0, v27, v0
	v_cvt_pk_bf16_f32 v4, v0, s0
	v_add_u32_e32 v0, 0x21b00, v66
	v_lshl_add_u64 v[2:3], v[0:1], 1, s[6:7]
	v_mul_f32_e32 v0, 0xbfb8aa3b, v12
	v_exp_f32_e32 v0, v0
	global_store_short v[2:3], v4, off
	v_add_f32_e32 v0, 1.0, v0
	v_rcp_f32_e32 v0, v0
	s_nop 0
	v_mul_f32_e32 v0, v12, v0
	v_mul_f32_e32 v0, v28, v0
	v_cvt_pk_bf16_f32 v4, v0, s0
	v_add_u32_e32 v0, 0x22600, v66
	v_lshl_add_u64 v[2:3], v[0:1], 1, s[6:7]
	v_mul_f32_e32 v0, 0xbfb8aa3b, v13
	v_exp_f32_e32 v0, v0
	global_store_short v[2:3], v4, off
	v_add_f32_e32 v0, 1.0, v0
	v_rcp_f32_e32 v0, v0
	s_nop 0
	v_mul_f32_e32 v0, v13, v0
	v_mul_f32_e32 v0, v29, v0
	v_cvt_pk_bf16_f32 v4, v0, s0
	v_add_u32_e32 v0, 0x23100, v66
	v_lshl_add_u64 v[2:3], v[0:1], 1, s[6:7]
	v_mul_f32_e32 v0, 0xbfb8aa3b, v14
	v_exp_f32_e32 v0, v0
	global_store_short v[2:3], v4, off
	v_add_f32_e32 v0, 1.0, v0
	v_rcp_f32_e32 v0, v0
	s_nop 0
	v_mul_f32_e32 v0, v14, v0
	v_mul_f32_e32 v0, v30, v0
	v_cvt_pk_bf16_f32 v4, v0, s0
	v_add_u32_e32 v0, 0x26800, v66
	v_lshl_add_u64 v[2:3], v[0:1], 1, s[6:7]
	v_mul_f32_e32 v0, 0xbfb8aa3b, v15
	v_exp_f32_e32 v0, v0
	global_store_short v[2:3], v4, off
	v_add_f32_e32 v0, 1.0, v0
	v_rcp_f32_e32 v0, v0
	s_nop 0
	v_mul_f32_e32 v0, v15, v0
	v_mul_f32_e32 v0, v31, v0
	v_cvt_pk_bf16_f32 v4, v0, s0
	v_add_u32_e32 v0, 0x27300, v66
	v_lshl_add_u64 v[2:3], v[0:1], 1, s[6:7]
	v_mul_f32_e32 v0, 0xbfb8aa3b, v16
	v_exp_f32_e32 v0, v0
	global_store_short v[2:3], v4, off
	v_add_f32_e32 v0, 1.0, v0
	v_rcp_f32_e32 v0, v0
	s_nop 0
	v_mul_f32_e32 v0, v16, v0
	v_mul_f32_e32 v0, v32, v0
	v_cvt_pk_bf16_f32 v4, v0, s0
	v_add_u32_e32 v0, 0x27e00, v66
	v_lshl_add_u64 v[2:3], v[0:1], 1, s[6:7]
	v_mul_f32_e32 v0, 0xbfb8aa3b, v17
	v_exp_f32_e32 v0, v0
	global_store_short v[2:3], v4, off
	v_add_f32_e32 v0, 1.0, v0
	v_rcp_f32_e32 v0, v0
	s_nop 0
	v_mul_f32_e32 v0, v17, v0
	v_mul_f32_e32 v0, v33, v0
	v_cvt_pk_bf16_f32 v4, v0, s0
	v_add_u32_e32 v0, 0x28900, v66
	v_lshl_add_u64 v[2:3], v[0:1], 1, s[6:7]
	global_store_short v[2:3], v4, off
	v_readlane_b32 s16, v245, 0
	s_cmp_eq_u32 s16, 1
	s_cbranch_scc1 .Lgu2_done
	s_add_i32 s15, s15, s53
	s_add_i32 s14, s14, s56
	s_cmpk_lt_u32 s14, 0x1600
	s_cbranch_scc1 .LBB0_1206

; #define MFMA(a, b, c) __builtin_amdgcn_mfma_f32_32x32x16_bf16((a), (b), (c), 0, 0, 0)
; #define TIDX opaque_tid()
; template <int AI, int BI>
; DI void gemm_tile(const u16* __restrict__ A, int lda, const u16* __restrict__ B, int ldb, int nk, bool swap,
;                   f32x16 (&acc)[AI][BI], char* lds) {
;   const int tid = TIDX, lane = tid & 63, wid = tid >> 6;
;   gemm_stage<AI, BI>(A, lda, B, ldb, lds, tid);
;   asm volatile("s_waitcnt vmcnt(0)" ::: "memory");
;   __syncthreads();
;   const int wa = wid >> 1, wb = wid & 1, r = lane & 31, h = lane >> 5, sw = (r >> 1) & 7;
;   const int offA = (swap ? 16384 : 0) + (wa * 32 * AI + r) * 128;
;   const int offB = (swap ? 0 : 16384) + (wb * 32 * BI + r) * 128;
;   for (int kt = 0; kt < nk; ++kt) {
;     const char* cur = lds + (kt & 1) * 32768;
;     if (kt + 1 < nk) gemm_stage<AI, BI>(A + (kt + 1) * 64, lda, B + (kt + 1) * 64, ldb, lds + ((kt + 1) & 1) * 32768, tid);
; #pragma unroll
;     for (int ks = 0; ks < 4; ++ks) {
;       const int co = ((ks * 2 + h) ^ sw) << 4;
;       s16x8 fa[AI], fb[BI];
; #pragma unroll
;       for (int i = 0; i < AI; ++i) fa[i] = *(const s16x8*)(cur + offA + i * 4096 + co);
; #pragma unroll
;       for (int i = 0; i < BI; ++i) fb[i] = *(const s16x8*)(cur + offB + i * 4096 + co);
; #pragma unroll
;       for (int i = 0; i < AI; ++i)
; #pragma unroll
;         for (int j = 0; j < BI; ++j) acc[i][j] = MFMA(fa[i], fb[j], acc[i][j]);
;     }
;     asm volatile("s_waitcnt vmcnt(0)" ::: "memory");
;     __syncthreads();
;   }
.LBB0_1210:
	s_and_b32 s8, s14, 0xffff
	s_mul_hi_u32 s9, s8, 0xba2e8c
	s_mul_i32 s8, s8, 0xba2f
	s_lshr_b32 s8, s8, 24
	s_lshl_b32 s8, s8, 9
	s_and_b32 s17, s16, 0x1c0
	s_mulk_i32 s9, 0x1600
	s_or_b32 s17, s8, s17
	s_sub_i32 s9, s15, s9
	s_addk_i32 s17, 0x4000
	s_and_b32 s8, s9, 0xffffff80
	v_mov_b32_e32 v46, v178
	v_mov_b32_e32 v47, v178
	s_lshl_b32 s9, s17, 11
	v_mov_b32_e32 v8, v178
	s_add_u32 s28, s10, s9
	s_addc_u32 s29, s11, 0
	v_lshrrev_b32_e32 v0, 4, v8
	s_ashr_i32 s9, s8, 31
	v_xor_b32_e32 v0, v0, v8
	v_add_u32_e32 v9, 0x100, v8
	s_lshl_b64 s[34:35], s[8:9], 11
	v_lshlrev_b32_e32 v0, 4, v0
	v_ashrrev_i32_e32 v4, 3, v8
	v_ashrrev_i32_e32 v6, 3, v9
	s_add_u32 s34, s12, s34
	v_and_b32_e32 v0, 0x70, v0
	v_ashrrev_i32_e32 v5, 31, v4
	v_ashrrev_i32_e32 v7, 31, v6
	s_addc_u32 s35, s13, s35
	v_lshl_add_u64 v[2:3], s[28:29], 0, v[0:1]
	v_lshlrev_b64 v[4:5], 11, v[4:5]
	v_lshlrev_b64 v[6:7], 11, v[6:7]
	v_lshl_add_u64 v[34:35], v[2:3], 0, v[4:5]
	v_lshl_add_u64 v[36:37], v[2:3], 0, v[6:7]
	v_lshl_add_u64 v[2:3], s[34:35], 0, v[0:1]
	v_add_u32_e32 v0, 0x200, v8
	v_lshl_add_u64 v[40:41], v[2:3], 0, v[4:5]
	v_ashrrev_i32_e32 v4, 3, v0
	v_ashrrev_i32_e32 v5, 31, v4
	v_lshl_add_u64 v[38:39], v[2:3], 0, v[6:7]
	v_lshlrev_b64 v[4:5], 11, v[4:5]
	v_add_u32_e32 v6, 0x300, v8
	v_lshl_add_u64 v[42:43], v[2:3], 0, v[4:5]
	v_ashrrev_i32_e32 v4, 3, v6
	v_ashrrev_i32_e32 v5, 31, v4
	v_lshlrev_b32_e32 v55, 4, v8
	v_lshlrev_b64 v[4:5], 11, v[4:5]
	v_readfirstlane_b32 s9, v55
	v_lshlrev_b32_e32 v56, 4, v9
	v_lshl_add_u64 v[44:45], v[2:3], 0, v[4:5]
	v_and_b32_e32 v2, 31, v8
	v_lshrrev_b32_e32 v7, 2, v8
	s_mov_b32 m0, s9
	v_readfirstlane_b32 s18, v56
	v_add_u32_e32 v57, 0x4000, v55
	v_and_or_b32 v2, v7, s52, v2
	global_load_lds_dwordx4 v[34:35], off
	s_mov_b32 m0, s18
	v_readfirstlane_b32 s28, v57
	v_add_u32_e32 v59, 0x4000, v56
	v_lshlrev_b32_e32 v0, 4, v0
	v_lshlrev_b32_e32 v4, 4, v6
	v_lshrrev_b32_e32 v3, 5, v8
	v_bfe_u32 v6, v8, 1, 3
	v_lshlrev_b32_e32 v53, 7, v2
	v_lshlrev_b32_e32 v2, 7, v8
	global_load_lds_dwordx4 v[36:37], off
	s_mov_b32 m0, s28
	v_readfirstlane_b32 s29, v59
	v_add_u32_e32 v65, 0x4000, v0
	v_bfe_u32 v5, v8, 5, 1
	v_and_b32_e32 v67, 0x2f80, v2
	v_bitop3_b32 v2, v3, v6, 1 bitop3:0x6c
	global_load_lds_dwordx4 v[40:41], off
	s_mov_b32 m0, s29
	v_readfirstlane_b32 s34, v65
	v_add_u32_e32 v66, 0x4000, v4
	v_lshlrev_b32_e32 v7, 4, v2
	v_bitop3_b32 v2, v5, v6, 2 bitop3:0x36
	global_load_lds_dwordx4 v[38:39], off
	s_mov_b32 m0, s34
	v_readfirstlane_b32 s41, v66
	v_lshlrev_b32_e32 v49, 4, v2
	v_bitop3_b32 v2, v5, v6, 4 bitop3:0x36
	v_add_u32_e32 v64, 0x8000, v55
	global_load_lds_dwordx4 v[42:43], off
	s_mov_b32 m0, s41
	v_lshlrev_b32_e32 v51, 4, v2
	v_bitop3_b32 v2, v5, v6, 6 bitop3:0x36
	v_readfirstlane_b32 s35, v64
	v_add_u32_e32 v61, 0x8000, v56
	global_load_lds_dwordx4 v[44:45], off
	v_lshlrev_b32_e32 v80, 4, v2
	v_lshl_add_u64 v[2:3], v[34:35], 0, s[64:65]
	s_mov_b32 m0, s35
	v_readfirstlane_b32 s36, v61
	v_add_u32_e32 v58, 0xc000, v55
	s_waitcnt vmcnt(0)
	s_waitcnt vmcnt(0) lgkmcnt(0)
	s_barrier
	global_load_lds_dwordx4 v[2:3], off
	v_lshl_add_u64 v[2:3], v[36:37], 0, s[64:65]
	s_mov_b32 m0, s36
	v_readfirstlane_b32 s37, v58
	v_add_u32_e32 v60, 0xc000, v56
	global_load_lds_dwordx4 v[2:3], off
	v_lshl_add_u64 v[2:3], v[40:41], 0, s[64:65]
	s_mov_b32 m0, s37
	v_readfirstlane_b32 s40, v60
	v_add_u32_e32 v62, 0xc000, v0
	global_load_lds_dwordx4 v[2:3], off
	v_lshl_add_u64 v[2:3], v[38:39], 0, s[64:65]
	s_mov_b32 m0, s40
	v_readfirstlane_b32 s46, v62
	v_add_u32_e32 v63, 0xc000, v4
	global_load_lds_dwordx4 v[2:3], off
	v_lshl_add_u64 v[2:3], v[42:43], 0, s[64:65]
	s_mov_b32 m0, s46
	v_readfirstlane_b32 s47, v63
	global_load_lds_dwordx4 v[2:3], off
	v_lshl_add_u64 v[2:3], v[44:45], 0, s[64:65]
	s_mov_b32 m0, s47
	v_or_b32_e32 v0, v53, v7
	global_load_lds_dwordx4 v[2:3], off
	ds_read_b128 v[18:21], v0
	v_or_b32_e32 v50, v67, v7
	ds_read_b128 v[2:5], v50 offset:16384
	ds_read_b128 v[22:25], v50 offset:20480
	v_or_b32_e32 v48, v53, v49
	ds_read_b128 v[68:71], v48
	s_waitcnt lgkmcnt(0)
	v_mfma_f32_32x32x16_bf16 v[2:17], v[18:21], v[2:5], 0
	v_or_b32_e32 v49, v67, v49
	ds_read_b128 v[72:75], v49 offset:16384
	ds_read_b128 v[76:79], v49 offset:20480
	v_or_b32_e32 v52, v53, v51
	v_or_b32_e32 v51, v67, v51
	v_or_b32_e32 v54, v53, v80
	v_or_b32_e32 v53, v67, v80
	s_mov_b32 m0, s9
	v_mfma_f32_32x32x16_bf16 v[18:33], v[18:21], v[22:25], 0
	s_ashr_i32 s8, s8, 1
	s_waitcnt lgkmcnt(1)
	v_mfma_f32_32x32x16_bf16 v[2:17], v[68:71], v[72:75], v[2:17]
	s_waitcnt lgkmcnt(0)
	v_mfma_f32_32x32x16_bf16 v[18:33], v[68:71], v[76:79], v[18:33]
	ds_read_b128 v[68:71], v52
	ds_read_b128 v[72:75], v51 offset:16384
	ds_read_b128 v[76:79], v51 offset:20480
	s_waitcnt lgkmcnt(1)
	v_mfma_f32_32x32x16_bf16 v[2:17], v[68:71], v[72:75], v[2:17]
	s_waitcnt lgkmcnt(0)
	v_mfma_f32_32x32x16_bf16 v[18:33], v[68:71], v[76:79], v[18:33]
	ds_read_b128 v[68:71], v54
	ds_read_b128 v[72:75], v53 offset:16384
	ds_read_b128 v[76:79], v53 offset:20480
	s_waitcnt lgkmcnt(0)
	v_mfma_f32_32x32x16_bf16 v[2:17], v[68:71], v[72:75], v[2:17]
	v_mfma_f32_32x32x16_bf16 v[18:33], v[68:71], v[76:79], v[18:33]
	s_waitcnt vmcnt(0)
	s_barrier
; #define MFMA(a, b, c) __builtin_amdgcn_mfma_f32_32x32x16_bf16((a), (b), (c), 0, 0, 0)
; template <int AI, int BI>
; DI void gemm_tile(const u16* __restrict__ A, int lda, const u16* __restrict__ B, int ldb, int nk, bool swap,
;                   f32x16 (&acc)[AI][BI], char* lds) {
;     ...
;   for (int kt = 0; kt < nk; ++kt) {
;     const char* cur = lds + (kt & 1) * 32768;
;     if (kt + 1 < nk) gemm_stage<AI, BI>(A + (kt + 1) * 64, lda, B + (kt + 1) * 64, ldb, lds + ((kt + 1) & 1) * 32768, tid);
; #pragma unroll
;     for (int ks = 0; ks < 4; ++ks) {
;       const int co = ((ks * 2 + h) ^ sw) << 4;
;       s16x8 fa[AI], fb[BI];
; #pragma unroll
;       for (int i = 0; i < AI; ++i) fa[i] = *(const s16x8*)(cur + offA + i * 4096 + co);
; #pragma unroll
;       for (int i = 0; i < BI; ++i) fb[i] = *(const s16x8*)(cur + offB + i * 4096 + co);
; #pragma unroll
;       for (int i = 0; i < AI; ++i)
; #pragma unroll
;         for (int j = 0; j < BI; ++j) acc[i][j] = MFMA(fa[i], fb[j], acc[i][j]);
;     }
;     asm volatile("s_waitcnt vmcnt(0)" ::: "memory");
;     __syncthreads();
;   }
	v_lshl_add_u64 v[68:69], v[34:35], 0, s[4:5]
	global_load_lds_dwordx4 v[68:69], off
	v_lshl_add_u64 v[68:69], v[36:37], 0, s[4:5]
	s_mov_b32 m0, s18
	s_nop 0
	global_load_lds_dwordx4 v[68:69], off
	v_lshl_add_u64 v[68:69], v[40:41], 0, s[4:5]
	s_mov_b32 m0, s28
	s_nop 0
	global_load_lds_dwordx4 v[68:69], off
	v_lshl_add_u64 v[68:69], v[38:39], 0, s[4:5]
	s_mov_b32 m0, s29
	s_nop 0
	global_load_lds_dwordx4 v[68:69], off
	v_lshl_add_u64 v[68:69], v[42:43], 0, s[4:5]
	s_mov_b32 m0, s34
	s_nop 0
	global_load_lds_dwordx4 v[68:69], off
	v_lshl_add_u64 v[68:69], v[44:45], 0, s[4:5]
	s_mov_b32 m0, s41
	s_nop 0
	global_load_lds_dwordx4 v[68:69], off
	ds_read_b128 v[68:71], v0 offset:32768
	ds_read_b128 v[72:75], v50 offset:49152
	ds_read_b128 v[76:79], v50 offset:53248
	s_waitcnt lgkmcnt(0)
	v_mfma_f32_32x32x16_bf16 v[2:17], v[68:71], v[72:75], v[2:17]
	s_mov_b32 m0, s35
	v_mfma_f32_32x32x16_bf16 v[18:33], v[68:71], v[76:79], v[18:33]
	ds_read_b128 v[68:71], v48 offset:32768
	ds_read_b128 v[72:75], v49 offset:49152
	ds_read_b128 v[76:79], v49 offset:53248
	s_waitcnt lgkmcnt(1)
	v_mfma_f32_32x32x16_bf16 v[2:17], v[68:71], v[72:75], v[2:17]
	s_waitcnt lgkmcnt(0)
	v_mfma_f32_32x32x16_bf16 v[18:33], v[68:71], v[76:79], v[18:33]
	ds_read_b128 v[68:71], v52 offset:32768
	ds_read_b128 v[72:75], v51 offset:49152
	ds_read_b128 v[76:79], v51 offset:53248
	s_waitcnt lgkmcnt(1)
	v_mfma_f32_32x32x16_bf16 v[2:17], v[68:71], v[72:75], v[2:17]
	s_waitcnt lgkmcnt(0)
	v_mfma_f32_32x32x16_bf16 v[18:33], v[68:71], v[76:79], v[18:33]
	ds_read_b128 v[68:71], v54 offset:32768
	ds_read_b128 v[72:75], v53 offset:49152
	ds_read_b128 v[76:79], v53 offset:53248
	s_waitcnt lgkmcnt(0)
	v_mfma_f32_32x32x16_bf16 v[2:17], v[68:71], v[72:75], v[2:17]
	v_mfma_f32_32x32x16_bf16 v[18:33], v[68:71], v[76:79], v[18:33]
	s_waitcnt vmcnt(0)
	s_barrier
	v_lshl_add_u64 v[68:69], v[34:35], 0, s[66:67]
	global_load_lds_dwordx4 v[68:69], off
	v_lshl_add_u64 v[68:69], v[36:37], 0, s[66:67]
	s_mov_b32 m0, s36
	s_nop 0
	global_load_lds_dwordx4 v[68:69], off
	v_lshl_add_u64 v[68:69], v[40:41], 0, s[66:67]
	s_mov_b32 m0, s37
	s_nop 0
	global_load_lds_dwordx4 v[68:69], off
	v_lshl_add_u64 v[68:69], v[38:39], 0, s[66:67]
	s_mov_b32 m0, s40
	s_nop 0
	global_load_lds_dwordx4 v[68:69], off
	v_lshl_add_u64 v[68:69], v[42:43], 0, s[66:67]
	s_mov_b32 m0, s46
	s_nop 0
	global_load_lds_dwordx4 v[68:69], off
	v_lshl_add_u64 v[68:69], v[44:45], 0, s[66:67]
	s_mov_b32 m0, s47
	s_nop 0
	global_load_lds_dwordx4 v[68:69], off
	ds_read_b128 v[68:71], v0
	ds_read_b128 v[72:75], v50 offset:16384
	ds_read_b128 v[76:79], v50 offset:20480
	s_waitcnt lgkmcnt(0)
	v_mfma_f32_32x32x16_bf16 v[2:17], v[68:71], v[72:75], v[2:17]
	s_mov_b32 m0, s9
	v_mfma_f32_32x32x16_bf16 v[18:33], v[68:71], v[76:79], v[18:33]
	ds_read_b128 v[68:71], v48
	ds_read_b128 v[72:75], v49 offset:16384
	ds_read_b128 v[76:79], v49 offset:20480
	s_waitcnt lgkmcnt(1)
	v_mfma_f32_32x32x16_bf16 v[2:17], v[68:71], v[72:75], v[2:17]
	s_waitcnt lgkmcnt(0)
	v_mfma_f32_32x32x16_bf16 v[18:33], v[68:71], v[76:79], v[18:33]
	ds_read_b128 v[68:71], v52
	ds_read_b128 v[72:75], v51 offset:16384
	ds_read_b128 v[76:79], v51 offset:20480
	s_waitcnt lgkmcnt(1)
	v_mfma_f32_32x32x16_bf16 v[2:17], v[68:71], v[72:75], v[2:17]
	s_waitcnt lgkmcnt(0)
	v_mfma_f32_32x32x16_bf16 v[18:33], v[68:71], v[76:79], v[18:33]
	ds_read_b128 v[68:71], v54
	ds_read_b128 v[72:75], v53 offset:16384
	ds_read_b128 v[76:79], v53 offset:20480
	s_waitcnt lgkmcnt(0)
	v_mfma_f32_32x32x16_bf16 v[2:17], v[68:71], v[72:75], v[2:17]
	v_mfma_f32_32x32x16_bf16 v[18:33], v[68:71], v[76:79], v[18:33]
	s_waitcnt vmcnt(0)
	s_barrier
	v_lshl_add_u64 v[68:69], v[34:35], 0, s[56:57]
	global_load_lds_dwordx4 v[68:69], off
	v_lshl_add_u64 v[68:69], v[36:37], 0, s[56:57]
	s_mov_b32 m0, s18
	s_nop 0
	global_load_lds_dwordx4 v[68:69], off
	v_lshl_add_u64 v[68:69], v[40:41], 0, s[56:57]
	s_mov_b32 m0, s28
	s_nop 0
	global_load_lds_dwordx4 v[68:69], off
	v_lshl_add_u64 v[68:69], v[38:39], 0, s[56:57]
	s_mov_b32 m0, s29
	s_nop 0
	global_load_lds_dwordx4 v[68:69], off
	v_lshl_add_u64 v[68:69], v[42:43], 0, s[56:57]
	s_mov_b32 m0, s34
	s_nop 0
	global_load_lds_dwordx4 v[68:69], off
	v_lshl_add_u64 v[68:69], v[44:45], 0, s[56:57]
	s_mov_b32 m0, s41
	s_nop 0
	global_load_lds_dwordx4 v[68:69], off
	ds_read_b128 v[68:71], v0 offset:32768
	ds_read_b128 v[72:75], v50 offset:49152
	ds_read_b128 v[76:79], v50 offset:53248
	s_waitcnt lgkmcnt(0)
	v_mfma_f32_32x32x16_bf16 v[2:17], v[68:71], v[72:75], v[2:17]
	s_mov_b32 m0, s35
	v_mfma_f32_32x32x16_bf16 v[18:33], v[68:71], v[76:79], v[18:33]
	ds_read_b128 v[68:71], v48 offset:32768
	ds_read_b128 v[72:75], v49 offset:49152
	ds_read_b128 v[76:79], v49 offset:53248
	s_waitcnt lgkmcnt(1)
	v_mfma_f32_32x32x16_bf16 v[2:17], v[68:71], v[72:75], v[2:17]
	s_waitcnt lgkmcnt(0)
	v_mfma_f32_32x32x16_bf16 v[18:33], v[68:71], v[76:79], v[18:33]
	ds_read_b128 v[68:71], v52 offset:32768
	ds_read_b128 v[72:75], v51 offset:49152
	ds_read_b128 v[76:79], v51 offset:53248
	s_waitcnt lgkmcnt(1)
	v_mfma_f32_32x32x16_bf16 v[2:17], v[68:71], v[72:75], v[2:17]
	s_waitcnt lgkmcnt(0)
	v_mfma_f32_32x32x16_bf16 v[18:33], v[68:71], v[76:79], v[18:33]
	ds_read_b128 v[68:71], v54 offset:32768
	ds_read_b128 v[72:75], v53 offset:49152
	ds_read_b128 v[76:79], v53 offset:53248
	s_waitcnt lgkmcnt(0)
	v_mfma_f32_32x32x16_bf16 v[2:17], v[68:71], v[72:75], v[2:17]
	v_mfma_f32_32x32x16_bf16 v[18:33], v[68:71], v[76:79], v[18:33]
	s_waitcnt vmcnt(0)
	s_barrier
; #define MFMA(a, b, c) __builtin_amdgcn_mfma_f32_32x32x16_bf16((a), (b), (c), 0, 0, 0)
; template <int AI, int BI>
; DI void gemm_tile(const u16* __restrict__ A, int lda, const u16* __restrict__ B, int ldb, int nk, bool swap,
;                   f32x16 (&acc)[AI][BI], char* lds) {
;     ...
;   for (int kt = 0; kt < nk; ++kt) {
;     const char* cur = lds + (kt & 1) * 32768;
;     if (kt + 1 < nk) gemm_stage<AI, BI>(A + (kt + 1) * 64, lda, B + (kt + 1) * 64, ldb, lds + ((kt + 1) & 1) * 32768, tid);
; #pragma unroll
;     for (int ks = 0; ks < 4; ++ks) {
;       const int co = ((ks * 2 + h) ^ sw) << 4;
;       s16x8 fa[AI], fb[BI];
; #pragma unroll
;       for (int i = 0; i < AI; ++i) fa[i] = *(const s16x8*)(cur + offA + i * 4096 + co);
; #pragma unroll
;       for (int i = 0; i < BI; ++i) fb[i] = *(const s16x8*)(cur + offB + i * 4096 + co);
; #pragma unroll
;       for (int i = 0; i < AI; ++i)
; #pragma unroll
;         for (int j = 0; j < BI; ++j) acc[i][j] = MFMA(fa[i], fb[j], acc[i][j]);
;     }
;     asm volatile("s_waitcnt vmcnt(0)" ::: "memory");
;     __syncthreads();
;   }
	v_lshl_add_u64 v[68:69], v[34:35], 0, s[68:69]
	global_load_lds_dwordx4 v[68:69], off
	v_lshl_add_u64 v[68:69], v[36:37], 0, s[68:69]
	s_mov_b32 m0, s36
	s_nop 0
	global_load_lds_dwordx4 v[68:69], off
	v_lshl_add_u64 v[68:69], v[40:41], 0, s[68:69]
	s_mov_b32 m0, s37
	s_nop 0
	global_load_lds_dwordx4 v[68:69], off
	v_lshl_add_u64 v[68:69], v[38:39], 0, s[68:69]
	s_mov_b32 m0, s40
	s_nop 0
	global_load_lds_dwordx4 v[68:69], off
	v_lshl_add_u64 v[68:69], v[42:43], 0, s[68:69]
	s_mov_b32 m0, s46
	s_nop 0
	global_load_lds_dwordx4 v[68:69], off
	v_lshl_add_u64 v[68:69], v[44:45], 0, s[68:69]
	s_mov_b32 m0, s47
	s_nop 0
	global_load_lds_dwordx4 v[68:69], off
	ds_read_b128 v[68:71], v0
	ds_read_b128 v[72:75], v50 offset:16384
	ds_read_b128 v[76:79], v50 offset:20480
	s_waitcnt lgkmcnt(0)
	v_mfma_f32_32x32x16_bf16 v[2:17], v[68:71], v[72:75], v[2:17]
	s_mov_b32 m0, s9
	v_mfma_f32_32x32x16_bf16 v[18:33], v[68:71], v[76:79], v[18:33]
	ds_read_b128 v[68:71], v48
	ds_read_b128 v[72:75], v49 offset:16384
	ds_read_b128 v[76:79], v49 offset:20480
	s_waitcnt lgkmcnt(1)
	v_mfma_f32_32x32x16_bf16 v[2:17], v[68:71], v[72:75], v[2:17]
	s_waitcnt lgkmcnt(0)
	v_mfma_f32_32x32x16_bf16 v[18:33], v[68:71], v[76:79], v[18:33]
	ds_read_b128 v[68:71], v52
	ds_read_b128 v[72:75], v51 offset:16384
	ds_read_b128 v[76:79], v51 offset:20480
	s_waitcnt lgkmcnt(1)
	v_mfma_f32_32x32x16_bf16 v[2:17], v[68:71], v[72:75], v[2:17]
	s_waitcnt lgkmcnt(0)
	v_mfma_f32_32x32x16_bf16 v[18:33], v[68:71], v[76:79], v[18:33]
	ds_read_b128 v[68:71], v54
	ds_read_b128 v[72:75], v53 offset:16384
	ds_read_b128 v[76:79], v53 offset:20480
	s_waitcnt lgkmcnt(0)
	v_mfma_f32_32x32x16_bf16 v[2:17], v[68:71], v[72:75], v[2:17]
	v_mfma_f32_32x32x16_bf16 v[18:33], v[68:71], v[76:79], v[18:33]
	s_waitcnt vmcnt(0)
	s_barrier
	v_lshl_add_u64 v[68:69], v[34:35], 0, s[70:71]
	global_load_lds_dwordx4 v[68:69], off
	v_lshl_add_u64 v[68:69], v[36:37], 0, s[70:71]
	s_mov_b32 m0, s18
	s_nop 0
	global_load_lds_dwordx4 v[68:69], off
	v_lshl_add_u64 v[68:69], v[40:41], 0, s[70:71]
	s_mov_b32 m0, s28
	s_nop 0
	global_load_lds_dwordx4 v[68:69], off
	v_lshl_add_u64 v[68:69], v[38:39], 0, s[70:71]
	s_mov_b32 m0, s29
	s_nop 0
	global_load_lds_dwordx4 v[68:69], off
	v_lshl_add_u64 v[68:69], v[42:43], 0, s[70:71]
	s_mov_b32 m0, s34
	s_nop 0
	global_load_lds_dwordx4 v[68:69], off
	v_lshl_add_u64 v[68:69], v[44:45], 0, s[70:71]
	s_mov_b32 m0, s41
	s_nop 0
	global_load_lds_dwordx4 v[68:69], off
	ds_read_b128 v[68:71], v0 offset:32768
	ds_read_b128 v[72:75], v50 offset:49152
	ds_read_b128 v[76:79], v50 offset:53248
	s_waitcnt lgkmcnt(0)
	v_mfma_f32_32x32x16_bf16 v[2:17], v[68:71], v[72:75], v[2:17]
	s_mov_b32 m0, s35
	v_mfma_f32_32x32x16_bf16 v[18:33], v[68:71], v[76:79], v[18:33]
	ds_read_b128 v[68:71], v48 offset:32768
	ds_read_b128 v[72:75], v49 offset:49152
	ds_read_b128 v[76:79], v49 offset:53248
	s_waitcnt lgkmcnt(1)
	v_mfma_f32_32x32x16_bf16 v[2:17], v[68:71], v[72:75], v[2:17]
	s_waitcnt lgkmcnt(0)
	v_mfma_f32_32x32x16_bf16 v[18:33], v[68:71], v[76:79], v[18:33]
	ds_read_b128 v[68:71], v52 offset:32768
	ds_read_b128 v[72:75], v51 offset:49152
	ds_read_b128 v[76:79], v51 offset:53248
	s_waitcnt lgkmcnt(1)
	v_mfma_f32_32x32x16_bf16 v[2:17], v[68:71], v[72:75], v[2:17]
	s_waitcnt lgkmcnt(0)
	v_mfma_f32_32x32x16_bf16 v[18:33], v[68:71], v[76:79], v[18:33]
	ds_read_b128 v[68:71], v54 offset:32768
	ds_read_b128 v[72:75], v53 offset:49152
	ds_read_b128 v[76:79], v53 offset:53248
	s_waitcnt lgkmcnt(0)
	v_mfma_f32_32x32x16_bf16 v[2:17], v[68:71], v[72:75], v[2:17]
	v_mfma_f32_32x32x16_bf16 v[18:33], v[68:71], v[76:79], v[18:33]
	s_waitcnt vmcnt(0)
	s_barrier
	v_lshl_add_u64 v[68:69], v[34:35], 0, s[72:73]
	global_load_lds_dwordx4 v[68:69], off
	v_lshl_add_u64 v[68:69], v[36:37], 0, s[72:73]
	s_mov_b32 m0, s36
	s_nop 0
	global_load_lds_dwordx4 v[68:69], off
	v_lshl_add_u64 v[68:69], v[40:41], 0, s[72:73]
	s_mov_b32 m0, s37
	s_nop 0
	global_load_lds_dwordx4 v[68:69], off
	v_lshl_add_u64 v[68:69], v[38:39], 0, s[72:73]
	s_mov_b32 m0, s40
	s_nop 0
	global_load_lds_dwordx4 v[68:69], off
	v_lshl_add_u64 v[68:69], v[42:43], 0, s[72:73]
	s_mov_b32 m0, s46
	s_nop 0
	global_load_lds_dwordx4 v[68:69], off
	v_lshl_add_u64 v[68:69], v[44:45], 0, s[72:73]
	s_mov_b32 m0, s47
	s_nop 0
	global_load_lds_dwordx4 v[68:69], off
	ds_read_b128 v[68:71], v0
	ds_read_b128 v[72:75], v50 offset:16384
	ds_read_b128 v[76:79], v50 offset:20480
	s_waitcnt lgkmcnt(0)
	v_mfma_f32_32x32x16_bf16 v[2:17], v[68:71], v[72:75], v[2:17]
	s_mov_b32 m0, s9
	v_mfma_f32_32x32x16_bf16 v[18:33], v[68:71], v[76:79], v[18:33]
	ds_read_b128 v[68:71], v48
	ds_read_b128 v[72:75], v49 offset:16384
	ds_read_b128 v[76:79], v49 offset:20480
	s_waitcnt lgkmcnt(1)
	v_mfma_f32_32x32x16_bf16 v[2:17], v[68:71], v[72:75], v[2:17]
	s_waitcnt lgkmcnt(0)
	v_mfma_f32_32x32x16_bf16 v[18:33], v[68:71], v[76:79], v[18:33]
	ds_read_b128 v[68:71], v52
	ds_read_b128 v[72:75], v51 offset:16384
	ds_read_b128 v[76:79], v51 offset:20480
	s_waitcnt lgkmcnt(1)
	v_mfma_f32_32x32x16_bf16 v[2:17], v[68:71], v[72:75], v[2:17]
	s_waitcnt lgkmcnt(0)
	v_mfma_f32_32x32x16_bf16 v[18:33], v[68:71], v[76:79], v[18:33]
	ds_read_b128 v[68:71], v54
	ds_read_b128 v[72:75], v53 offset:16384
	ds_read_b128 v[76:79], v53 offset:20480
	s_waitcnt lgkmcnt(0)
	v_mfma_f32_32x32x16_bf16 v[2:17], v[68:71], v[72:75], v[2:17]
	v_mfma_f32_32x32x16_bf16 v[18:33], v[68:71], v[76:79], v[18:33]
	s_waitcnt vmcnt(0)
	s_barrier
; #define MFMA(a, b, c) __builtin_amdgcn_mfma_f32_32x32x16_bf16((a), (b), (c), 0, 0, 0)
; template <int AI, int BI>
; DI void gemm_stage(const u16* __restrict__ A, int lda, const u16* __restrict__ B, int ldb, char* buf, int tid) {
; #pragma unroll
;   for (int i = 0; i < 2 * AI; ++i) {
;     const int S = tid + NTHR * i, row = S >> 3, c = (S & 7) ^ ((row >> 1) & 7);
;     __builtin_amdgcn_global_load_lds((const unsigned*)(A + (size_t)row * lda + c * 8), (__attribute__((address_space(3))) unsigned*)(buf + S * 16), 16, 0, 0);
;   }
; #pragma unroll
;   for (int i = 0; i < 2 * BI; ++i) {
;     const int S = tid + NTHR * i, row = S >> 3, c = (S & 7) ^ ((row >> 1) & 7);
;     __builtin_amdgcn_global_load_lds((const unsigned*)(B + (size_t)row * ldb + c * 8), (__attribute__((address_space(3))) unsigned*)(buf + 16384 + S * 16), 16, 0, 0);
;   }
; }
; template <int AI, int BI>
; DI void gemm_tile(const u16* __restrict__ A, int lda, const u16* __restrict__ B, int ldb, int nk, bool swap,
;                   f32x16 (&acc)[AI][BI], char* lds) {
;     ...
;   for (int kt = 0; kt < nk; ++kt) {
;     const char* cur = lds + (kt & 1) * 32768;
;     if (kt + 1 < nk) gemm_stage<AI, BI>(A + (kt + 1) * 64, lda, B + (kt + 1) * 64, ldb, lds + ((kt + 1) & 1) * 32768, tid);
; #pragma unroll
;     for (int ks = 0; ks < 4; ++ks) {
;       const int co = ((ks * 2 + h) ^ sw) << 4;
;       s16x8 fa[AI], fb[BI];
; #pragma unroll
;       for (int i = 0; i < AI; ++i) fa[i] = *(const s16x8*)(cur + offA + i * 4096 + co);
; #pragma unroll
;       for (int i = 0; i < BI; ++i) fb[i] = *(const s16x8*)(cur + offB + i * 4096 + co);
; #pragma unroll
;       for (int i = 0; i < AI; ++i)
; #pragma unroll
;         for (int j = 0; j < BI; ++j) acc[i][j] = MFMA(fa[i], fb[j], acc[i][j]);
;     }
;     asm volatile("s_waitcnt vmcnt(0)" ::: "memory");
;     __syncthreads();
;   }
	v_lshl_add_u64 v[68:69], v[34:35], 0, s[74:75]
	global_load_lds_dwordx4 v[68:69], off
	v_lshl_add_u64 v[68:69], v[36:37], 0, s[74:75]
	s_mov_b32 m0, s18
	s_nop 0
	global_load_lds_dwordx4 v[68:69], off
	v_lshl_add_u64 v[68:69], v[40:41], 0, s[74:75]
	s_mov_b32 m0, s28
	s_nop 0
	global_load_lds_dwordx4 v[68:69], off
	v_lshl_add_u64 v[68:69], v[38:39], 0, s[74:75]
	s_mov_b32 m0, s29
	s_nop 0
	global_load_lds_dwordx4 v[68:69], off
	v_lshl_add_u64 v[68:69], v[42:43], 0, s[74:75]
	s_mov_b32 m0, s34
	s_nop 0
	global_load_lds_dwordx4 v[68:69], off
	v_lshl_add_u64 v[68:69], v[44:45], 0, s[74:75]
	s_mov_b32 m0, s41
	s_nop 0
	global_load_lds_dwordx4 v[68:69], off
	ds_read_b128 v[68:71], v0 offset:32768
	ds_read_b128 v[72:75], v50 offset:49152
	ds_read_b128 v[76:79], v50 offset:53248
	s_waitcnt lgkmcnt(0)
	v_mfma_f32_32x32x16_bf16 v[2:17], v[68:71], v[72:75], v[2:17]
	s_mov_b32 m0, s35
	v_mfma_f32_32x32x16_bf16 v[18:33], v[68:71], v[76:79], v[18:33]
	ds_read_b128 v[68:71], v48 offset:32768
	ds_read_b128 v[72:75], v49 offset:49152
	ds_read_b128 v[76:79], v49 offset:53248
	s_waitcnt lgkmcnt(1)
	v_mfma_f32_32x32x16_bf16 v[2:17], v[68:71], v[72:75], v[2:17]
	s_waitcnt lgkmcnt(0)
	v_mfma_f32_32x32x16_bf16 v[18:33], v[68:71], v[76:79], v[18:33]
	ds_read_b128 v[68:71], v52 offset:32768
	ds_read_b128 v[72:75], v51 offset:49152
	ds_read_b128 v[76:79], v51 offset:53248
	s_waitcnt lgkmcnt(1)
	v_mfma_f32_32x32x16_bf16 v[2:17], v[68:71], v[72:75], v[2:17]
	s_waitcnt lgkmcnt(0)
	v_mfma_f32_32x32x16_bf16 v[18:33], v[68:71], v[76:79], v[18:33]
	ds_read_b128 v[68:71], v54 offset:32768
	ds_read_b128 v[72:75], v53 offset:49152
	ds_read_b128 v[76:79], v53 offset:53248
	s_waitcnt lgkmcnt(0)
	v_mfma_f32_32x32x16_bf16 v[2:17], v[68:71], v[72:75], v[2:17]
	v_mfma_f32_32x32x16_bf16 v[18:33], v[68:71], v[76:79], v[18:33]
	s_waitcnt vmcnt(0)
	s_barrier
	v_lshl_add_u64 v[68:69], v[34:35], 0, s[76:77]
	global_load_lds_dwordx4 v[68:69], off
	v_lshl_add_u64 v[68:69], v[36:37], 0, s[76:77]
	s_mov_b32 m0, s36
	s_nop 0
	global_load_lds_dwordx4 v[68:69], off
	v_lshl_add_u64 v[68:69], v[40:41], 0, s[76:77]
	s_mov_b32 m0, s37
	s_nop 0
	global_load_lds_dwordx4 v[68:69], off
	v_lshl_add_u64 v[68:69], v[38:39], 0, s[76:77]
	s_mov_b32 m0, s40
	s_nop 0
	global_load_lds_dwordx4 v[68:69], off
	v_lshl_add_u64 v[68:69], v[42:43], 0, s[76:77]
	s_mov_b32 m0, s46
	s_nop 0
	global_load_lds_dwordx4 v[68:69], off
	v_lshl_add_u64 v[68:69], v[44:45], 0, s[76:77]
	s_mov_b32 m0, s47
	s_nop 0
	global_load_lds_dwordx4 v[68:69], off
	ds_read_b128 v[68:71], v0
	ds_read_b128 v[72:75], v50 offset:16384
	ds_read_b128 v[76:79], v50 offset:20480
	s_waitcnt lgkmcnt(0)
	v_mfma_f32_32x32x16_bf16 v[2:17], v[68:71], v[72:75], v[2:17]
	s_mov_b32 m0, s9
	v_readfirstlane_b32 s9, v55
	v_and_b32_e32 v55, 31, v46
	v_mfma_f32_32x32x16_bf16 v[18:33], v[68:71], v[76:79], v[18:33]
	ds_read_b128 v[68:71], v48
	ds_read_b128 v[72:75], v49 offset:16384
	ds_read_b128 v[76:79], v49 offset:20480
	s_waitcnt lgkmcnt(1)
	v_mfma_f32_32x32x16_bf16 v[2:17], v[68:71], v[72:75], v[2:17]
	s_waitcnt lgkmcnt(0)
	v_mfma_f32_32x32x16_bf16 v[18:33], v[68:71], v[76:79], v[18:33]
	ds_read_b128 v[68:71], v52
	ds_read_b128 v[72:75], v51 offset:16384
	ds_read_b128 v[76:79], v51 offset:20480
	s_waitcnt lgkmcnt(1)
	v_mfma_f32_32x32x16_bf16 v[2:17], v[68:71], v[72:75], v[2:17]
	s_waitcnt lgkmcnt(0)
	v_mfma_f32_32x32x16_bf16 v[18:33], v[68:71], v[76:79], v[18:33]
	ds_read_b128 v[68:71], v54
	ds_read_b128 v[72:75], v53 offset:16384
	ds_read_b128 v[76:79], v53 offset:20480
	s_waitcnt lgkmcnt(0)
	v_mfma_f32_32x32x16_bf16 v[2:17], v[68:71], v[72:75], v[2:17]
	v_mfma_f32_32x32x16_bf16 v[18:33], v[68:71], v[76:79], v[18:33]
	s_waitcnt vmcnt(0)
	s_barrier
	v_lshl_add_u64 v[68:69], v[34:35], 0, s[80:81]
	global_load_lds_dwordx4 v[68:69], off
	v_lshl_add_u64 v[68:69], v[36:37], 0, s[80:81]
	s_mov_b32 m0, s18
	v_readfirstlane_b32 s18, v56
	global_load_lds_dwordx4 v[68:69], off
	v_lshl_add_u64 v[68:69], v[40:41], 0, s[80:81]
	s_mov_b32 m0, s28
	v_readfirstlane_b32 s28, v57
	global_load_lds_dwordx4 v[68:69], off
	v_lshl_add_u64 v[68:69], v[38:39], 0, s[80:81]
	s_mov_b32 m0, s29
	v_readfirstlane_b32 s29, v59
	global_load_lds_dwordx4 v[68:69], off
	v_lshl_add_u64 v[68:69], v[42:43], 0, s[80:81]
	s_mov_b32 m0, s34
	v_lshl_add_u64 v[56:57], v[38:39], 0, s[84:85]
	global_load_lds_dwordx4 v[68:69], off
	v_lshl_add_u64 v[68:69], v[44:45], 0, s[80:81]
	s_mov_b32 m0, s41
	v_readfirstlane_b32 s34, v65
	global_load_lds_dwordx4 v[68:69], off
	ds_read_b128 v[68:71], v0 offset:32768
	ds_read_b128 v[72:75], v50 offset:49152
	ds_read_b128 v[76:79], v50 offset:53248
	s_waitcnt lgkmcnt(0)
	v_mfma_f32_32x32x16_bf16 v[2:17], v[68:71], v[72:75], v[2:17]
	s_mov_b32 m0, s35
	v_readfirstlane_b32 s35, v66
	v_readfirstlane_b32 s41, v60
	v_mfma_f32_32x32x16_bf16 v[18:33], v[68:71], v[76:79], v[18:33]
	ds_read_b128 v[68:71], v48 offset:32768
	ds_read_b128 v[72:75], v49 offset:49152
	ds_read_b128 v[76:79], v49 offset:53248
	s_waitcnt lgkmcnt(1)
	v_mfma_f32_32x32x16_bf16 v[2:17], v[68:71], v[72:75], v[2:17]
	s_waitcnt lgkmcnt(0)
	v_mfma_f32_32x32x16_bf16 v[18:33], v[68:71], v[76:79], v[18:33]
	ds_read_b128 v[68:71], v52 offset:32768
	ds_read_b128 v[72:75], v51 offset:49152
	ds_read_b128 v[76:79], v51 offset:53248
	s_waitcnt lgkmcnt(1)
	v_mfma_f32_32x32x16_bf16 v[2:17], v[68:71], v[72:75], v[2:17]
	s_waitcnt lgkmcnt(0)
	v_mfma_f32_32x32x16_bf16 v[18:33], v[68:71], v[76:79], v[18:33]
	ds_read_b128 v[68:71], v54 offset:32768
	ds_read_b128 v[72:75], v53 offset:49152
	ds_read_b128 v[76:79], v53 offset:53248
	s_waitcnt lgkmcnt(0)
	v_mfma_f32_32x32x16_bf16 v[2:17], v[68:71], v[72:75], v[2:17]
	v_mfma_f32_32x32x16_bf16 v[18:33], v[68:71], v[76:79], v[18:33]
	s_waitcnt vmcnt(0)
	s_barrier
; #define MFMA(a, b, c) __builtin_amdgcn_mfma_f32_32x32x16_bf16((a), (b), (c), 0, 0, 0)
; template <int AI, int BI>
; DI void gemm_stage(const u16* __restrict__ A, int lda, const u16* __restrict__ B, int ldb, char* buf, int tid) {
; #pragma unroll
;   for (int i = 0; i < 2 * AI; ++i) {
;     const int S = tid + NTHR * i, row = S >> 3, c = (S & 7) ^ ((row >> 1) & 7);
;     __builtin_amdgcn_global_load_lds((const unsigned*)(A + (size_t)row * lda + c * 8), (__attribute__((address_space(3))) unsigned*)(buf + S * 16), 16, 0, 0);
;   }
; #pragma unroll
;   for (int i = 0; i < 2 * BI; ++i) {
;     const int S = tid + NTHR * i, row = S >> 3, c = (S & 7) ^ ((row >> 1) & 7);
;     __builtin_amdgcn_global_load_lds((const unsigned*)(B + (size_t)row * ldb + c * 8), (__attribute__((address_space(3))) unsigned*)(buf + 16384 + S * 16), 16, 0, 0);
;   }
; }
; template <int AI, int BI>
; DI void gemm_tile(const u16* __restrict__ A, int lda, const u16* __restrict__ B, int ldb, int nk, bool swap,
;                   f32x16 (&acc)[AI][BI], char* lds) {
;     ...
;   for (int kt = 0; kt < nk; ++kt) {
;     const char* cur = lds + (kt & 1) * 32768;
;     if (kt + 1 < nk) gemm_stage<AI, BI>(A + (kt + 1) * 64, lda, B + (kt + 1) * 64, ldb, lds + ((kt + 1) & 1) * 32768, tid);
; #pragma unroll
;     for (int ks = 0; ks < 4; ++ks) {
;       const int co = ((ks * 2 + h) ^ sw) << 4;
;       s16x8 fa[AI], fb[BI];
; #pragma unroll
;       for (int i = 0; i < AI; ++i) fa[i] = *(const s16x8*)(cur + offA + i * 4096 + co);
; #pragma unroll
;       for (int i = 0; i < BI; ++i) fb[i] = *(const s16x8*)(cur + offB + i * 4096 + co);
; #pragma unroll
;       for (int i = 0; i < AI; ++i)
; #pragma unroll
;         for (int j = 0; j < BI; ++j) acc[i][j] = MFMA(fa[i], fb[j], acc[i][j]);
;     }
;     asm volatile("s_waitcnt vmcnt(0)" ::: "memory");
;     __syncthreads();
;   }
	v_lshl_add_u64 v[68:69], v[34:35], 0, s[82:83]
	global_load_lds_dwordx4 v[68:69], off
	v_lshl_add_u64 v[68:69], v[36:37], 0, s[82:83]
	s_mov_b32 m0, s36
	v_readfirstlane_b32 s36, v64
	global_load_lds_dwordx4 v[68:69], off
	v_lshl_add_u64 v[68:69], v[40:41], 0, s[82:83]
	s_mov_b32 m0, s37
	v_readfirstlane_b32 s37, v61
	global_load_lds_dwordx4 v[68:69], off
	v_lshl_add_u64 v[68:69], v[38:39], 0, s[82:83]
	s_mov_b32 m0, s40
	v_readfirstlane_b32 s40, v58
	global_load_lds_dwordx4 v[68:69], off
	v_lshl_add_u64 v[68:69], v[42:43], 0, s[82:83]
	s_mov_b32 m0, s46
	v_readfirstlane_b32 s46, v62
	global_load_lds_dwordx4 v[68:69], off
	v_lshl_add_u64 v[68:69], v[44:45], 0, s[82:83]
	s_mov_b32 m0, s47
	v_readfirstlane_b32 s47, v63
	global_load_lds_dwordx4 v[68:69], off
	ds_read_b128 v[68:71], v0
	ds_read_b128 v[72:75], v50 offset:16384
	ds_read_b128 v[76:79], v50 offset:20480
	s_waitcnt lgkmcnt(0)
	v_mfma_f32_32x32x16_bf16 v[2:17], v[68:71], v[72:75], v[2:17]
	s_mov_b32 m0, s9
	v_mfma_f32_32x32x16_bf16 v[18:33], v[68:71], v[76:79], v[18:33]
	ds_read_b128 v[68:71], v48
	ds_read_b128 v[72:75], v49 offset:16384
	ds_read_b128 v[76:79], v49 offset:20480
	s_waitcnt lgkmcnt(1)
	v_mfma_f32_32x32x16_bf16 v[2:17], v[68:71], v[72:75], v[2:17]
	s_waitcnt lgkmcnt(0)
	v_mfma_f32_32x32x16_bf16 v[18:33], v[68:71], v[76:79], v[18:33]
	ds_read_b128 v[68:71], v52
	ds_read_b128 v[72:75], v51 offset:16384
	ds_read_b128 v[76:79], v51 offset:20480
	s_waitcnt lgkmcnt(1)
	v_mfma_f32_32x32x16_bf16 v[2:17], v[68:71], v[72:75], v[2:17]
	s_waitcnt lgkmcnt(0)
	v_mfma_f32_32x32x16_bf16 v[18:33], v[68:71], v[76:79], v[18:33]
	ds_read_b128 v[68:71], v54
	ds_read_b128 v[72:75], v53 offset:16384
	ds_read_b128 v[76:79], v53 offset:20480
	s_waitcnt lgkmcnt(0)
	v_mfma_f32_32x32x16_bf16 v[2:17], v[68:71], v[72:75], v[2:17]
	v_mfma_f32_32x32x16_bf16 v[18:33], v[68:71], v[76:79], v[18:33]
	s_waitcnt vmcnt(0)
	s_barrier
	v_lshl_add_u64 v[68:69], v[34:35], 0, s[84:85]
	global_load_lds_dwordx4 v[68:69], off
	v_lshl_add_u64 v[68:69], v[36:37], 0, s[84:85]
	s_mov_b32 m0, s18
	s_nop 0
	global_load_lds_dwordx4 v[68:69], off
	v_lshl_add_u64 v[68:69], v[40:41], 0, s[84:85]
	s_mov_b32 m0, s28
	s_nop 0
	global_load_lds_dwordx4 v[68:69], off
	s_mov_b32 m0, s29
	s_nop 0
	global_load_lds_dwordx4 v[56:57], off
	v_lshl_add_u64 v[56:57], v[42:43], 0, s[84:85]
	s_mov_b32 m0, s34
	s_nop 0
	global_load_lds_dwordx4 v[56:57], off
	v_lshl_add_u64 v[56:57], v[44:45], 0, s[84:85]
	s_mov_b32 m0, s35
	s_nop 0
	global_load_lds_dwordx4 v[56:57], off
	ds_read_b128 v[66:69], v0 offset:32768
	ds_read_b128 v[70:73], v50 offset:49152
	ds_read_b128 v[74:77], v50 offset:53248
	s_waitcnt lgkmcnt(0)
	v_mfma_f32_32x32x16_bf16 v[2:17], v[66:69], v[70:73], v[2:17]
	v_lshl_add_u64 v[56:57], v[34:35], 0, s[78:79]
	s_mov_b32 m0, s36
	v_mfma_f32_32x32x16_bf16 v[18:33], v[66:69], v[74:77], v[18:33]
	ds_read_b128 v[66:69], v48 offset:32768
	ds_read_b128 v[70:73], v49 offset:49152
	ds_read_b128 v[74:77], v49 offset:53248
	s_waitcnt lgkmcnt(1)
	v_mfma_f32_32x32x16_bf16 v[2:17], v[66:69], v[70:73], v[2:17]
	s_waitcnt lgkmcnt(0)
	v_mfma_f32_32x32x16_bf16 v[18:33], v[66:69], v[74:77], v[18:33]
	ds_read_b128 v[66:69], v52 offset:32768
	ds_read_b128 v[70:73], v51 offset:49152
	ds_read_b128 v[74:77], v51 offset:53248
	s_waitcnt lgkmcnt(1)
	v_mfma_f32_32x32x16_bf16 v[2:17], v[66:69], v[70:73], v[2:17]
	s_waitcnt lgkmcnt(0)
	v_mfma_f32_32x32x16_bf16 v[18:33], v[66:69], v[74:77], v[18:33]
	ds_read_b128 v[66:69], v54 offset:32768
	ds_read_b128 v[70:73], v53 offset:49152
	ds_read_b128 v[74:77], v53 offset:53248
	s_waitcnt vmcnt(0)
	s_waitcnt lgkmcnt(0)
	s_barrier
	global_load_lds_dwordx4 v[56:57], off
	v_lshl_add_u64 v[56:57], v[36:37], 0, s[78:79]
	s_mov_b32 m0, s37
	v_mfma_f32_32x32x16_bf16 v[2:17], v[66:69], v[70:73], v[2:17]
	global_load_lds_dwordx4 v[56:57], off
	v_lshl_add_u64 v[56:57], v[40:41], 0, s[78:79]
	s_mov_b32 m0, s40
	s_nop 0
	global_load_lds_dwordx4 v[56:57], off
	v_lshl_add_u64 v[56:57], v[38:39], 0, s[78:79]
	s_mov_b32 m0, s41
	v_mfma_f32_32x32x16_bf16 v[18:33], v[66:69], v[74:77], v[18:33]
	global_load_lds_dwordx4 v[56:57], off
	v_lshl_add_u64 v[56:57], v[42:43], 0, s[78:79]
	s_mov_b32 m0, s46
	s_nop 0
	global_load_lds_dwordx4 v[56:57], off
	v_lshl_add_u64 v[56:57], v[44:45], 0, s[78:79]
	s_mov_b32 m0, s47
	s_nop 0
	global_load_lds_dwordx4 v[56:57], off
	ds_read_b128 v[56:59], v0
	ds_read_b128 v[60:63], v50 offset:16384
	ds_read_b128 v[64:67], v50 offset:20480
	s_waitcnt lgkmcnt(0)
	v_mfma_f32_32x32x16_bf16 v[2:17], v[56:59], v[60:63], v[2:17]
	s_mov_b32 m0, s9
	v_mfma_f32_32x32x16_bf16 v[18:33], v[56:59], v[64:67], v[18:33]
	ds_read_b128 v[56:59], v48
	ds_read_b128 v[60:63], v49 offset:16384
	ds_read_b128 v[64:67], v49 offset:20480
	s_waitcnt lgkmcnt(1)
	v_mfma_f32_32x32x16_bf16 v[2:17], v[56:59], v[60:63], v[2:17]
	s_waitcnt lgkmcnt(0)
	v_mfma_f32_32x32x16_bf16 v[18:33], v[56:59], v[64:67], v[18:33]
	ds_read_b128 v[56:59], v52
	ds_read_b128 v[60:63], v51 offset:16384
	ds_read_b128 v[64:67], v51 offset:20480
	s_waitcnt lgkmcnt(1)
	v_mfma_f32_32x32x16_bf16 v[2:17], v[56:59], v[60:63], v[2:17]
	s_waitcnt lgkmcnt(0)
	v_mfma_f32_32x32x16_bf16 v[18:33], v[56:59], v[64:67], v[18:33]
	ds_read_b128 v[56:59], v54
	ds_read_b128 v[60:63], v53 offset:16384
	ds_read_b128 v[64:67], v53 offset:20480
	s_waitcnt lgkmcnt(0)
	v_mfma_f32_32x32x16_bf16 v[2:17], v[56:59], v[60:63], v[2:17]
	v_mfma_f32_32x32x16_bf16 v[18:33], v[56:59], v[64:67], v[18:33]
	s_waitcnt vmcnt(0)
	s_barrier
; #define MFMA(a, b, c) __builtin_amdgcn_mfma_f32_32x32x16_bf16((a), (b), (c), 0, 0, 0)
; template <int AI, int BI>
; DI void gemm_stage(const u16* __restrict__ A, int lda, const u16* __restrict__ B, int ldb, char* buf, int tid) {
; #pragma unroll
;   for (int i = 0; i < 2 * AI; ++i) {
;     const int S = tid + NTHR * i, row = S >> 3, c = (S & 7) ^ ((row >> 1) & 7);
;     __builtin_amdgcn_global_load_lds((const unsigned*)(A + (size_t)row * lda + c * 8), (__attribute__((address_space(3))) unsigned*)(buf + S * 16), 16, 0, 0);
;   }
; #pragma unroll
;   for (int i = 0; i < 2 * BI; ++i) {
;     const int S = tid + NTHR * i, row = S >> 3, c = (S & 7) ^ ((row >> 1) & 7);
;     __builtin_amdgcn_global_load_lds((const unsigned*)(B + (size_t)row * ldb + c * 8), (__attribute__((address_space(3))) unsigned*)(buf + 16384 + S * 16), 16, 0, 0);
;   }
; }
; template <int AI, int BI>
; DI void gemm_tile(const u16* __restrict__ A, int lda, const u16* __restrict__ B, int ldb, int nk, bool swap,
;                   f32x16 (&acc)[AI][BI], char* lds) {
;     ...
;   for (int kt = 0; kt < nk; ++kt) {
;     const char* cur = lds + (kt & 1) * 32768;
;     if (kt + 1 < nk) gemm_stage<AI, BI>(A + (kt + 1) * 64, lda, B + (kt + 1) * 64, ldb, lds + ((kt + 1) & 1) * 32768, tid);
; #pragma unroll
;     for (int ks = 0; ks < 4; ++ks) {
;       const int co = ((ks * 2 + h) ^ sw) << 4;
;       s16x8 fa[AI], fb[BI];
; #pragma unroll
;       for (int i = 0; i < AI; ++i) fa[i] = *(const s16x8*)(cur + offA + i * 4096 + co);
; #pragma unroll
;       for (int i = 0; i < BI; ++i) fb[i] = *(const s16x8*)(cur + offB + i * 4096 + co);
; #pragma unroll
;       for (int i = 0; i < AI; ++i)
; #pragma unroll
;         for (int j = 0; j < BI; ++j) acc[i][j] = MFMA(fa[i], fb[j], acc[i][j]);
;     }
;     asm volatile("s_waitcnt vmcnt(0)" ::: "memory");
;     __syncthreads();
;   }
	v_lshl_add_u64 v[56:57], v[34:35], 0, s[2:3]
	global_load_lds_dwordx4 v[56:57], off
	v_lshl_add_u64 v[56:57], v[36:37], 0, s[2:3]
	s_mov_b32 m0, s18
	v_lshl_add_u64 v[34:35], v[34:35], 0, s[30:31]
	global_load_lds_dwordx4 v[56:57], off
	v_lshl_add_u64 v[56:57], v[40:41], 0, s[2:3]
	s_mov_b32 m0, s28
	s_nop 0
	global_load_lds_dwordx4 v[56:57], off
	v_lshl_add_u64 v[56:57], v[38:39], 0, s[2:3]
	s_mov_b32 m0, s29
	s_nop 0
	global_load_lds_dwordx4 v[56:57], off
	v_lshl_add_u64 v[56:57], v[42:43], 0, s[2:3]
	s_mov_b32 m0, s34
	s_nop 0
	global_load_lds_dwordx4 v[56:57], off
	v_lshl_add_u64 v[56:57], v[44:45], 0, s[2:3]
	s_mov_b32 m0, s35
	s_nop 0
	global_load_lds_dwordx4 v[56:57], off
	ds_read_b128 v[56:59], v0 offset:32768
	ds_read_b128 v[60:63], v50 offset:49152
	ds_read_b128 v[64:67], v50 offset:53248
	s_waitcnt lgkmcnt(0)
	v_mfma_f32_32x32x16_bf16 v[2:17], v[56:59], v[60:63], v[2:17]
	s_mov_b32 m0, s36
	v_mfma_f32_32x32x16_bf16 v[18:33], v[56:59], v[64:67], v[18:33]
	ds_read_b128 v[56:59], v48 offset:32768
	ds_read_b128 v[60:63], v49 offset:49152
	ds_read_b128 v[64:67], v49 offset:53248
	s_waitcnt lgkmcnt(1)
	v_mfma_f32_32x32x16_bf16 v[2:17], v[56:59], v[60:63], v[2:17]
	s_waitcnt lgkmcnt(0)
	v_mfma_f32_32x32x16_bf16 v[18:33], v[56:59], v[64:67], v[18:33]
	ds_read_b128 v[56:59], v52 offset:32768
	ds_read_b128 v[60:63], v51 offset:49152
	ds_read_b128 v[64:67], v51 offset:53248
	s_waitcnt lgkmcnt(1)
	v_mfma_f32_32x32x16_bf16 v[2:17], v[56:59], v[60:63], v[2:17]
	s_waitcnt lgkmcnt(0)
	v_mfma_f32_32x32x16_bf16 v[18:33], v[56:59], v[64:67], v[18:33]
	ds_read_b128 v[56:59], v54 offset:32768
	ds_read_b128 v[60:63], v53 offset:49152
	ds_read_b128 v[64:67], v53 offset:53248
	s_waitcnt vmcnt(0)
	s_waitcnt lgkmcnt(0)
	s_barrier
	global_load_lds_dwordx4 v[34:35], off
	v_lshl_add_u64 v[34:35], v[36:37], 0, s[30:31]
	s_mov_b32 m0, s37
	v_mfma_f32_32x32x16_bf16 v[2:17], v[56:59], v[60:63], v[2:17]
	global_load_lds_dwordx4 v[34:35], off
	v_lshl_add_u64 v[34:35], v[40:41], 0, s[30:31]
	s_mov_b32 m0, s40
	s_nop 0
	global_load_lds_dwordx4 v[34:35], off
	v_lshl_add_u64 v[34:35], v[38:39], 0, s[30:31]
	s_mov_b32 m0, s41
	v_mfma_f32_32x32x16_bf16 v[18:33], v[56:59], v[64:67], v[18:33]
	global_load_lds_dwordx4 v[34:35], off
	v_lshl_add_u64 v[34:35], v[42:43], 0, s[30:31]
	s_mov_b32 m0, s46
	s_nop 0
	global_load_lds_dwordx4 v[34:35], off
	v_lshl_add_u64 v[34:35], v[44:45], 0, s[30:31]
	s_mov_b32 m0, s47
	s_nop 0
	global_load_lds_dwordx4 v[34:35], off
	ds_read_b128 v[34:37], v0
	ds_read_b128 v[38:41], v50 offset:16384
	ds_read_b128 v[42:45], v50 offset:20480
	s_waitcnt lgkmcnt(0)
	v_mfma_f32_32x32x16_bf16 v[2:17], v[34:37], v[38:41], v[2:17]
	v_mfma_f32_32x32x16_bf16 v[18:33], v[34:37], v[42:45], v[18:33]
	ds_read_b128 v[34:37], v48
	ds_read_b128 v[38:41], v49 offset:16384
	ds_read_b128 v[42:45], v49 offset:20480
	s_waitcnt lgkmcnt(1)
	v_mfma_f32_32x32x16_bf16 v[2:17], v[34:37], v[38:41], v[2:17]
	s_waitcnt lgkmcnt(0)
	v_mfma_f32_32x32x16_bf16 v[18:33], v[34:37], v[42:45], v[18:33]
	ds_read_b128 v[34:37], v52
	ds_read_b128 v[38:41], v51 offset:16384
	ds_read_b128 v[42:45], v51 offset:20480
	s_waitcnt lgkmcnt(1)
	v_mfma_f32_32x32x16_bf16 v[2:17], v[34:37], v[38:41], v[2:17]
	s_waitcnt lgkmcnt(0)
	v_mfma_f32_32x32x16_bf16 v[18:33], v[34:37], v[42:45], v[18:33]
	ds_read_b128 v[34:37], v54
	ds_read_b128 v[38:41], v53 offset:16384
	ds_read_b128 v[42:45], v53 offset:20480
	s_waitcnt lgkmcnt(0)
	v_mfma_f32_32x32x16_bf16 v[2:17], v[34:37], v[38:41], v[2:17]
	v_mfma_f32_32x32x16_bf16 v[18:33], v[34:37], v[42:45], v[18:33]
	s_waitcnt vmcnt(0)
	s_barrier
	ds_read_b128 v[34:37], v50 offset:53248
	ds_read_b128 v[38:41], v50 offset:49152
	ds_read_b128 v[42:45], v0 offset:32768
	v_mov_b32_e32 v0, v1
	s_waitcnt lgkmcnt(0)
	v_mfma_f32_32x32x16_bf16 v[2:17], v[42:45], v[38:41], v[2:17]
	v_mfma_f32_32x32x16_bf16 v[18:33], v[42:45], v[34:37], v[18:33]
	ds_read_b128 v[34:37], v48 offset:32768
	ds_read_b128 v[38:41], v49 offset:49152
	ds_read_b128 v[42:45], v49 offset:53248
	s_waitcnt lgkmcnt(1)
	v_mfma_f32_32x32x16_bf16 v[2:17], v[34:37], v[38:41], v[2:17]
	s_waitcnt lgkmcnt(0)
	v_mfma_f32_32x32x16_bf16 v[18:33], v[34:37], v[42:45], v[18:33]
	ds_read_b128 v[34:37], v52 offset:32768
	ds_read_b128 v[38:41], v51 offset:49152
	ds_read_b128 v[42:45], v51 offset:53248
	s_waitcnt lgkmcnt(1)
	v_mfma_f32_32x32x16_bf16 v[2:17], v[34:37], v[38:41], v[2:17]
	s_waitcnt lgkmcnt(0)
	v_mfma_f32_32x32x16_bf16 v[18:33], v[34:37], v[42:45], v[18:33]
	ds_read_b128 v[34:37], v54 offset:32768
	ds_read_b128 v[38:41], v53 offset:49152
	ds_read_b128 v[42:45], v53 offset:53248
	s_waitcnt vmcnt(0)
	s_waitcnt lgkmcnt(0)
	s_barrier
; #define GAS __attribute__((address_space(1)))
; DI int opaque0() { int z = 0; asm volatile("" : "+v"(z)); return z; }
; template <int AI>
; DI void gu_tile(char* wsb, int sub, int m0, int n0, char* lds) {
;     ...
;   const int m0e = m0 + opaque0();
;   const int hc = (n0 >> 1) + wb * 32 + r;
;   GAS u16* HIDu = uptr(HID);
;   const unsigned ib = (unsigned)((m0e + wa * 32 * AI + 4 * h) * 2816 + hc);
; #pragma unroll
;   for (int ai = 0; ai < AI; ++ai)
; #pragma unroll
;     for (int reg = 0; reg < 16; ++reg) {
;       float g = acc[ai][0][reg], u = acc[ai][1][reg];
;       float v = g * __builtin_amdgcn_rcpf(1.f + __expf(-g)) * u;
;       HIDu[ib + (unsigned)((ai * 32 + (reg & 3) + 8 * (reg >> 2)) * 2816)] = f2bf(v);
;       if ((reg & 7) == 7) __builtin_amdgcn_sched_barrier(0);
;     }
	v_mfma_f32_32x32x16_bf16 v[2:17], v[34:37], v[38:41], v[2:17]
	v_mfma_f32_32x32x16_bf16 v[18:33], v[34:37], v[42:45], v[18:33]
	v_lshrrev_b32_e32 v36, 3, v46
	v_lshrrev_b32_e32 v34, 1, v47
	v_lshrrev_b32_e32 v35, 2, v47
	v_and_b32_e32 v36, 4, v36
	v_and_b32_e32 v34, 32, v34
	v_and_or_b32 v35, v35, s53, v36
	v_add3_u32 v35, v35, s17, v0
	v_or3_b32 v0, v34, v55, s8
	s_nop 2
	v_mul_f32_e32 v34, 0xbfb8aa3b, v2
	v_exp_f32_e32 v34, v34
	s_nop 0
	v_add_f32_e32 v34, 1.0, v34
	v_rcp_f32_e32 v34, v34
	s_nop 0
	v_mul_f32_e32 v2, v2, v34
	v_mad_u64_u32 v[34:35], s[8:9], v35, s51, v[0:1]
	v_mul_f32_e32 v0, 0xbfb8aa3b, v3
	v_exp_f32_e32 v0, v0
	v_mul_f32_e32 v2, v18, v2
	v_mov_b32_e32 v35, v1
	v_cvt_pk_bf16_f32 v2, v2, s0
	v_add_f32_e32 v0, 1.0, v0
	v_rcp_f32_e32 v0, v0
	v_lshl_add_u64 v[36:37], v[34:35], 1, s[6:7]
	global_store_short v[36:37], v2, off
	v_mul_f32_e32 v0, v3, v0
	v_mul_f32_e32 v0, v19, v0
	v_cvt_pk_bf16_f32 v18, v0, s0
	v_add_u32_e32 v0, 0xb00, v34
	v_lshl_add_u64 v[2:3], v[0:1], 1, s[6:7]
	v_mul_f32_e32 v0, 0xbfb8aa3b, v4
	v_exp_f32_e32 v0, v0
	global_store_short v[2:3], v18, off
	v_add_f32_e32 v0, 1.0, v0
	v_rcp_f32_e32 v0, v0
	s_nop 0
	v_mul_f32_e32 v0, v4, v0
	v_mul_f32_e32 v0, v20, v0
	v_cvt_pk_bf16_f32 v4, v0, s0
	v_add_u32_e32 v0, 0x1600, v34
	v_lshl_add_u64 v[2:3], v[0:1], 1, s[6:7]
	v_mul_f32_e32 v0, 0xbfb8aa3b, v5
	v_exp_f32_e32 v0, v0
	global_store_short v[2:3], v4, off
	v_add_f32_e32 v0, 1.0, v0
	v_rcp_f32_e32 v0, v0
	s_nop 0
	v_mul_f32_e32 v0, v5, v0
	v_mul_f32_e32 v0, v21, v0
	v_cvt_pk_bf16_f32 v4, v0, s0
	v_add_u32_e32 v0, 0x2100, v34
	v_lshl_add_u64 v[2:3], v[0:1], 1, s[6:7]
	v_mul_f32_e32 v0, 0xbfb8aa3b, v6
	v_exp_f32_e32 v0, v0
	global_store_short v[2:3], v4, off
	v_add_f32_e32 v0, 1.0, v0
	v_rcp_f32_e32 v0, v0
	s_nop 0
	v_mul_f32_e32 v0, v6, v0
	v_mul_f32_e32 v0, v22, v0
	v_cvt_pk_bf16_f32 v4, v0, s0
	v_add_u32_e32 v0, 0x5800, v34
	v_lshl_add_u64 v[2:3], v[0:1], 1, s[6:7]
	v_mul_f32_e32 v0, 0xbfb8aa3b, v7
	v_exp_f32_e32 v0, v0
	global_store_short v[2:3], v4, off
	v_add_f32_e32 v0, 1.0, v0
	v_rcp_f32_e32 v0, v0
	s_nop 0
	v_mul_f32_e32 v0, v7, v0
	v_mul_f32_e32 v0, v23, v0
	v_cvt_pk_bf16_f32 v4, v0, s0
	v_add_u32_e32 v0, 0x6300, v34
	v_lshl_add_u64 v[2:3], v[0:1], 1, s[6:7]
	v_mul_f32_e32 v0, 0xbfb8aa3b, v8
	v_exp_f32_e32 v0, v0
	global_store_short v[2:3], v4, off
	v_add_f32_e32 v0, 1.0, v0
	v_rcp_f32_e32 v0, v0
	s_nop 0
	v_mul_f32_e32 v0, v8, v0
	v_mul_f32_e32 v0, v24, v0
	v_cvt_pk_bf16_f32 v4, v0, s0
	v_add_u32_e32 v0, 0x6e00, v34
	v_lshl_add_u64 v[2:3], v[0:1], 1, s[6:7]
	v_mul_f32_e32 v0, 0xbfb8aa3b, v9
	v_exp_f32_e32 v0, v0
	global_store_short v[2:3], v4, off
	v_add_f32_e32 v0, 1.0, v0
	v_rcp_f32_e32 v0, v0
	s_nop 0
	v_mul_f32_e32 v0, v9, v0
	v_mul_f32_e32 v0, v25, v0
	v_cvt_pk_bf16_f32 v4, v0, s0
	v_add_u32_e32 v0, 0x7900, v34
	v_lshl_add_u64 v[2:3], v[0:1], 1, s[6:7]
	global_store_short v[2:3], v4, off
	v_mul_f32_e32 v0, 0xbfb8aa3b, v10
	v_exp_f32_e32 v0, v0
	s_nop 0
	v_add_f32_e32 v0, 1.0, v0
	v_rcp_f32_e32 v0, v0
	s_nop 0
	v_mul_f32_e32 v0, v10, v0
	v_mul_f32_e32 v0, v26, v0
	v_cvt_pk_bf16_f32 v4, v0, s0
	v_add_u32_e32 v0, 0xb000, v34
	v_lshl_add_u64 v[2:3], v[0:1], 1, s[6:7]
	v_mul_f32_e32 v0, 0xbfb8aa3b, v11
	v_exp_f32_e32 v0, v0
	global_store_short v[2:3], v4, off
	v_add_f32_e32 v0, 1.0, v0
	v_rcp_f32_e32 v0, v0
	s_nop 0
	v_mul_f32_e32 v0, v11, v0
	v_mul_f32_e32 v0, v27, v0
	v_cvt_pk_bf16_f32 v4, v0, s0
	v_add_u32_e32 v0, 0xbb00, v34
	v_lshl_add_u64 v[2:3], v[0:1], 1, s[6:7]
	v_mul_f32_e32 v0, 0xbfb8aa3b, v12
	v_exp_f32_e32 v0, v0
	global_store_short v[2:3], v4, off
	v_add_f32_e32 v0, 1.0, v0
	v_rcp_f32_e32 v0, v0
	s_nop 0
	v_mul_f32_e32 v0, v12, v0
	v_mul_f32_e32 v0, v28, v0
	v_cvt_pk_bf16_f32 v4, v0, s0
	v_add_u32_e32 v0, 0xc600, v34
	v_lshl_add_u64 v[2:3], v[0:1], 1, s[6:7]
	v_mul_f32_e32 v0, 0xbfb8aa3b, v13
	v_exp_f32_e32 v0, v0
	global_store_short v[2:3], v4, off
	v_add_f32_e32 v0, 1.0, v0
	v_rcp_f32_e32 v0, v0
	s_nop 0
	v_mul_f32_e32 v0, v13, v0
	v_mul_f32_e32 v0, v29, v0
	v_cvt_pk_bf16_f32 v4, v0, s0
	v_add_u32_e32 v0, 0xd100, v34
	v_lshl_add_u64 v[2:3], v[0:1], 1, s[6:7]
	v_mul_f32_e32 v0, 0xbfb8aa3b, v14
	v_exp_f32_e32 v0, v0
	global_store_short v[2:3], v4, off
	v_add_f32_e32 v0, 1.0, v0
	v_rcp_f32_e32 v0, v0
	s_nop 0
	v_mul_f32_e32 v0, v14, v0
	v_mul_f32_e32 v0, v30, v0
	v_cvt_pk_bf16_f32 v4, v0, s0
	v_add_u32_e32 v0, 0x10800, v34
	v_lshl_add_u64 v[2:3], v[0:1], 1, s[6:7]
	v_mul_f32_e32 v0, 0xbfb8aa3b, v15
	v_exp_f32_e32 v0, v0
	global_store_short v[2:3], v4, off
	v_add_f32_e32 v0, 1.0, v0
	v_rcp_f32_e32 v0, v0
	s_nop 0
	v_mul_f32_e32 v0, v15, v0
	v_mul_f32_e32 v0, v31, v0
	v_cvt_pk_bf16_f32 v4, v0, s0
	v_add_u32_e32 v0, 0x11300, v34
	v_lshl_add_u64 v[2:3], v[0:1], 1, s[6:7]
	v_mul_f32_e32 v0, 0xbfb8aa3b, v16
	v_exp_f32_e32 v0, v0
	global_store_short v[2:3], v4, off
	v_add_f32_e32 v0, 1.0, v0
	v_rcp_f32_e32 v0, v0
	s_nop 0
	v_mul_f32_e32 v0, v16, v0
	v_mul_f32_e32 v0, v32, v0
	v_cvt_pk_bf16_f32 v4, v0, s0
	v_add_u32_e32 v0, 0x11e00, v34
	v_lshl_add_u64 v[2:3], v[0:1], 1, s[6:7]
	v_mul_f32_e32 v0, 0xbfb8aa3b, v17
	v_exp_f32_e32 v0, v0
	global_store_short v[2:3], v4, off
	v_add_f32_e32 v0, 1.0, v0
	v_rcp_f32_e32 v0, v0
	s_nop 0
	v_mul_f32_e32 v0, v17, v0
	v_mul_f32_e32 v0, v33, v0
	v_cvt_pk_bf16_f32 v4, v0, s0
	v_add_u32_e32 v0, 0x12900, v34
	v_lshl_add_u64 v[2:3], v[0:1], 1, s[6:7]
	global_store_short v[2:3], v4, off
	s_add_i32 s16, s16, s49
	s_add_i32 s15, s15, s50
	s_add_i32 s14, s14, s48
	s_cmpk_gt_u32 s14, 0x57f
	s_cbranch_scc0 .LBB0_1210

; #define MFMA(a, b, c) __builtin_amdgcn_mfma_f32_32x32x16_bf16((a), (b), (c), 0, 0, 0)
; template <int AI, int BI>
; DI void gemm_stage(const u16* __restrict__ A, int lda, const u16* __restrict__ B, int ldb, char* buf, int tid) {
; #pragma unroll
;   for (int i = 0; i < 2 * AI; ++i) {
;     const int S = tid + NTHR * i, row = S >> 3, c = (S & 7) ^ ((row >> 1) & 7);
;     __builtin_amdgcn_global_load_lds((const unsigned*)(A + (size_t)row * lda + c * 8), (__attribute__((address_space(3))) unsigned*)(buf + S * 16), 16, 0, 0);
;   }
; #pragma unroll
;   for (int i = 0; i < 2 * BI; ++i) {
;     const int S = tid + NTHR * i, row = S >> 3, c = (S & 7) ^ ((row >> 1) & 7);
;     __builtin_amdgcn_global_load_lds((const unsigned*)(B + (size_t)row * ldb + c * 8), (__attribute__((address_space(3))) unsigned*)(buf + 16384 + S * 16), 16, 0, 0);
;   }
; }
; template <int AI, int BI>
; DI void gemm_tile(const u16* __restrict__ A, int lda, const u16* __restrict__ B, int ldb, int nk, bool swap,
;                   f32x16 (&acc)[AI][BI], char* lds) {
;     ...
;   for (int kt = 0; kt < nk; ++kt) {
;     const char* cur = lds + (kt & 1) * 32768;
;     if (kt + 1 < nk) gemm_stage<AI, BI>(A + (kt + 1) * 64, lda, B + (kt + 1) * 64, ldb, lds + ((kt + 1) & 1) * 32768, tid);
; #pragma unroll
;     for (int ks = 0; ks < 4; ++ks) {
;       const int co = ((ks * 2 + h) ^ sw) << 4;
;       s16x8 fa[AI], fb[BI];
; #pragma unroll
;       for (int i = 0; i < AI; ++i) fa[i] = *(const s16x8*)(cur + offA + i * 4096 + co);
; #pragma unroll
;       for (int i = 0; i < BI; ++i) fb[i] = *(const s16x8*)(cur + offB + i * 4096 + co);
; #pragma unroll
;       for (int i = 0; i < AI; ++i)
; #pragma unroll
;         for (int j = 0; j < BI; ++j) acc[i][j] = MFMA(fa[i], fb[j], acc[i][j]);
;     }
;     asm volatile("s_waitcnt vmcnt(0)" ::: "memory");
;     __syncthreads();
;   }
.LBB0_1264:
	s_add_i32 s15, s13, 0xffff8000
	s_and_b32 s41, s15, 0x8000
	s_and_b32 s15, s13, 0x8000
	v_add_u32_e32 v93, s15, v85
	v_add_u32_e32 v96, s15, v86
	v_readfirstlane_b32 s46, v93
	v_lshl_add_u64 v[94:95], v[66:67], 0, s[6:7]
	s_mov_b32 m0, s46
	v_readfirstlane_b32 s46, v96
	v_add_u32_e32 v97, s15, v87
	global_load_lds_dwordx4 v[94:95], off
	v_lshl_add_u64 v[94:95], v[68:69], 0, s[6:7]
	s_mov_b32 m0, s46
	v_readfirstlane_b32 s46, v97
	v_add_u32_e32 v98, s15, v89
	global_load_lds_dwordx4 v[94:95], off
	v_lshl_add_u64 v[94:95], v[70:71], 0, s[6:7]
	s_mov_b32 m0, s46
	v_readfirstlane_b32 s46, v98
	v_add_u32_e32 v93, 0x4000, v93
	global_load_lds_dwordx4 v[94:95], off
	v_lshl_add_u64 v[94:95], v[72:73], 0, s[6:7]
	s_mov_b32 m0, s46
	v_readfirstlane_b32 s46, v93
	v_add_u32_e32 v93, 0x4000, v96
	global_load_lds_dwordx4 v[94:95], off
	v_lshl_add_u64 v[94:95], v[74:75], 0, s[6:7]
	s_mov_b32 m0, s46
	v_readfirstlane_b32 s46, v93
	v_add_u32_e32 v93, 0x4000, v97
	global_load_lds_dwordx4 v[94:95], off
	v_lshl_add_u64 v[94:95], v[76:77], 0, s[6:7]
	s_mov_b32 m0, s46
	v_readfirstlane_b32 s46, v93
	v_add_u32_e32 v93, 0x4000, v98
	global_load_lds_dwordx4 v[94:95], off
	v_lshl_add_u64 v[94:95], v[78:79], 0, s[6:7]
	s_mov_b32 m0, s46
	v_readfirstlane_b32 s46, v93
	global_load_lds_dwordx4 v[94:95], off
	v_lshl_add_u64 v[94:95], v[80:81], 0, s[6:7]
	s_mov_b32 m0, s46
	v_add_u32_e32 v93, s41, v91
	global_load_lds_dwordx4 v[94:95], off
	v_or_b32_e32 v110, s41, v92
	v_add_u32_e32 v98, v93, v90
	v_add_u32_e32 v106, v110, v90
	ds_read_b128 v[94:97], v98
	ds_read_b128 v[98:101], v98 offset:4096
	ds_read_b128 v[102:105], v106 offset:16384
	ds_read_b128 v[106:109], v106 offset:20480
	s_waitcnt lgkmcnt(0)
	v_mfma_f32_32x32x16_bf16 v[50:65], v[94:97], v[102:105], v[50:65]
	s_add_u32 s6, s6, 0x80
	s_addc_u32 s7, s7, 0
	s_add_i32 s13, s13, 0x8000
	s_cmpk_eq_i32 s6, 0x1580
	v_mfma_f32_32x32x16_bf16 v[18:33], v[94:97], v[106:109], v[18:33]
	v_mfma_f32_32x32x16_bf16 v[34:49], v[98:101], v[102:105], v[34:49]
	v_mfma_f32_32x32x16_bf16 v[2:17], v[98:101], v[106:109], v[2:17]
	v_add_u32_e32 v98, v93, v88
	v_add_u32_e32 v106, v110, v88
	ds_read_b128 v[94:97], v98
	ds_read_b128 v[98:101], v98 offset:4096
	ds_read_b128 v[102:105], v106 offset:16384
	ds_read_b128 v[106:109], v106 offset:20480
	s_waitcnt lgkmcnt(1)
	v_mfma_f32_32x32x16_bf16 v[50:65], v[94:97], v[102:105], v[50:65]
	s_waitcnt lgkmcnt(0)
	v_mfma_f32_32x32x16_bf16 v[18:33], v[94:97], v[106:109], v[18:33]
	v_mfma_f32_32x32x16_bf16 v[34:49], v[98:101], v[102:105], v[34:49]
	v_mfma_f32_32x32x16_bf16 v[2:17], v[98:101], v[106:109], v[2:17]
	v_add_u32_e32 v98, v93, v84
	v_add_u32_e32 v106, v110, v84
	ds_read_b128 v[94:97], v98
	ds_read_b128 v[98:101], v98 offset:4096
	ds_read_b128 v[102:105], v106 offset:16384
	ds_read_b128 v[106:109], v106 offset:20480
	v_add_u32_e32 v93, v93, v0
	s_waitcnt lgkmcnt(1)
	v_mfma_f32_32x32x16_bf16 v[50:65], v[94:97], v[102:105], v[50:65]
	s_waitcnt lgkmcnt(0)
	v_mfma_f32_32x32x16_bf16 v[18:33], v[94:97], v[106:109], v[18:33]
	v_mfma_f32_32x32x16_bf16 v[34:49], v[98:101], v[102:105], v[34:49]
	v_mfma_f32_32x32x16_bf16 v[2:17], v[98:101], v[106:109], v[2:17]
	ds_read_b128 v[94:97], v93
	ds_read_b128 v[98:101], v93 offset:4096
	v_add_u32_e32 v93, v110, v0
	ds_read_b128 v[102:105], v93 offset:16384
	ds_read_b128 v[106:109], v93 offset:20480
	s_waitcnt lgkmcnt(0)
	v_mfma_f32_32x32x16_bf16 v[50:65], v[94:97], v[102:105], v[50:65]
	v_mfma_f32_32x32x16_bf16 v[18:33], v[94:97], v[106:109], v[18:33]
	v_mfma_f32_32x32x16_bf16 v[34:49], v[98:101], v[102:105], v[34:49]
	v_mfma_f32_32x32x16_bf16 v[2:17], v[98:101], v[106:109], v[2:17]
	s_waitcnt vmcnt(0)
	s_barrier
	s_cbranch_scc0 .LBB0_1264
	v_add_u32_e32 v86, s15, v91
	v_add_u32_e32 v87, s15, v92
	v_add_u32_e32 v70, v86, v90
	v_add_u32_e32 v78, v87, v90
	ds_read_b128 v[66:69], v70
	ds_read_b128 v[70:73], v70 offset:4096
	ds_read_b128 v[74:77], v78 offset:16384
	ds_read_b128 v[78:81], v78 offset:20480
	s_waitcnt lgkmcnt(1)
	v_mfma_f32_32x32x16_bf16 v[50:65], v[66:69], v[74:77], v[50:65]
	s_lshr_b32 s7, s40, 7
	s_lshl_b32 s6, s12, 7
	s_mul_i32 s7, s7, 0x9000
	v_and_b32_e32 v85, 31, v82
	s_add_u32 s7, s34, s7
	s_addc_u32 s13, s35, 0
	s_add_u32 s12, s7, 0xc000
	s_waitcnt lgkmcnt(0)
	v_mfma_f32_32x32x16_bf16 v[18:33], v[66:69], v[78:81], v[18:33]
	s_addc_u32 s13, s13, 0
	s_and_b64 vcc, exec, s[48:49]
	v_mfma_f32_32x32x16_bf16 v[34:49], v[70:73], v[74:77], v[34:49]
	v_mfma_f32_32x32x16_bf16 v[2:17], v[70:73], v[78:81], v[2:17]
	v_add_u32_e32 v70, v86, v88
	v_add_u32_e32 v78, v87, v88
	ds_read_b128 v[66:69], v70
	ds_read_b128 v[70:73], v70 offset:4096
	ds_read_b128 v[74:77], v78 offset:16384
	ds_read_b128 v[78:81], v78 offset:20480
	s_waitcnt lgkmcnt(1)
	v_mfma_f32_32x32x16_bf16 v[50:65], v[66:69], v[74:77], v[50:65]
	s_waitcnt lgkmcnt(0)
	v_mfma_f32_32x32x16_bf16 v[18:33], v[66:69], v[78:81], v[18:33]
	v_mfma_f32_32x32x16_bf16 v[34:49], v[70:73], v[74:77], v[34:49]
	v_mfma_f32_32x32x16_bf16 v[2:17], v[70:73], v[78:81], v[2:17]
	v_add_u32_e32 v70, v86, v84
	v_add_u32_e32 v78, v87, v84
	ds_read_b128 v[66:69], v70
	ds_read_b128 v[70:73], v70 offset:4096
	ds_read_b128 v[74:77], v78 offset:16384
	ds_read_b128 v[78:81], v78 offset:20480
	s_waitcnt lgkmcnt(1)
	v_mfma_f32_32x32x16_bf16 v[50:65], v[66:69], v[74:77], v[50:65]
	s_waitcnt lgkmcnt(0)
	v_mfma_f32_32x32x16_bf16 v[18:33], v[66:69], v[78:81], v[18:33]
	v_mfma_f32_32x32x16_bf16 v[34:49], v[70:73], v[74:77], v[34:49]
	v_mfma_f32_32x32x16_bf16 v[2:17], v[70:73], v[78:81], v[2:17]
	v_add_u32_e32 v70, v86, v0
	v_add_u32_e32 v0, v87, v0
	ds_read_b128 v[66:69], v70
	ds_read_b128 v[70:73], v70 offset:4096
	ds_read_b128 v[74:77], v0 offset:16384
	ds_read_b128 v[78:81], v0 offset:20480
	v_mov_b32_e32 v0, v1
	s_waitcnt vmcnt(0)
	s_waitcnt lgkmcnt(0)
	v_mfma_f32_32x32x16_bf16 v[50:65], v[66:69], v[74:77], v[50:65]
	s_barrier
; #define GAS __attribute__((address_space(1)))
; DI int opaque0() { int z = 0; asm volatile("" : "+v"(z)); return z; }
; template <int AI, int BI>
; DI void dn_tile(const Params& p, char* wsb, int layer, int sub, bool final_out, int m0, int n0, char* lds) {
;     ...
;   const int m0e = m0 + opaque0();
;   const int mr = m0 < TL ? (m0 >> 11) : 8;
;   const float* gate = mods + (size_t)mr * 9216 + (2 + 6 * sub) * 1024;
;   GAS float* xsu = uptr(xs);
;   GAS float* outu = uptr(p.out);
; #pragma unroll
;   for (int bi = 0; bi < BI; ++bi) {
;     const int n = n0 + wb * 32 * BI + bi * 32 + r;
;     const float gv = 0.5f * gate[n];
;     const unsigned ib = (unsigned)((m0e + wa * 32 * AI + 4 * h) * 1024 + n);
; #pragma unroll
;     for (int ai = 0; ai < AI; ++ai)
; #pragma unroll
;       for (int reg = 0; reg < 16; ++reg) {
;         const unsigned idx = ib + (unsigned)((ai * 32 + (reg & 3) + 8 * (reg >> 2)) * 1024);
;         float v = xsu[idx] + gv * acc[ai][bi][reg];
;         if (final_out) outu[idx] = v; else xsu[idx] = v;
;         if ((reg & 7) == 7) __builtin_amdgcn_sched_barrier(0);
;       }
;   }
	v_mfma_f32_32x32x16_bf16 v[18:33], v[66:69], v[78:81], v[18:33]
	v_mfma_f32_32x32x16_bf16 v[34:49], v[70:73], v[74:77], v[34:49]
	v_mfma_f32_32x32x16_bf16 v[2:17], v[70:73], v[78:81], v[2:17]
	v_and_b32_e32 v143, 31, v178
	v_and_b32_e32 v140, 64, v178
	v_or_b32_e32 v140, v140, v143
	v_bfe_u32 v143, v178, 5, 1
	v_bfe_u32 v139, v178, 7, 1
	v_lshlrev_b32_e32 v139, 6, v139
	v_lshl_add_u32 v139, v143, 2, v139
	v_lshl_add_u32 v139, v139, 10, v140
	v_lshlrev_b32_e32 v139, 2, v139
	v_add_u32_e32 v140, s14, v140
	v_lshlrev_b32_e32 v140, 2, v140
	global_load_dword v141, v140, s[12:13]
	global_load_dword v142, v140, s[12:13] offset:128
	s_lshl_b32 s56, s6, 10
	s_add_u32 s56, s56, s14
	s_lshl_b32 s56, s56, 2
	s_add_u32 s54, s8, s56
	s_addc_u32 s55, s9, 0
	s_mov_b64 s[52:53], s[54:55]
	global_load_dword v66, v139, s[52:53]
	global_load_dword v67, v139, s[52:53] offset:128
	s_add_u32 s52, s52, 4096
	s_addc_u32 s53, s53, 0
	global_load_dword v68, v139, s[52:53]
	global_load_dword v69, v139, s[52:53] offset:128
	s_add_u32 s52, s52, 4096
	s_addc_u32 s53, s53, 0
	global_load_dword v70, v139, s[52:53]
	global_load_dword v71, v139, s[52:53] offset:128
	s_add_u32 s52, s52, 4096
	s_addc_u32 s53, s53, 0
	global_load_dword v72, v139, s[52:53]
	global_load_dword v73, v139, s[52:53] offset:128
	s_add_u32 s52, s52, 20480
	s_addc_u32 s53, s53, 0
	global_load_dword v74, v139, s[52:53]
	global_load_dword v75, v139, s[52:53] offset:128
	s_add_u32 s52, s52, 4096
	s_addc_u32 s53, s53, 0
	global_load_dword v76, v139, s[52:53]
	global_load_dword v77, v139, s[52:53] offset:128
	s_add_u32 s52, s52, 4096
	s_addc_u32 s53, s53, 0
	global_load_dword v78, v139, s[52:53]
	global_load_dword v79, v139, s[52:53] offset:128
	s_add_u32 s52, s52, 4096
	s_addc_u32 s53, s53, 0
	global_load_dword v80, v139, s[52:53]
	global_load_dword v81, v139, s[52:53] offset:128
	s_add_u32 s52, s52, 20480
	s_addc_u32 s53, s53, 0
	global_load_dword v82, v139, s[52:53]
	global_load_dword v83, v139, s[52:53] offset:128
	s_add_u32 s52, s52, 4096
	s_addc_u32 s53, s53, 0
	global_load_dword v84, v139, s[52:53]
	global_load_dword v85, v139, s[52:53] offset:128
	s_add_u32 s52, s52, 4096
	s_addc_u32 s53, s53, 0
	global_load_dword v86, v139, s[52:53]
	global_load_dword v87, v139, s[52:53] offset:128
	s_add_u32 s52, s52, 4096
	s_addc_u32 s53, s53, 0
	global_load_dword v88, v139, s[52:53]
	global_load_dword v89, v139, s[52:53] offset:128
	s_add_u32 s52, s52, 20480
	s_addc_u32 s53, s53, 0
	global_load_dword v90, v139, s[52:53]
	global_load_dword v91, v139, s[52:53] offset:128
	s_add_u32 s52, s52, 4096
	s_addc_u32 s53, s53, 0
	global_load_dword v92, v139, s[52:53]
	global_load_dword v93, v139, s[52:53] offset:128
	s_add_u32 s52, s52, 4096
	s_addc_u32 s53, s53, 0
	global_load_dword v94, v139, s[52:53]
	global_load_dword v95, v139, s[52:53] offset:128
	s_add_u32 s52, s52, 4096
	s_addc_u32 s53, s53, 0
	global_load_dword v96, v139, s[52:53]
	global_load_dword v97, v139, s[52:53] offset:128
	s_add_u32 s52, s52, 20480
	s_addc_u32 s53, s53, 0
	global_load_dword v98, v139, s[52:53]
	global_load_dword v99, v139, s[52:53] offset:128
	s_add_u32 s52, s52, 4096
	s_addc_u32 s53, s53, 0
	global_load_dword v100, v139, s[52:53]
	global_load_dword v101, v139, s[52:53] offset:128
	s_add_u32 s52, s52, 4096
	s_addc_u32 s53, s53, 0
	global_load_dword v102, v139, s[52:53]
	global_load_dword v103, v139, s[52:53] offset:128
	s_add_u32 s52, s52, 4096
	s_addc_u32 s53, s53, 0
	global_load_dword v104, v139, s[52:53]
	global_load_dword v105, v139, s[52:53] offset:128
	s_add_u32 s52, s52, 20480
	s_addc_u32 s53, s53, 0
	global_load_dword v106, v139, s[52:53]
	global_load_dword v107, v139, s[52:53] offset:128
	s_add_u32 s52, s52, 4096
	s_addc_u32 s53, s53, 0
	global_load_dword v108, v139, s[52:53]
	global_load_dword v109, v139, s[52:53] offset:128
	s_add_u32 s52, s52, 4096
	s_addc_u32 s53, s53, 0
	global_load_dword v110, v139, s[52:53]
	global_load_dword v111, v139, s[52:53] offset:128
	s_add_u32 s52, s52, 4096
	s_addc_u32 s53, s53, 0
	global_load_dword v112, v139, s[52:53]
	global_load_dword v113, v139, s[52:53] offset:128
	s_add_u32 s52, s52, 20480
	s_addc_u32 s53, s53, 0
	global_load_dword v114, v139, s[52:53]
	global_load_dword v115, v139, s[52:53] offset:128
	s_add_u32 s52, s52, 4096
	s_addc_u32 s53, s53, 0
	global_load_dword v116, v139, s[52:53]
	global_load_dword v117, v139, s[52:53] offset:128
	s_add_u32 s52, s52, 4096
	s_addc_u32 s53, s53, 0
	global_load_dword v118, v139, s[52:53]
	global_load_dword v119, v139, s[52:53] offset:128
	s_add_u32 s52, s52, 4096
	s_addc_u32 s53, s53, 0
	global_load_dword v120, v139, s[52:53]
	global_load_dword v121, v139, s[52:53] offset:128
	s_add_u32 s52, s52, 20480
	s_addc_u32 s53, s53, 0
	global_load_dword v122, v139, s[52:53]
	global_load_dword v123, v139, s[52:53] offset:128
	s_add_u32 s52, s52, 4096
	s_addc_u32 s53, s53, 0
	global_load_dword v124, v139, s[52:53]
	global_load_dword v134, v139, s[52:53] offset:128
	s_add_u32 s52, s52, 4096
	s_addc_u32 s53, s53, 0
	global_load_dword v135, v139, s[52:53]
	global_load_dword v136, v139, s[52:53] offset:128
	s_add_u32 s52, s52, 4096
	s_addc_u32 s53, s53, 0
	global_load_dword v137, v139, s[52:53]
	global_load_dword v138, v139, s[52:53] offset:128
	s_waitcnt vmcnt(48)
	v_mul_f32_e32 v141, 0.5, v141
	v_mul_f32_e32 v142, 0.5, v142
	v_fmac_f32_e32 v66, v50, v141
	v_fmac_f32_e32 v67, v18, v142
	v_fmac_f32_e32 v68, v51, v141
	v_fmac_f32_e32 v69, v19, v142
	v_fmac_f32_e32 v70, v52, v141
	v_fmac_f32_e32 v71, v20, v142
	v_fmac_f32_e32 v72, v53, v141
	v_fmac_f32_e32 v73, v21, v142
	v_fmac_f32_e32 v74, v54, v141
	v_fmac_f32_e32 v75, v22, v142
	v_fmac_f32_e32 v76, v55, v141
	v_fmac_f32_e32 v77, v23, v142
	v_fmac_f32_e32 v78, v56, v141
	v_fmac_f32_e32 v79, v24, v142
	v_fmac_f32_e32 v80, v57, v141
	v_fmac_f32_e32 v81, v25, v142
	s_waitcnt vmcnt(32)
; template <int AI, int BI>
; DI void dn_tile(const Params& p, char* wsb, int layer, int sub, bool final_out, int m0, int n0, char* lds) {
;     ...
; #pragma unroll
;   for (int bi = 0; bi < BI; ++bi) {
;     const int n = n0 + wb * 32 * BI + bi * 32 + r;
;     const float gv = 0.5f * gate[n];
;     const unsigned ib = (unsigned)((m0e + wa * 32 * AI + 4 * h) * 1024 + n);
; #pragma unroll
;     for (int ai = 0; ai < AI; ++ai)
; #pragma unroll
;       for (int reg = 0; reg < 16; ++reg) {
;         const unsigned idx = ib + (unsigned)((ai * 32 + (reg & 3) + 8 * (reg >> 2)) * 1024);
;         float v = xsu[idx] + gv * acc[ai][bi][reg];
;         if (final_out) outu[idx] = v; else xsu[idx] = v;
;         if ((reg & 7) == 7) __builtin_amdgcn_sched_barrier(0);
;       }
;   }
	v_fmac_f32_e32 v82, v58, v141
	v_fmac_f32_e32 v83, v26, v142
	v_fmac_f32_e32 v84, v59, v141
	v_fmac_f32_e32 v85, v27, v142
	v_fmac_f32_e32 v86, v60, v141
	v_fmac_f32_e32 v87, v28, v142
	v_fmac_f32_e32 v88, v61, v141
	v_fmac_f32_e32 v89, v29, v142
	v_fmac_f32_e32 v90, v62, v141
	v_fmac_f32_e32 v91, v30, v142
	v_fmac_f32_e32 v92, v63, v141
	v_fmac_f32_e32 v93, v31, v142
	v_fmac_f32_e32 v94, v64, v141
	v_fmac_f32_e32 v95, v32, v142
	v_fmac_f32_e32 v96, v65, v141
	v_fmac_f32_e32 v97, v33, v142
	s_waitcnt vmcnt(16)
	v_fmac_f32_e32 v98, v34, v141
	v_fmac_f32_e32 v99, v2, v142
	v_fmac_f32_e32 v100, v35, v141
	v_fmac_f32_e32 v101, v3, v142
	v_fmac_f32_e32 v102, v36, v141
	v_fmac_f32_e32 v103, v4, v142
	v_fmac_f32_e32 v104, v37, v141
	v_fmac_f32_e32 v105, v5, v142
	v_fmac_f32_e32 v106, v38, v141
	v_fmac_f32_e32 v107, v6, v142
	v_fmac_f32_e32 v108, v39, v141
	v_fmac_f32_e32 v109, v7, v142
	v_fmac_f32_e32 v110, v40, v141
	v_fmac_f32_e32 v111, v8, v142
	v_fmac_f32_e32 v112, v41, v141
	v_fmac_f32_e32 v113, v9, v142
	s_waitcnt vmcnt(0)
	v_fmac_f32_e32 v114, v42, v141
	v_fmac_f32_e32 v115, v10, v142
	v_fmac_f32_e32 v116, v43, v141
	v_fmac_f32_e32 v117, v11, v142
	v_fmac_f32_e32 v118, v44, v141
	v_fmac_f32_e32 v119, v12, v142
	v_fmac_f32_e32 v120, v45, v141
	v_fmac_f32_e32 v121, v13, v142
	v_fmac_f32_e32 v122, v46, v141
	v_fmac_f32_e32 v123, v14, v142
	v_fmac_f32_e32 v124, v47, v141
	v_fmac_f32_e32 v134, v15, v142
	v_fmac_f32_e32 v135, v48, v141
	v_fmac_f32_e32 v136, v16, v142
	v_fmac_f32_e32 v137, v49, v141
	v_fmac_f32_e32 v138, v17, v142
	s_and_b64 s[64:65], s[48:49], exec
	s_cselect_b32 s64, s8, s24
	s_cselect_b32 s65, s9, s25
	s_add_u32 s54, s64, s56
	s_addc_u32 s55, s65, 0
	s_mov_b64 s[52:53], s[54:55]
	global_store_dword v139, v66, s[52:53]
	global_store_dword v139, v67, s[52:53] offset:128
	s_add_u32 s52, s52, 4096
	s_addc_u32 s53, s53, 0
	global_store_dword v139, v68, s[52:53]
	global_store_dword v139, v69, s[52:53] offset:128
	s_add_u32 s52, s52, 4096
	s_addc_u32 s53, s53, 0
	global_store_dword v139, v70, s[52:53]
	global_store_dword v139, v71, s[52:53] offset:128
	s_add_u32 s52, s52, 4096
	s_addc_u32 s53, s53, 0
	global_store_dword v139, v72, s[52:53]
	global_store_dword v139, v73, s[52:53] offset:128
	s_add_u32 s52, s52, 20480
	s_addc_u32 s53, s53, 0
	global_store_dword v139, v74, s[52:53]
	global_store_dword v139, v75, s[52:53] offset:128
	s_add_u32 s52, s52, 4096
	s_addc_u32 s53, s53, 0
	global_store_dword v139, v76, s[52:53]
	global_store_dword v139, v77, s[52:53] offset:128
	s_add_u32 s52, s52, 4096
	s_addc_u32 s53, s53, 0
	global_store_dword v139, v78, s[52:53]
	global_store_dword v139, v79, s[52:53] offset:128
	s_add_u32 s52, s52, 4096
	s_addc_u32 s53, s53, 0
	global_store_dword v139, v80, s[52:53]
	global_store_dword v139, v81, s[52:53] offset:128
	s_add_u32 s52, s52, 20480
	s_addc_u32 s53, s53, 0
	global_store_dword v139, v82, s[52:53]
	global_store_dword v139, v83, s[52:53] offset:128
	s_add_u32 s52, s52, 4096
	s_addc_u32 s53, s53, 0
	global_store_dword v139, v84, s[52:53]
	global_store_dword v139, v85, s[52:53] offset:128
	s_add_u32 s52, s52, 4096
	s_addc_u32 s53, s53, 0
	global_store_dword v139, v86, s[52:53]
	global_store_dword v139, v87, s[52:53] offset:128
	s_add_u32 s52, s52, 4096
	s_addc_u32 s53, s53, 0
	global_store_dword v139, v88, s[52:53]
	global_store_dword v139, v89, s[52:53] offset:128
	s_add_u32 s52, s52, 20480
	s_addc_u32 s53, s53, 0
	global_store_dword v139, v90, s[52:53]
	global_store_dword v139, v91, s[52:53] offset:128
	s_add_u32 s52, s52, 4096
	s_addc_u32 s53, s53, 0
	global_store_dword v139, v92, s[52:53]
	global_store_dword v139, v93, s[52:53] offset:128
	s_add_u32 s52, s52, 4096
	s_addc_u32 s53, s53, 0
	global_store_dword v139, v94, s[52:53]
	global_store_dword v139, v95, s[52:53] offset:128
	s_add_u32 s52, s52, 4096
	s_addc_u32 s53, s53, 0
	global_store_dword v139, v96, s[52:53]
	global_store_dword v139, v97, s[52:53] offset:128
	s_add_u32 s52, s52, 20480
	s_addc_u32 s53, s53, 0
	global_store_dword v139, v98, s[52:53]
	global_store_dword v139, v99, s[52:53] offset:128
	s_add_u32 s52, s52, 4096
	s_addc_u32 s53, s53, 0
	global_store_dword v139, v100, s[52:53]
	global_store_dword v139, v101, s[52:53] offset:128
	s_add_u32 s52, s52, 4096
	s_addc_u32 s53, s53, 0
	global_store_dword v139, v102, s[52:53]
	global_store_dword v139, v103, s[52:53] offset:128
	s_add_u32 s52, s52, 4096
	s_addc_u32 s53, s53, 0
	global_store_dword v139, v104, s[52:53]
	global_store_dword v139, v105, s[52:53] offset:128
	s_add_u32 s52, s52, 20480
	s_addc_u32 s53, s53, 0
	global_store_dword v139, v106, s[52:53]
	global_store_dword v139, v107, s[52:53] offset:128
	s_add_u32 s52, s52, 4096
	s_addc_u32 s53, s53, 0
	global_store_dword v139, v108, s[52:53]
	global_store_dword v139, v109, s[52:53] offset:128
	s_add_u32 s52, s52, 4096
	s_addc_u32 s53, s53, 0
	global_store_dword v139, v110, s[52:53]
	global_store_dword v139, v111, s[52:53] offset:128
	s_add_u32 s52, s52, 4096
	s_addc_u32 s53, s53, 0
	global_store_dword v139, v112, s[52:53]
	global_store_dword v139, v113, s[52:53] offset:128
	s_add_u32 s52, s52, 20480
	s_addc_u32 s53, s53, 0
	global_store_dword v139, v114, s[52:53]
	global_store_dword v139, v115, s[52:53] offset:128
	s_add_u32 s52, s52, 4096
	s_addc_u32 s53, s53, 0
	global_store_dword v139, v116, s[52:53]
	global_store_dword v139, v117, s[52:53] offset:128
	s_add_u32 s52, s52, 4096
	s_addc_u32 s53, s53, 0
	global_store_dword v139, v118, s[52:53]
	global_store_dword v139, v119, s[52:53] offset:128
	s_add_u32 s52, s52, 4096
	s_addc_u32 s53, s53, 0
	global_store_dword v139, v120, s[52:53]
	global_store_dword v139, v121, s[52:53] offset:128
	s_add_u32 s52, s52, 20480
	s_addc_u32 s53, s53, 0
	global_store_dword v139, v122, s[52:53]
	global_store_dword v139, v123, s[52:53] offset:128
	s_add_u32 s52, s52, 4096
	s_addc_u32 s53, s53, 0
	global_store_dword v139, v124, s[52:53]
	global_store_dword v139, v134, s[52:53] offset:128
	s_add_u32 s52, s52, 4096
	s_addc_u32 s53, s53, 0
	global_store_dword v139, v135, s[52:53]
	global_store_dword v139, v136, s[52:53] offset:128
	s_add_u32 s52, s52, 4096
	s_addc_u32 s53, s53, 0
	global_store_dword v139, v137, s[52:53]
	global_store_dword v139, v138, s[52:53] offset:128
	v_readlane_b32 s14, v243, 7
	s_branch .LBB0_1262

; #define MFMA(a, b, c) __builtin_amdgcn_mfma_f32_32x32x16_bf16((a), (b), (c), 0, 0, 0)
; #define GAS __attribute__((address_space(1)))
; DI int opaque0() { int z = 0; asm volatile("" : "+v"(z)); return z; }
; template <int AI, int BI>
; DI void gemm_tile(const u16* __restrict__ A, int lda, const u16* __restrict__ B, int ldb, int nk, bool swap,
;                   f32x16 (&acc)[AI][BI], char* lds) {
;     ...
;   for (int kt = 0; kt < nk; ++kt) {
;     const char* cur = lds + (kt & 1) * 32768;
;     if (kt + 1 < nk) gemm_stage<AI, BI>(A + (kt + 1) * 64, lda, B + (kt + 1) * 64, ldb, lds + ((kt + 1) & 1) * 32768, tid);
; #pragma unroll
;     for (int ks = 0; ks < 4; ++ks) {
;       const int co = ((ks * 2 + h) ^ sw) << 4;
;       s16x8 fa[AI], fb[BI];
; #pragma unroll
;       for (int i = 0; i < AI; ++i) fa[i] = *(const s16x8*)(cur + offA + i * 4096 + co);
; #pragma unroll
;       for (int i = 0; i < BI; ++i) fb[i] = *(const s16x8*)(cur + offB + i * 4096 + co);
; #pragma unroll
;       for (int i = 0; i < AI; ++i)
; #pragma unroll
;         for (int j = 0; j < BI; ++j) acc[i][j] = MFMA(fa[i], fb[j], acc[i][j]);
;     }
;     asm volatile("s_waitcnt vmcnt(0)" ::: "memory");
;     __syncthreads();
;   }
; template <int AI, int BI>
; DI void dn_tile(const Params& p, char* wsb, int layer, int sub, bool final_out, int m0, int n0, char* lds) {
;     ...
;   const int m0e = m0 + opaque0();
;   const int mr = m0 < TL ? (m0 >> 11) : 8;
;   const float* gate = mods + (size_t)mr * 9216 + (2 + 6 * sub) * 1024;
;   GAS float* xsu = uptr(xs);
;   GAS float* outu = uptr(p.out);
; #pragma unroll
;   for (int bi = 0; bi < BI; ++bi) {
;     const int n = n0 + wb * 32 * BI + bi * 32 + r;
;     const float gv = 0.5f * gate[n];
;     const unsigned ib = (unsigned)((m0e + wa * 32 * AI + 4 * h) * 1024 + n);
; #pragma unroll
;     for (int ai = 0; ai < AI; ++ai)
; #pragma unroll
;       for (int reg = 0; reg < 16; ++reg) {
;         const unsigned idx = ib + (unsigned)((ai * 32 + (reg & 3) + 8 * (reg >> 2)) * 1024);
;         float v = xsu[idx] + gv * acc[ai][bi][reg];
;         if (final_out) outu[idx] = v; else xsu[idx] = v;
;         if ((reg & 7) == 7) __builtin_amdgcn_sched_barrier(0);
;       }
;   }
.LBB0_1525:
	s_add_i32 s40, s37, 0xffff8000
	s_and_b32 s41, s40, 0x8000
	s_and_b32 s40, s37, 0x8000
	v_add_u32_e32 v35, s40, v28
	v_add_u32_e32 v38, s40, v29
	v_readfirstlane_b32 s46, v35
	v_lshl_add_u64 v[36:37], v[18:19], 0, s[12:13]
	s_mov_b32 m0, s46
	v_readfirstlane_b32 s46, v38
	v_add_u32_e32 v35, 0x4000, v35
	global_load_lds_dwordx4 v[36:37], off
	v_lshl_add_u64 v[36:37], v[20:21], 0, s[12:13]
	s_mov_b32 m0, s46
	v_readfirstlane_b32 s46, v35
	v_add_u32_e32 v35, 0x4000, v38
	global_load_lds_dwordx4 v[36:37], off
	v_lshl_add_u64 v[36:37], v[22:23], 0, s[12:13]
	s_mov_b32 m0, s46
	v_readfirstlane_b32 s46, v35
	global_load_lds_dwordx4 v[36:37], off
	v_lshl_add_u64 v[36:37], v[24:25], 0, s[12:13]
	s_mov_b32 m0, s46
	v_add_u32_e32 v35, s41, v33
	global_load_lds_dwordx4 v[36:37], off
	v_add_u32_e32 v36, v35, v32
	ds_read_b128 v[36:39], v36
	v_or_b32_e32 v44, s41, v34
	v_add_u32_e32 v40, v44, v32
	ds_read_b128 v[40:43], v40 offset:16384
	s_add_u32 s12, s12, 0x80
	s_waitcnt lgkmcnt(0)
	v_mfma_f32_32x32x16_bf16 v[2:17], v[36:39], v[40:43], v[2:17]
	v_add_u32_e32 v36, v35, v31
	ds_read_b128 v[36:39], v36
	v_add_u32_e32 v40, v44, v31
	ds_read_b128 v[40:43], v40 offset:16384
	s_addc_u32 s13, s13, 0
	s_add_i32 s37, s37, 0x8000
	s_cmpk_eq_i32 s12, 0x1580
	s_waitcnt lgkmcnt(0)
	v_mfma_f32_32x32x16_bf16 v[2:17], v[36:39], v[40:43], v[2:17]
	v_add_u32_e32 v36, v35, v30
	ds_read_b128 v[36:39], v36
	v_add_u32_e32 v40, v44, v30
	ds_read_b128 v[40:43], v40 offset:16384
	v_add_u32_e32 v35, v35, v0
	s_waitcnt lgkmcnt(0)
	v_mfma_f32_32x32x16_bf16 v[2:17], v[36:39], v[40:43], v[2:17]
	ds_read_b128 v[36:39], v35
	v_add_u32_e32 v35, v44, v0
	ds_read_b128 v[40:43], v35 offset:16384
	s_waitcnt lgkmcnt(0)
	v_mfma_f32_32x32x16_bf16 v[2:17], v[36:39], v[40:43], v[2:17]
	s_waitcnt vmcnt(0)
	s_barrier
	s_cbranch_scc0 .LBB0_1525
	v_add_u32_e32 v29, s40, v33
	v_add_u32_e32 v18, v29, v32
	ds_read_b128 v[18:21], v18
	v_add_u32_e32 v33, s40, v34
	v_add_u32_e32 v22, v33, v32
	ds_read_b128 v[22:25], v22 offset:16384
	v_and_b32_e32 v28, 31, v26
	s_waitcnt lgkmcnt(0)
	v_mfma_f32_32x32x16_bf16 v[2:17], v[18:21], v[22:25], v[2:17]
	v_add_u32_e32 v18, v29, v31
	ds_read_b128 v[18:21], v18
	v_add_u32_e32 v22, v33, v31
	ds_read_b128 v[22:25], v22 offset:16384
	s_waitcnt lgkmcnt(0)
	v_mfma_f32_32x32x16_bf16 v[2:17], v[18:21], v[22:25], v[2:17]
	v_add_u32_e32 v18, v29, v30
	ds_read_b128 v[18:21], v18
	v_add_u32_e32 v22, v33, v30
	ds_read_b128 v[22:25], v22 offset:16384
	s_waitcnt lgkmcnt(0)
	v_mfma_f32_32x32x16_bf16 v[2:17], v[18:21], v[22:25], v[2:17]
	v_add_u32_e32 v18, v29, v0
	ds_read_b128 v[18:21], v18
	v_add_u32_e32 v0, v33, v0
	ds_read_b128 v[22:25], v0 offset:16384
	v_mov_b32_e32 v0, v1
	s_waitcnt vmcnt(0)
	s_waitcnt lgkmcnt(0)
	v_mfma_f32_32x32x16_bf16 v[2:17], v[18:21], v[22:25], v[2:17]
	v_lshrrev_b32_e32 v18, 1, v27
	v_and_b32_e32 v18, 32, v18
	v_or3_b32 v18, v28, v18, s36
	v_lshlrev_b32_e32 v19, 2, v18
	s_barrier
	global_load_dword v19, v19, s[6:7]
	v_lshrrev_b32_e32 v20, 2, v27
	v_lshrrev_b32_e32 v21, 3, v26
	v_and_b32_e32 v20, 0x3fffe0, v20
	v_and_or_b32 v21, v21, 4, s35
	v_add3_u32 v0, v21, v20, v0
	v_lshl_or_b32 v0, v0, 10, v18
	s_waitcnt vmcnt(0)
	v_mul_f32_e32 v20, 0.5, v19
	v_lshl_add_u64 v[18:19], v[0:1], 2, s[8:9]
	global_load_dword v21, v[18:19], off
	s_waitcnt vmcnt(0)
	v_fmac_f32_e32 v21, v2, v20
	global_store_dword v[18:19], v21, off
	v_add_u32_e32 v18, 0x400, v0
	v_mov_b32_e32 v19, v1
	v_lshl_add_u64 v[18:19], v[18:19], 2, s[8:9]
	global_load_dword v2, v[18:19], off
	s_waitcnt vmcnt(0)
	v_fmac_f32_e32 v2, v3, v20
	global_store_dword v[18:19], v2, off
	v_add_u32_e32 v2, 0x800, v0
	v_mov_b32_e32 v3, v1
	v_lshl_add_u64 v[2:3], v[2:3], 2, s[8:9]
	global_load_dword v18, v[2:3], off
	s_waitcnt vmcnt(0)
	v_fmac_f32_e32 v18, v4, v20
	global_store_dword v[2:3], v18, off
	v_add_u32_e32 v2, 0xc00, v0
	v_mov_b32_e32 v3, v1
	v_lshl_add_u64 v[2:3], v[2:3], 2, s[8:9]
	global_load_dword v4, v[2:3], off
	s_waitcnt vmcnt(0)
	v_fmac_f32_e32 v4, v5, v20
	global_store_dword v[2:3], v4, off
	v_add_u32_e32 v2, 0x2000, v0
	v_mov_b32_e32 v3, v1
	v_lshl_add_u64 v[2:3], v[2:3], 2, s[8:9]
	global_load_dword v4, v[2:3], off
	s_waitcnt vmcnt(0)
	v_fmac_f32_e32 v4, v6, v20
	global_store_dword v[2:3], v4, off
	v_add_u32_e32 v2, 0x2400, v0
	v_mov_b32_e32 v3, v1
	v_lshl_add_u64 v[2:3], v[2:3], 2, s[8:9]
	global_load_dword v4, v[2:3], off
	s_waitcnt vmcnt(0)
	v_fmac_f32_e32 v4, v7, v20
	global_store_dword v[2:3], v4, off
	v_add_u32_e32 v2, 0x2800, v0
	v_mov_b32_e32 v3, v1
	v_lshl_add_u64 v[2:3], v[2:3], 2, s[8:9]
	global_load_dword v4, v[2:3], off
	s_waitcnt vmcnt(0)
	v_fmac_f32_e32 v4, v8, v20
	global_store_dword v[2:3], v4, off
	v_add_u32_e32 v2, 0x2c00, v0
	v_mov_b32_e32 v3, v1
	v_lshl_add_u64 v[2:3], v[2:3], 2, s[8:9]
	global_load_dword v4, v[2:3], off
	s_waitcnt vmcnt(0)
	v_fmac_f32_e32 v4, v9, v20
	global_store_dword v[2:3], v4, off
	v_add_u32_e32 v2, 0x4000, v0
	v_mov_b32_e32 v3, v1
	v_lshl_add_u64 v[2:3], v[2:3], 2, s[8:9]
	global_load_dword v4, v[2:3], off
	s_waitcnt vmcnt(0)
	v_fmac_f32_e32 v4, v10, v20
	global_store_dword v[2:3], v4, off
	v_add_u32_e32 v2, 0x4400, v0
	v_mov_b32_e32 v3, v1
	v_lshl_add_u64 v[2:3], v[2:3], 2, s[8:9]
	global_load_dword v4, v[2:3], off
	s_waitcnt vmcnt(0)
	v_fmac_f32_e32 v4, v11, v20
	global_store_dword v[2:3], v4, off
	v_add_u32_e32 v2, 0x4800, v0
	v_mov_b32_e32 v3, v1
	v_lshl_add_u64 v[2:3], v[2:3], 2, s[8:9]
	global_load_dword v4, v[2:3], off
	s_waitcnt vmcnt(0)
	v_fmac_f32_e32 v4, v12, v20
	global_store_dword v[2:3], v4, off
	v_add_u32_e32 v2, 0x4c00, v0
	v_mov_b32_e32 v3, v1
	v_lshl_add_u64 v[2:3], v[2:3], 2, s[8:9]
	global_load_dword v4, v[2:3], off
	s_waitcnt vmcnt(0)
	v_fmac_f32_e32 v4, v13, v20
	global_store_dword v[2:3], v4, off
	v_add_u32_e32 v2, 0x6000, v0
	v_mov_b32_e32 v3, v1
	v_lshl_add_u64 v[2:3], v[2:3], 2, s[8:9]
	global_load_dword v4, v[2:3], off
	s_waitcnt vmcnt(0)
	v_fmac_f32_e32 v4, v14, v20
	global_store_dword v[2:3], v4, off
	v_add_u32_e32 v2, 0x6400, v0
	v_mov_b32_e32 v3, v1
	v_lshl_add_u64 v[2:3], v[2:3], 2, s[8:9]
	global_load_dword v4, v[2:3], off
	s_waitcnt vmcnt(0)
	v_fmac_f32_e32 v4, v15, v20
	global_store_dword v[2:3], v4, off
	v_add_u32_e32 v2, 0x6800, v0
	v_mov_b32_e32 v3, v1
	v_lshl_add_u64 v[2:3], v[2:3], 2, s[8:9]
	global_load_dword v4, v[2:3], off
	v_add_u32_e32 v0, 0x6c00, v0
	s_waitcnt vmcnt(0)
	v_fmac_f32_e32 v4, v16, v20
	global_store_dword v[2:3], v4, off
	v_lshl_add_u64 v[2:3], v[0:1], 2, s[8:9]
	global_load_dword v0, v[2:3], off
	s_waitcnt vmcnt(0)
	v_fmac_f32_e32 v0, v17, v20
	global_store_dword v[2:3], v0, off
	v_readlane_b32 s12, v243, 7
	s_add_i32 s34, s34, s12
	v_readlane_b32 s12, v243, 20
	s_add_i32 s29, s29, s12
	s_cmpk_gt_u32 s34, 0x1ff
	s_cbranch_scc0 .LBB0_1524
